# speedup vs baseline: 1.0845x; 1.0044x over previous
; #define STAGE_A(P,br,kt) STAGE_G(P,c.A,c.lda,br,(long)(kt)*c.kstr)
; #define STAGE_B(P,br,kt) STAGE_G(P,c.Bt,c.K,br,(long)(kt)*BK)
; #define LDA(dst,b,h) for(int m=0;m<4;++m)for(int k=0;k<2;++k) \
;     dst[m][k]=*reinterpret_cast<const bf16x8*>((char*)SA(b,h)+lds_byte(wr*64+m*16+fr,k*32+fq*8))
; #define LDB(dst,b,h) for(int n=0;n<2;++n)for(int k=0;k<2;++k) \
;     dst[n][k]=*reinterpret_cast<const bf16x8*>((char*)SB(b,h)+lds_byte(wc*32+n*16+fr,k*32+fq*8))
; #define MMA(ai,bj,At,Bt_) do{__builtin_amdgcn_s_setprio(1); \
;     for(int m=0;m<4;++m)for(int n=0;n<2;++n)for(int k=0;k<2;++k) \
;       acc[ai][bj][m][n]=__builtin_amdgcn_mfma_f32_16x16x32_bf16(Bt_[n][k],At[m][k],acc[ai][bj][m][n],0,0,0); \
;     __builtin_amdgcn_s_setprio(0);}while(0)
; #define WAIT_L(n) asm volatile("s_waitcnt lgkmcnt(" #n ")":::"memory")
; #define BAR __builtin_amdgcn_s_barrier()
; #define SCHED __builtin_amdgcn_sched_barrier(0)
; template <int EPI>
; __device__ __forceinline__ void gemm_run(const GD& c, const bool has_next, const GD& nx, const Ctx& e, bf16* shm, float* rs, float* rs_nxt, float* racc_) {
;     ...
;   for(int t=0;t<nt-2;t+=2){
;     LDB(B0,0,0); SCHED; LDA(At,0,0); STAGE_A(SA(1,1),brow+HALF,t+1);
;     WAIT_L(8); BAR; WAIT_L(0); MMA(0,0,At,B0); BAR; SCHED;
;     LDB(B1,0,1); STAGE_B(SB(0,0),bcol,t+2);
;     BAR; WAIT_L(0); MMA(0,1,At,B1); BAR;
;     LDA(At,0,1); STAGE_A(SA(0,0),brow,t+2);
;     BAR; WAIT_L(0); MMA(1,0,At,B0); BAR; SCHED;
.LBB0_267:
	ds_read_b128 v[158:161], v154
	ds_read_b128 v[166:169], v154 offset:1024
	ds_read_b128 v[170:173], v154 offset:2048
	ds_read_b128 v[190:193], v154 offset:3072
	v_add_u32_e32 v162, 0xc000, v141
	v_lshl_add_u64 v[174:175], s[4:5], 0, v[130:131]
	v_readfirstlane_b32 s3, v162
	v_add_u32_e32 v163, 0xe000, v141
	v_lshl_add_u64 v[156:157], v[174:175], 0, s[94:95]
	s_mov_b32 m0, s3
	v_lshl_add_u64 v[186:187], s[4:5], 0, v[132:133]
	v_readfirstlane_b32 s3, v163
	ds_read_b128 v[194:197], v145
	ds_read_b128 v[198:201], v145 offset:1024
	ds_read_b128 v[202:205], v144
	ds_read_b128 v[206:209], v144 offset:1024
	ds_read_b128 v[210:213], v143
	ds_read_b128 v[214:217], v143 offset:1024
	ds_read_b128 v[218:221], v142
	ds_read_b128 v[222:225], v142 offset:1024
	global_load_lds_dwordx4 v[156:157], off
	v_lshl_add_u64 v[156:157], v[186:187], 0, s[94:95]
	s_mov_b32 m0, s3
	s_nop 0
	global_load_lds_dwordx4 v[156:157], off
	s_waitcnt lgkmcnt(8)
	s_barrier
	s_waitcnt lgkmcnt(0)
	v_mfma_f32_16x16x32_bf16 v[126:129], v[158:161], v[194:197], v[126:129]
	v_mfma_f32_16x16x32_bf16 v[122:125], v[170:173], v[194:197], v[122:125]
	v_mfma_f32_16x16x32_bf16 v[118:121], v[158:161], v[202:205], v[118:121]
	v_mfma_f32_16x16x32_bf16 v[114:117], v[170:173], v[202:205], v[114:117]
	v_mfma_f32_16x16x32_bf16 v[110:113], v[158:161], v[210:213], v[110:113]
	v_mfma_f32_16x16x32_bf16 v[106:109], v[170:173], v[210:213], v[106:109]
	v_mfma_f32_16x16x32_bf16 v[102:105], v[158:161], v[218:221], v[102:105]
	v_mfma_f32_16x16x32_bf16 v[98:101], v[170:173], v[218:221], v[98:101]
	v_mfma_f32_16x16x32_bf16 v[126:129], v[166:169], v[198:201], v[126:129]
	v_mfma_f32_16x16x32_bf16 v[122:125], v[190:193], v[198:201], v[122:125]
	v_mfma_f32_16x16x32_bf16 v[118:121], v[166:169], v[206:209], v[118:121]
	v_mfma_f32_16x16x32_bf16 v[114:117], v[190:193], v[206:209], v[114:117]
	v_mfma_f32_16x16x32_bf16 v[110:113], v[166:169], v[214:217], v[110:113]
	v_mfma_f32_16x16x32_bf16 v[106:109], v[190:193], v[214:217], v[106:109]
	v_mfma_f32_16x16x32_bf16 v[102:105], v[166:169], v[222:225], v[102:105]
	v_mfma_f32_16x16x32_bf16 v[98:101], v[190:193], v[222:225], v[98:101]
	s_barrier
	v_add_u32_e32 v155, s33, v147
	v_lshl_add_u64 v[188:189], s[4:5], 0, v[136:137]
	v_readfirstlane_b32 s3, v155
	v_lshl_add_u64 v[156:157], v[188:189], 0, s[68:69]
	s_mov_b32 m0, s3
	ds_read_b128 v[226:229], v153
	ds_read_b128 v[230:233], v153 offset:1024
	ds_read_b128 v[234:237], v153 offset:2048
	ds_read_b128 v[238:241], v153 offset:3072
	global_load_lds_dwordx4 v[156:157], off
	v_add_u32_e32 v156, 0x2000, v155
	v_lshl_add_u64 v[246:247], s[4:5], 0, v[138:139]
	v_readfirstlane_b32 s3, v156
	v_lshl_add_u64 v[242:243], v[246:247], 0, s[68:69]
	s_mov_b32 m0, s3
	s_nop 0
	global_load_lds_dwordx4 v[242:243], off
	s_barrier
	s_waitcnt lgkmcnt(0)
	v_mfma_f32_16x16x32_bf16 v[94:97], v[226:229], v[194:197], v[94:97]
	v_mfma_f32_16x16x32_bf16 v[90:93], v[234:237], v[194:197], v[90:93]
	v_mfma_f32_16x16x32_bf16 v[86:89], v[226:229], v[202:205], v[86:89]
	v_mfma_f32_16x16x32_bf16 v[82:85], v[234:237], v[202:205], v[82:85]
	v_readfirstlane_b32 s3, v141
	v_mfma_f32_16x16x32_bf16 v[78:81], v[226:229], v[210:213], v[78:81]
	v_add_u32_e32 v157, 0x2000, v141
	v_mfma_f32_16x16x32_bf16 v[74:77], v[234:237], v[210:213], v[74:77]
	v_lshl_add_u64 v[242:243], v[174:175], 0, s[84:85]
	v_mfma_f32_16x16x32_bf16 v[70:73], v[226:229], v[218:221], v[70:73]
	s_mov_b32 m0, s3
	v_mfma_f32_16x16x32_bf16 v[66:69], v[234:237], v[218:221], v[66:69]
	v_readfirstlane_b32 s3, v157
	v_mfma_f32_16x16x32_bf16 v[94:97], v[230:233], v[198:201], v[94:97]
	v_mfma_f32_16x16x32_bf16 v[90:93], v[238:241], v[198:201], v[90:93]
	v_mfma_f32_16x16x32_bf16 v[86:89], v[230:233], v[206:209], v[86:89]
	v_mfma_f32_16x16x32_bf16 v[82:85], v[238:241], v[206:209], v[82:85]
	v_mfma_f32_16x16x32_bf16 v[78:81], v[230:233], v[214:217], v[78:81]
	v_mfma_f32_16x16x32_bf16 v[74:77], v[238:241], v[214:217], v[74:77]
	v_mfma_f32_16x16x32_bf16 v[70:73], v[230:233], v[222:225], v[70:73]
	v_mfma_f32_16x16x32_bf16 v[66:69], v[238:241], v[222:225], v[66:69]
	s_barrier
	ds_read_b128 v[194:197], v145 offset:16384
	ds_read_b128 v[198:201], v145 offset:17408
	ds_read_b128 v[202:205], v144 offset:16384
	ds_read_b128 v[206:209], v144 offset:17408
	ds_read_b128 v[210:213], v143 offset:16384
	ds_read_b128 v[214:217], v143 offset:17408
	ds_read_b128 v[218:221], v142 offset:16384
	ds_read_b128 v[222:225], v142 offset:17408
	global_load_lds_dwordx4 v[242:243], off
	v_lshl_add_u64 v[242:243], v[186:187], 0, s[84:85]
	s_mov_b32 m0, s3
	s_nop 0
	global_load_lds_dwordx4 v[242:243], off
	s_barrier
	s_waitcnt lgkmcnt(0)
	v_mfma_f32_16x16x32_bf16 v[62:65], v[158:161], v[194:197], v[62:65]
	v_mfma_f32_16x16x32_bf16 v[58:61], v[170:173], v[194:197], v[58:61]
	v_mfma_f32_16x16x32_bf16 v[54:57], v[158:161], v[202:205], v[54:57]
	v_mfma_f32_16x16x32_bf16 v[50:53], v[170:173], v[202:205], v[50:53]
	v_mfma_f32_16x16x32_bf16 v[46:49], v[158:161], v[210:213], v[46:49]
	v_mfma_f32_16x16x32_bf16 v[42:45], v[170:173], v[210:213], v[42:45]
	v_mfma_f32_16x16x32_bf16 v[38:41], v[158:161], v[218:221], v[38:41]
	v_mfma_f32_16x16x32_bf16 v[34:37], v[170:173], v[218:221], v[34:37]
	v_mfma_f32_16x16x32_bf16 v[62:65], v[166:169], v[198:201], v[62:65]
	v_mfma_f32_16x16x32_bf16 v[58:61], v[190:193], v[198:201], v[58:61]
	v_mfma_f32_16x16x32_bf16 v[54:57], v[166:169], v[206:209], v[54:57]
	v_mfma_f32_16x16x32_bf16 v[50:53], v[190:193], v[206:209], v[50:53]
	v_mfma_f32_16x16x32_bf16 v[46:49], v[166:169], v[214:217], v[46:49]
	v_mfma_f32_16x16x32_bf16 v[42:45], v[190:193], v[214:217], v[42:45]
	v_mfma_f32_16x16x32_bf16 v[38:41], v[166:169], v[222:225], v[38:41]
	v_mfma_f32_16x16x32_bf16 v[34:37], v[190:193], v[222:225], v[34:37]
	s_barrier
; #define STAGE_A(P,br,kt) STAGE_G(P,c.A,c.lda,br,(long)(kt)*c.kstr)
; #define STAGE_B(P,br,kt) STAGE_G(P,c.Bt,c.K,br,(long)(kt)*BK)
; #define LDA(dst,b,h) for(int m=0;m<4;++m)for(int k=0;k<2;++k) \
;     dst[m][k]=*reinterpret_cast<const bf16x8*>((char*)SA(b,h)+lds_byte(wr*64+m*16+fr,k*32+fq*8))
; #define LDB(dst,b,h) for(int n=0;n<2;++n)for(int k=0;k<2;++k) \
;     dst[n][k]=*reinterpret_cast<const bf16x8*>((char*)SB(b,h)+lds_byte(wc*32+n*16+fr,k*32+fq*8))
; #define MMA(ai,bj,At,Bt_) do{__builtin_amdgcn_s_setprio(1); \
;     for(int m=0;m<4;++m)for(int n=0;n<2;++n)for(int k=0;k<2;++k) \
;       acc[ai][bj][m][n]=__builtin_amdgcn_mfma_f32_16x16x32_bf16(Bt_[n][k],At[m][k],acc[ai][bj][m][n],0,0,0); \
;     __builtin_amdgcn_s_setprio(0);}while(0)
; #define WAIT_V(n) asm volatile("s_waitcnt vmcnt(" #n ")":::"memory")
; #define WAIT_L(n) asm volatile("s_waitcnt lgkmcnt(" #n ")":::"memory")
; #define BAR __builtin_amdgcn_s_barrier()
; #define SCHED __builtin_amdgcn_sched_barrier(0)
; template <int EPI>
; __device__ __forceinline__ void gemm_run(const GD& c, const bool has_next, const GD& nx, const Ctx& e, bf16* shm, float* rs, float* rs_nxt, float* racc_) {
;     ...
;     STAGE_B(SB(0,1),bcol+HALF,t+2);
;     WAIT_V(6); BAR; MMA(1,1,At,B1); BAR;
;     LDB(B0,1,0); SCHED; LDA(At,1,0); STAGE_A(SA(0,1),brow+HALF,t+2);
;     WAIT_L(8); BAR; WAIT_L(0); MMA(0,0,At,B0); BAR; SCHED;
;     LDB(B1,1,1); STAGE_B(SB(1,0),bcol,t+3);
;     BAR; WAIT_L(0); MMA(0,1,At,B1); BAR;
	v_add_u32_e32 v158, s86, v147
	v_add_u32_e32 v159, 0x2000, v158
	v_readfirstlane_b32 s3, v158
	v_lshl_add_u64 v[160:161], v[188:189], 0, s[14:15]
	s_mov_b32 m0, s3
	v_readfirstlane_b32 s3, v159
	global_load_lds_dwordx4 v[160:161], off
	v_lshl_add_u64 v[160:161], v[246:247], 0, s[14:15]
	s_mov_b32 m0, s3
	s_nop 0
	global_load_lds_dwordx4 v[160:161], off
	s_waitcnt vmcnt(6)
	s_barrier
	v_mfma_f32_16x16x32_bf16 v[30:33], v[226:229], v[194:197], v[30:33]
	v_mfma_f32_16x16x32_bf16 v[26:29], v[234:237], v[194:197], v[26:29]
	v_mfma_f32_16x16x32_bf16 v[22:25], v[226:229], v[202:205], v[22:25]
	v_mfma_f32_16x16x32_bf16 v[18:21], v[234:237], v[202:205], v[18:21]
	v_mfma_f32_16x16x32_bf16 v[14:17], v[226:229], v[210:213], v[14:17]
	v_mfma_f32_16x16x32_bf16 v[10:13], v[234:237], v[210:213], v[10:13]
	v_mfma_f32_16x16x32_bf16 v[6:9], v[226:229], v[218:221], v[6:9]
	v_mfma_f32_16x16x32_bf16 v[2:5], v[234:237], v[218:221], v[2:5]
	v_mfma_f32_16x16x32_bf16 v[30:33], v[230:233], v[198:201], v[30:33]
	v_mfma_f32_16x16x32_bf16 v[26:29], v[238:241], v[198:201], v[26:29]
	v_mfma_f32_16x16x32_bf16 v[22:25], v[230:233], v[206:209], v[22:25]
	v_mfma_f32_16x16x32_bf16 v[18:21], v[238:241], v[206:209], v[18:21]
	v_mfma_f32_16x16x32_bf16 v[14:17], v[230:233], v[214:217], v[14:17]
	v_mfma_f32_16x16x32_bf16 v[10:13], v[238:241], v[214:217], v[10:13]
	v_mfma_f32_16x16x32_bf16 v[6:9], v[230:233], v[222:225], v[6:9]
	v_mfma_f32_16x16x32_bf16 v[2:5], v[238:241], v[222:225], v[2:5]
	s_barrier
	ds_read_b128 v[166:169], v148
	ds_read_b128 v[170:173], v148 offset:1024
	ds_read_b128 v[190:193], v148 offset:2048
	ds_read_b128 v[194:197], v148 offset:3072
	v_add_u32_e32 v160, 0x4000, v141
	v_add_u32_e32 v161, 0x6000, v141
	v_readfirstlane_b32 s3, v160
	v_lshl_add_u64 v[230:231], v[174:175], 0, s[92:93]
	s_mov_b32 m0, s3
	v_readfirstlane_b32 s3, v161
	ds_read_b128 v[198:201], v145 offset:32768
	ds_read_b128 v[202:205], v145 offset:33792
	ds_read_b128 v[206:209], v144 offset:32768
	ds_read_b128 v[210:213], v144 offset:33792
	ds_read_b128 v[214:217], v143 offset:32768
	ds_read_b128 v[218:221], v143 offset:33792
	ds_read_b128 v[222:225], v142 offset:32768
	ds_read_b128 v[226:229], v142 offset:33792
	global_load_lds_dwordx4 v[230:231], off
	v_lshl_add_u64 v[230:231], v[186:187], 0, s[92:93]
	s_mov_b32 m0, s3
	s_nop 0
	global_load_lds_dwordx4 v[230:231], off
	s_waitcnt lgkmcnt(8)
	s_barrier
	s_waitcnt lgkmcnt(0)
	v_mfma_f32_16x16x32_bf16 v[126:129], v[166:169], v[198:201], v[126:129]
	v_mfma_f32_16x16x32_bf16 v[122:125], v[190:193], v[198:201], v[122:125]
	v_mfma_f32_16x16x32_bf16 v[118:121], v[166:169], v[206:209], v[118:121]
	v_mfma_f32_16x16x32_bf16 v[114:117], v[190:193], v[206:209], v[114:117]
	v_mfma_f32_16x16x32_bf16 v[110:113], v[166:169], v[214:217], v[110:113]
	v_mfma_f32_16x16x32_bf16 v[106:109], v[190:193], v[214:217], v[106:109]
	v_mfma_f32_16x16x32_bf16 v[102:105], v[166:169], v[222:225], v[102:105]
	v_mfma_f32_16x16x32_bf16 v[98:101], v[190:193], v[222:225], v[98:101]
	v_mfma_f32_16x16x32_bf16 v[126:129], v[170:173], v[202:205], v[126:129]
	v_mfma_f32_16x16x32_bf16 v[122:125], v[194:197], v[202:205], v[122:125]
	v_mfma_f32_16x16x32_bf16 v[118:121], v[170:173], v[210:213], v[118:121]
	v_mfma_f32_16x16x32_bf16 v[114:117], v[194:197], v[210:213], v[114:117]
	v_mfma_f32_16x16x32_bf16 v[110:113], v[170:173], v[218:221], v[110:113]
	v_mfma_f32_16x16x32_bf16 v[106:109], v[194:197], v[218:221], v[106:109]
	v_mfma_f32_16x16x32_bf16 v[102:105], v[170:173], v[226:229], v[102:105]
	v_mfma_f32_16x16x32_bf16 v[98:101], v[194:197], v[226:229], v[98:101]
	s_barrier
	v_readfirstlane_b32 s3, v149
	v_add_u32_e32 v176, 0x2000, v149
	v_lshl_add_u64 v[248:249], v[188:189], 0, s[26:27]
	s_mov_b32 m0, s3
	v_readfirstlane_b32 s3, v176
	ds_read_b128 v[230:233], v146
	ds_read_b128 v[234:237], v146 offset:1024
	ds_read_b128 v[238:241], v146 offset:2048
	ds_read_b128 v[242:245], v146 offset:3072
	global_load_lds_dwordx4 v[248:249], off
	v_lshl_add_u64 v[248:249], v[246:247], 0, s[26:27]
	s_mov_b32 m0, s3
	s_nop 0
	global_load_lds_dwordx4 v[248:249], off
	s_barrier
	s_waitcnt lgkmcnt(0)
	v_mfma_f32_16x16x32_bf16 v[94:97], v[230:233], v[198:201], v[94:97]
	v_mfma_f32_16x16x32_bf16 v[90:93], v[238:241], v[198:201], v[90:93]
	v_mfma_f32_16x16x32_bf16 v[86:89], v[230:233], v[206:209], v[86:89]
	v_mfma_f32_16x16x32_bf16 v[82:85], v[238:241], v[206:209], v[82:85]
	v_readfirstlane_b32 s3, v150
	v_mfma_f32_16x16x32_bf16 v[78:81], v[230:233], v[214:217], v[78:81]
	v_lshl_add_u64 v[174:175], v[174:175], 0, s[80:81]
	v_mfma_f32_16x16x32_bf16 v[74:77], v[238:241], v[214:217], v[74:77]
	s_mov_b32 m0, s3
	v_mfma_f32_16x16x32_bf16 v[70:73], v[230:233], v[222:225], v[70:73]
	v_readfirstlane_b32 s3, v151
	v_mfma_f32_16x16x32_bf16 v[66:69], v[238:241], v[222:225], v[66:69]
	v_mfma_f32_16x16x32_bf16 v[94:97], v[234:237], v[202:205], v[94:97]
	v_mfma_f32_16x16x32_bf16 v[90:93], v[242:245], v[202:205], v[90:93]
	v_mfma_f32_16x16x32_bf16 v[86:89], v[234:237], v[210:213], v[86:89]
	v_mfma_f32_16x16x32_bf16 v[82:85], v[242:245], v[210:213], v[82:85]
	v_mfma_f32_16x16x32_bf16 v[78:81], v[234:237], v[218:221], v[78:81]
	v_mfma_f32_16x16x32_bf16 v[74:77], v[242:245], v[218:221], v[74:77]
	v_mfma_f32_16x16x32_bf16 v[70:73], v[234:237], v[226:229], v[70:73]
	v_mfma_f32_16x16x32_bf16 v[66:69], v[242:245], v[226:229], v[66:69]
	s_barrier
	ds_read_b128 v[198:201], v145 offset:49152
	ds_read_b128 v[202:205], v145 offset:50176
	ds_read_b128 v[206:209], v144 offset:49152
	ds_read_b128 v[210:213], v144 offset:50176
	ds_read_b128 v[214:217], v143 offset:49152
	ds_read_b128 v[218:221], v143 offset:50176
	ds_read_b128 v[222:225], v142 offset:49152
	ds_read_b128 v[226:229], v142 offset:50176
	global_load_lds_dwordx4 v[174:175], off
	v_lshl_add_u64 v[174:175], v[186:187], 0, s[80:81]
	s_mov_b32 m0, s3
	s_nop 0
	global_load_lds_dwordx4 v[174:175], off
	s_barrier
; #define STAGE_A(P,br,kt) STAGE_G(P,c.A,c.lda,br,(long)(kt)*c.kstr)
; #define STAGE_B(P,br,kt) STAGE_G(P,c.Bt,c.K,br,(long)(kt)*BK)
; #define LDA(dst,b,h) for(int m=0;m<4;++m)for(int k=0;k<2;++k) \
;     dst[m][k]=*reinterpret_cast<const bf16x8*>((char*)SA(b,h)+lds_byte(wr*64+m*16+fr,k*32+fq*8))
; #define LDB(dst,b,h) for(int n=0;n<2;++n)for(int k=0;k<2;++k) \
;     dst[n][k]=*reinterpret_cast<const bf16x8*>((char*)SB(b,h)+lds_byte(wc*32+n*16+fr,k*32+fq*8))
; #define MMA(ai,bj,At,Bt_) do{__builtin_amdgcn_s_setprio(1); \
;     for(int m=0;m<4;++m)for(int n=0;n<2;++n)for(int k=0;k<2;++k) \
;       acc[ai][bj][m][n]=__builtin_amdgcn_mfma_f32_16x16x32_bf16(Bt_[n][k],At[m][k],acc[ai][bj][m][n],0,0,0); \
;     __builtin_amdgcn_s_setprio(0);}while(0)
; #define WAIT_V(n) asm volatile("s_waitcnt vmcnt(" #n ")":::"memory")
; #define WAIT_L(n) asm volatile("s_waitcnt lgkmcnt(" #n ")":::"memory")
; #define BAR __builtin_amdgcn_s_barrier()
; #define SCHED __builtin_amdgcn_sched_barrier(0)
; template <int EPI>
; __device__ __forceinline__ void gemm_run(const GD& c, const bool has_next, const GD& nx, const Ctx& e, bf16* shm, float* rs, float* rs_nxt, float* racc_) {
;     ...
;     LDA(At,1,1); STAGE_A(SA(1,0),brow,t+3);
;     BAR; WAIT_L(0); MMA(1,0,At,B0); BAR; SCHED;
;     STAGE_B(SB(1,1),bcol+HALF,t+3);
;     WAIT_V(6); BAR; MMA(1,1,At,B1); BAR;
;   }
;   { LDB(B0,0,0); LDA(At,0,0); STAGE_A(SA(1,1),brow+HALF,nt-1);
;     BAR; WAIT_L(0); MMA(0,0,At,B0); BAR;
;     LDB(B1,0,1); BAR; WAIT_L(0); MMA(0,1,At,B1); BAR;
	s_waitcnt lgkmcnt(0)
	v_mfma_f32_16x16x32_bf16 v[62:65], v[166:169], v[198:201], v[62:65]
	v_mfma_f32_16x16x32_bf16 v[58:61], v[190:193], v[198:201], v[58:61]
	v_mfma_f32_16x16x32_bf16 v[54:57], v[166:169], v[206:209], v[54:57]
	v_mfma_f32_16x16x32_bf16 v[50:53], v[190:193], v[206:209], v[50:53]
	v_mfma_f32_16x16x32_bf16 v[46:49], v[166:169], v[214:217], v[46:49]
	v_mfma_f32_16x16x32_bf16 v[42:45], v[190:193], v[214:217], v[42:45]
	v_mfma_f32_16x16x32_bf16 v[38:41], v[166:169], v[222:225], v[38:41]
	v_mfma_f32_16x16x32_bf16 v[34:37], v[190:193], v[222:225], v[34:37]
	v_mfma_f32_16x16x32_bf16 v[62:65], v[170:173], v[202:205], v[62:65]
	v_mfma_f32_16x16x32_bf16 v[58:61], v[194:197], v[202:205], v[58:61]
	v_mfma_f32_16x16x32_bf16 v[54:57], v[170:173], v[210:213], v[54:57]
	v_mfma_f32_16x16x32_bf16 v[50:53], v[194:197], v[210:213], v[50:53]
	v_mfma_f32_16x16x32_bf16 v[46:49], v[170:173], v[218:221], v[46:49]
	v_mfma_f32_16x16x32_bf16 v[42:45], v[194:197], v[218:221], v[42:45]
	v_mfma_f32_16x16x32_bf16 v[38:41], v[170:173], v[226:229], v[38:41]
	v_mfma_f32_16x16x32_bf16 v[34:37], v[194:197], v[226:229], v[34:37]
	s_barrier
	v_readfirstlane_b32 s3, v152
	v_add_u32_e32 v168, 0x2000, v152
	v_lshl_add_u64 v[166:167], v[188:189], 0, s[28:29]
	s_mov_b32 m0, s3
	v_readfirstlane_b32 s3, v168
	global_load_lds_dwordx4 v[166:167], off
	v_lshl_add_u64 v[166:167], v[246:247], 0, s[28:29]
	s_mov_b32 m0, s3
	s_nop 0
	global_load_lds_dwordx4 v[166:167], off
	s_waitcnt vmcnt(6)
	s_barrier
	v_mfma_f32_16x16x32_bf16 v[30:33], v[230:233], v[198:201], v[30:33]
	v_mfma_f32_16x16x32_bf16 v[26:29], v[238:241], v[198:201], v[26:29]
	v_mfma_f32_16x16x32_bf16 v[22:25], v[230:233], v[206:209], v[22:25]
	v_mfma_f32_16x16x32_bf16 v[18:21], v[238:241], v[206:209], v[18:21]
	s_add_i32 s2, s2, 2
	v_mfma_f32_16x16x32_bf16 v[14:17], v[230:233], v[214:217], v[14:17]
	v_lshl_add_u64 v[130:131], v[130:131], 0, s[88:89]
	v_mfma_f32_16x16x32_bf16 v[10:13], v[238:241], v[214:217], v[10:13]
	v_lshl_add_u64 v[132:133], v[132:133], 0, s[88:89]
	v_mfma_f32_16x16x32_bf16 v[6:9], v[230:233], v[222:225], v[6:9]
	v_lshl_add_u64 v[136:137], v[136:137], 0, s[88:89]
	v_mfma_f32_16x16x32_bf16 v[2:5], v[238:241], v[222:225], v[2:5]
	s_cmp_lt_u32 s2, 12
	v_mfma_f32_16x16x32_bf16 v[30:33], v[234:237], v[202:205], v[30:33]
	v_lshl_add_u64 v[138:139], v[138:139], 0, s[88:89]
	v_mfma_f32_16x16x32_bf16 v[26:29], v[242:245], v[202:205], v[26:29]
	v_mfma_f32_16x16x32_bf16 v[22:25], v[234:237], v[210:213], v[22:25]
	v_mfma_f32_16x16x32_bf16 v[18:21], v[242:245], v[210:213], v[18:21]
	v_mfma_f32_16x16x32_bf16 v[14:17], v[234:237], v[218:221], v[14:17]
	v_mfma_f32_16x16x32_bf16 v[10:13], v[242:245], v[218:221], v[10:13]
	v_mfma_f32_16x16x32_bf16 v[6:9], v[234:237], v[226:229], v[6:9]
	v_mfma_f32_16x16x32_bf16 v[2:5], v[242:245], v[226:229], v[2:5]
	s_barrier
	s_cbranch_scc1 .LBB0_267
	s_or_b32 s2, s10, 0x80
	s_ashr_i32 s3, s2, 31
	s_lshl_b64 s[2:3], s[2:3], 11
	s_add_u32 s2, s18, s2
	s_addc_u32 s3, s19, s3
	v_lshl_add_u64 v[150:151], s[2:3], 0, v[0:1]
	s_mov_b64 s[14:15], 0x780
	v_readfirstlane_b32 s11, v162
	v_lshl_add_u64 v[150:151], v[150:151], 0, s[14:15]
	s_mov_b32 m0, s11
	ds_read_b128 v[130:133], v154
	ds_read_b128 v[136:139], v154 offset:1024
	ds_read_b128 v[166:169], v154 offset:2048
	ds_read_b128 v[170:173], v154 offset:3072
	ds_read_b128 v[190:193], v145
	ds_read_b128 v[194:197], v145 offset:1024
	ds_read_b128 v[198:201], v144
	ds_read_b128 v[202:205], v144 offset:1024
	ds_read_b128 v[206:209], v143
	ds_read_b128 v[210:213], v143 offset:1024
	ds_read_b128 v[214:217], v142
	ds_read_b128 v[218:221], v142 offset:1024
	global_load_lds_dwordx4 v[150:151], off
	v_lshl_add_u64 v[150:151], s[2:3], 0, v[134:135]
	v_readfirstlane_b32 s2, v163
	v_lshl_add_u64 v[150:151], v[150:151], 0, s[14:15]
	s_mov_b32 m0, s2
	s_nop 0
	global_load_lds_dwordx4 v[150:151], off
	s_barrier
	s_waitcnt lgkmcnt(0)
	v_mfma_f32_16x16x32_bf16 v[126:129], v[130:133], v[190:193], v[126:129]
	v_mfma_f32_16x16x32_bf16 v[122:125], v[166:169], v[190:193], v[122:125]
	v_mfma_f32_16x16x32_bf16 v[118:121], v[130:133], v[198:201], v[118:121]
	v_mfma_f32_16x16x32_bf16 v[106:109], v[166:169], v[206:209], v[106:109]
	v_mfma_f32_16x16x32_bf16 v[102:105], v[130:133], v[214:217], v[102:105]
	v_mfma_f32_16x16x32_bf16 v[126:129], v[136:139], v[194:197], v[126:129]
	v_mfma_f32_16x16x32_bf16 v[122:125], v[170:173], v[194:197], v[122:125]
	v_mfma_f32_16x16x32_bf16 v[118:121], v[136:139], v[202:205], v[118:121]
	v_mfma_f32_16x16x32_bf16 v[114:117], v[166:169], v[198:201], v[114:117]
	v_mfma_f32_16x16x32_bf16 v[110:113], v[130:133], v[206:209], v[110:113]
	v_mfma_f32_16x16x32_bf16 v[106:109], v[170:173], v[210:213], v[106:109]
	v_mfma_f32_16x16x32_bf16 v[102:105], v[136:139], v[218:221], v[102:105]
	v_mfma_f32_16x16x32_bf16 v[98:101], v[166:169], v[214:217], v[98:101]
	v_mfma_f32_16x16x32_bf16 v[222:225], v[170:173], v[202:205], v[114:117]
	v_mfma_f32_16x16x32_bf16 v[226:229], v[136:139], v[210:213], v[110:113]
	v_mfma_f32_16x16x32_bf16 v[230:233], v[170:173], v[218:221], v[98:101]
	s_barrier
	s_nop 2
	ds_read_b128 v[98:101], v153
	ds_read_b128 v[110:113], v153 offset:1024
	ds_read_b128 v[114:117], v153 offset:2048
	ds_read_b128 v[150:153], v153 offset:3072
	s_barrier
; #define LDA(dst,b,h) for(int m=0;m<4;++m)for(int k=0;k<2;++k) \
;     dst[m][k]=*reinterpret_cast<const bf16x8*>((char*)SA(b,h)+lds_byte(wr*64+m*16+fr,k*32+fq*8))
; #define LDB(dst,b,h) for(int n=0;n<2;++n)for(int k=0;k<2;++k) \
;     dst[n][k]=*reinterpret_cast<const bf16x8*>((char*)SB(b,h)+lds_byte(wc*32+n*16+fr,k*32+fq*8))
; #define MMA(ai,bj,At,Bt_) do{__builtin_amdgcn_s_setprio(1); \
;     for(int m=0;m<4;++m)for(int n=0;n<2;++n)for(int k=0;k<2;++k) \
;       acc[ai][bj][m][n]=__builtin_amdgcn_mfma_f32_16x16x32_bf16(Bt_[n][k],At[m][k],acc[ai][bj][m][n],0,0,0); \
;     __builtin_amdgcn_s_setprio(0);}while(0)
; #define WAIT_V(n) asm volatile("s_waitcnt vmcnt(" #n ")":::"memory")
; #define WAIT_L(n) asm volatile("s_waitcnt lgkmcnt(" #n ")":::"memory")
; #define BAR __builtin_amdgcn_s_barrier()
; template <int EPI>
; __device__ __forceinline__ void gemm_run(const GD& c, const bool has_next, const GD& nx, const Ctx& e, bf16* shm, float* rs, float* rs_nxt, float* racc_) {
;     ...
;     LDB(B1,0,1); BAR; WAIT_L(0); MMA(0,1,At,B1); BAR;
;     LDA(At,0,1); WAIT_V(4); BAR; WAIT_L(0); MMA(1,0,At,B0); MMA(1,1,At,B1); BAR; }
;   { LDB(B0,1,0); LDA(At,1,0); WAIT_V(2); BAR; WAIT_L(0); MMA(0,0,At,B0); BAR;
	s_waitcnt lgkmcnt(0)
	v_mfma_f32_16x16x32_bf16 v[90:93], v[114:117], v[190:193], v[90:93]
	v_mfma_f32_16x16x32_bf16 v[86:89], v[98:101], v[198:201], v[86:89]
	v_mfma_f32_16x16x32_bf16 v[74:77], v[114:117], v[206:209], v[74:77]
	v_mfma_f32_16x16x32_bf16 v[70:73], v[98:101], v[214:217], v[70:73]
	v_mfma_f32_16x16x32_bf16 v[66:69], v[114:117], v[214:217], v[66:69]
	v_mfma_f32_16x16x32_bf16 v[94:97], v[98:101], v[190:193], v[94:97]
	v_mfma_f32_16x16x32_bf16 v[90:93], v[150:153], v[194:197], v[90:93]
	v_mfma_f32_16x16x32_bf16 v[86:89], v[110:113], v[202:205], v[86:89]
	v_mfma_f32_16x16x32_bf16 v[82:85], v[114:117], v[198:201], v[82:85]
	v_mfma_f32_16x16x32_bf16 v[78:81], v[98:101], v[206:209], v[78:81]
	v_mfma_f32_16x16x32_bf16 v[74:77], v[150:153], v[210:213], v[74:77]
	v_mfma_f32_16x16x32_bf16 v[70:73], v[110:113], v[218:221], v[70:73]
	v_mfma_f32_16x16x32_bf16 v[66:69], v[150:153], v[218:221], v[66:69]
	v_mfma_f32_16x16x32_bf16 v[234:237], v[110:113], v[194:197], v[94:97]
	v_mfma_f32_16x16x32_bf16 v[190:193], v[150:153], v[202:205], v[82:85]
	v_mfma_f32_16x16x32_bf16 v[194:197], v[110:113], v[210:213], v[78:81]
	s_barrier
	s_nop 0
	ds_read_b128 v[78:81], v145 offset:16384
	ds_read_b128 v[82:85], v145 offset:17408
	ds_read_b128 v[94:97], v144 offset:16384
	ds_read_b128 v[198:201], v144 offset:17408
	ds_read_b128 v[202:205], v143 offset:16384
	ds_read_b128 v[206:209], v143 offset:17408
	ds_read_b128 v[210:213], v142 offset:16384
	ds_read_b128 v[214:217], v142 offset:17408
	s_waitcnt vmcnt(4)
	s_barrier
	s_waitcnt lgkmcnt(0)
	v_mfma_f32_16x16x32_bf16 v[62:65], v[130:133], v[78:81], v[62:65]
	v_mfma_f32_16x16x32_bf16 v[58:61], v[166:169], v[78:81], v[58:61]
	v_mfma_f32_16x16x32_bf16 v[54:57], v[130:133], v[94:97], v[54:57]
	v_mfma_f32_16x16x32_bf16 v[42:45], v[166:169], v[202:205], v[42:45]
	v_mfma_f32_16x16x32_bf16 v[38:41], v[130:133], v[210:213], v[38:41]
	v_mfma_f32_16x16x32_bf16 v[62:65], v[136:139], v[82:85], v[62:65]
	v_mfma_f32_16x16x32_bf16 v[58:61], v[170:173], v[82:85], v[58:61]
	v_mfma_f32_16x16x32_bf16 v[54:57], v[136:139], v[198:201], v[54:57]
	v_mfma_f32_16x16x32_bf16 v[50:53], v[166:169], v[94:97], v[50:53]
	v_mfma_f32_16x16x32_bf16 v[46:49], v[130:133], v[202:205], v[46:49]
	v_mfma_f32_16x16x32_bf16 v[42:45], v[170:173], v[206:209], v[42:45]
	v_mfma_f32_16x16x32_bf16 v[38:41], v[136:139], v[214:217], v[38:41]
	v_mfma_f32_16x16x32_bf16 v[34:37], v[166:169], v[210:213], v[34:37]
	v_mfma_f32_16x16x32_bf16 v[218:221], v[170:173], v[198:201], v[50:53]
	v_mfma_f32_16x16x32_bf16 v[238:241], v[136:139], v[206:209], v[46:49]
	v_mfma_f32_16x16x32_bf16 v[136:139], v[170:173], v[214:217], v[34:37]
	v_mfma_f32_16x16x32_bf16 v[26:29], v[114:117], v[78:81], v[26:29]
	v_mfma_f32_16x16x32_bf16 v[22:25], v[98:101], v[94:97], v[22:25]
	v_mfma_f32_16x16x32_bf16 v[10:13], v[114:117], v[202:205], v[10:13]
	v_mfma_f32_16x16x32_bf16 v[6:9], v[98:101], v[210:213], v[6:9]
	v_mfma_f32_16x16x32_bf16 v[30:33], v[98:101], v[78:81], v[30:33]
	v_mfma_f32_16x16x32_bf16 v[26:29], v[150:153], v[82:85], v[26:29]
	v_mfma_f32_16x16x32_bf16 v[22:25], v[110:113], v[198:201], v[22:25]
	v_mfma_f32_16x16x32_bf16 v[18:21], v[114:117], v[94:97], v[18:21]
	v_mfma_f32_16x16x32_bf16 v[14:17], v[98:101], v[202:205], v[14:17]
	v_mfma_f32_16x16x32_bf16 v[10:13], v[150:153], v[206:209], v[10:13]
	v_mfma_f32_16x16x32_bf16 v[6:9], v[110:113], v[214:217], v[6:9]
	v_mfma_f32_16x16x32_bf16 v[2:5], v[114:117], v[210:213], v[2:5]
	v_mfma_f32_16x16x32_bf16 v[166:169], v[110:113], v[82:85], v[30:33]
	v_mfma_f32_16x16x32_bf16 v[170:173], v[150:153], v[198:201], v[18:21]
	v_mfma_f32_16x16x32_bf16 v[198:201], v[110:113], v[206:209], v[14:17]
	v_mfma_f32_16x16x32_bf16 v[2:5], v[150:153], v[214:217], v[2:5]
	s_barrier
	ds_read_b128 v[14:17], v148
	ds_read_b128 v[18:21], v148 offset:1024
	ds_read_b128 v[150:153], v148 offset:2048
	ds_read_b128 v[202:205], v148 offset:3072
	ds_read_b128 v[30:33], v145 offset:32768
	ds_read_b128 v[34:37], v145 offset:33792
	ds_read_b128 v[46:49], v144 offset:32768
	ds_read_b128 v[50:53], v144 offset:33792
	ds_read_b128 v[206:209], v143 offset:32768
	ds_read_b128 v[210:213], v143 offset:33792
	ds_read_b128 v[214:217], v142 offset:32768
	ds_read_b128 v[242:245], v142 offset:33792
	s_waitcnt vmcnt(2)
	s_barrier
; #define LDA(dst,b,h) for(int m=0;m<4;++m)for(int k=0;k<2;++k) \
;     dst[m][k]=*reinterpret_cast<const bf16x8*>((char*)SA(b,h)+lds_byte(wr*64+m*16+fr,k*32+fq*8))
; #define LDB(dst,b,h) for(int n=0;n<2;++n)for(int k=0;k<2;++k) \
;     dst[n][k]=*reinterpret_cast<const bf16x8*>((char*)SB(b,h)+lds_byte(wc*32+n*16+fr,k*32+fq*8))
; #define MMA(ai,bj,At,Bt_) do{__builtin_amdgcn_s_setprio(1); \
;     for(int m=0;m<4;++m)for(int n=0;n<2;++n)for(int k=0;k<2;++k) \
;       acc[ai][bj][m][n]=__builtin_amdgcn_mfma_f32_16x16x32_bf16(Bt_[n][k],At[m][k],acc[ai][bj][m][n],0,0,0); \
;     __builtin_amdgcn_s_setprio(0);}while(0)
; #define WAIT_V(n) asm volatile("s_waitcnt vmcnt(" #n ")":::"memory")
; #define WAIT_L(n) asm volatile("s_waitcnt lgkmcnt(" #n ")":::"memory")
; #define BAR __builtin_amdgcn_s_barrier()
; template <int EPI>
; __device__ __forceinline__ void gemm_run(const GD& c, const bool has_next, const GD& nx, const Ctx& e, bf16* shm, float* rs, float* rs_nxt, float* racc_) {
;     ...
;   { LDB(B0,1,0); LDA(At,1,0); WAIT_V(2); BAR; WAIT_L(0); MMA(0,0,At,B0); BAR;
;     LDB(B1,1,1); WAIT_V(0); BAR; WAIT_L(0); MMA(0,1,At,B1); BAR;
;     LDA(At,1,1); BAR; WAIT_L(0); MMA(1,0,At,B0); MMA(1,1,At,B1); BAR; }
;   if(wr==0)BAR;
	s_waitcnt lgkmcnt(0)
	v_mfma_f32_16x16x32_bf16 v[78:81], v[14:17], v[30:33], v[126:129]
	v_mfma_f32_16x16x32_bf16 v[130:133], v[18:21], v[34:37], v[78:81]
	v_mfma_f32_16x16x32_bf16 v[78:81], v[150:153], v[30:33], v[122:125]
	v_mfma_f32_16x16x32_bf16 v[126:129], v[202:205], v[34:37], v[78:81]
	v_mfma_f32_16x16x32_bf16 v[78:81], v[14:17], v[46:49], v[118:121]
	v_mfma_f32_16x16x32_bf16 v[114:117], v[18:21], v[50:53], v[78:81]
	v_mfma_f32_16x16x32_bf16 v[78:81], v[150:153], v[46:49], v[222:225]
	v_mfma_f32_16x16x32_bf16 v[110:113], v[202:205], v[50:53], v[78:81]
	v_mfma_f32_16x16x32_bf16 v[78:81], v[14:17], v[206:209], v[226:229]
	v_mfma_f32_16x16x32_bf16 v[98:101], v[18:21], v[210:213], v[78:81]
	v_mfma_f32_16x16x32_bf16 v[78:81], v[150:153], v[206:209], v[106:109]
	v_mfma_f32_16x16x32_bf16 v[94:97], v[202:205], v[210:213], v[78:81]
	v_mfma_f32_16x16x32_bf16 v[78:81], v[14:17], v[214:217], v[102:105]
	v_mfma_f32_16x16x32_bf16 v[82:85], v[18:21], v[242:245], v[78:81]
	v_mfma_f32_16x16x32_bf16 v[78:81], v[150:153], v[214:217], v[230:233]
	v_mfma_f32_16x16x32_bf16 v[78:81], v[202:205], v[242:245], v[78:81]
	s_barrier
	ds_read_b128 v[222:225], v146
	ds_read_b128 v[226:229], v146 offset:1024
	ds_read_b128 v[230:233], v146 offset:2048
	ds_read_b128 v[146:149], v146 offset:3072
	s_waitcnt vmcnt(0)
	s_barrier
	s_waitcnt lgkmcnt(0)
	v_mfma_f32_16x16x32_bf16 v[102:105], v[222:225], v[30:33], v[234:237]
	v_mfma_f32_16x16x32_bf16 v[30:33], v[230:233], v[30:33], v[90:93]
	v_mfma_f32_16x16x32_bf16 v[118:121], v[146:149], v[34:37], v[30:33]
	v_mfma_f32_16x16x32_bf16 v[30:33], v[222:225], v[46:49], v[86:89]
	v_mfma_f32_16x16x32_bf16 v[106:109], v[226:229], v[50:53], v[30:33]
	v_mfma_f32_16x16x32_bf16 v[30:33], v[230:233], v[46:49], v[190:193]
	v_mfma_f32_16x16x32_bf16 v[122:125], v[226:229], v[34:37], v[102:105]
	v_mfma_f32_16x16x32_bf16 v[102:105], v[146:149], v[50:53], v[30:33]
	v_mfma_f32_16x16x32_bf16 v[30:33], v[222:225], v[206:209], v[194:197]
	v_mfma_f32_16x16x32_bf16 v[90:93], v[226:229], v[210:213], v[30:33]
	v_mfma_f32_16x16x32_bf16 v[30:33], v[230:233], v[206:209], v[74:77]
	v_mfma_f32_16x16x32_bf16 v[86:89], v[146:149], v[210:213], v[30:33]
	v_mfma_f32_16x16x32_bf16 v[30:33], v[222:225], v[214:217], v[70:73]
	v_mfma_f32_16x16x32_bf16 v[74:77], v[226:229], v[242:245], v[30:33]
	v_mfma_f32_16x16x32_bf16 v[30:33], v[230:233], v[214:217], v[66:69]
	v_mfma_f32_16x16x32_bf16 v[70:73], v[146:149], v[242:245], v[30:33]
	s_barrier
	ds_read_b128 v[190:193], v145 offset:49152
	ds_read_b128 v[194:197], v145 offset:50176
	ds_read_b128 v[206:209], v144 offset:49152
	ds_read_b128 v[210:213], v144 offset:50176
	ds_read_b128 v[214:217], v143 offset:49152
	ds_read_b128 v[234:237], v143 offset:50176
	ds_read_b128 v[242:245], v142 offset:49152
	ds_read_b128 v[142:145], v142 offset:50176
	s_barrier
	s_waitcnt lgkmcnt(0)
	v_mfma_f32_16x16x32_bf16 v[30:33], v[14:17], v[190:193], v[62:65]
	v_mfma_f32_16x16x32_bf16 v[66:69], v[18:21], v[194:197], v[30:33]
	v_mfma_f32_16x16x32_bf16 v[30:33], v[150:153], v[190:193], v[58:61]
	v_mfma_f32_16x16x32_bf16 v[62:65], v[202:205], v[194:197], v[30:33]
	v_mfma_f32_16x16x32_bf16 v[30:33], v[14:17], v[206:209], v[54:57]
	v_mfma_f32_16x16x32_bf16 v[50:53], v[18:21], v[210:213], v[30:33]
	v_mfma_f32_16x16x32_bf16 v[30:33], v[150:153], v[206:209], v[218:221]
	v_mfma_f32_16x16x32_bf16 v[46:49], v[202:205], v[210:213], v[30:33]
	v_mfma_f32_16x16x32_bf16 v[30:33], v[14:17], v[214:217], v[238:241]
	v_mfma_f32_16x16x32_bf16 v[14:17], v[14:17], v[242:245], v[38:41]
	v_mfma_f32_16x16x32_bf16 v[34:37], v[18:21], v[234:237], v[30:33]
	v_mfma_f32_16x16x32_bf16 v[30:33], v[150:153], v[214:217], v[42:45]
	v_mfma_f32_16x16x32_bf16 v[18:21], v[18:21], v[142:145], v[14:17]
	v_mfma_f32_16x16x32_bf16 v[14:17], v[150:153], v[242:245], v[136:139]
	v_mfma_f32_16x16x32_bf16 v[30:33], v[202:205], v[234:237], v[30:33]
	v_mfma_f32_16x16x32_bf16 v[14:17], v[202:205], v[142:145], v[14:17]
	v_mfma_f32_16x16x32_bf16 v[22:25], v[222:225], v[206:209], v[22:25]
	v_mfma_f32_16x16x32_bf16 v[38:41], v[222:225], v[190:193], v[166:169]
	v_mfma_f32_16x16x32_bf16 v[42:45], v[226:229], v[210:213], v[22:25]
	v_mfma_f32_16x16x32_bf16 v[22:25], v[230:233], v[206:209], v[170:173]
	v_mfma_f32_16x16x32_bf16 v[58:61], v[226:229], v[194:197], v[38:41]
	v_mfma_f32_16x16x32_bf16 v[26:29], v[230:233], v[190:193], v[26:29]
	v_mfma_f32_16x16x32_bf16 v[38:41], v[146:149], v[210:213], v[22:25]
	v_mfma_f32_16x16x32_bf16 v[22:25], v[222:225], v[214:217], v[198:201]
	v_mfma_f32_16x16x32_bf16 v[10:13], v[230:233], v[214:217], v[10:13]
	v_mfma_f32_16x16x32_bf16 v[6:9], v[222:225], v[242:245], v[6:9]
	v_mfma_f32_16x16x32_bf16 v[2:5], v[230:233], v[242:245], v[2:5]
	v_mfma_f32_16x16x32_bf16 v[54:57], v[146:149], v[194:197], v[26:29]
	v_mfma_f32_16x16x32_bf16 v[26:29], v[226:229], v[234:237], v[22:25]
	v_mfma_f32_16x16x32_bf16 v[22:25], v[146:149], v[234:237], v[10:13]
	v_mfma_f32_16x16x32_bf16 v[10:13], v[226:229], v[142:145], v[6:9]
	v_mfma_f32_16x16x32_bf16 v[6:9], v[146:149], v[142:145], v[2:5]
	v_cmp_gt_u32_e32 vcc, s96, v140
	s_barrier
	s_and_saveexec_b64 s[2:3], vcc
	s_cbranch_execz .LBB0_270
	s_barrier

; #define STAGE_A(P,br,kt) STAGE_G(P,c.A,c.lda,br,(long)(kt)*c.kstr)
; #define STAGE_B(P,br,kt) STAGE_G(P,c.Bt,c.K,br,(long)(kt)*BK)
; #define LDA(dst,b,h) for(int m=0;m<4;++m)for(int k=0;k<2;++k) \
;     dst[m][k]=*reinterpret_cast<const bf16x8*>((char*)SA(b,h)+lds_byte(wr*64+m*16+fr,k*32+fq*8))
; #define LDB(dst,b,h) for(int n=0;n<2;++n)for(int k=0;k<2;++k) \
;     dst[n][k]=*reinterpret_cast<const bf16x8*>((char*)SB(b,h)+lds_byte(wc*32+n*16+fr,k*32+fq*8))
; #define MMA(ai,bj,At,Bt_) do{__builtin_amdgcn_s_setprio(1); \
;     for(int m=0;m<4;++m)for(int n=0;n<2;++n)for(int k=0;k<2;++k) \
;       acc[ai][bj][m][n]=__builtin_amdgcn_mfma_f32_16x16x32_bf16(Bt_[n][k],At[m][k],acc[ai][bj][m][n],0,0,0); \
;     __builtin_amdgcn_s_setprio(0);}while(0)
; #define WAIT_L(n) asm volatile("s_waitcnt lgkmcnt(" #n ")":::"memory")
; #define BAR __builtin_amdgcn_s_barrier()
; #define SCHED __builtin_amdgcn_sched_barrier(0)
; template <int EPI>
; __device__ __forceinline__ void gemm_run(const GD& c, const bool has_next, const GD& nx, const Ctx& e, bf16* shm, float* rs, float* rs_nxt, float* racc_) {
;     ...
;     LDB(B0,0,0); SCHED; LDA(At,0,0); STAGE_A(SA(1,1),brow+HALF,t+1);
;     WAIT_L(8); BAR; WAIT_L(0); MMA(0,0,At,B0); BAR; SCHED;
;     LDB(B1,0,1); STAGE_B(SB(0,0),bcol,t+2);
;     BAR; WAIT_L(0); MMA(0,1,At,B1); BAR;
;     LDA(At,0,1); STAGE_A(SA(0,0),brow,t+2);
;     BAR; WAIT_L(0); MMA(1,0,At,B0); BAR; SCHED;
.LBB0_326:
	ds_read_b128 v[168:171], v155
	ds_read_b128 v[172:175], v155 offset:1024
	ds_read_b128 v[190:193], v155 offset:2048
	ds_read_b128 v[194:197], v155 offset:3072
	v_add_u32_e32 v163, 0xc000, v142
	v_lshl_add_u64 v[186:187], s[6:7], 0, v[132:133]
	v_readfirstlane_b32 s3, v163
	v_add_u32_e32 v166, 0xe000, v142
	v_lshl_add_u64 v[156:157], v[186:187], 0, s[90:91]
	s_mov_b32 m0, s3
	v_lshl_add_u64 v[188:189], s[6:7], 0, v[134:135]
	v_readfirstlane_b32 s3, v166
	ds_read_b128 v[158:161], v146
	ds_read_b128 v[198:201], v146 offset:1024
	ds_read_b128 v[202:205], v145
	ds_read_b128 v[206:209], v145 offset:1024
	ds_read_b128 v[210:213], v144
	ds_read_b128 v[214:217], v144 offset:1024
	ds_read_b128 v[218:221], v143
	ds_read_b128 v[222:225], v143 offset:1024
	global_load_lds_dwordx4 v[156:157], off
	v_lshl_add_u64 v[156:157], v[188:189], 0, s[90:91]
	s_mov_b32 m0, s3
	s_nop 0
	global_load_lds_dwordx4 v[156:157], off
	s_waitcnt lgkmcnt(8)
	s_barrier
	s_waitcnt lgkmcnt(0)
	v_mfma_f32_16x16x32_bf16 v[126:129], v[168:171], v[158:161], v[126:129]
	v_mfma_f32_16x16x32_bf16 v[122:125], v[190:193], v[158:161], v[122:125]
	v_mfma_f32_16x16x32_bf16 v[118:121], v[168:171], v[202:205], v[118:121]
	v_mfma_f32_16x16x32_bf16 v[114:117], v[190:193], v[202:205], v[114:117]
	v_mfma_f32_16x16x32_bf16 v[110:113], v[168:171], v[210:213], v[110:113]
	v_mfma_f32_16x16x32_bf16 v[106:109], v[190:193], v[210:213], v[106:109]
	v_mfma_f32_16x16x32_bf16 v[102:105], v[168:171], v[218:221], v[102:105]
	v_mfma_f32_16x16x32_bf16 v[98:101], v[190:193], v[218:221], v[98:101]
	v_mfma_f32_16x16x32_bf16 v[126:129], v[172:175], v[198:201], v[126:129]
	v_mfma_f32_16x16x32_bf16 v[122:125], v[194:197], v[198:201], v[122:125]
	v_mfma_f32_16x16x32_bf16 v[118:121], v[172:175], v[206:209], v[118:121]
	v_mfma_f32_16x16x32_bf16 v[114:117], v[194:197], v[206:209], v[114:117]
	v_mfma_f32_16x16x32_bf16 v[110:113], v[172:175], v[214:217], v[110:113]
	v_mfma_f32_16x16x32_bf16 v[106:109], v[194:197], v[214:217], v[106:109]
	v_mfma_f32_16x16x32_bf16 v[102:105], v[172:175], v[222:225], v[102:105]
	v_mfma_f32_16x16x32_bf16 v[98:101], v[194:197], v[222:225], v[98:101]
	s_barrier
	v_add_u32_e32 v156, s33, v147
	v_lshl_add_u64 v[246:247], s[6:7], 0, v[136:137]
	v_readfirstlane_b32 s3, v156
	v_add_u32_e32 v157, 0x2000, v156
	v_lshl_add_u64 v[242:243], v[246:247], 0, s[26:27]
	s_mov_b32 m0, s3
	v_lshl_add_u64 v[248:249], s[6:7], 0, v[138:139]
	v_readfirstlane_b32 s3, v157
	ds_read_b128 v[226:229], v154
	ds_read_b128 v[230:233], v154 offset:1024
	ds_read_b128 v[234:237], v154 offset:2048
	ds_read_b128 v[238:241], v154 offset:3072
	global_load_lds_dwordx4 v[242:243], off
	v_lshl_add_u64 v[242:243], v[248:249], 0, s[26:27]
	s_mov_b32 m0, s3
	s_nop 0
	global_load_lds_dwordx4 v[242:243], off
	s_barrier
	s_waitcnt lgkmcnt(0)
	v_mfma_f32_16x16x32_bf16 v[94:97], v[226:229], v[158:161], v[94:97]
	v_mfma_f32_16x16x32_bf16 v[90:93], v[234:237], v[158:161], v[90:93]
	v_mfma_f32_16x16x32_bf16 v[86:89], v[226:229], v[202:205], v[86:89]
	v_mfma_f32_16x16x32_bf16 v[82:85], v[234:237], v[202:205], v[82:85]
	v_mfma_f32_16x16x32_bf16 v[78:81], v[226:229], v[210:213], v[78:81]
	v_mfma_f32_16x16x32_bf16 v[74:77], v[234:237], v[210:213], v[74:77]
	v_mfma_f32_16x16x32_bf16 v[70:73], v[226:229], v[218:221], v[70:73]
	v_mfma_f32_16x16x32_bf16 v[66:69], v[234:237], v[218:221], v[66:69]
	v_mfma_f32_16x16x32_bf16 v[94:97], v[230:233], v[198:201], v[94:97]
	v_mfma_f32_16x16x32_bf16 v[90:93], v[238:241], v[198:201], v[90:93]
	v_mfma_f32_16x16x32_bf16 v[86:89], v[230:233], v[206:209], v[86:89]
	v_mfma_f32_16x16x32_bf16 v[82:85], v[238:241], v[206:209], v[82:85]
	v_mfma_f32_16x16x32_bf16 v[78:81], v[230:233], v[214:217], v[78:81]
	v_mfma_f32_16x16x32_bf16 v[74:77], v[238:241], v[214:217], v[74:77]
	v_mfma_f32_16x16x32_bf16 v[70:73], v[230:233], v[222:225], v[70:73]
	v_mfma_f32_16x16x32_bf16 v[66:69], v[238:241], v[222:225], v[66:69]
	v_readfirstlane_b32 s3, v142
	v_lshl_add_u64 v[158:159], v[186:187], 0, s[0:1]
	s_mov_b32 m0, s3
	s_barrier
	ds_read_b128 v[198:201], v146 offset:16384
	ds_read_b128 v[202:205], v146 offset:17408
	ds_read_b128 v[206:209], v145 offset:16384
	ds_read_b128 v[210:213], v145 offset:17408
	ds_read_b128 v[214:217], v144 offset:16384
	ds_read_b128 v[218:221], v144 offset:17408
	ds_read_b128 v[222:225], v143 offset:16384
	ds_read_b128 v[242:245], v143 offset:17408
	global_load_lds_dwordx4 v[158:159], off
	v_add_u32_e32 v158, 0x2000, v142
	v_lshl_add_u64 v[160:161], v[188:189], 0, s[0:1]
	v_readfirstlane_b32 s3, v158
	s_mov_b32 m0, s3
	s_nop 0
	global_load_lds_dwordx4 v[160:161], off
	s_barrier
	s_waitcnt lgkmcnt(0)
	v_mfma_f32_16x16x32_bf16 v[62:65], v[168:171], v[198:201], v[62:65]
	v_mfma_f32_16x16x32_bf16 v[58:61], v[190:193], v[198:201], v[58:61]
	v_mfma_f32_16x16x32_bf16 v[54:57], v[168:171], v[206:209], v[54:57]
	v_mfma_f32_16x16x32_bf16 v[50:53], v[190:193], v[206:209], v[50:53]
	v_mfma_f32_16x16x32_bf16 v[46:49], v[168:171], v[214:217], v[46:49]
	v_mfma_f32_16x16x32_bf16 v[42:45], v[190:193], v[214:217], v[42:45]
	v_mfma_f32_16x16x32_bf16 v[38:41], v[168:171], v[222:225], v[38:41]
	v_mfma_f32_16x16x32_bf16 v[34:37], v[190:193], v[222:225], v[34:37]
	v_mfma_f32_16x16x32_bf16 v[62:65], v[172:175], v[202:205], v[62:65]
	v_mfma_f32_16x16x32_bf16 v[58:61], v[194:197], v[202:205], v[58:61]
	v_mfma_f32_16x16x32_bf16 v[54:57], v[172:175], v[210:213], v[54:57]
	v_mfma_f32_16x16x32_bf16 v[50:53], v[194:197], v[210:213], v[50:53]
	v_mfma_f32_16x16x32_bf16 v[46:49], v[172:175], v[218:221], v[46:49]
	v_mfma_f32_16x16x32_bf16 v[42:45], v[194:197], v[218:221], v[42:45]
	v_mfma_f32_16x16x32_bf16 v[38:41], v[172:175], v[242:245], v[38:41]
	v_mfma_f32_16x16x32_bf16 v[34:37], v[194:197], v[242:245], v[34:37]
	s_barrier
; #define STAGE_A(P,br,kt) STAGE_G(P,c.A,c.lda,br,(long)(kt)*c.kstr)
; #define STAGE_B(P,br,kt) STAGE_G(P,c.Bt,c.K,br,(long)(kt)*BK)
; #define LDA(dst,b,h) for(int m=0;m<4;++m)for(int k=0;k<2;++k) \
;     dst[m][k]=*reinterpret_cast<const bf16x8*>((char*)SA(b,h)+lds_byte(wr*64+m*16+fr,k*32+fq*8))
; #define LDB(dst,b,h) for(int n=0;n<2;++n)for(int k=0;k<2;++k) \
;     dst[n][k]=*reinterpret_cast<const bf16x8*>((char*)SB(b,h)+lds_byte(wc*32+n*16+fr,k*32+fq*8))
; #define MMA(ai,bj,At,Bt_) do{__builtin_amdgcn_s_setprio(1); \
;     for(int m=0;m<4;++m)for(int n=0;n<2;++n)for(int k=0;k<2;++k) \
;       acc[ai][bj][m][n]=__builtin_amdgcn_mfma_f32_16x16x32_bf16(Bt_[n][k],At[m][k],acc[ai][bj][m][n],0,0,0); \
;     __builtin_amdgcn_s_setprio(0);}while(0)
; #define WAIT_V(n) asm volatile("s_waitcnt vmcnt(" #n ")":::"memory")
; #define WAIT_L(n) asm volatile("s_waitcnt lgkmcnt(" #n ")":::"memory")
; #define BAR __builtin_amdgcn_s_barrier()
; #define SCHED __builtin_amdgcn_sched_barrier(0)
; template <int EPI>
; __device__ __forceinline__ void gemm_run(const GD& c, const bool has_next, const GD& nx, const Ctx& e, bf16* shm, float* rs, float* rs_nxt, float* racc_) {
;     ...
;   for(int t=0;t<nt-2;t+=2){
;     LDB(B0,0,0); SCHED; LDA(At,0,0); STAGE_A(SA(1,1),brow+HALF,t+1);
;     WAIT_L(8); BAR; WAIT_L(0); MMA(0,0,At,B0); BAR; SCHED;
;     LDB(B1,0,1); STAGE_B(SB(0,0),bcol,t+2);
;     BAR; WAIT_L(0); MMA(0,1,At,B1); BAR;
;     LDA(At,0,1); STAGE_A(SA(0,0),brow,t+2);
;     BAR; WAIT_L(0); MMA(1,0,At,B0); BAR; SCHED;
;     STAGE_B(SB(0,1),bcol+HALF,t+2);
;     WAIT_V(6); BAR; MMA(1,1,At,B1); BAR;
;     LDB(B0,1,0); SCHED; LDA(At,1,0); STAGE_A(SA(0,1),brow+HALF,t+2);
;     WAIT_L(8); BAR; WAIT_L(0); MMA(0,0,At,B0); BAR; SCHED;
;     LDB(B1,1,1); STAGE_B(SB(1,0),bcol,t+3);
;     BAR; WAIT_L(0); MMA(0,1,At,B1); BAR;
;     LDA(At,1,1); STAGE_A(SA(1,0),brow,t+3);
;     BAR; WAIT_L(0); MMA(1,0,At,B0); BAR; SCHED;
;     STAGE_B(SB(1,1),bcol+HALF,t+3);
;     WAIT_V(6); BAR; MMA(1,1,At,B1); BAR;
;   }
	v_add_u32_e32 v159, s86, v147
	v_lshl_add_u64 v[160:161], v[246:247], 0, s[28:29]
	v_readfirstlane_b32 s3, v159
	s_mov_b32 m0, s3
	v_lshl_add_u64 v[168:169], v[248:249], 0, s[28:29]
	global_load_lds_dwordx4 v[160:161], off
	v_add_u32_e32 v160, 0x2000, v159
	s_nop 0
	v_readfirstlane_b32 s3, v160
	s_mov_b32 m0, s3
	s_nop 0
	global_load_lds_dwordx4 v[168:169], off
	s_waitcnt vmcnt(6)
	s_barrier
	v_mfma_f32_16x16x32_bf16 v[30:33], v[226:229], v[198:201], v[30:33]
	v_mfma_f32_16x16x32_bf16 v[26:29], v[234:237], v[198:201], v[26:29]
	v_mfma_f32_16x16x32_bf16 v[22:25], v[226:229], v[206:209], v[22:25]
	v_mfma_f32_16x16x32_bf16 v[18:21], v[234:237], v[206:209], v[18:21]
	v_mfma_f32_16x16x32_bf16 v[14:17], v[226:229], v[214:217], v[14:17]
	v_mfma_f32_16x16x32_bf16 v[10:13], v[234:237], v[214:217], v[10:13]
	v_mfma_f32_16x16x32_bf16 v[6:9], v[226:229], v[222:225], v[6:9]
	v_mfma_f32_16x16x32_bf16 v[2:5], v[234:237], v[222:225], v[2:5]
	v_mfma_f32_16x16x32_bf16 v[30:33], v[230:233], v[202:205], v[30:33]
	v_mfma_f32_16x16x32_bf16 v[26:29], v[238:241], v[202:205], v[26:29]
	v_mfma_f32_16x16x32_bf16 v[22:25], v[230:233], v[210:213], v[22:25]
	v_mfma_f32_16x16x32_bf16 v[18:21], v[238:241], v[210:213], v[18:21]
	v_mfma_f32_16x16x32_bf16 v[14:17], v[230:233], v[218:221], v[14:17]
	v_mfma_f32_16x16x32_bf16 v[10:13], v[238:241], v[218:221], v[10:13]
	v_mfma_f32_16x16x32_bf16 v[6:9], v[230:233], v[242:245], v[6:9]
	v_mfma_f32_16x16x32_bf16 v[2:5], v[238:241], v[242:245], v[2:5]
	s_barrier
	ds_read_b128 v[168:171], v150
	ds_read_b128 v[172:175], v150 offset:1024
	ds_read_b128 v[190:193], v150 offset:2048
	ds_read_b128 v[194:197], v150 offset:3072
	v_add_u32_e32 v161, 0x4000, v142
	v_add_u32_e32 v162, 0x6000, v142
	v_readfirstlane_b32 s3, v161
	v_lshl_add_u64 v[230:231], v[186:187], 0, s[76:77]
	s_mov_b32 m0, s3
	v_readfirstlane_b32 s3, v162
	ds_read_b128 v[198:201], v146 offset:32768
	ds_read_b128 v[202:205], v146 offset:33792
	ds_read_b128 v[206:209], v145 offset:32768
	ds_read_b128 v[210:213], v145 offset:33792
	ds_read_b128 v[214:217], v144 offset:32768
	ds_read_b128 v[218:221], v144 offset:33792
	ds_read_b128 v[222:225], v143 offset:32768
	ds_read_b128 v[226:229], v143 offset:33792
	global_load_lds_dwordx4 v[230:231], off
	v_lshl_add_u64 v[230:231], v[188:189], 0, s[76:77]
	s_mov_b32 m0, s3
	s_nop 0
	global_load_lds_dwordx4 v[230:231], off
	s_waitcnt lgkmcnt(8)
	s_barrier
	s_waitcnt lgkmcnt(0)
	v_mfma_f32_16x16x32_bf16 v[126:129], v[168:171], v[198:201], v[126:129]
	v_mfma_f32_16x16x32_bf16 v[122:125], v[190:193], v[198:201], v[122:125]
	v_mfma_f32_16x16x32_bf16 v[118:121], v[168:171], v[206:209], v[118:121]
	v_mfma_f32_16x16x32_bf16 v[114:117], v[190:193], v[206:209], v[114:117]
	v_mfma_f32_16x16x32_bf16 v[110:113], v[168:171], v[214:217], v[110:113]
	v_mfma_f32_16x16x32_bf16 v[106:109], v[190:193], v[214:217], v[106:109]
	v_mfma_f32_16x16x32_bf16 v[102:105], v[168:171], v[222:225], v[102:105]
	v_mfma_f32_16x16x32_bf16 v[98:101], v[190:193], v[222:225], v[98:101]
	v_mfma_f32_16x16x32_bf16 v[126:129], v[172:175], v[202:205], v[126:129]
	v_mfma_f32_16x16x32_bf16 v[122:125], v[194:197], v[202:205], v[122:125]
	v_mfma_f32_16x16x32_bf16 v[118:121], v[172:175], v[210:213], v[118:121]
	v_mfma_f32_16x16x32_bf16 v[114:117], v[194:197], v[210:213], v[114:117]
	v_mfma_f32_16x16x32_bf16 v[110:113], v[172:175], v[218:221], v[110:113]
	v_mfma_f32_16x16x32_bf16 v[106:109], v[194:197], v[218:221], v[106:109]
	v_mfma_f32_16x16x32_bf16 v[102:105], v[172:175], v[226:229], v[102:105]
	v_mfma_f32_16x16x32_bf16 v[98:101], v[194:197], v[226:229], v[98:101]
	s_barrier
	v_readfirstlane_b32 s3, v149
	v_add_u32_e32 v167, 0x2000, v149
	v_lshl_add_u64 v[250:251], v[246:247], 0, s[30:31]
	s_mov_b32 m0, s3
	v_readfirstlane_b32 s3, v167
	ds_read_b128 v[230:233], v148
	ds_read_b128 v[234:237], v148 offset:1024
	ds_read_b128 v[238:241], v148 offset:2048
	ds_read_b128 v[242:245], v148 offset:3072
	global_load_lds_dwordx4 v[250:251], off
	v_lshl_add_u64 v[250:251], v[248:249], 0, s[30:31]
	s_mov_b32 m0, s3
	s_nop 0
	global_load_lds_dwordx4 v[250:251], off
	s_barrier
	s_waitcnt lgkmcnt(0)
	v_mfma_f32_16x16x32_bf16 v[94:97], v[230:233], v[198:201], v[94:97]
	v_mfma_f32_16x16x32_bf16 v[90:93], v[238:241], v[198:201], v[90:93]
	v_mfma_f32_16x16x32_bf16 v[86:89], v[230:233], v[206:209], v[86:89]
	v_mfma_f32_16x16x32_bf16 v[82:85], v[238:241], v[206:209], v[82:85]
	v_readfirstlane_b32 s3, v151
	v_mfma_f32_16x16x32_bf16 v[78:81], v[230:233], v[214:217], v[78:81]
	v_lshl_add_u64 v[186:187], v[186:187], 0, s[74:75]
	v_mfma_f32_16x16x32_bf16 v[74:77], v[238:241], v[214:217], v[74:77]
	s_mov_b32 m0, s3
	v_mfma_f32_16x16x32_bf16 v[70:73], v[230:233], v[222:225], v[70:73]
	v_readfirstlane_b32 s3, v152
	v_mfma_f32_16x16x32_bf16 v[66:69], v[238:241], v[222:225], v[66:69]
	v_mfma_f32_16x16x32_bf16 v[94:97], v[234:237], v[202:205], v[94:97]
	v_mfma_f32_16x16x32_bf16 v[90:93], v[242:245], v[202:205], v[90:93]
	v_mfma_f32_16x16x32_bf16 v[86:89], v[234:237], v[210:213], v[86:89]
	v_mfma_f32_16x16x32_bf16 v[82:85], v[242:245], v[210:213], v[82:85]
	v_mfma_f32_16x16x32_bf16 v[78:81], v[234:237], v[218:221], v[78:81]
	v_mfma_f32_16x16x32_bf16 v[74:77], v[242:245], v[218:221], v[74:77]
	v_mfma_f32_16x16x32_bf16 v[70:73], v[234:237], v[226:229], v[70:73]
	v_mfma_f32_16x16x32_bf16 v[66:69], v[242:245], v[226:229], v[66:69]
	s_barrier
	ds_read_b128 v[198:201], v146 offset:49152
	ds_read_b128 v[202:205], v146 offset:50176
	ds_read_b128 v[206:209], v145 offset:49152
	ds_read_b128 v[210:213], v145 offset:50176
	ds_read_b128 v[214:217], v144 offset:49152
	ds_read_b128 v[218:221], v144 offset:50176
	ds_read_b128 v[222:225], v143 offset:49152
	ds_read_b128 v[226:229], v143 offset:50176
	global_load_lds_dwordx4 v[186:187], off
	v_lshl_add_u64 v[186:187], v[188:189], 0, s[74:75]
	s_mov_b32 m0, s3
	s_nop 0
	global_load_lds_dwordx4 v[186:187], off
	s_barrier
; #define STAGE_A(P,br,kt) STAGE_G(P,c.A,c.lda,br,(long)(kt)*c.kstr)
; #define STAGE_B(P,br,kt) STAGE_G(P,c.Bt,c.K,br,(long)(kt)*BK)
; #define LDA(dst,b,h) for(int m=0;m<4;++m)for(int k=0;k<2;++k) \
;     dst[m][k]=*reinterpret_cast<const bf16x8*>((char*)SA(b,h)+lds_byte(wr*64+m*16+fr,k*32+fq*8))
; #define LDB(dst,b,h) for(int n=0;n<2;++n)for(int k=0;k<2;++k) \
;     dst[n][k]=*reinterpret_cast<const bf16x8*>((char*)SB(b,h)+lds_byte(wc*32+n*16+fr,k*32+fq*8))
; #define MMA(ai,bj,At,Bt_) do{__builtin_amdgcn_s_setprio(1); \
;     for(int m=0;m<4;++m)for(int n=0;n<2;++n)for(int k=0;k<2;++k) \
;       acc[ai][bj][m][n]=__builtin_amdgcn_mfma_f32_16x16x32_bf16(Bt_[n][k],At[m][k],acc[ai][bj][m][n],0,0,0); \
;     __builtin_amdgcn_s_setprio(0);}while(0)
; #define WAIT_V(n) asm volatile("s_waitcnt vmcnt(" #n ")":::"memory")
; #define WAIT_L(n) asm volatile("s_waitcnt lgkmcnt(" #n ")":::"memory")
; #define BAR __builtin_amdgcn_s_barrier()
; #define SCHED __builtin_amdgcn_sched_barrier(0)
; template <int EPI>
; __device__ __forceinline__ void gemm_run(const GD& c, const bool has_next, const GD& nx, const Ctx& e, bf16* shm, float* rs, float* rs_nxt, float* racc_) {
;     ...
;   for(int t=0;t<nt-2;t+=2){
;     LDB(B0,0,0); SCHED; LDA(At,0,0); STAGE_A(SA(1,1),brow+HALF,t+1);
;     WAIT_L(8); BAR; WAIT_L(0); MMA(0,0,At,B0); BAR; SCHED;
;     LDB(B1,0,1); STAGE_B(SB(0,0),bcol,t+2);
;     BAR; WAIT_L(0); MMA(0,1,At,B1); BAR;
;     LDA(At,0,1); STAGE_A(SA(0,0),brow,t+2);
;     BAR; WAIT_L(0); MMA(1,0,At,B0); BAR; SCHED;
;     STAGE_B(SB(0,1),bcol+HALF,t+2);
;     WAIT_V(6); BAR; MMA(1,1,At,B1); BAR;
;     LDB(B0,1,0); SCHED; LDA(At,1,0); STAGE_A(SA(0,1),brow+HALF,t+2);
;     WAIT_L(8); BAR; WAIT_L(0); MMA(0,0,At,B0); BAR; SCHED;
;     LDB(B1,1,1); STAGE_B(SB(1,0),bcol,t+3);
;     BAR; WAIT_L(0); MMA(0,1,At,B1); BAR;
;     LDA(At,1,1); STAGE_A(SA(1,0),brow,t+3);
;     BAR; WAIT_L(0); MMA(1,0,At,B0); BAR; SCHED;
;     STAGE_B(SB(1,1),bcol+HALF,t+3);
;     WAIT_V(6); BAR; MMA(1,1,At,B1); BAR;
;   }
;   { LDB(B0,0,0); LDA(At,0,0); STAGE_A(SA(1,1),brow+HALF,nt-1);
;     BAR; WAIT_L(0); MMA(0,0,At,B0); BAR;
;     LDB(B1,0,1); BAR; WAIT_L(0); MMA(0,1,At,B1); BAR;
;     LDA(At,0,1); WAIT_V(4); BAR; WAIT_L(0); MMA(1,0,At,B0); MMA(1,1,At,B1); BAR; }
;   { LDB(B0,1,0); LDA(At,1,0); WAIT_V(2); BAR; WAIT_L(0); MMA(0,0,At,B0); BAR;
	s_waitcnt lgkmcnt(0)
	v_mfma_f32_16x16x32_bf16 v[62:65], v[168:171], v[198:201], v[62:65]
	v_mfma_f32_16x16x32_bf16 v[58:61], v[190:193], v[198:201], v[58:61]
	v_mfma_f32_16x16x32_bf16 v[54:57], v[168:171], v[206:209], v[54:57]
	v_mfma_f32_16x16x32_bf16 v[50:53], v[190:193], v[206:209], v[50:53]
	v_mfma_f32_16x16x32_bf16 v[46:49], v[168:171], v[214:217], v[46:49]
	v_mfma_f32_16x16x32_bf16 v[42:45], v[190:193], v[214:217], v[42:45]
	v_mfma_f32_16x16x32_bf16 v[38:41], v[168:171], v[222:225], v[38:41]
	v_mfma_f32_16x16x32_bf16 v[34:37], v[190:193], v[222:225], v[34:37]
	v_mfma_f32_16x16x32_bf16 v[62:65], v[172:175], v[202:205], v[62:65]
	v_mfma_f32_16x16x32_bf16 v[58:61], v[194:197], v[202:205], v[58:61]
	v_mfma_f32_16x16x32_bf16 v[54:57], v[172:175], v[210:213], v[54:57]
	v_mfma_f32_16x16x32_bf16 v[50:53], v[194:197], v[210:213], v[50:53]
	v_mfma_f32_16x16x32_bf16 v[46:49], v[172:175], v[218:221], v[46:49]
	v_mfma_f32_16x16x32_bf16 v[42:45], v[194:197], v[218:221], v[42:45]
	v_mfma_f32_16x16x32_bf16 v[38:41], v[172:175], v[226:229], v[38:41]
	v_mfma_f32_16x16x32_bf16 v[34:37], v[194:197], v[226:229], v[34:37]
	s_barrier
	v_readfirstlane_b32 s3, v153
	v_add_u32_e32 v167, 0x2000, v153
	v_lshl_add_u64 v[168:169], v[246:247], 0, s[34:35]
	s_mov_b32 m0, s3
	v_readfirstlane_b32 s3, v167
	global_load_lds_dwordx4 v[168:169], off
	v_lshl_add_u64 v[168:169], v[248:249], 0, s[34:35]
	s_mov_b32 m0, s3
	s_nop 0
	global_load_lds_dwordx4 v[168:169], off
	s_waitcnt vmcnt(6)
	s_barrier
	v_mfma_f32_16x16x32_bf16 v[30:33], v[230:233], v[198:201], v[30:33]
	v_mfma_f32_16x16x32_bf16 v[26:29], v[238:241], v[198:201], v[26:29]
	v_mfma_f32_16x16x32_bf16 v[22:25], v[230:233], v[206:209], v[22:25]
	v_mfma_f32_16x16x32_bf16 v[18:21], v[238:241], v[206:209], v[18:21]
	s_add_i32 s2, s2, 2
	v_mfma_f32_16x16x32_bf16 v[14:17], v[230:233], v[214:217], v[14:17]
	v_lshl_add_u64 v[132:133], v[132:133], 0, s[88:89]
	v_mfma_f32_16x16x32_bf16 v[10:13], v[238:241], v[214:217], v[10:13]
	v_lshl_add_u64 v[134:135], v[134:135], 0, s[88:89]
	v_mfma_f32_16x16x32_bf16 v[6:9], v[230:233], v[222:225], v[6:9]
	v_lshl_add_u64 v[136:137], v[136:137], 0, s[88:89]
	v_mfma_f32_16x16x32_bf16 v[2:5], v[238:241], v[222:225], v[2:5]
	s_cmp_lt_u32 s2, 38
	v_mfma_f32_16x16x32_bf16 v[30:33], v[234:237], v[202:205], v[30:33]
	v_lshl_add_u64 v[138:139], v[138:139], 0, s[88:89]
	v_mfma_f32_16x16x32_bf16 v[26:29], v[242:245], v[202:205], v[26:29]
	v_mfma_f32_16x16x32_bf16 v[22:25], v[234:237], v[210:213], v[22:25]
	v_mfma_f32_16x16x32_bf16 v[18:21], v[242:245], v[210:213], v[18:21]
	v_mfma_f32_16x16x32_bf16 v[14:17], v[234:237], v[218:221], v[14:17]
	v_mfma_f32_16x16x32_bf16 v[10:13], v[242:245], v[218:221], v[10:13]
	v_mfma_f32_16x16x32_bf16 v[6:9], v[234:237], v[226:229], v[6:9]
	v_mfma_f32_16x16x32_bf16 v[2:5], v[242:245], v[226:229], v[2:5]
	s_barrier
	s_cbranch_scc1 .LBB0_326
	s_or_b32 s2, s15, 0x80
	s_mul_hi_i32 s3, s2, 0x1500
	s_mulk_i32 s2, 0x1500
	s_add_u32 s2, s21, s2
	s_addc_u32 s3, s22, s3
	v_readfirstlane_b32 s26, v163
	v_lshl_add_u64 v[152:153], s[2:3], 0, v[0:1]
	s_mov_b32 m0, s26
	ds_read_b128 v[132:135], v155
	ds_read_b128 v[136:139], v155 offset:1024
	ds_read_b128 v[168:171], v155 offset:2048
	ds_read_b128 v[172:175], v155 offset:3072
	ds_read_b128 v[190:193], v146
	ds_read_b128 v[194:197], v146 offset:1024
	ds_read_b128 v[198:201], v145
	ds_read_b128 v[202:205], v145 offset:1024
	ds_read_b128 v[206:209], v144
	ds_read_b128 v[210:213], v144 offset:1024
	ds_read_b128 v[214:217], v143
	ds_read_b128 v[218:221], v143 offset:1024
	global_load_lds_dwordx4 v[152:153], off
	v_lshl_add_u64 v[152:153], s[2:3], 0, v[130:131]
	v_readfirstlane_b32 s2, v166
	s_mov_b32 m0, s2
	s_nop 0
	global_load_lds_dwordx4 v[152:153], off
	s_barrier
	s_waitcnt lgkmcnt(0)
	v_mfma_f32_16x16x32_bf16 v[126:129], v[132:135], v[190:193], v[126:129]
	v_mfma_f32_16x16x32_bf16 v[122:125], v[168:171], v[190:193], v[122:125]
	v_mfma_f32_16x16x32_bf16 v[118:121], v[132:135], v[198:201], v[118:121]
	v_mfma_f32_16x16x32_bf16 v[114:117], v[168:171], v[198:201], v[114:117]
	v_mfma_f32_16x16x32_bf16 v[102:105], v[132:135], v[214:217], v[102:105]
	v_mfma_f32_16x16x32_bf16 v[98:101], v[168:171], v[214:217], v[98:101]
	v_mfma_f32_16x16x32_bf16 v[126:129], v[136:139], v[194:197], v[126:129]
	v_mfma_f32_16x16x32_bf16 v[122:125], v[172:175], v[194:197], v[122:125]
	v_mfma_f32_16x16x32_bf16 v[118:121], v[136:139], v[202:205], v[118:121]
	v_mfma_f32_16x16x32_bf16 v[114:117], v[172:175], v[202:205], v[114:117]
	v_mfma_f32_16x16x32_bf16 v[110:113], v[132:135], v[206:209], v[110:113]
	v_mfma_f32_16x16x32_bf16 v[106:109], v[168:171], v[206:209], v[106:109]
	v_mfma_f32_16x16x32_bf16 v[102:105], v[136:139], v[218:221], v[102:105]
	v_mfma_f32_16x16x32_bf16 v[98:101], v[172:175], v[218:221], v[98:101]
	v_mfma_f32_16x16x32_bf16 v[222:225], v[136:139], v[210:213], v[110:113]
	v_mfma_f32_16x16x32_bf16 v[226:229], v[172:175], v[210:213], v[106:109]
	s_barrier
	s_nop 1
	ds_read_b128 v[106:109], v154
	ds_read_b128 v[110:113], v154 offset:1024
	ds_read_b128 v[230:233], v154 offset:2048
	ds_read_b128 v[152:155], v154 offset:3072
	s_barrier
; #define LDA(dst,b,h) for(int m=0;m<4;++m)for(int k=0;k<2;++k) \
;     dst[m][k]=*reinterpret_cast<const bf16x8*>((char*)SA(b,h)+lds_byte(wr*64+m*16+fr,k*32+fq*8))
; #define LDB(dst,b,h) for(int n=0;n<2;++n)for(int k=0;k<2;++k) \
;     dst[n][k]=*reinterpret_cast<const bf16x8*>((char*)SB(b,h)+lds_byte(wc*32+n*16+fr,k*32+fq*8))
; #define MMA(ai,bj,At,Bt_) do{__builtin_amdgcn_s_setprio(1); \
;     for(int m=0;m<4;++m)for(int n=0;n<2;++n)for(int k=0;k<2;++k) \
;       acc[ai][bj][m][n]=__builtin_amdgcn_mfma_f32_16x16x32_bf16(Bt_[n][k],At[m][k],acc[ai][bj][m][n],0,0,0); \
;     __builtin_amdgcn_s_setprio(0);}while(0)
; #define WAIT_V(n) asm volatile("s_waitcnt vmcnt(" #n ")":::"memory")
; #define WAIT_L(n) asm volatile("s_waitcnt lgkmcnt(" #n ")":::"memory")
; #define BAR __builtin_amdgcn_s_barrier()
; template <int EPI>
; __device__ __forceinline__ void gemm_run(const GD& c, const bool has_next, const GD& nx, const Ctx& e, bf16* shm, float* rs, float* rs_nxt, float* racc_) {
;     ...
;     BAR; WAIT_L(0); MMA(0,0,At,B0); BAR;
;     LDB(B1,0,1); BAR; WAIT_L(0); MMA(0,1,At,B1); BAR;
;     LDA(At,0,1); WAIT_V(4); BAR; WAIT_L(0); MMA(1,0,At,B0); MMA(1,1,At,B1); BAR; }
;   { LDB(B0,1,0); LDA(At,1,0); WAIT_V(2); BAR; WAIT_L(0); MMA(0,0,At,B0); BAR;
	s_waitcnt lgkmcnt(0)
	v_mfma_f32_16x16x32_bf16 v[86:89], v[106:109], v[198:201], v[86:89]
	v_mfma_f32_16x16x32_bf16 v[82:85], v[230:233], v[198:201], v[82:85]
	v_mfma_f32_16x16x32_bf16 v[70:73], v[106:109], v[214:217], v[70:73]
	v_mfma_f32_16x16x32_bf16 v[66:69], v[230:233], v[214:217], v[66:69]
	v_mfma_f32_16x16x32_bf16 v[94:97], v[106:109], v[190:193], v[94:97]
	v_mfma_f32_16x16x32_bf16 v[90:93], v[230:233], v[190:193], v[90:93]
	v_mfma_f32_16x16x32_bf16 v[86:89], v[110:113], v[202:205], v[86:89]
	v_mfma_f32_16x16x32_bf16 v[82:85], v[152:155], v[202:205], v[82:85]
	v_mfma_f32_16x16x32_bf16 v[78:81], v[106:109], v[206:209], v[78:81]
	v_mfma_f32_16x16x32_bf16 v[74:77], v[230:233], v[206:209], v[74:77]
	v_mfma_f32_16x16x32_bf16 v[70:73], v[110:113], v[218:221], v[70:73]
	v_mfma_f32_16x16x32_bf16 v[66:69], v[152:155], v[218:221], v[66:69]
	v_mfma_f32_16x16x32_bf16 v[234:237], v[110:113], v[194:197], v[94:97]
	v_mfma_f32_16x16x32_bf16 v[190:193], v[152:155], v[194:197], v[90:93]
	v_mfma_f32_16x16x32_bf16 v[194:197], v[110:113], v[210:213], v[78:81]
	v_mfma_f32_16x16x32_bf16 v[198:201], v[152:155], v[210:213], v[74:77]
	s_barrier
	s_nop 0
	ds_read_b128 v[74:77], v146 offset:16384
	ds_read_b128 v[78:81], v146 offset:17408
	ds_read_b128 v[90:93], v145 offset:16384
	ds_read_b128 v[94:97], v145 offset:17408
	ds_read_b128 v[202:205], v144 offset:16384
	ds_read_b128 v[206:209], v144 offset:17408
	ds_read_b128 v[210:213], v143 offset:16384
	ds_read_b128 v[214:217], v143 offset:17408
	s_waitcnt vmcnt(4)
	s_barrier
	s_waitcnt lgkmcnt(0)
	v_mfma_f32_16x16x32_bf16 v[62:65], v[132:135], v[74:77], v[62:65]
	v_mfma_f32_16x16x32_bf16 v[58:61], v[168:171], v[74:77], v[58:61]
	v_mfma_f32_16x16x32_bf16 v[54:57], v[132:135], v[90:93], v[54:57]
	v_mfma_f32_16x16x32_bf16 v[50:53], v[168:171], v[90:93], v[50:53]
	v_mfma_f32_16x16x32_bf16 v[38:41], v[132:135], v[210:213], v[38:41]
	v_mfma_f32_16x16x32_bf16 v[34:37], v[168:171], v[210:213], v[34:37]
	v_mfma_f32_16x16x32_bf16 v[62:65], v[136:139], v[78:81], v[62:65]
	v_mfma_f32_16x16x32_bf16 v[58:61], v[172:175], v[78:81], v[58:61]
	v_mfma_f32_16x16x32_bf16 v[54:57], v[136:139], v[94:97], v[54:57]
	v_mfma_f32_16x16x32_bf16 v[50:53], v[172:175], v[94:97], v[50:53]
	v_mfma_f32_16x16x32_bf16 v[46:49], v[132:135], v[202:205], v[46:49]
	v_mfma_f32_16x16x32_bf16 v[42:45], v[168:171], v[202:205], v[42:45]
	v_mfma_f32_16x16x32_bf16 v[38:41], v[136:139], v[214:217], v[38:41]
	v_mfma_f32_16x16x32_bf16 v[34:37], v[172:175], v[214:217], v[34:37]
	v_mfma_f32_16x16x32_bf16 v[218:221], v[136:139], v[206:209], v[46:49]
	v_mfma_f32_16x16x32_bf16 v[238:241], v[172:175], v[206:209], v[42:45]
	v_mfma_f32_16x16x32_bf16 v[22:25], v[106:109], v[90:93], v[22:25]
	v_mfma_f32_16x16x32_bf16 v[18:21], v[230:233], v[90:93], v[18:21]
	v_mfma_f32_16x16x32_bf16 v[6:9], v[106:109], v[210:213], v[6:9]
	v_mfma_f32_16x16x32_bf16 v[2:5], v[230:233], v[210:213], v[2:5]
	v_mfma_f32_16x16x32_bf16 v[30:33], v[106:109], v[74:77], v[30:33]
	v_mfma_f32_16x16x32_bf16 v[26:29], v[230:233], v[74:77], v[26:29]
	v_mfma_f32_16x16x32_bf16 v[22:25], v[110:113], v[94:97], v[22:25]
	v_mfma_f32_16x16x32_bf16 v[18:21], v[152:155], v[94:97], v[18:21]
	v_mfma_f32_16x16x32_bf16 v[14:17], v[106:109], v[202:205], v[14:17]
	v_mfma_f32_16x16x32_bf16 v[10:13], v[230:233], v[202:205], v[10:13]
	v_mfma_f32_16x16x32_bf16 v[6:9], v[110:113], v[214:217], v[6:9]
	v_mfma_f32_16x16x32_bf16 v[2:5], v[152:155], v[214:217], v[2:5]
	v_mfma_f32_16x16x32_bf16 v[132:135], v[110:113], v[78:81], v[30:33]
	v_mfma_f32_16x16x32_bf16 v[136:139], v[152:155], v[78:81], v[26:29]
	v_mfma_f32_16x16x32_bf16 v[166:169], v[110:113], v[206:209], v[14:17]
	v_mfma_f32_16x16x32_bf16 v[170:173], v[152:155], v[206:209], v[10:13]
	s_barrier
	s_nop 0
	ds_read_b128 v[10:13], v150
	ds_read_b128 v[14:17], v150 offset:1024
	ds_read_b128 v[152:155], v150 offset:2048
	ds_read_b128 v[202:205], v150 offset:3072
	ds_read_b128 v[26:29], v146 offset:32768
	ds_read_b128 v[30:33], v146 offset:33792
	ds_read_b128 v[42:45], v145 offset:32768
	ds_read_b128 v[46:49], v145 offset:33792
	ds_read_b128 v[206:209], v144 offset:32768
	ds_read_b128 v[210:213], v144 offset:33792
	ds_read_b128 v[214:217], v143 offset:32768
	ds_read_b128 v[230:233], v143 offset:33792
	s_waitcnt vmcnt(2)
	s_barrier
; #define LDA(dst,b,h) for(int m=0;m<4;++m)for(int k=0;k<2;++k) \
;     dst[m][k]=*reinterpret_cast<const bf16x8*>((char*)SA(b,h)+lds_byte(wr*64+m*16+fr,k*32+fq*8))
; #define LDB(dst,b,h) for(int n=0;n<2;++n)for(int k=0;k<2;++k) \
;     dst[n][k]=*reinterpret_cast<const bf16x8*>((char*)SB(b,h)+lds_byte(wc*32+n*16+fr,k*32+fq*8))
; #define MMA(ai,bj,At,Bt_) do{__builtin_amdgcn_s_setprio(1); \
;     for(int m=0;m<4;++m)for(int n=0;n<2;++n)for(int k=0;k<2;++k) \
;       acc[ai][bj][m][n]=__builtin_amdgcn_mfma_f32_16x16x32_bf16(Bt_[n][k],At[m][k],acc[ai][bj][m][n],0,0,0); \
;     __builtin_amdgcn_s_setprio(0);}while(0)
; #define WAIT_V(n) asm volatile("s_waitcnt vmcnt(" #n ")":::"memory")
; #define WAIT_L(n) asm volatile("s_waitcnt lgkmcnt(" #n ")":::"memory")
; #define BAR __builtin_amdgcn_s_barrier()
; template <int EPI>
; __device__ __forceinline__ void gemm_run(const GD& c, const bool has_next, const GD& nx, const Ctx& e, bf16* shm, float* rs, float* rs_nxt, float* racc_) {
;     ...
;     LDA(At,0,1); WAIT_V(4); BAR; WAIT_L(0); MMA(1,0,At,B0); MMA(1,1,At,B1); BAR; }
;   { LDB(B0,1,0); LDA(At,1,0); WAIT_V(2); BAR; WAIT_L(0); MMA(0,0,At,B0); BAR;
;     LDB(B1,1,1); WAIT_V(0); BAR; WAIT_L(0); MMA(0,1,At,B1); BAR;
;     LDA(At,1,1); BAR; WAIT_L(0); MMA(1,0,At,B0); MMA(1,1,At,B1); BAR; }
;   if(wr==0)BAR;
	s_waitcnt lgkmcnt(0)
	v_mfma_f32_16x16x32_bf16 v[74:77], v[10:13], v[26:29], v[126:129]
	v_mfma_f32_16x16x32_bf16 v[126:129], v[14:17], v[30:33], v[74:77]
	v_mfma_f32_16x16x32_bf16 v[74:77], v[152:155], v[26:29], v[122:125]
	v_mfma_f32_16x16x32_bf16 v[122:125], v[202:205], v[30:33], v[74:77]
	v_mfma_f32_16x16x32_bf16 v[74:77], v[10:13], v[42:45], v[118:121]
	v_mfma_f32_16x16x32_bf16 v[110:113], v[14:17], v[46:49], v[74:77]
	v_mfma_f32_16x16x32_bf16 v[74:77], v[152:155], v[42:45], v[114:117]
	v_mfma_f32_16x16x32_bf16 v[106:109], v[202:205], v[46:49], v[74:77]
	v_mfma_f32_16x16x32_bf16 v[74:77], v[10:13], v[206:209], v[222:225]
	v_mfma_f32_16x16x32_bf16 v[94:97], v[14:17], v[210:213], v[74:77]
	v_mfma_f32_16x16x32_bf16 v[74:77], v[152:155], v[206:209], v[226:229]
	v_mfma_f32_16x16x32_bf16 v[90:93], v[202:205], v[210:213], v[74:77]
	v_mfma_f32_16x16x32_bf16 v[74:77], v[10:13], v[214:217], v[102:105]
	v_mfma_f32_16x16x32_bf16 v[78:81], v[14:17], v[230:233], v[74:77]
	v_mfma_f32_16x16x32_bf16 v[74:77], v[152:155], v[214:217], v[98:101]
	v_mfma_f32_16x16x32_bf16 v[74:77], v[202:205], v[230:233], v[74:77]
	s_barrier
	ds_read_b128 v[222:225], v148
	ds_read_b128 v[226:229], v148 offset:1024
	ds_read_b128 v[242:245], v148 offset:2048
	ds_read_b128 v[148:151], v148 offset:3072
	s_waitcnt vmcnt(0)
	s_barrier
	s_waitcnt lgkmcnt(0)
	v_mfma_f32_16x16x32_bf16 v[98:101], v[222:225], v[26:29], v[234:237]
	v_mfma_f32_16x16x32_bf16 v[26:29], v[242:245], v[26:29], v[190:193]
	v_mfma_f32_16x16x32_bf16 v[114:117], v[148:151], v[30:33], v[26:29]
	v_mfma_f32_16x16x32_bf16 v[26:29], v[222:225], v[42:45], v[86:89]
	v_mfma_f32_16x16x32_bf16 v[102:105], v[226:229], v[46:49], v[26:29]
	v_mfma_f32_16x16x32_bf16 v[26:29], v[242:245], v[42:45], v[82:85]
	v_mfma_f32_16x16x32_bf16 v[118:121], v[226:229], v[30:33], v[98:101]
	v_mfma_f32_16x16x32_bf16 v[98:101], v[148:151], v[46:49], v[26:29]
	v_mfma_f32_16x16x32_bf16 v[26:29], v[222:225], v[206:209], v[194:197]
	v_mfma_f32_16x16x32_bf16 v[86:89], v[226:229], v[210:213], v[26:29]
	v_mfma_f32_16x16x32_bf16 v[26:29], v[242:245], v[206:209], v[198:201]
	v_mfma_f32_16x16x32_bf16 v[82:85], v[148:151], v[210:213], v[26:29]
	v_mfma_f32_16x16x32_bf16 v[26:29], v[222:225], v[214:217], v[70:73]
	v_mfma_f32_16x16x32_bf16 v[70:73], v[226:229], v[230:233], v[26:29]
	v_mfma_f32_16x16x32_bf16 v[26:29], v[242:245], v[214:217], v[66:69]
	v_mfma_f32_16x16x32_bf16 v[66:69], v[148:151], v[230:233], v[26:29]
	s_barrier
	ds_read_b128 v[190:193], v146 offset:49152
	ds_read_b128 v[194:197], v146 offset:50176
	ds_read_b128 v[198:201], v145 offset:49152
	ds_read_b128 v[206:209], v145 offset:50176
	ds_read_b128 v[210:213], v144 offset:49152
	ds_read_b128 v[144:147], v144 offset:50176
	ds_read_b128 v[214:217], v143 offset:49152
	ds_read_b128 v[230:233], v143 offset:50176
	s_barrier
	s_waitcnt lgkmcnt(0)
	v_mfma_f32_16x16x32_bf16 v[26:29], v[10:13], v[190:193], v[62:65]
	v_mfma_f32_16x16x32_bf16 v[62:65], v[14:17], v[194:197], v[26:29]
	v_mfma_f32_16x16x32_bf16 v[26:29], v[152:155], v[190:193], v[58:61]
	v_mfma_f32_16x16x32_bf16 v[58:61], v[202:205], v[194:197], v[26:29]
	v_mfma_f32_16x16x32_bf16 v[26:29], v[10:13], v[198:201], v[54:57]
	v_mfma_f32_16x16x32_bf16 v[46:49], v[14:17], v[206:209], v[26:29]
	v_mfma_f32_16x16x32_bf16 v[26:29], v[152:155], v[198:201], v[50:53]
	v_mfma_f32_16x16x32_bf16 v[42:45], v[202:205], v[206:209], v[26:29]
	v_mfma_f32_16x16x32_bf16 v[26:29], v[10:13], v[210:213], v[218:221]
	v_mfma_f32_16x16x32_bf16 v[10:13], v[10:13], v[214:217], v[38:41]
	v_mfma_f32_16x16x32_bf16 v[30:33], v[14:17], v[144:147], v[26:29]
	v_mfma_f32_16x16x32_bf16 v[26:29], v[152:155], v[210:213], v[238:241]
	v_mfma_f32_16x16x32_bf16 v[14:17], v[14:17], v[230:233], v[10:13]
	v_mfma_f32_16x16x32_bf16 v[10:13], v[152:155], v[214:217], v[34:37]
	v_mfma_f32_16x16x32_bf16 v[26:29], v[202:205], v[144:147], v[26:29]
	v_mfma_f32_16x16x32_bf16 v[10:13], v[202:205], v[230:233], v[10:13]
	v_mfma_f32_16x16x32_bf16 v[34:37], v[222:225], v[190:193], v[132:135]
	v_mfma_f32_16x16x32_bf16 v[54:57], v[226:229], v[194:197], v[34:37]
	v_mfma_f32_16x16x32_bf16 v[34:37], v[242:245], v[190:193], v[136:139]
	v_mfma_f32_16x16x32_bf16 v[18:21], v[242:245], v[198:201], v[18:21]
	v_mfma_f32_16x16x32_bf16 v[50:53], v[148:151], v[194:197], v[34:37]
	v_mfma_f32_16x16x32_bf16 v[22:25], v[222:225], v[198:201], v[22:25]
	v_mfma_f32_16x16x32_bf16 v[34:37], v[148:151], v[206:209], v[18:21]
	v_mfma_f32_16x16x32_bf16 v[18:21], v[222:225], v[210:213], v[166:169]
	v_mfma_f32_16x16x32_bf16 v[38:41], v[226:229], v[206:209], v[22:25]
	v_mfma_f32_16x16x32_bf16 v[22:25], v[226:229], v[144:147], v[18:21]
	v_mfma_f32_16x16x32_bf16 v[18:21], v[242:245], v[210:213], v[170:173]
	v_mfma_f32_16x16x32_bf16 v[6:9], v[222:225], v[214:217], v[6:9]
	v_mfma_f32_16x16x32_bf16 v[2:5], v[242:245], v[214:217], v[2:5]
	v_mfma_f32_16x16x32_bf16 v[18:21], v[148:151], v[144:147], v[18:21]
	v_mfma_f32_16x16x32_bf16 v[6:9], v[226:229], v[230:233], v[6:9]
	v_mfma_f32_16x16x32_bf16 v[2:5], v[148:151], v[230:233], v[2:5]
	v_cmp_gt_u32_e32 vcc, s96, v141
	s_barrier
	s_and_saveexec_b64 s[2:3], vcc
	s_cbranch_execz .LBB0_329
	s_barrier

; #define STAGE_A(P,br,kt) STAGE_G(P,c.A,c.lda,br,(long)(kt)*c.kstr)
; #define STAGE_B(P,br,kt) STAGE_G(P,c.Bt,c.K,br,(long)(kt)*BK)
; #define LDA(dst,b,h) for(int m=0;m<4;++m)for(int k=0;k<2;++k) \
;     dst[m][k]=*reinterpret_cast<const bf16x8*>((char*)SA(b,h)+lds_byte(wr*64+m*16+fr,k*32+fq*8))
; #define LDB(dst,b,h) for(int n=0;n<2;++n)for(int k=0;k<2;++k) \
;     dst[n][k]=*reinterpret_cast<const bf16x8*>((char*)SB(b,h)+lds_byte(wc*32+n*16+fr,k*32+fq*8))
; #define MMA(ai,bj,At,Bt_) do{__builtin_amdgcn_s_setprio(1); \
;     for(int m=0;m<4;++m)for(int n=0;n<2;++n)for(int k=0;k<2;++k) \
;       acc[ai][bj][m][n]=__builtin_amdgcn_mfma_f32_16x16x32_bf16(Bt_[n][k],At[m][k],acc[ai][bj][m][n],0,0,0); \
;     __builtin_amdgcn_s_setprio(0);}while(0)
; #define WAIT_V(n) asm volatile("s_waitcnt vmcnt(" #n ")":::"memory")
; #define WAIT_L(n) asm volatile("s_waitcnt lgkmcnt(" #n ")":::"memory")
; #define BAR __builtin_amdgcn_s_barrier()
; #define SCHED __builtin_amdgcn_sched_barrier(0)
; template <int EPI>
; __device__ __forceinline__ void gemm_run(const GD& c, const bool has_next, const GD& nx, const Ctx& e, bf16* shm, float* rs, float* rs_nxt, float* racc_) {
;     ...
;   for(int t=0;t<nt-2;t+=2){
;     LDB(B0,0,0); SCHED; LDA(At,0,0); STAGE_A(SA(1,1),brow+HALF,t+1);
;     WAIT_L(8); BAR; WAIT_L(0); MMA(0,0,At,B0); BAR; SCHED;
;     LDB(B1,0,1); STAGE_B(SB(0,0),bcol,t+2);
;     BAR; WAIT_L(0); MMA(0,1,At,B1); BAR;
;     LDA(At,0,1); STAGE_A(SA(0,0),brow,t+2);
;     BAR; WAIT_L(0); MMA(1,0,At,B0); BAR; SCHED;
;     STAGE_B(SB(0,1),bcol+HALF,t+2);
;     WAIT_V(6); BAR; MMA(1,1,At,B1); BAR;
.LBB0_357:
	ds_read_b128 v[158:161], v155
	ds_read_b128 v[166:169], v155 offset:1024
	ds_read_b128 v[170:173], v155 offset:2048
	ds_read_b128 v[190:193], v155 offset:3072
	v_add_u32_e32 v156, 0xc000, v150
	v_lshl_add_u64 v[162:163], v[132:133], 0, s[4:5]
	v_readfirstlane_b32 s12, v156
	v_lshl_add_u64 v[174:175], v[162:163], 0, s[90:91]
	s_mov_b32 m0, s12
	v_add_u32_e32 v157, 0xe000, v150
	ds_read_b128 v[194:197], v145
	ds_read_b128 v[198:201], v145 offset:1024
	ds_read_b128 v[202:205], v144
	ds_read_b128 v[206:209], v144 offset:1024
	ds_read_b128 v[210:213], v143
	ds_read_b128 v[214:217], v143 offset:1024
	ds_read_b128 v[218:221], v142
	ds_read_b128 v[222:225], v142 offset:1024
	global_load_lds_dwordx4 v[174:175], off
	v_lshl_add_u64 v[174:175], v[134:135], 0, s[4:5]
	v_readfirstlane_b32 s12, v157
	v_lshl_add_u64 v[186:187], v[174:175], 0, s[90:91]
	s_mov_b32 m0, s12
	s_nop 0
	global_load_lds_dwordx4 v[186:187], off
	s_waitcnt lgkmcnt(8)
	s_barrier
	s_waitcnt lgkmcnt(0)
	v_mfma_f32_16x16x32_bf16 v[126:129], v[158:161], v[194:197], v[126:129]
	v_mfma_f32_16x16x32_bf16 v[122:125], v[170:173], v[194:197], v[122:125]
	v_mfma_f32_16x16x32_bf16 v[118:121], v[158:161], v[202:205], v[118:121]
	v_mfma_f32_16x16x32_bf16 v[114:117], v[170:173], v[202:205], v[114:117]
	v_mfma_f32_16x16x32_bf16 v[110:113], v[158:161], v[210:213], v[110:113]
	v_mfma_f32_16x16x32_bf16 v[106:109], v[170:173], v[210:213], v[106:109]
	v_mfma_f32_16x16x32_bf16 v[102:105], v[158:161], v[218:221], v[102:105]
	v_mfma_f32_16x16x32_bf16 v[98:101], v[170:173], v[218:221], v[98:101]
	v_mfma_f32_16x16x32_bf16 v[126:129], v[166:169], v[198:201], v[126:129]
	v_mfma_f32_16x16x32_bf16 v[122:125], v[190:193], v[198:201], v[122:125]
	v_mfma_f32_16x16x32_bf16 v[118:121], v[166:169], v[206:209], v[118:121]
	v_mfma_f32_16x16x32_bf16 v[114:117], v[190:193], v[206:209], v[114:117]
	v_mfma_f32_16x16x32_bf16 v[110:113], v[166:169], v[214:217], v[110:113]
	v_mfma_f32_16x16x32_bf16 v[106:109], v[190:193], v[214:217], v[106:109]
	v_mfma_f32_16x16x32_bf16 v[102:105], v[166:169], v[222:225], v[102:105]
	v_mfma_f32_16x16x32_bf16 v[98:101], v[190:193], v[222:225], v[98:101]
	s_barrier
	v_add_u32_e32 v176, s33, v146
	v_lshl_add_u64 v[186:187], v[136:137], 0, s[4:5]
	v_readfirstlane_b32 s12, v176
	v_lshl_add_u64 v[188:189], v[186:187], 0, s[26:27]
	s_mov_b32 m0, s12
	v_add_u32_e32 v176, 0x2000, v176
	ds_read_b128 v[226:229], v154
	ds_read_b128 v[230:233], v154 offset:1024
	ds_read_b128 v[234:237], v154 offset:2048
	ds_read_b128 v[238:241], v154 offset:3072
	global_load_lds_dwordx4 v[188:189], off
	v_lshl_add_u64 v[188:189], v[138:139], 0, s[4:5]
	v_readfirstlane_b32 s12, v176
	v_lshl_add_u64 v[242:243], v[188:189], 0, s[26:27]
	s_mov_b32 m0, s12
	s_add_i32 s11, s11, 2
	global_load_lds_dwordx4 v[242:243], off
	s_barrier
	s_waitcnt lgkmcnt(0)
	v_mfma_f32_16x16x32_bf16 v[94:97], v[226:229], v[194:197], v[94:97]
	v_mfma_f32_16x16x32_bf16 v[90:93], v[234:237], v[194:197], v[90:93]
	v_mfma_f32_16x16x32_bf16 v[86:89], v[226:229], v[202:205], v[86:89]
	v_mfma_f32_16x16x32_bf16 v[82:85], v[234:237], v[202:205], v[82:85]
	v_readfirstlane_b32 s12, v150
	v_mfma_f32_16x16x32_bf16 v[78:81], v[226:229], v[210:213], v[78:81]
	v_add_u32_e32 v176, 0x2000, v150
	v_mfma_f32_16x16x32_bf16 v[74:77], v[234:237], v[210:213], v[74:77]
	v_lshl_add_u64 v[242:243], v[162:163], 0, s[0:1]
	v_mfma_f32_16x16x32_bf16 v[70:73], v[226:229], v[218:221], v[70:73]
	s_mov_b32 m0, s12
	v_mfma_f32_16x16x32_bf16 v[66:69], v[234:237], v[218:221], v[66:69]
	v_readfirstlane_b32 s12, v176
	v_mfma_f32_16x16x32_bf16 v[94:97], v[230:233], v[198:201], v[94:97]
	v_mfma_f32_16x16x32_bf16 v[90:93], v[238:241], v[198:201], v[90:93]
	v_mfma_f32_16x16x32_bf16 v[86:89], v[230:233], v[206:209], v[86:89]
	v_mfma_f32_16x16x32_bf16 v[82:85], v[238:241], v[206:209], v[82:85]
	v_mfma_f32_16x16x32_bf16 v[78:81], v[230:233], v[214:217], v[78:81]
	v_mfma_f32_16x16x32_bf16 v[74:77], v[238:241], v[214:217], v[74:77]
	v_mfma_f32_16x16x32_bf16 v[70:73], v[230:233], v[222:225], v[70:73]
	v_mfma_f32_16x16x32_bf16 v[66:69], v[238:241], v[222:225], v[66:69]
	s_barrier
	ds_read_b128 v[194:197], v145 offset:16384
	ds_read_b128 v[198:201], v145 offset:17408
	ds_read_b128 v[202:205], v144 offset:16384
	ds_read_b128 v[206:209], v144 offset:17408
	ds_read_b128 v[210:213], v143 offset:16384
	ds_read_b128 v[214:217], v143 offset:17408
	ds_read_b128 v[218:221], v142 offset:16384
	ds_read_b128 v[222:225], v142 offset:17408
	global_load_lds_dwordx4 v[242:243], off
	v_lshl_add_u64 v[242:243], v[174:175], 0, s[0:1]
	s_mov_b32 m0, s12
	s_nop 0
	global_load_lds_dwordx4 v[242:243], off
	s_barrier
	s_waitcnt lgkmcnt(0)
	v_mfma_f32_16x16x32_bf16 v[62:65], v[158:161], v[194:197], v[62:65]
	v_mfma_f32_16x16x32_bf16 v[58:61], v[170:173], v[194:197], v[58:61]
	v_mfma_f32_16x16x32_bf16 v[54:57], v[158:161], v[202:205], v[54:57]
	v_mfma_f32_16x16x32_bf16 v[50:53], v[170:173], v[202:205], v[50:53]
	v_mfma_f32_16x16x32_bf16 v[46:49], v[158:161], v[210:213], v[46:49]
	v_mfma_f32_16x16x32_bf16 v[42:45], v[170:173], v[210:213], v[42:45]
	v_mfma_f32_16x16x32_bf16 v[38:41], v[158:161], v[218:221], v[38:41]
	v_mfma_f32_16x16x32_bf16 v[34:37], v[170:173], v[218:221], v[34:37]
	v_mfma_f32_16x16x32_bf16 v[62:65], v[166:169], v[198:201], v[62:65]
	v_mfma_f32_16x16x32_bf16 v[58:61], v[190:193], v[198:201], v[58:61]
	v_mfma_f32_16x16x32_bf16 v[54:57], v[166:169], v[206:209], v[54:57]
	v_mfma_f32_16x16x32_bf16 v[50:53], v[190:193], v[206:209], v[50:53]
	v_mfma_f32_16x16x32_bf16 v[46:49], v[166:169], v[214:217], v[46:49]
	v_mfma_f32_16x16x32_bf16 v[42:45], v[190:193], v[214:217], v[42:45]
	v_mfma_f32_16x16x32_bf16 v[38:41], v[166:169], v[222:225], v[38:41]
	v_mfma_f32_16x16x32_bf16 v[34:37], v[190:193], v[222:225], v[34:37]
	s_barrier
; #define STAGE_A(P,br,kt) STAGE_G(P,c.A,c.lda,br,(long)(kt)*c.kstr)
; #define STAGE_B(P,br,kt) STAGE_G(P,c.Bt,c.K,br,(long)(kt)*BK)
; #define LDA(dst,b,h) for(int m=0;m<4;++m)for(int k=0;k<2;++k) \
;     dst[m][k]=*reinterpret_cast<const bf16x8*>((char*)SA(b,h)+lds_byte(wr*64+m*16+fr,k*32+fq*8))
; #define LDB(dst,b,h) for(int n=0;n<2;++n)for(int k=0;k<2;++k) \
;     dst[n][k]=*reinterpret_cast<const bf16x8*>((char*)SB(b,h)+lds_byte(wc*32+n*16+fr,k*32+fq*8))
; #define MMA(ai,bj,At,Bt_) do{__builtin_amdgcn_s_setprio(1); \
;     for(int m=0;m<4;++m)for(int n=0;n<2;++n)for(int k=0;k<2;++k) \
;       acc[ai][bj][m][n]=__builtin_amdgcn_mfma_f32_16x16x32_bf16(Bt_[n][k],At[m][k],acc[ai][bj][m][n],0,0,0); \
;     __builtin_amdgcn_s_setprio(0);}while(0)
; #define WAIT_V(n) asm volatile("s_waitcnt vmcnt(" #n ")":::"memory")
; #define WAIT_L(n) asm volatile("s_waitcnt lgkmcnt(" #n ")":::"memory")
; #define BAR __builtin_amdgcn_s_barrier()
; #define SCHED __builtin_amdgcn_sched_barrier(0)
; template <int EPI>
; __device__ __forceinline__ void gemm_run(const GD& c, const bool has_next, const GD& nx, const Ctx& e, bf16* shm, float* rs, float* rs_nxt, float* racc_) {
;     ...
;     WAIT_V(6); BAR; MMA(1,1,At,B1); BAR;
;     LDB(B0,1,0); SCHED; LDA(At,1,0); STAGE_A(SA(0,1),brow+HALF,t+2);
;     WAIT_L(8); BAR; WAIT_L(0); MMA(0,0,At,B0); BAR; SCHED;
;     LDB(B1,1,1); STAGE_B(SB(1,0),bcol,t+3);
;     BAR; WAIT_L(0); MMA(0,1,At,B1); BAR;
;     LDA(At,1,1); STAGE_A(SA(1,0),brow,t+3);
;     BAR; WAIT_L(0); MMA(1,0,At,B0); BAR; SCHED;
;     STAGE_B(SB(1,1),bcol+HALF,t+3);
;     WAIT_V(6); BAR; MMA(1,1,At,B1); BAR;
	v_add_u32_e32 v160, s86, v146
	v_lshl_add_u64 v[158:159], v[186:187], 0, s[28:29]
	v_readfirstlane_b32 s12, v160
	v_add_u32_e32 v160, 0x2000, v160
	s_mov_b32 m0, s12
	v_readfirstlane_b32 s12, v160
	global_load_lds_dwordx4 v[158:159], off
	v_lshl_add_u64 v[158:159], v[188:189], 0, s[28:29]
	s_mov_b32 m0, s12
	s_nop 0
	global_load_lds_dwordx4 v[158:159], off
	s_waitcnt vmcnt(6)
	s_barrier
	v_mfma_f32_16x16x32_bf16 v[30:33], v[226:229], v[194:197], v[30:33]
	v_mfma_f32_16x16x32_bf16 v[26:29], v[234:237], v[194:197], v[26:29]
	v_mfma_f32_16x16x32_bf16 v[22:25], v[226:229], v[202:205], v[22:25]
	v_mfma_f32_16x16x32_bf16 v[18:21], v[234:237], v[202:205], v[18:21]
	v_mfma_f32_16x16x32_bf16 v[14:17], v[226:229], v[210:213], v[14:17]
	v_mfma_f32_16x16x32_bf16 v[10:13], v[234:237], v[210:213], v[10:13]
	v_mfma_f32_16x16x32_bf16 v[6:9], v[226:229], v[218:221], v[6:9]
	v_mfma_f32_16x16x32_bf16 v[2:5], v[234:237], v[218:221], v[2:5]
	v_mfma_f32_16x16x32_bf16 v[30:33], v[230:233], v[198:201], v[30:33]
	v_mfma_f32_16x16x32_bf16 v[26:29], v[238:241], v[198:201], v[26:29]
	v_mfma_f32_16x16x32_bf16 v[22:25], v[230:233], v[206:209], v[22:25]
	v_mfma_f32_16x16x32_bf16 v[18:21], v[238:241], v[206:209], v[18:21]
	v_mfma_f32_16x16x32_bf16 v[14:17], v[230:233], v[214:217], v[14:17]
	v_mfma_f32_16x16x32_bf16 v[10:13], v[238:241], v[214:217], v[10:13]
	v_mfma_f32_16x16x32_bf16 v[6:9], v[230:233], v[222:225], v[6:9]
	v_mfma_f32_16x16x32_bf16 v[2:5], v[238:241], v[222:225], v[2:5]
	s_barrier
	ds_read_b128 v[158:161], v149
	ds_read_b128 v[166:169], v149 offset:1024
	ds_read_b128 v[170:173], v149 offset:2048
	ds_read_b128 v[190:193], v149 offset:3072
	v_add_u32_e32 v176, 0x4000, v150
	v_lshl_add_u64 v[226:227], v[162:163], 0, s[76:77]
	v_readfirstlane_b32 s12, v176
	v_add_u32_e32 v176, 0x6000, v150
	s_mov_b32 m0, s12
	v_readfirstlane_b32 s12, v176
	ds_read_b128 v[194:197], v145 offset:32768
	ds_read_b128 v[198:201], v145 offset:33792
	ds_read_b128 v[202:205], v144 offset:32768
	ds_read_b128 v[206:209], v144 offset:33792
	ds_read_b128 v[210:213], v143 offset:32768
	ds_read_b128 v[214:217], v143 offset:33792
	ds_read_b128 v[218:221], v142 offset:32768
	ds_read_b128 v[222:225], v142 offset:33792
	global_load_lds_dwordx4 v[226:227], off
	v_lshl_add_u64 v[226:227], v[174:175], 0, s[76:77]
	s_mov_b32 m0, s12
	s_nop 0
	global_load_lds_dwordx4 v[226:227], off
	s_waitcnt lgkmcnt(8)
	s_barrier
	s_waitcnt lgkmcnt(0)
	v_mfma_f32_16x16x32_bf16 v[126:129], v[158:161], v[194:197], v[126:129]
	v_mfma_f32_16x16x32_bf16 v[122:125], v[170:173], v[194:197], v[122:125]
	v_mfma_f32_16x16x32_bf16 v[118:121], v[158:161], v[202:205], v[118:121]
	v_mfma_f32_16x16x32_bf16 v[114:117], v[170:173], v[202:205], v[114:117]
	v_mfma_f32_16x16x32_bf16 v[110:113], v[158:161], v[210:213], v[110:113]
	v_mfma_f32_16x16x32_bf16 v[106:109], v[170:173], v[210:213], v[106:109]
	v_mfma_f32_16x16x32_bf16 v[102:105], v[158:161], v[218:221], v[102:105]
	v_mfma_f32_16x16x32_bf16 v[98:101], v[170:173], v[218:221], v[98:101]
	v_mfma_f32_16x16x32_bf16 v[126:129], v[166:169], v[198:201], v[126:129]
	v_mfma_f32_16x16x32_bf16 v[122:125], v[190:193], v[198:201], v[122:125]
	v_mfma_f32_16x16x32_bf16 v[118:121], v[166:169], v[206:209], v[118:121]
	v_mfma_f32_16x16x32_bf16 v[114:117], v[190:193], v[206:209], v[114:117]
	v_mfma_f32_16x16x32_bf16 v[110:113], v[166:169], v[214:217], v[110:113]
	v_mfma_f32_16x16x32_bf16 v[106:109], v[190:193], v[214:217], v[106:109]
	v_mfma_f32_16x16x32_bf16 v[102:105], v[166:169], v[222:225], v[102:105]
	v_mfma_f32_16x16x32_bf16 v[98:101], v[190:193], v[222:225], v[98:101]
	s_barrier
	v_readfirstlane_b32 s12, v148
	v_add_u32_e32 v176, 0x2000, v148
	v_lshl_add_u64 v[242:243], v[186:187], 0, s[30:31]
	s_mov_b32 m0, s12
	v_readfirstlane_b32 s12, v176
	ds_read_b128 v[226:229], v147
	ds_read_b128 v[230:233], v147 offset:1024
	ds_read_b128 v[234:237], v147 offset:2048
	ds_read_b128 v[238:241], v147 offset:3072
	global_load_lds_dwordx4 v[242:243], off
	v_lshl_add_u64 v[242:243], v[188:189], 0, s[30:31]
	s_mov_b32 m0, s12
	s_nop 0
	global_load_lds_dwordx4 v[242:243], off
	s_barrier
	s_waitcnt lgkmcnt(0)
	v_mfma_f32_16x16x32_bf16 v[94:97], v[226:229], v[194:197], v[94:97]
	v_mfma_f32_16x16x32_bf16 v[90:93], v[234:237], v[194:197], v[90:93]
	v_mfma_f32_16x16x32_bf16 v[86:89], v[226:229], v[202:205], v[86:89]
	v_mfma_f32_16x16x32_bf16 v[82:85], v[234:237], v[202:205], v[82:85]
	v_readfirstlane_b32 s12, v151
	v_mfma_f32_16x16x32_bf16 v[78:81], v[226:229], v[210:213], v[78:81]
	v_lshl_add_u64 v[162:163], v[162:163], 0, s[74:75]
	v_mfma_f32_16x16x32_bf16 v[74:77], v[234:237], v[210:213], v[74:77]
	s_mov_b32 m0, s12
	v_mfma_f32_16x16x32_bf16 v[70:73], v[226:229], v[218:221], v[70:73]
	v_readfirstlane_b32 s12, v152
	v_mfma_f32_16x16x32_bf16 v[66:69], v[234:237], v[218:221], v[66:69]
	v_mfma_f32_16x16x32_bf16 v[94:97], v[230:233], v[198:201], v[94:97]
	v_mfma_f32_16x16x32_bf16 v[90:93], v[238:241], v[198:201], v[90:93]
	v_mfma_f32_16x16x32_bf16 v[86:89], v[230:233], v[206:209], v[86:89]
	v_mfma_f32_16x16x32_bf16 v[82:85], v[238:241], v[206:209], v[82:85]
	v_mfma_f32_16x16x32_bf16 v[78:81], v[230:233], v[214:217], v[78:81]
	v_mfma_f32_16x16x32_bf16 v[74:77], v[238:241], v[214:217], v[74:77]
	v_mfma_f32_16x16x32_bf16 v[70:73], v[230:233], v[222:225], v[70:73]
	v_mfma_f32_16x16x32_bf16 v[66:69], v[238:241], v[222:225], v[66:69]
	s_barrier
	ds_read_b128 v[194:197], v145 offset:49152
	ds_read_b128 v[198:201], v145 offset:50176
	ds_read_b128 v[202:205], v144 offset:49152
	ds_read_b128 v[206:209], v144 offset:50176
	ds_read_b128 v[210:213], v143 offset:49152
	ds_read_b128 v[214:217], v143 offset:50176
	ds_read_b128 v[218:221], v142 offset:49152
	ds_read_b128 v[222:225], v142 offset:50176
	global_load_lds_dwordx4 v[162:163], off
	v_lshl_add_u64 v[162:163], v[174:175], 0, s[74:75]
	s_mov_b32 m0, s12
	s_nop 0
	global_load_lds_dwordx4 v[162:163], off
	s_barrier
; #define STAGE_A(P,br,kt) STAGE_G(P,c.A,c.lda,br,(long)(kt)*c.kstr)
; #define STAGE_B(P,br,kt) STAGE_G(P,c.Bt,c.K,br,(long)(kt)*BK)
; #define LDA(dst,b,h) for(int m=0;m<4;++m)for(int k=0;k<2;++k) \
;     dst[m][k]=*reinterpret_cast<const bf16x8*>((char*)SA(b,h)+lds_byte(wr*64+m*16+fr,k*32+fq*8))
; #define LDB(dst,b,h) for(int n=0;n<2;++n)for(int k=0;k<2;++k) \
;     dst[n][k]=*reinterpret_cast<const bf16x8*>((char*)SB(b,h)+lds_byte(wc*32+n*16+fr,k*32+fq*8))
; #define MMA(ai,bj,At,Bt_) do{__builtin_amdgcn_s_setprio(1); \
;     for(int m=0;m<4;++m)for(int n=0;n<2;++n)for(int k=0;k<2;++k) \
;       acc[ai][bj][m][n]=__builtin_amdgcn_mfma_f32_16x16x32_bf16(Bt_[n][k],At[m][k],acc[ai][bj][m][n],0,0,0); \
;     __builtin_amdgcn_s_setprio(0);}while(0)
; #define WAIT_V(n) asm volatile("s_waitcnt vmcnt(" #n ")":::"memory")
; #define WAIT_L(n) asm volatile("s_waitcnt lgkmcnt(" #n ")":::"memory")
; #define BAR __builtin_amdgcn_s_barrier()
; #define SCHED __builtin_amdgcn_sched_barrier(0)
; template <int EPI>
; __device__ __forceinline__ void gemm_run(const GD& c, const bool has_next, const GD& nx, const Ctx& e, bf16* shm, float* rs, float* rs_nxt, float* racc_) {
;     ...
;     BAR; WAIT_L(0); MMA(1,0,At,B0); BAR; SCHED;
;     STAGE_B(SB(1,1),bcol+HALF,t+3);
;     WAIT_V(6); BAR; MMA(1,1,At,B1); BAR;
;   }
;   { LDB(B0,0,0); LDA(At,0,0); STAGE_A(SA(1,1),brow+HALF,nt-1);
;     BAR; WAIT_L(0); MMA(0,0,At,B0); BAR;
	s_waitcnt lgkmcnt(0)
	v_mfma_f32_16x16x32_bf16 v[62:65], v[158:161], v[194:197], v[62:65]
	v_mfma_f32_16x16x32_bf16 v[58:61], v[170:173], v[194:197], v[58:61]
	v_mfma_f32_16x16x32_bf16 v[54:57], v[158:161], v[202:205], v[54:57]
	v_mfma_f32_16x16x32_bf16 v[50:53], v[170:173], v[202:205], v[50:53]
	v_mfma_f32_16x16x32_bf16 v[46:49], v[158:161], v[210:213], v[46:49]
	v_mfma_f32_16x16x32_bf16 v[42:45], v[170:173], v[210:213], v[42:45]
	v_mfma_f32_16x16x32_bf16 v[38:41], v[158:161], v[218:221], v[38:41]
	v_mfma_f32_16x16x32_bf16 v[34:37], v[170:173], v[218:221], v[34:37]
	v_mfma_f32_16x16x32_bf16 v[62:65], v[166:169], v[198:201], v[62:65]
	v_mfma_f32_16x16x32_bf16 v[58:61], v[190:193], v[198:201], v[58:61]
	v_mfma_f32_16x16x32_bf16 v[54:57], v[166:169], v[206:209], v[54:57]
	v_mfma_f32_16x16x32_bf16 v[50:53], v[190:193], v[206:209], v[50:53]
	v_mfma_f32_16x16x32_bf16 v[46:49], v[166:169], v[214:217], v[46:49]
	v_mfma_f32_16x16x32_bf16 v[42:45], v[190:193], v[214:217], v[42:45]
	v_mfma_f32_16x16x32_bf16 v[38:41], v[166:169], v[222:225], v[38:41]
	v_mfma_f32_16x16x32_bf16 v[34:37], v[190:193], v[222:225], v[34:37]
	s_barrier
	v_readfirstlane_b32 s12, v153
	v_add_u32_e32 v160, 0x2000, v153
	v_lshl_add_u64 v[158:159], v[186:187], 0, s[34:35]
	s_mov_b32 m0, s12
	v_readfirstlane_b32 s12, v160
	global_load_lds_dwordx4 v[158:159], off
	v_lshl_add_u64 v[158:159], v[188:189], 0, s[34:35]
	s_mov_b32 m0, s12
	s_nop 0
	global_load_lds_dwordx4 v[158:159], off
	s_waitcnt vmcnt(6)
	s_barrier
	v_mfma_f32_16x16x32_bf16 v[30:33], v[226:229], v[194:197], v[30:33]
	v_mfma_f32_16x16x32_bf16 v[26:29], v[234:237], v[194:197], v[26:29]
	v_mfma_f32_16x16x32_bf16 v[22:25], v[226:229], v[202:205], v[22:25]
	v_mfma_f32_16x16x32_bf16 v[18:21], v[234:237], v[202:205], v[18:21]
	v_lshl_add_u64 v[132:133], v[132:133], 0, s[88:89]
	v_mfma_f32_16x16x32_bf16 v[14:17], v[226:229], v[210:213], v[14:17]
	v_lshl_add_u64 v[134:135], v[134:135], 0, s[88:89]
	v_mfma_f32_16x16x32_bf16 v[10:13], v[234:237], v[210:213], v[10:13]
	v_lshl_add_u64 v[136:137], v[136:137], 0, s[88:89]
	v_mfma_f32_16x16x32_bf16 v[6:9], v[226:229], v[218:221], v[6:9]
	s_cmp_lt_u32 s11, s10
	v_mfma_f32_16x16x32_bf16 v[2:5], v[234:237], v[218:221], v[2:5]
	v_lshl_add_u64 v[138:139], v[138:139], 0, s[88:89]
	v_mfma_f32_16x16x32_bf16 v[30:33], v[230:233], v[198:201], v[30:33]
	v_mfma_f32_16x16x32_bf16 v[26:29], v[238:241], v[198:201], v[26:29]
	v_mfma_f32_16x16x32_bf16 v[22:25], v[230:233], v[206:209], v[22:25]
	v_mfma_f32_16x16x32_bf16 v[18:21], v[238:241], v[206:209], v[18:21]
	v_mfma_f32_16x16x32_bf16 v[14:17], v[230:233], v[214:217], v[14:17]
	v_mfma_f32_16x16x32_bf16 v[10:13], v[238:241], v[214:217], v[10:13]
	v_mfma_f32_16x16x32_bf16 v[6:9], v[230:233], v[222:225], v[6:9]
	v_mfma_f32_16x16x32_bf16 v[2:5], v[238:241], v[222:225], v[2:5]
	s_barrier
	s_cbranch_scc1 .LBB0_357
	s_lshl_b32 s4, s9, 7
	s_add_u32 s2, s2, s4
	s_addc_u32 s3, s3, 0
	s_movk_i32 s10, 0xff80
	v_lshl_add_u64 v[162:163], s[2:3], 0, v[0:1]
	s_mov_b32 s11, -1
	v_readfirstlane_b32 s4, v156
	v_lshl_add_u64 v[162:163], v[162:163], 0, s[10:11]
	s_mov_b32 m0, s4
	v_lshl_add_u64 v[130:131], s[2:3], 0, v[130:131]
	v_readfirstlane_b32 s2, v157
	ds_read_b128 v[132:135], v155
	ds_read_b128 v[136:139], v155 offset:1024
	ds_read_b128 v[150:153], v155 offset:2048
	ds_read_b128 v[158:161], v155 offset:3072
	ds_read_b128 v[166:169], v145
	ds_read_b128 v[170:173], v145 offset:1024
	ds_read_b128 v[190:193], v144
	ds_read_b128 v[194:197], v144 offset:1024
	ds_read_b128 v[198:201], v143
	ds_read_b128 v[202:205], v143 offset:1024
	ds_read_b128 v[206:209], v142
	ds_read_b128 v[210:213], v142 offset:1024
	global_load_lds_dwordx4 v[162:163], off
	v_lshl_add_u64 v[130:131], v[130:131], 0, s[10:11]
	s_mov_b32 m0, s2
	s_nop 0
	global_load_lds_dwordx4 v[130:131], off
	s_barrier
	s_waitcnt lgkmcnt(0)
	v_mfma_f32_16x16x32_bf16 v[126:129], v[132:135], v[166:169], v[126:129]
	v_mfma_f32_16x16x32_bf16 v[122:125], v[150:153], v[166:169], v[122:125]
	v_mfma_f32_16x16x32_bf16 v[118:121], v[132:135], v[190:193], v[118:121]
	v_mfma_f32_16x16x32_bf16 v[114:117], v[150:153], v[190:193], v[114:117]
	v_mfma_f32_16x16x32_bf16 v[110:113], v[132:135], v[198:201], v[110:113]
	v_mfma_f32_16x16x32_bf16 v[106:109], v[150:153], v[198:201], v[106:109]
	v_mfma_f32_16x16x32_bf16 v[102:105], v[132:135], v[206:209], v[102:105]
	v_mfma_f32_16x16x32_bf16 v[98:101], v[150:153], v[206:209], v[98:101]
	v_mfma_f32_16x16x32_bf16 v[126:129], v[136:139], v[170:173], v[126:129]
	v_mfma_f32_16x16x32_bf16 v[122:125], v[158:161], v[170:173], v[122:125]
	v_mfma_f32_16x16x32_bf16 v[118:121], v[136:139], v[194:197], v[118:121]
	v_mfma_f32_16x16x32_bf16 v[114:117], v[158:161], v[194:197], v[114:117]
	v_mfma_f32_16x16x32_bf16 v[110:113], v[136:139], v[202:205], v[110:113]
	v_mfma_f32_16x16x32_bf16 v[106:109], v[158:161], v[202:205], v[106:109]
	v_mfma_f32_16x16x32_bf16 v[102:105], v[136:139], v[210:213], v[102:105]
	v_mfma_f32_16x16x32_bf16 v[98:101], v[158:161], v[210:213], v[98:101]
	s_barrier
	ds_read_b128 v[214:217], v154
	ds_read_b128 v[218:221], v154 offset:1024
	ds_read_b128 v[222:225], v154 offset:2048
	ds_read_b128 v[154:157], v154 offset:3072
	s_barrier
; #define LDA(dst,b,h) for(int m=0;m<4;++m)for(int k=0;k<2;++k) \
;     dst[m][k]=*reinterpret_cast<const bf16x8*>((char*)SA(b,h)+lds_byte(wr*64+m*16+fr,k*32+fq*8))
; #define LDB(dst,b,h) for(int n=0;n<2;++n)for(int k=0;k<2;++k) \
;     dst[n][k]=*reinterpret_cast<const bf16x8*>((char*)SB(b,h)+lds_byte(wc*32+n*16+fr,k*32+fq*8))
; #define MMA(ai,bj,At,Bt_) do{__builtin_amdgcn_s_setprio(1); \
;     for(int m=0;m<4;++m)for(int n=0;n<2;++n)for(int k=0;k<2;++k) \
;       acc[ai][bj][m][n]=__builtin_amdgcn_mfma_f32_16x16x32_bf16(Bt_[n][k],At[m][k],acc[ai][bj][m][n],0,0,0); \
;     __builtin_amdgcn_s_setprio(0);}while(0)
; #define WAIT_V(n) asm volatile("s_waitcnt vmcnt(" #n ")":::"memory")
; #define WAIT_L(n) asm volatile("s_waitcnt lgkmcnt(" #n ")":::"memory")
; #define BAR __builtin_amdgcn_s_barrier()
; template <int EPI>
; __device__ __forceinline__ void gemm_run(const GD& c, const bool has_next, const GD& nx, const Ctx& e, bf16* shm, float* rs, float* rs_nxt, float* racc_) {
;     ...
;     BAR; WAIT_L(0); MMA(0,0,At,B0); BAR;
;     LDB(B1,0,1); BAR; WAIT_L(0); MMA(0,1,At,B1); BAR;
;     LDA(At,0,1); WAIT_V(4); BAR; WAIT_L(0); MMA(1,0,At,B0); MMA(1,1,At,B1); BAR; }
;   { LDB(B0,1,0); LDA(At,1,0); WAIT_V(2); BAR; WAIT_L(0); MMA(0,0,At,B0); BAR;
	s_waitcnt lgkmcnt(0)
	v_mfma_f32_16x16x32_bf16 v[94:97], v[214:217], v[166:169], v[94:97]
	v_mfma_f32_16x16x32_bf16 v[90:93], v[222:225], v[166:169], v[90:93]
	v_mfma_f32_16x16x32_bf16 v[86:89], v[214:217], v[190:193], v[86:89]
	v_mfma_f32_16x16x32_bf16 v[82:85], v[222:225], v[190:193], v[82:85]
	v_mfma_f32_16x16x32_bf16 v[74:77], v[222:225], v[198:201], v[74:77]
	v_mfma_f32_16x16x32_bf16 v[70:73], v[214:217], v[206:209], v[70:73]
	v_mfma_f32_16x16x32_bf16 v[94:97], v[218:221], v[170:173], v[94:97]
	v_mfma_f32_16x16x32_bf16 v[90:93], v[154:157], v[170:173], v[90:93]
	v_mfma_f32_16x16x32_bf16 v[86:89], v[218:221], v[194:197], v[86:89]
	v_mfma_f32_16x16x32_bf16 v[82:85], v[154:157], v[194:197], v[82:85]
	v_mfma_f32_16x16x32_bf16 v[78:81], v[214:217], v[198:201], v[78:81]
	v_mfma_f32_16x16x32_bf16 v[74:77], v[154:157], v[202:205], v[74:77]
	v_mfma_f32_16x16x32_bf16 v[70:73], v[218:221], v[210:213], v[70:73]
	v_mfma_f32_16x16x32_bf16 v[66:69], v[222:225], v[206:209], v[66:69]
	v_mfma_f32_16x16x32_bf16 v[166:169], v[218:221], v[202:205], v[78:81]
	v_mfma_f32_16x16x32_bf16 v[170:173], v[154:157], v[210:213], v[66:69]
	s_barrier
	s_nop 3
	ds_read_b128 v[66:69], v145 offset:16384
	ds_read_b128 v[78:81], v145 offset:17408
	ds_read_b128 v[190:193], v144 offset:16384
	ds_read_b128 v[194:197], v144 offset:17408
	ds_read_b128 v[198:201], v143 offset:16384
	ds_read_b128 v[202:205], v143 offset:17408
	ds_read_b128 v[206:209], v142 offset:16384
	ds_read_b128 v[210:213], v142 offset:17408
	s_waitcnt vmcnt(4)
	s_barrier
	s_waitcnt lgkmcnt(0)
	v_mfma_f32_16x16x32_bf16 v[62:65], v[132:135], v[66:69], v[62:65]
	v_mfma_f32_16x16x32_bf16 v[54:57], v[132:135], v[190:193], v[54:57]
	v_mfma_f32_16x16x32_bf16 v[46:49], v[132:135], v[198:201], v[46:49]
	v_mfma_f32_16x16x32_bf16 v[38:41], v[132:135], v[206:209], v[38:41]
	v_mfma_f32_16x16x32_bf16 v[62:65], v[136:139], v[78:81], v[62:65]
	v_mfma_f32_16x16x32_bf16 v[58:61], v[150:153], v[66:69], v[58:61]
	v_mfma_f32_16x16x32_bf16 v[54:57], v[136:139], v[194:197], v[54:57]
	v_mfma_f32_16x16x32_bf16 v[50:53], v[150:153], v[190:193], v[50:53]
	v_mfma_f32_16x16x32_bf16 v[46:49], v[136:139], v[202:205], v[46:49]
	v_mfma_f32_16x16x32_bf16 v[42:45], v[150:153], v[198:201], v[42:45]
	v_mfma_f32_16x16x32_bf16 v[38:41], v[136:139], v[210:213], v[38:41]
	v_mfma_f32_16x16x32_bf16 v[34:37], v[150:153], v[206:209], v[34:37]
	v_mfma_f32_16x16x32_bf16 v[226:229], v[158:161], v[78:81], v[58:61]
	v_mfma_f32_16x16x32_bf16 v[230:233], v[158:161], v[194:197], v[50:53]
	v_mfma_f32_16x16x32_bf16 v[234:237], v[158:161], v[202:205], v[42:45]
	v_mfma_f32_16x16x32_bf16 v[130:133], v[158:161], v[210:213], v[34:37]
	v_mfma_f32_16x16x32_bf16 v[30:33], v[214:217], v[66:69], v[30:33]
	v_mfma_f32_16x16x32_bf16 v[26:29], v[222:225], v[66:69], v[26:29]
	v_mfma_f32_16x16x32_bf16 v[22:25], v[214:217], v[190:193], v[22:25]
	v_mfma_f32_16x16x32_bf16 v[18:21], v[222:225], v[190:193], v[18:21]
	v_mfma_f32_16x16x32_bf16 v[14:17], v[214:217], v[198:201], v[14:17]
	v_mfma_f32_16x16x32_bf16 v[10:13], v[222:225], v[198:201], v[10:13]
	v_mfma_f32_16x16x32_bf16 v[6:9], v[214:217], v[206:209], v[6:9]
	v_mfma_f32_16x16x32_bf16 v[2:5], v[222:225], v[206:209], v[2:5]
	v_mfma_f32_16x16x32_bf16 v[134:137], v[218:221], v[78:81], v[30:33]
	v_mfma_f32_16x16x32_bf16 v[150:153], v[154:157], v[78:81], v[26:29]
	v_mfma_f32_16x16x32_bf16 v[158:161], v[218:221], v[194:197], v[22:25]
	v_mfma_f32_16x16x32_bf16 v[190:193], v[154:157], v[194:197], v[18:21]
	v_mfma_f32_16x16x32_bf16 v[194:197], v[218:221], v[202:205], v[14:17]
	v_mfma_f32_16x16x32_bf16 v[198:201], v[154:157], v[202:205], v[10:13]
	v_mfma_f32_16x16x32_bf16 v[202:205], v[218:221], v[210:213], v[6:9]
	v_mfma_f32_16x16x32_bf16 v[154:157], v[154:157], v[210:213], v[2:5]
	s_barrier
	ds_read_b128 v[34:37], v149
	ds_read_b128 v[206:209], v149 offset:1024
	ds_read_b128 v[210:213], v149 offset:2048
	ds_read_b128 v[214:217], v149 offset:3072
	ds_read_b128 v[42:45], v145 offset:32768
	ds_read_b128 v[50:53], v145 offset:33792
	ds_read_b128 v[58:61], v144 offset:32768
	ds_read_b128 v[66:69], v144 offset:33792
	ds_read_b128 v[218:221], v143 offset:32768
	ds_read_b128 v[222:225], v143 offset:33792
	ds_read_b128 v[238:241], v142 offset:32768
	ds_read_b128 v[242:245], v142 offset:33792
	s_waitcnt vmcnt(2)
	s_barrier
; #define LDA(dst,b,h) for(int m=0;m<4;++m)for(int k=0;k<2;++k) \
;     dst[m][k]=*reinterpret_cast<const bf16x8*>((char*)SA(b,h)+lds_byte(wr*64+m*16+fr,k*32+fq*8))
; #define LDB(dst,b,h) for(int n=0;n<2;++n)for(int k=0;k<2;++k) \
;     dst[n][k]=*reinterpret_cast<const bf16x8*>((char*)SB(b,h)+lds_byte(wc*32+n*16+fr,k*32+fq*8))
; #define MMA(ai,bj,At,Bt_) do{__builtin_amdgcn_s_setprio(1); \
;     for(int m=0;m<4;++m)for(int n=0;n<2;++n)for(int k=0;k<2;++k) \
;       acc[ai][bj][m][n]=__builtin_amdgcn_mfma_f32_16x16x32_bf16(Bt_[n][k],At[m][k],acc[ai][bj][m][n],0,0,0); \
;     __builtin_amdgcn_s_setprio(0);}while(0)
; #define WAIT_V(n) asm volatile("s_waitcnt vmcnt(" #n ")":::"memory")
; #define WAIT_L(n) asm volatile("s_waitcnt lgkmcnt(" #n ")":::"memory")
; #define BAR __builtin_amdgcn_s_barrier()
; template <int EPI>
; __device__ __forceinline__ void gemm_run(const GD& c, const bool has_next, const GD& nx, const Ctx& e, bf16* shm, float* rs, float* rs_nxt, float* racc_) {
;     ...
;     LDA(At,0,1); WAIT_V(4); BAR; WAIT_L(0); MMA(1,0,At,B0); MMA(1,1,At,B1); BAR; }
;   { LDB(B0,1,0); LDA(At,1,0); WAIT_V(2); BAR; WAIT_L(0); MMA(0,0,At,B0); BAR;
;     LDB(B1,1,1); WAIT_V(0); BAR; WAIT_L(0); MMA(0,1,At,B1); BAR;
;     LDA(At,1,1); BAR; WAIT_L(0); MMA(1,0,At,B0); MMA(1,1,At,B1); BAR; }
;   if(wr==0)BAR;
	s_waitcnt lgkmcnt(0)
	v_mfma_f32_16x16x32_bf16 v[2:5], v[34:37], v[42:45], v[126:129]
	v_mfma_f32_16x16x32_bf16 v[26:29], v[206:209], v[50:53], v[2:5]
	v_mfma_f32_16x16x32_bf16 v[2:5], v[210:213], v[42:45], v[122:125]
	v_mfma_f32_16x16x32_bf16 v[30:33], v[214:217], v[50:53], v[2:5]
	v_mfma_f32_16x16x32_bf16 v[2:5], v[34:37], v[58:61], v[118:121]
	v_mfma_f32_16x16x32_bf16 v[18:21], v[206:209], v[66:69], v[2:5]
	v_mfma_f32_16x16x32_bf16 v[2:5], v[210:213], v[58:61], v[114:117]
	v_mfma_f32_16x16x32_bf16 v[22:25], v[214:217], v[66:69], v[2:5]
	v_mfma_f32_16x16x32_bf16 v[2:5], v[34:37], v[218:221], v[110:113]
	v_mfma_f32_16x16x32_bf16 v[10:13], v[206:209], v[222:225], v[2:5]
	v_mfma_f32_16x16x32_bf16 v[2:5], v[210:213], v[218:221], v[106:109]
	v_mfma_f32_16x16x32_bf16 v[14:17], v[214:217], v[222:225], v[2:5]
	v_mfma_f32_16x16x32_bf16 v[2:5], v[34:37], v[238:241], v[102:105]
	v_mfma_f32_16x16x32_bf16 v[6:9], v[210:213], v[238:241], v[98:101]
	v_mfma_f32_16x16x32_bf16 v[2:5], v[206:209], v[242:245], v[2:5]
	v_mfma_f32_16x16x32_bf16 v[6:9], v[214:217], v[242:245], v[6:9]
	s_barrier
	ds_read_b128 v[246:249], v147
	ds_read_b128 v[250:253], v147 offset:1024
	ds_read_b128 v[186:189], v147 offset:2048
	ds_read_b128 v[146:149], v147 offset:3072
	s_waitcnt vmcnt(0)
	s_barrier
	s_waitcnt lgkmcnt(0)
	v_mfma_f32_16x16x32_bf16 v[78:81], v[246:249], v[42:45], v[94:97]
	v_mfma_f32_16x16x32_bf16 v[42:45], v[186:189], v[42:45], v[90:93]
	v_mfma_f32_16x16x32_bf16 v[102:105], v[146:149], v[50:53], v[42:45]
	v_mfma_f32_16x16x32_bf16 v[42:45], v[246:249], v[58:61], v[86:89]
	v_mfma_f32_16x16x32_bf16 v[98:101], v[250:253], v[50:53], v[78:81]
	v_mfma_f32_16x16x32_bf16 v[78:81], v[250:253], v[66:69], v[42:45]
	v_mfma_f32_16x16x32_bf16 v[42:45], v[186:189], v[58:61], v[82:85]
	v_mfma_f32_16x16x32_bf16 v[86:89], v[146:149], v[66:69], v[42:45]
	v_mfma_f32_16x16x32_bf16 v[42:45], v[246:249], v[218:221], v[166:169]
	v_mfma_f32_16x16x32_bf16 v[58:61], v[250:253], v[222:225], v[42:45]
	v_mfma_f32_16x16x32_bf16 v[42:45], v[186:189], v[218:221], v[74:77]
	v_mfma_f32_16x16x32_bf16 v[66:69], v[146:149], v[222:225], v[42:45]
	v_mfma_f32_16x16x32_bf16 v[42:45], v[246:249], v[238:241], v[70:73]
	v_mfma_f32_16x16x32_bf16 v[50:53], v[186:189], v[238:241], v[170:173]
	v_mfma_f32_16x16x32_bf16 v[42:45], v[250:253], v[242:245], v[42:45]
	v_mfma_f32_16x16x32_bf16 v[50:53], v[146:149], v[242:245], v[50:53]
	s_barrier
	ds_read_b128 v[74:77], v145 offset:49152
	ds_read_b128 v[94:97], v145 offset:50176
	ds_read_b128 v[106:109], v144 offset:49152
	ds_read_b128 v[110:113], v144 offset:50176
	ds_read_b128 v[166:169], v143 offset:49152
	ds_read_b128 v[170:173], v143 offset:50176
	ds_read_b128 v[218:221], v142 offset:49152
	ds_read_b128 v[142:145], v142 offset:50176
	s_barrier
	s_waitcnt lgkmcnt(0)
	v_mfma_f32_16x16x32_bf16 v[62:65], v[34:37], v[74:77], v[62:65]
	v_mfma_f32_16x16x32_bf16 v[82:85], v[206:209], v[94:97], v[62:65]
	v_mfma_f32_16x16x32_bf16 v[62:65], v[210:213], v[74:77], v[226:229]
	v_mfma_f32_16x16x32_bf16 v[54:57], v[34:37], v[106:109], v[54:57]
	v_mfma_f32_16x16x32_bf16 v[90:93], v[214:217], v[94:97], v[62:65]
	v_mfma_f32_16x16x32_bf16 v[62:65], v[206:209], v[110:113], v[54:57]
	v_mfma_f32_16x16x32_bf16 v[54:57], v[210:213], v[106:109], v[230:233]
	v_mfma_f32_16x16x32_bf16 v[70:73], v[214:217], v[110:113], v[54:57]
	v_mfma_f32_16x16x32_bf16 v[46:49], v[34:37], v[166:169], v[46:49]
	v_mfma_f32_16x16x32_bf16 v[54:57], v[210:213], v[166:169], v[234:237]
	v_mfma_f32_16x16x32_bf16 v[34:37], v[34:37], v[218:221], v[38:41]
	v_mfma_f32_16x16x32_bf16 v[38:41], v[210:213], v[218:221], v[130:133]
	v_mfma_f32_16x16x32_bf16 v[46:49], v[206:209], v[170:173], v[46:49]
	v_mfma_f32_16x16x32_bf16 v[54:57], v[214:217], v[170:173], v[54:57]
	v_mfma_f32_16x16x32_bf16 v[34:37], v[206:209], v[142:145], v[34:37]
	v_mfma_f32_16x16x32_bf16 v[38:41], v[214:217], v[142:145], v[38:41]
	v_mfma_f32_16x16x32_bf16 v[114:117], v[246:249], v[74:77], v[134:137]
	v_mfma_f32_16x16x32_bf16 v[74:77], v[186:189], v[74:77], v[150:153]
	v_mfma_f32_16x16x32_bf16 v[126:129], v[146:149], v[94:97], v[74:77]
	v_mfma_f32_16x16x32_bf16 v[74:77], v[246:249], v[106:109], v[158:161]
	v_mfma_f32_16x16x32_bf16 v[122:125], v[250:253], v[94:97], v[114:117]
	v_mfma_f32_16x16x32_bf16 v[114:117], v[250:253], v[110:113], v[74:77]
	v_mfma_f32_16x16x32_bf16 v[74:77], v[186:189], v[106:109], v[190:193]
	v_mfma_f32_16x16x32_bf16 v[118:121], v[146:149], v[110:113], v[74:77]
	v_mfma_f32_16x16x32_bf16 v[74:77], v[246:249], v[166:169], v[194:197]
	v_mfma_f32_16x16x32_bf16 v[106:109], v[250:253], v[170:173], v[74:77]
	v_mfma_f32_16x16x32_bf16 v[74:77], v[186:189], v[166:169], v[198:201]
	v_mfma_f32_16x16x32_bf16 v[110:113], v[146:149], v[170:173], v[74:77]
	v_mfma_f32_16x16x32_bf16 v[74:77], v[246:249], v[218:221], v[202:205]
	v_mfma_f32_16x16x32_bf16 v[94:97], v[250:253], v[142:145], v[74:77]
	v_mfma_f32_16x16x32_bf16 v[74:77], v[186:189], v[218:221], v[154:157]
	v_mfma_f32_16x16x32_bf16 v[74:77], v[146:149], v[142:145], v[74:77]
	v_cmp_gt_u32_e32 vcc, s96, v141
	s_barrier
	s_and_saveexec_b64 s[2:3], vcc
	s_cbranch_execz .LBB0_353
	s_barrier
	s_branch .LBB0_353

; #define STAGE_A(P,br,kt) STAGE_G(P,c.A,c.lda,br,(long)(kt)*c.kstr)
; #define STAGE_B(P,br,kt) STAGE_G(P,c.Bt,c.K,br,(long)(kt)*BK)
; #define LDA(dst,b,h) for(int m=0;m<4;++m)for(int k=0;k<2;++k) \
;     dst[m][k]=*reinterpret_cast<const bf16x8*>((char*)SA(b,h)+lds_byte(wr*64+m*16+fr,k*32+fq*8))
; #define LDB(dst,b,h) for(int n=0;n<2;++n)for(int k=0;k<2;++k) \
;     dst[n][k]=*reinterpret_cast<const bf16x8*>((char*)SB(b,h)+lds_byte(wc*32+n*16+fr,k*32+fq*8))
; #define MMA(ai,bj,At,Bt_) do{__builtin_amdgcn_s_setprio(1); \
;     for(int m=0;m<4;++m)for(int n=0;n<2;++n)for(int k=0;k<2;++k) \
;       acc[ai][bj][m][n]=__builtin_amdgcn_mfma_f32_16x16x32_bf16(Bt_[n][k],At[m][k],acc[ai][bj][m][n],0,0,0); \
;     __builtin_amdgcn_s_setprio(0);}while(0)
; #define WAIT_V(n) asm volatile("s_waitcnt vmcnt(" #n ")":::"memory")
; #define WAIT_L(n) asm volatile("s_waitcnt lgkmcnt(" #n ")":::"memory")
; #define BAR __builtin_amdgcn_s_barrier()
; #define SCHED __builtin_amdgcn_sched_barrier(0)
; template <int EPI>
; __device__ __forceinline__ void gemm_run(const GD& c, const bool has_next, const GD& nx, const Ctx& e, bf16* shm, float* rs, float* rs_nxt, float* racc_) {
;     ...
;   for(int t=0;t<nt-2;t+=2){
;     LDB(B0,0,0); SCHED; LDA(At,0,0); STAGE_A(SA(1,1),brow+HALF,t+1);
;     WAIT_L(8); BAR; WAIT_L(0); MMA(0,0,At,B0); BAR; SCHED;
;     LDB(B1,0,1); STAGE_B(SB(0,0),bcol,t+2);
;     BAR; WAIT_L(0); MMA(0,1,At,B1); BAR;
;     LDA(At,0,1); STAGE_A(SA(0,0),brow,t+2);
;     BAR; WAIT_L(0); MMA(1,0,At,B0); BAR; SCHED;
;     STAGE_B(SB(0,1),bcol+HALF,t+2);
;     WAIT_V(6); BAR; MMA(1,1,At,B1); BAR;
.LBB0_464:
	ds_read_b128 v[158:161], v154
	ds_read_b128 v[166:169], v154 offset:1024
	ds_read_b128 v[170:173], v154 offset:2048
	ds_read_b128 v[190:193], v154 offset:3072
	v_add_u32_e32 v162, 0xc000, v141
	v_lshl_add_u64 v[174:175], s[14:15], 0, v[130:131]
	v_readfirstlane_b32 s3, v162
	v_add_u32_e32 v163, 0xe000, v141
	v_lshl_add_u64 v[156:157], v[174:175], 0, s[94:95]
	s_mov_b32 m0, s3
	v_lshl_add_u64 v[186:187], s[14:15], 0, v[132:133]
	v_readfirstlane_b32 s3, v163
	ds_read_b128 v[194:197], v145
	ds_read_b128 v[198:201], v145 offset:1024
	ds_read_b128 v[202:205], v144
	ds_read_b128 v[206:209], v144 offset:1024
	ds_read_b128 v[210:213], v143
	ds_read_b128 v[214:217], v143 offset:1024
	ds_read_b128 v[218:221], v142
	ds_read_b128 v[222:225], v142 offset:1024
	global_load_lds_dwordx4 v[156:157], off
	v_lshl_add_u64 v[156:157], v[186:187], 0, s[94:95]
	s_mov_b32 m0, s3
	s_nop 0
	global_load_lds_dwordx4 v[156:157], off
	s_waitcnt lgkmcnt(8)
	s_barrier
	s_waitcnt lgkmcnt(0)
	v_mfma_f32_16x16x32_bf16 v[126:129], v[158:161], v[194:197], v[126:129]
	v_mfma_f32_16x16x32_bf16 v[122:125], v[170:173], v[194:197], v[122:125]
	v_mfma_f32_16x16x32_bf16 v[118:121], v[158:161], v[202:205], v[118:121]
	v_mfma_f32_16x16x32_bf16 v[114:117], v[170:173], v[202:205], v[114:117]
	v_mfma_f32_16x16x32_bf16 v[110:113], v[158:161], v[210:213], v[110:113]
	v_mfma_f32_16x16x32_bf16 v[106:109], v[170:173], v[210:213], v[106:109]
	v_mfma_f32_16x16x32_bf16 v[102:105], v[158:161], v[218:221], v[102:105]
	v_mfma_f32_16x16x32_bf16 v[98:101], v[170:173], v[218:221], v[98:101]
	v_mfma_f32_16x16x32_bf16 v[126:129], v[166:169], v[198:201], v[126:129]
	v_mfma_f32_16x16x32_bf16 v[122:125], v[190:193], v[198:201], v[122:125]
	v_mfma_f32_16x16x32_bf16 v[118:121], v[166:169], v[206:209], v[118:121]
	v_mfma_f32_16x16x32_bf16 v[114:117], v[190:193], v[206:209], v[114:117]
	v_mfma_f32_16x16x32_bf16 v[110:113], v[166:169], v[214:217], v[110:113]
	v_mfma_f32_16x16x32_bf16 v[106:109], v[190:193], v[214:217], v[106:109]
	v_mfma_f32_16x16x32_bf16 v[102:105], v[166:169], v[222:225], v[102:105]
	v_mfma_f32_16x16x32_bf16 v[98:101], v[190:193], v[222:225], v[98:101]
	s_barrier
	v_add_u32_e32 v155, s33, v147
	v_lshl_add_u64 v[246:247], s[14:15], 0, v[136:137]
	v_readfirstlane_b32 s3, v155
	v_lshl_add_u64 v[156:157], v[246:247], 0, s[6:7]
	s_mov_b32 m0, s3
	ds_read_b128 v[226:229], v153
	ds_read_b128 v[230:233], v153 offset:1024
	ds_read_b128 v[234:237], v153 offset:2048
	ds_read_b128 v[238:241], v153 offset:3072
	global_load_lds_dwordx4 v[156:157], off
	v_add_u32_e32 v156, 0x2000, v155
	v_lshl_add_u64 v[248:249], s[14:15], 0, v[138:139]
	v_readfirstlane_b32 s3, v156
	v_lshl_add_u64 v[242:243], v[248:249], 0, s[6:7]
	s_mov_b32 m0, s3
	s_nop 0
	global_load_lds_dwordx4 v[242:243], off
	s_barrier
	s_waitcnt lgkmcnt(0)
	v_mfma_f32_16x16x32_bf16 v[94:97], v[226:229], v[194:197], v[94:97]
	v_mfma_f32_16x16x32_bf16 v[90:93], v[234:237], v[194:197], v[90:93]
	v_mfma_f32_16x16x32_bf16 v[86:89], v[226:229], v[202:205], v[86:89]
	v_mfma_f32_16x16x32_bf16 v[82:85], v[234:237], v[202:205], v[82:85]
	v_readfirstlane_b32 s3, v141
	v_mfma_f32_16x16x32_bf16 v[78:81], v[226:229], v[210:213], v[78:81]
	v_add_u32_e32 v157, 0x2000, v141
	v_mfma_f32_16x16x32_bf16 v[74:77], v[234:237], v[210:213], v[74:77]
	v_lshl_add_u64 v[242:243], v[174:175], 0, s[84:85]
	v_mfma_f32_16x16x32_bf16 v[70:73], v[226:229], v[218:221], v[70:73]
	s_mov_b32 m0, s3
	v_mfma_f32_16x16x32_bf16 v[66:69], v[234:237], v[218:221], v[66:69]
	v_readfirstlane_b32 s3, v157
	v_mfma_f32_16x16x32_bf16 v[94:97], v[230:233], v[198:201], v[94:97]
	v_mfma_f32_16x16x32_bf16 v[90:93], v[238:241], v[198:201], v[90:93]
	v_mfma_f32_16x16x32_bf16 v[86:89], v[230:233], v[206:209], v[86:89]
	v_mfma_f32_16x16x32_bf16 v[82:85], v[238:241], v[206:209], v[82:85]
	v_mfma_f32_16x16x32_bf16 v[78:81], v[230:233], v[214:217], v[78:81]
	v_mfma_f32_16x16x32_bf16 v[74:77], v[238:241], v[214:217], v[74:77]
	v_mfma_f32_16x16x32_bf16 v[70:73], v[230:233], v[222:225], v[70:73]
	v_mfma_f32_16x16x32_bf16 v[66:69], v[238:241], v[222:225], v[66:69]
	s_barrier
	ds_read_b128 v[194:197], v145 offset:16384
	ds_read_b128 v[198:201], v145 offset:17408
	ds_read_b128 v[202:205], v144 offset:16384
	ds_read_b128 v[206:209], v144 offset:17408
	ds_read_b128 v[210:213], v143 offset:16384
	ds_read_b128 v[214:217], v143 offset:17408
	ds_read_b128 v[218:221], v142 offset:16384
	ds_read_b128 v[222:225], v142 offset:17408
	global_load_lds_dwordx4 v[242:243], off
	v_lshl_add_u64 v[242:243], v[186:187], 0, s[84:85]
	s_mov_b32 m0, s3
	s_nop 0
	global_load_lds_dwordx4 v[242:243], off
	s_barrier
	s_waitcnt lgkmcnt(0)
	v_mfma_f32_16x16x32_bf16 v[62:65], v[158:161], v[194:197], v[62:65]
	v_mfma_f32_16x16x32_bf16 v[58:61], v[170:173], v[194:197], v[58:61]
	v_mfma_f32_16x16x32_bf16 v[54:57], v[158:161], v[202:205], v[54:57]
	v_mfma_f32_16x16x32_bf16 v[50:53], v[170:173], v[202:205], v[50:53]
	v_mfma_f32_16x16x32_bf16 v[46:49], v[158:161], v[210:213], v[46:49]
	v_mfma_f32_16x16x32_bf16 v[42:45], v[170:173], v[210:213], v[42:45]
	v_mfma_f32_16x16x32_bf16 v[38:41], v[158:161], v[218:221], v[38:41]
	v_mfma_f32_16x16x32_bf16 v[34:37], v[170:173], v[218:221], v[34:37]
	v_mfma_f32_16x16x32_bf16 v[62:65], v[166:169], v[198:201], v[62:65]
	v_mfma_f32_16x16x32_bf16 v[58:61], v[190:193], v[198:201], v[58:61]
	v_mfma_f32_16x16x32_bf16 v[54:57], v[166:169], v[206:209], v[54:57]
	v_mfma_f32_16x16x32_bf16 v[50:53], v[190:193], v[206:209], v[50:53]
	v_mfma_f32_16x16x32_bf16 v[46:49], v[166:169], v[214:217], v[46:49]
	v_mfma_f32_16x16x32_bf16 v[42:45], v[190:193], v[214:217], v[42:45]
	v_mfma_f32_16x16x32_bf16 v[38:41], v[166:169], v[222:225], v[38:41]
	v_mfma_f32_16x16x32_bf16 v[34:37], v[190:193], v[222:225], v[34:37]
	s_barrier
; #define STAGE_A(P,br,kt) STAGE_G(P,c.A,c.lda,br,(long)(kt)*c.kstr)
; #define STAGE_B(P,br,kt) STAGE_G(P,c.Bt,c.K,br,(long)(kt)*BK)
; #define LDA(dst,b,h) for(int m=0;m<4;++m)for(int k=0;k<2;++k) \
;     dst[m][k]=*reinterpret_cast<const bf16x8*>((char*)SA(b,h)+lds_byte(wr*64+m*16+fr,k*32+fq*8))
; #define LDB(dst,b,h) for(int n=0;n<2;++n)for(int k=0;k<2;++k) \
;     dst[n][k]=*reinterpret_cast<const bf16x8*>((char*)SB(b,h)+lds_byte(wc*32+n*16+fr,k*32+fq*8))
; #define MMA(ai,bj,At,Bt_) do{__builtin_amdgcn_s_setprio(1); \
;     for(int m=0;m<4;++m)for(int n=0;n<2;++n)for(int k=0;k<2;++k) \
;       acc[ai][bj][m][n]=__builtin_amdgcn_mfma_f32_16x16x32_bf16(Bt_[n][k],At[m][k],acc[ai][bj][m][n],0,0,0); \
;     __builtin_amdgcn_s_setprio(0);}while(0)
; #define WAIT_V(n) asm volatile("s_waitcnt vmcnt(" #n ")":::"memory")
; #define WAIT_L(n) asm volatile("s_waitcnt lgkmcnt(" #n ")":::"memory")
; #define BAR __builtin_amdgcn_s_barrier()
; #define SCHED __builtin_amdgcn_sched_barrier(0)
; template <int EPI>
; __device__ __forceinline__ void gemm_run(const GD& c, const bool has_next, const GD& nx, const Ctx& e, bf16* shm, float* rs, float* rs_nxt, float* racc_) {
;     ...
;     WAIT_V(6); BAR; MMA(1,1,At,B1); BAR;
;     LDB(B0,1,0); SCHED; LDA(At,1,0); STAGE_A(SA(0,1),brow+HALF,t+2);
;     WAIT_L(8); BAR; WAIT_L(0); MMA(0,0,At,B0); BAR; SCHED;
;     LDB(B1,1,1); STAGE_B(SB(1,0),bcol,t+3);
;     BAR; WAIT_L(0); MMA(0,1,At,B1); BAR;
;     LDA(At,1,1); STAGE_A(SA(1,0),brow,t+3);
;     BAR; WAIT_L(0); MMA(1,0,At,B0); BAR; SCHED;
;     STAGE_B(SB(1,1),bcol+HALF,t+3);
;     WAIT_V(6); BAR; MMA(1,1,At,B1); BAR;
	v_add_u32_e32 v158, s86, v147
	v_add_u32_e32 v159, 0x2000, v158
	v_readfirstlane_b32 s3, v158
	v_lshl_add_u64 v[160:161], v[246:247], 0, s[40:41]
	s_mov_b32 m0, s3
	v_readfirstlane_b32 s3, v159
	global_load_lds_dwordx4 v[160:161], off
	v_lshl_add_u64 v[160:161], v[248:249], 0, s[40:41]
	s_mov_b32 m0, s3
	s_nop 0
	global_load_lds_dwordx4 v[160:161], off
	s_waitcnt vmcnt(6)
	s_barrier
	v_mfma_f32_16x16x32_bf16 v[30:33], v[226:229], v[194:197], v[30:33]
	v_mfma_f32_16x16x32_bf16 v[26:29], v[234:237], v[194:197], v[26:29]
	v_mfma_f32_16x16x32_bf16 v[22:25], v[226:229], v[202:205], v[22:25]
	v_mfma_f32_16x16x32_bf16 v[18:21], v[234:237], v[202:205], v[18:21]
	v_mfma_f32_16x16x32_bf16 v[14:17], v[226:229], v[210:213], v[14:17]
	v_mfma_f32_16x16x32_bf16 v[10:13], v[234:237], v[210:213], v[10:13]
	v_mfma_f32_16x16x32_bf16 v[6:9], v[226:229], v[218:221], v[6:9]
	v_mfma_f32_16x16x32_bf16 v[2:5], v[234:237], v[218:221], v[2:5]
	v_mfma_f32_16x16x32_bf16 v[30:33], v[230:233], v[198:201], v[30:33]
	v_mfma_f32_16x16x32_bf16 v[26:29], v[238:241], v[198:201], v[26:29]
	v_mfma_f32_16x16x32_bf16 v[22:25], v[230:233], v[206:209], v[22:25]
	v_mfma_f32_16x16x32_bf16 v[18:21], v[238:241], v[206:209], v[18:21]
	v_mfma_f32_16x16x32_bf16 v[14:17], v[230:233], v[214:217], v[14:17]
	v_mfma_f32_16x16x32_bf16 v[10:13], v[238:241], v[214:217], v[10:13]
	v_mfma_f32_16x16x32_bf16 v[6:9], v[230:233], v[222:225], v[6:9]
	v_mfma_f32_16x16x32_bf16 v[2:5], v[238:241], v[222:225], v[2:5]
	s_barrier
	ds_read_b128 v[166:169], v148
	ds_read_b128 v[170:173], v148 offset:1024
	ds_read_b128 v[190:193], v148 offset:2048
	ds_read_b128 v[194:197], v148 offset:3072
	v_add_u32_e32 v160, 0x4000, v141
	v_add_u32_e32 v161, 0x6000, v141
	v_readfirstlane_b32 s3, v160
	v_lshl_add_u64 v[230:231], v[174:175], 0, s[92:93]
	s_mov_b32 m0, s3
	v_readfirstlane_b32 s3, v161
	ds_read_b128 v[198:201], v145 offset:32768
	ds_read_b128 v[202:205], v145 offset:33792
	ds_read_b128 v[206:209], v144 offset:32768
	ds_read_b128 v[210:213], v144 offset:33792
	ds_read_b128 v[214:217], v143 offset:32768
	ds_read_b128 v[218:221], v143 offset:33792
	ds_read_b128 v[222:225], v142 offset:32768
	ds_read_b128 v[226:229], v142 offset:33792
	global_load_lds_dwordx4 v[230:231], off
	v_lshl_add_u64 v[230:231], v[186:187], 0, s[92:93]
	s_mov_b32 m0, s3
	s_nop 0
	global_load_lds_dwordx4 v[230:231], off
	s_waitcnt lgkmcnt(8)
	s_barrier
	s_waitcnt lgkmcnt(0)
	v_mfma_f32_16x16x32_bf16 v[126:129], v[166:169], v[198:201], v[126:129]
	v_mfma_f32_16x16x32_bf16 v[122:125], v[190:193], v[198:201], v[122:125]
	v_mfma_f32_16x16x32_bf16 v[118:121], v[166:169], v[206:209], v[118:121]
	v_mfma_f32_16x16x32_bf16 v[114:117], v[190:193], v[206:209], v[114:117]
	v_mfma_f32_16x16x32_bf16 v[110:113], v[166:169], v[214:217], v[110:113]
	v_mfma_f32_16x16x32_bf16 v[106:109], v[190:193], v[214:217], v[106:109]
	v_mfma_f32_16x16x32_bf16 v[102:105], v[166:169], v[222:225], v[102:105]
	v_mfma_f32_16x16x32_bf16 v[98:101], v[190:193], v[222:225], v[98:101]
	v_mfma_f32_16x16x32_bf16 v[126:129], v[170:173], v[202:205], v[126:129]
	v_mfma_f32_16x16x32_bf16 v[122:125], v[194:197], v[202:205], v[122:125]
	v_mfma_f32_16x16x32_bf16 v[118:121], v[170:173], v[210:213], v[118:121]
	v_mfma_f32_16x16x32_bf16 v[114:117], v[194:197], v[210:213], v[114:117]
	v_mfma_f32_16x16x32_bf16 v[110:113], v[170:173], v[218:221], v[110:113]
	v_mfma_f32_16x16x32_bf16 v[106:109], v[194:197], v[218:221], v[106:109]
	v_mfma_f32_16x16x32_bf16 v[102:105], v[170:173], v[226:229], v[102:105]
	v_mfma_f32_16x16x32_bf16 v[98:101], v[194:197], v[226:229], v[98:101]
	s_barrier
	v_readfirstlane_b32 s3, v149
	v_add_u32_e32 v176, 0x2000, v149
	v_lshl_add_u64 v[250:251], v[246:247], 0, s[42:43]
	s_mov_b32 m0, s3
	v_readfirstlane_b32 s3, v176
	ds_read_b128 v[230:233], v146
	ds_read_b128 v[234:237], v146 offset:1024
	ds_read_b128 v[238:241], v146 offset:2048
	ds_read_b128 v[242:245], v146 offset:3072
	global_load_lds_dwordx4 v[250:251], off
	v_lshl_add_u64 v[250:251], v[248:249], 0, s[42:43]
	s_mov_b32 m0, s3
	s_nop 0
	global_load_lds_dwordx4 v[250:251], off
	s_barrier
	s_waitcnt lgkmcnt(0)
	v_mfma_f32_16x16x32_bf16 v[94:97], v[230:233], v[198:201], v[94:97]
	v_mfma_f32_16x16x32_bf16 v[90:93], v[238:241], v[198:201], v[90:93]
	v_mfma_f32_16x16x32_bf16 v[86:89], v[230:233], v[206:209], v[86:89]
	v_mfma_f32_16x16x32_bf16 v[82:85], v[238:241], v[206:209], v[82:85]
	v_readfirstlane_b32 s3, v150
	v_mfma_f32_16x16x32_bf16 v[78:81], v[230:233], v[214:217], v[78:81]
	v_lshl_add_u64 v[174:175], v[174:175], 0, s[80:81]
	v_mfma_f32_16x16x32_bf16 v[74:77], v[238:241], v[214:217], v[74:77]
	s_mov_b32 m0, s3
	v_mfma_f32_16x16x32_bf16 v[70:73], v[230:233], v[222:225], v[70:73]
	v_readfirstlane_b32 s3, v151
	v_mfma_f32_16x16x32_bf16 v[66:69], v[238:241], v[222:225], v[66:69]
	v_mfma_f32_16x16x32_bf16 v[94:97], v[234:237], v[202:205], v[94:97]
	v_mfma_f32_16x16x32_bf16 v[90:93], v[242:245], v[202:205], v[90:93]
	v_mfma_f32_16x16x32_bf16 v[86:89], v[234:237], v[210:213], v[86:89]
	v_mfma_f32_16x16x32_bf16 v[82:85], v[242:245], v[210:213], v[82:85]
	v_mfma_f32_16x16x32_bf16 v[78:81], v[234:237], v[218:221], v[78:81]
	v_mfma_f32_16x16x32_bf16 v[74:77], v[242:245], v[218:221], v[74:77]
	v_mfma_f32_16x16x32_bf16 v[70:73], v[234:237], v[226:229], v[70:73]
	v_mfma_f32_16x16x32_bf16 v[66:69], v[242:245], v[226:229], v[66:69]
	s_barrier
	ds_read_b128 v[198:201], v145 offset:49152
	ds_read_b128 v[202:205], v145 offset:50176
	ds_read_b128 v[206:209], v144 offset:49152
	ds_read_b128 v[210:213], v144 offset:50176
	ds_read_b128 v[214:217], v143 offset:49152
	ds_read_b128 v[218:221], v143 offset:50176
	ds_read_b128 v[222:225], v142 offset:49152
	ds_read_b128 v[226:229], v142 offset:50176
	global_load_lds_dwordx4 v[174:175], off
	v_lshl_add_u64 v[174:175], v[186:187], 0, s[80:81]
	s_mov_b32 m0, s3
	s_nop 0
	global_load_lds_dwordx4 v[174:175], off
	s_barrier
; #define STAGE_A(P,br,kt) STAGE_G(P,c.A,c.lda,br,(long)(kt)*c.kstr)
; #define STAGE_B(P,br,kt) STAGE_G(P,c.Bt,c.K,br,(long)(kt)*BK)
; #define LDA(dst,b,h) for(int m=0;m<4;++m)for(int k=0;k<2;++k) \
;     dst[m][k]=*reinterpret_cast<const bf16x8*>((char*)SA(b,h)+lds_byte(wr*64+m*16+fr,k*32+fq*8))
; #define LDB(dst,b,h) for(int n=0;n<2;++n)for(int k=0;k<2;++k) \
;     dst[n][k]=*reinterpret_cast<const bf16x8*>((char*)SB(b,h)+lds_byte(wc*32+n*16+fr,k*32+fq*8))
; #define MMA(ai,bj,At,Bt_) do{__builtin_amdgcn_s_setprio(1); \
;     for(int m=0;m<4;++m)for(int n=0;n<2;++n)for(int k=0;k<2;++k) \
;       acc[ai][bj][m][n]=__builtin_amdgcn_mfma_f32_16x16x32_bf16(Bt_[n][k],At[m][k],acc[ai][bj][m][n],0,0,0); \
;     __builtin_amdgcn_s_setprio(0);}while(0)
; #define WAIT_V(n) asm volatile("s_waitcnt vmcnt(" #n ")":::"memory")
; #define WAIT_L(n) asm volatile("s_waitcnt lgkmcnt(" #n ")":::"memory")
; #define BAR __builtin_amdgcn_s_barrier()
; #define SCHED __builtin_amdgcn_sched_barrier(0)
; template <int EPI>
; __device__ __forceinline__ void gemm_run(const GD& c, const bool has_next, const GD& nx, const Ctx& e, bf16* shm, float* rs, float* rs_nxt, float* racc_) {
;     ...
;     BAR; WAIT_L(0); MMA(1,0,At,B0); BAR; SCHED;
;     STAGE_B(SB(1,1),bcol+HALF,t+3);
;     WAIT_V(6); BAR; MMA(1,1,At,B1); BAR;
;   }
;   { LDB(B0,0,0); LDA(At,0,0); STAGE_A(SA(1,1),brow+HALF,nt-1);
;     BAR; WAIT_L(0); MMA(0,0,At,B0); BAR;
	s_waitcnt lgkmcnt(0)
	v_mfma_f32_16x16x32_bf16 v[62:65], v[166:169], v[198:201], v[62:65]
	v_mfma_f32_16x16x32_bf16 v[58:61], v[190:193], v[198:201], v[58:61]
	v_mfma_f32_16x16x32_bf16 v[54:57], v[166:169], v[206:209], v[54:57]
	v_mfma_f32_16x16x32_bf16 v[50:53], v[190:193], v[206:209], v[50:53]
	v_mfma_f32_16x16x32_bf16 v[46:49], v[166:169], v[214:217], v[46:49]
	v_mfma_f32_16x16x32_bf16 v[42:45], v[190:193], v[214:217], v[42:45]
	v_mfma_f32_16x16x32_bf16 v[38:41], v[166:169], v[222:225], v[38:41]
	v_mfma_f32_16x16x32_bf16 v[34:37], v[190:193], v[222:225], v[34:37]
	v_mfma_f32_16x16x32_bf16 v[62:65], v[170:173], v[202:205], v[62:65]
	v_mfma_f32_16x16x32_bf16 v[58:61], v[194:197], v[202:205], v[58:61]
	v_mfma_f32_16x16x32_bf16 v[54:57], v[170:173], v[210:213], v[54:57]
	v_mfma_f32_16x16x32_bf16 v[50:53], v[194:197], v[210:213], v[50:53]
	v_mfma_f32_16x16x32_bf16 v[46:49], v[170:173], v[218:221], v[46:49]
	v_mfma_f32_16x16x32_bf16 v[42:45], v[194:197], v[218:221], v[42:45]
	v_mfma_f32_16x16x32_bf16 v[38:41], v[170:173], v[226:229], v[38:41]
	v_mfma_f32_16x16x32_bf16 v[34:37], v[194:197], v[226:229], v[34:37]
	s_barrier
	v_readfirstlane_b32 s3, v152
	v_add_u32_e32 v168, 0x2000, v152
	v_lshl_add_u64 v[166:167], v[246:247], 0, s[44:45]
	s_mov_b32 m0, s3
	v_readfirstlane_b32 s3, v168
	global_load_lds_dwordx4 v[166:167], off
	v_lshl_add_u64 v[166:167], v[248:249], 0, s[44:45]
	s_mov_b32 m0, s3
	s_nop 0
	global_load_lds_dwordx4 v[166:167], off
	s_waitcnt vmcnt(6)
	s_barrier
	v_mfma_f32_16x16x32_bf16 v[30:33], v[230:233], v[198:201], v[30:33]
	v_mfma_f32_16x16x32_bf16 v[26:29], v[238:241], v[198:201], v[26:29]
	v_mfma_f32_16x16x32_bf16 v[22:25], v[230:233], v[206:209], v[22:25]
	v_mfma_f32_16x16x32_bf16 v[18:21], v[238:241], v[206:209], v[18:21]
	s_add_i32 s2, s2, 2
	v_mfma_f32_16x16x32_bf16 v[14:17], v[230:233], v[214:217], v[14:17]
	v_lshl_add_u64 v[130:131], v[130:131], 0, s[88:89]
	v_mfma_f32_16x16x32_bf16 v[10:13], v[238:241], v[214:217], v[10:13]
	v_lshl_add_u64 v[132:133], v[132:133], 0, s[88:89]
	v_mfma_f32_16x16x32_bf16 v[6:9], v[230:233], v[222:225], v[6:9]
	v_lshl_add_u64 v[136:137], v[136:137], 0, s[88:89]
	v_mfma_f32_16x16x32_bf16 v[2:5], v[238:241], v[222:225], v[2:5]
	s_cmp_lt_u32 s2, 12
	v_mfma_f32_16x16x32_bf16 v[30:33], v[234:237], v[202:205], v[30:33]
	v_lshl_add_u64 v[138:139], v[138:139], 0, s[88:89]
	v_mfma_f32_16x16x32_bf16 v[26:29], v[242:245], v[202:205], v[26:29]
	v_mfma_f32_16x16x32_bf16 v[22:25], v[234:237], v[210:213], v[22:25]
	v_mfma_f32_16x16x32_bf16 v[18:21], v[242:245], v[210:213], v[18:21]
	v_mfma_f32_16x16x32_bf16 v[14:17], v[234:237], v[218:221], v[14:17]
	v_mfma_f32_16x16x32_bf16 v[10:13], v[242:245], v[218:221], v[10:13]
	v_mfma_f32_16x16x32_bf16 v[6:9], v[234:237], v[226:229], v[6:9]
	v_mfma_f32_16x16x32_bf16 v[2:5], v[242:245], v[226:229], v[2:5]
	s_barrier
	s_cbranch_scc1 .LBB0_464
	s_or_b32 s2, s36, 0x80
	s_ashr_i32 s3, s2, 31
	s_lshl_b64 s[2:3], s[2:3], 11
	s_add_u32 s2, s50, s2
	s_addc_u32 s3, s51, s3
	v_lshl_add_u64 v[150:151], s[2:3], 0, v[0:1]
	s_mov_b64 s[40:41], 0x780
	v_readfirstlane_b32 s6, v162
	v_lshl_add_u64 v[150:151], v[150:151], 0, s[40:41]
	s_mov_b32 m0, s6
	ds_read_b128 v[130:133], v154
	ds_read_b128 v[136:139], v154 offset:1024
	ds_read_b128 v[166:169], v154 offset:2048
	ds_read_b128 v[170:173], v154 offset:3072
	ds_read_b128 v[190:193], v145
	ds_read_b128 v[194:197], v145 offset:1024
	ds_read_b128 v[198:201], v144
	ds_read_b128 v[202:205], v144 offset:1024
	ds_read_b128 v[206:209], v143
	ds_read_b128 v[210:213], v143 offset:1024
	ds_read_b128 v[214:217], v142
	ds_read_b128 v[218:221], v142 offset:1024
	global_load_lds_dwordx4 v[150:151], off
	v_lshl_add_u64 v[150:151], s[2:3], 0, v[134:135]
	v_readfirstlane_b32 s2, v163
	v_lshl_add_u64 v[150:151], v[150:151], 0, s[40:41]
	s_mov_b32 m0, s2
	s_nop 0
	global_load_lds_dwordx4 v[150:151], off
	s_barrier
	s_waitcnt lgkmcnt(0)
	v_mfma_f32_16x16x32_bf16 v[126:129], v[130:133], v[190:193], v[126:129]
	v_mfma_f32_16x16x32_bf16 v[122:125], v[166:169], v[190:193], v[122:125]
	v_mfma_f32_16x16x32_bf16 v[118:121], v[130:133], v[198:201], v[118:121]
	v_mfma_f32_16x16x32_bf16 v[106:109], v[166:169], v[206:209], v[106:109]
	v_mfma_f32_16x16x32_bf16 v[102:105], v[130:133], v[214:217], v[102:105]
	v_mfma_f32_16x16x32_bf16 v[126:129], v[136:139], v[194:197], v[126:129]
	v_mfma_f32_16x16x32_bf16 v[122:125], v[170:173], v[194:197], v[122:125]
	v_mfma_f32_16x16x32_bf16 v[118:121], v[136:139], v[202:205], v[118:121]
	v_mfma_f32_16x16x32_bf16 v[114:117], v[166:169], v[198:201], v[114:117]
	v_mfma_f32_16x16x32_bf16 v[110:113], v[130:133], v[206:209], v[110:113]
	v_mfma_f32_16x16x32_bf16 v[106:109], v[170:173], v[210:213], v[106:109]
	v_mfma_f32_16x16x32_bf16 v[102:105], v[136:139], v[218:221], v[102:105]
	v_mfma_f32_16x16x32_bf16 v[98:101], v[166:169], v[214:217], v[98:101]
	v_mfma_f32_16x16x32_bf16 v[222:225], v[170:173], v[202:205], v[114:117]
	v_mfma_f32_16x16x32_bf16 v[226:229], v[136:139], v[210:213], v[110:113]
	v_mfma_f32_16x16x32_bf16 v[230:233], v[170:173], v[218:221], v[98:101]
	s_barrier
	s_nop 2
	ds_read_b128 v[98:101], v153
	ds_read_b128 v[110:113], v153 offset:1024
	ds_read_b128 v[114:117], v153 offset:2048
	ds_read_b128 v[150:153], v153 offset:3072
	s_barrier
; #define LDA(dst,b,h) for(int m=0;m<4;++m)for(int k=0;k<2;++k) \
;     dst[m][k]=*reinterpret_cast<const bf16x8*>((char*)SA(b,h)+lds_byte(wr*64+m*16+fr,k*32+fq*8))
; #define LDB(dst,b,h) for(int n=0;n<2;++n)for(int k=0;k<2;++k) \
;     dst[n][k]=*reinterpret_cast<const bf16x8*>((char*)SB(b,h)+lds_byte(wc*32+n*16+fr,k*32+fq*8))
; #define MMA(ai,bj,At,Bt_) do{__builtin_amdgcn_s_setprio(1); \
;     for(int m=0;m<4;++m)for(int n=0;n<2;++n)for(int k=0;k<2;++k) \
;       acc[ai][bj][m][n]=__builtin_amdgcn_mfma_f32_16x16x32_bf16(Bt_[n][k],At[m][k],acc[ai][bj][m][n],0,0,0); \
;     __builtin_amdgcn_s_setprio(0);}while(0)
; #define WAIT_V(n) asm volatile("s_waitcnt vmcnt(" #n ")":::"memory")
; #define WAIT_L(n) asm volatile("s_waitcnt lgkmcnt(" #n ")":::"memory")
; #define BAR __builtin_amdgcn_s_barrier()
; template <int EPI>
; __device__ __forceinline__ void gemm_run(const GD& c, const bool has_next, const GD& nx, const Ctx& e, bf16* shm, float* rs, float* rs_nxt, float* racc_) {
;     ...
;     BAR; WAIT_L(0); MMA(0,0,At,B0); BAR;
;     LDB(B1,0,1); BAR; WAIT_L(0); MMA(0,1,At,B1); BAR;
;     LDA(At,0,1); WAIT_V(4); BAR; WAIT_L(0); MMA(1,0,At,B0); MMA(1,1,At,B1); BAR; }
;   { LDB(B0,1,0); LDA(At,1,0); WAIT_V(2); BAR; WAIT_L(0); MMA(0,0,At,B0); BAR;
	s_waitcnt lgkmcnt(0)
	v_mfma_f32_16x16x32_bf16 v[90:93], v[114:117], v[190:193], v[90:93]
	v_mfma_f32_16x16x32_bf16 v[86:89], v[98:101], v[198:201], v[86:89]
	v_mfma_f32_16x16x32_bf16 v[74:77], v[114:117], v[206:209], v[74:77]
	v_mfma_f32_16x16x32_bf16 v[70:73], v[98:101], v[214:217], v[70:73]
	v_mfma_f32_16x16x32_bf16 v[66:69], v[114:117], v[214:217], v[66:69]
	v_mfma_f32_16x16x32_bf16 v[94:97], v[98:101], v[190:193], v[94:97]
	v_mfma_f32_16x16x32_bf16 v[90:93], v[150:153], v[194:197], v[90:93]
	v_mfma_f32_16x16x32_bf16 v[86:89], v[110:113], v[202:205], v[86:89]
	v_mfma_f32_16x16x32_bf16 v[82:85], v[114:117], v[198:201], v[82:85]
	v_mfma_f32_16x16x32_bf16 v[78:81], v[98:101], v[206:209], v[78:81]
	v_mfma_f32_16x16x32_bf16 v[74:77], v[150:153], v[210:213], v[74:77]
	v_mfma_f32_16x16x32_bf16 v[70:73], v[110:113], v[218:221], v[70:73]
	v_mfma_f32_16x16x32_bf16 v[66:69], v[150:153], v[218:221], v[66:69]
	v_mfma_f32_16x16x32_bf16 v[234:237], v[110:113], v[194:197], v[94:97]
	v_mfma_f32_16x16x32_bf16 v[190:193], v[150:153], v[202:205], v[82:85]
	v_mfma_f32_16x16x32_bf16 v[194:197], v[110:113], v[210:213], v[78:81]
	s_barrier
	s_nop 0
	ds_read_b128 v[78:81], v145 offset:16384
	ds_read_b128 v[82:85], v145 offset:17408
	ds_read_b128 v[94:97], v144 offset:16384
	ds_read_b128 v[198:201], v144 offset:17408
	ds_read_b128 v[202:205], v143 offset:16384
	ds_read_b128 v[206:209], v143 offset:17408
	ds_read_b128 v[210:213], v142 offset:16384
	ds_read_b128 v[214:217], v142 offset:17408
	s_waitcnt vmcnt(4)
	s_barrier
	s_waitcnt lgkmcnt(0)
	v_mfma_f32_16x16x32_bf16 v[62:65], v[130:133], v[78:81], v[62:65]
	v_mfma_f32_16x16x32_bf16 v[58:61], v[166:169], v[78:81], v[58:61]
	v_mfma_f32_16x16x32_bf16 v[54:57], v[130:133], v[94:97], v[54:57]
	v_mfma_f32_16x16x32_bf16 v[42:45], v[166:169], v[202:205], v[42:45]
	v_mfma_f32_16x16x32_bf16 v[38:41], v[130:133], v[210:213], v[38:41]
	v_mfma_f32_16x16x32_bf16 v[62:65], v[136:139], v[82:85], v[62:65]
	v_mfma_f32_16x16x32_bf16 v[58:61], v[170:173], v[82:85], v[58:61]
	v_mfma_f32_16x16x32_bf16 v[54:57], v[136:139], v[198:201], v[54:57]
	v_mfma_f32_16x16x32_bf16 v[50:53], v[166:169], v[94:97], v[50:53]
	v_mfma_f32_16x16x32_bf16 v[46:49], v[130:133], v[202:205], v[46:49]
	v_mfma_f32_16x16x32_bf16 v[42:45], v[170:173], v[206:209], v[42:45]
	v_mfma_f32_16x16x32_bf16 v[38:41], v[136:139], v[214:217], v[38:41]
	v_mfma_f32_16x16x32_bf16 v[34:37], v[166:169], v[210:213], v[34:37]
	v_mfma_f32_16x16x32_bf16 v[218:221], v[170:173], v[198:201], v[50:53]
	v_mfma_f32_16x16x32_bf16 v[238:241], v[136:139], v[206:209], v[46:49]
	v_mfma_f32_16x16x32_bf16 v[136:139], v[170:173], v[214:217], v[34:37]
	v_mfma_f32_16x16x32_bf16 v[26:29], v[114:117], v[78:81], v[26:29]
	v_mfma_f32_16x16x32_bf16 v[22:25], v[98:101], v[94:97], v[22:25]
	v_mfma_f32_16x16x32_bf16 v[10:13], v[114:117], v[202:205], v[10:13]
	v_mfma_f32_16x16x32_bf16 v[6:9], v[98:101], v[210:213], v[6:9]
	v_mfma_f32_16x16x32_bf16 v[30:33], v[98:101], v[78:81], v[30:33]
	v_mfma_f32_16x16x32_bf16 v[26:29], v[150:153], v[82:85], v[26:29]
	v_mfma_f32_16x16x32_bf16 v[22:25], v[110:113], v[198:201], v[22:25]
	v_mfma_f32_16x16x32_bf16 v[18:21], v[114:117], v[94:97], v[18:21]
	v_mfma_f32_16x16x32_bf16 v[14:17], v[98:101], v[202:205], v[14:17]
	v_mfma_f32_16x16x32_bf16 v[10:13], v[150:153], v[206:209], v[10:13]
	v_mfma_f32_16x16x32_bf16 v[6:9], v[110:113], v[214:217], v[6:9]
	v_mfma_f32_16x16x32_bf16 v[2:5], v[114:117], v[210:213], v[2:5]
	v_mfma_f32_16x16x32_bf16 v[166:169], v[110:113], v[82:85], v[30:33]
	v_mfma_f32_16x16x32_bf16 v[170:173], v[150:153], v[198:201], v[18:21]
	v_mfma_f32_16x16x32_bf16 v[198:201], v[110:113], v[206:209], v[14:17]
	v_mfma_f32_16x16x32_bf16 v[2:5], v[150:153], v[214:217], v[2:5]
	s_barrier
	ds_read_b128 v[14:17], v148
	ds_read_b128 v[18:21], v148 offset:1024
	ds_read_b128 v[150:153], v148 offset:2048
	ds_read_b128 v[202:205], v148 offset:3072
	ds_read_b128 v[30:33], v145 offset:32768
	ds_read_b128 v[34:37], v145 offset:33792
	ds_read_b128 v[46:49], v144 offset:32768
	ds_read_b128 v[50:53], v144 offset:33792
	ds_read_b128 v[206:209], v143 offset:32768
	ds_read_b128 v[210:213], v143 offset:33792
	ds_read_b128 v[214:217], v142 offset:32768
	ds_read_b128 v[242:245], v142 offset:33792
	s_waitcnt vmcnt(2)
	s_barrier
; #define LDA(dst,b,h) for(int m=0;m<4;++m)for(int k=0;k<2;++k) \
;     dst[m][k]=*reinterpret_cast<const bf16x8*>((char*)SA(b,h)+lds_byte(wr*64+m*16+fr,k*32+fq*8))
; #define LDB(dst,b,h) for(int n=0;n<2;++n)for(int k=0;k<2;++k) \
;     dst[n][k]=*reinterpret_cast<const bf16x8*>((char*)SB(b,h)+lds_byte(wc*32+n*16+fr,k*32+fq*8))
; #define MMA(ai,bj,At,Bt_) do{__builtin_amdgcn_s_setprio(1); \
;     for(int m=0;m<4;++m)for(int n=0;n<2;++n)for(int k=0;k<2;++k) \
;       acc[ai][bj][m][n]=__builtin_amdgcn_mfma_f32_16x16x32_bf16(Bt_[n][k],At[m][k],acc[ai][bj][m][n],0,0,0); \
;     __builtin_amdgcn_s_setprio(0);}while(0)
; #define WAIT_V(n) asm volatile("s_waitcnt vmcnt(" #n ")":::"memory")
; #define WAIT_L(n) asm volatile("s_waitcnt lgkmcnt(" #n ")":::"memory")
; #define BAR __builtin_amdgcn_s_barrier()
; template <int EPI>
; __device__ __forceinline__ void gemm_run(const GD& c, const bool has_next, const GD& nx, const Ctx& e, bf16* shm, float* rs, float* rs_nxt, float* racc_) {
;     ...
;     LDA(At,0,1); WAIT_V(4); BAR; WAIT_L(0); MMA(1,0,At,B0); MMA(1,1,At,B1); BAR; }
;   { LDB(B0,1,0); LDA(At,1,0); WAIT_V(2); BAR; WAIT_L(0); MMA(0,0,At,B0); BAR;
;     LDB(B1,1,1); WAIT_V(0); BAR; WAIT_L(0); MMA(0,1,At,B1); BAR;
;     LDA(At,1,1); BAR; WAIT_L(0); MMA(1,0,At,B0); MMA(1,1,At,B1); BAR; }
;   if(wr==0)BAR;
	s_waitcnt lgkmcnt(0)
	v_mfma_f32_16x16x32_bf16 v[78:81], v[14:17], v[30:33], v[126:129]
	v_mfma_f32_16x16x32_bf16 v[130:133], v[18:21], v[34:37], v[78:81]
	v_mfma_f32_16x16x32_bf16 v[78:81], v[150:153], v[30:33], v[122:125]
	v_mfma_f32_16x16x32_bf16 v[126:129], v[202:205], v[34:37], v[78:81]
	v_mfma_f32_16x16x32_bf16 v[78:81], v[14:17], v[46:49], v[118:121]
	v_mfma_f32_16x16x32_bf16 v[114:117], v[18:21], v[50:53], v[78:81]
	v_mfma_f32_16x16x32_bf16 v[78:81], v[150:153], v[46:49], v[222:225]
	v_mfma_f32_16x16x32_bf16 v[110:113], v[202:205], v[50:53], v[78:81]
	v_mfma_f32_16x16x32_bf16 v[78:81], v[14:17], v[206:209], v[226:229]
	v_mfma_f32_16x16x32_bf16 v[98:101], v[18:21], v[210:213], v[78:81]
	v_mfma_f32_16x16x32_bf16 v[78:81], v[150:153], v[206:209], v[106:109]
	v_mfma_f32_16x16x32_bf16 v[94:97], v[202:205], v[210:213], v[78:81]
	v_mfma_f32_16x16x32_bf16 v[78:81], v[14:17], v[214:217], v[102:105]
	v_mfma_f32_16x16x32_bf16 v[82:85], v[18:21], v[242:245], v[78:81]
	v_mfma_f32_16x16x32_bf16 v[78:81], v[150:153], v[214:217], v[230:233]
	v_mfma_f32_16x16x32_bf16 v[78:81], v[202:205], v[242:245], v[78:81]
	s_barrier
	ds_read_b128 v[222:225], v146
	ds_read_b128 v[226:229], v146 offset:1024
	ds_read_b128 v[230:233], v146 offset:2048
	ds_read_b128 v[146:149], v146 offset:3072
	s_waitcnt vmcnt(0)
	s_barrier
	s_waitcnt lgkmcnt(0)
	v_mfma_f32_16x16x32_bf16 v[102:105], v[222:225], v[30:33], v[234:237]
	v_mfma_f32_16x16x32_bf16 v[30:33], v[230:233], v[30:33], v[90:93]
	v_mfma_f32_16x16x32_bf16 v[118:121], v[146:149], v[34:37], v[30:33]
	v_mfma_f32_16x16x32_bf16 v[30:33], v[222:225], v[46:49], v[86:89]
	v_mfma_f32_16x16x32_bf16 v[106:109], v[226:229], v[50:53], v[30:33]
	v_mfma_f32_16x16x32_bf16 v[30:33], v[230:233], v[46:49], v[190:193]
	v_mfma_f32_16x16x32_bf16 v[122:125], v[226:229], v[34:37], v[102:105]
	v_mfma_f32_16x16x32_bf16 v[102:105], v[146:149], v[50:53], v[30:33]
	v_mfma_f32_16x16x32_bf16 v[30:33], v[222:225], v[206:209], v[194:197]
	v_mfma_f32_16x16x32_bf16 v[90:93], v[226:229], v[210:213], v[30:33]
	v_mfma_f32_16x16x32_bf16 v[30:33], v[230:233], v[206:209], v[74:77]
	v_mfma_f32_16x16x32_bf16 v[86:89], v[146:149], v[210:213], v[30:33]
	v_mfma_f32_16x16x32_bf16 v[30:33], v[222:225], v[214:217], v[70:73]
	v_mfma_f32_16x16x32_bf16 v[74:77], v[226:229], v[242:245], v[30:33]
	v_mfma_f32_16x16x32_bf16 v[30:33], v[230:233], v[214:217], v[66:69]
	v_mfma_f32_16x16x32_bf16 v[70:73], v[146:149], v[242:245], v[30:33]
	s_barrier
	ds_read_b128 v[190:193], v145 offset:49152
	ds_read_b128 v[194:197], v145 offset:50176
	ds_read_b128 v[206:209], v144 offset:49152
	ds_read_b128 v[210:213], v144 offset:50176
	ds_read_b128 v[214:217], v143 offset:49152
	ds_read_b128 v[234:237], v143 offset:50176
	ds_read_b128 v[242:245], v142 offset:49152
	ds_read_b128 v[142:145], v142 offset:50176
	s_barrier
	s_waitcnt lgkmcnt(0)
	v_mfma_f32_16x16x32_bf16 v[30:33], v[14:17], v[190:193], v[62:65]
	v_mfma_f32_16x16x32_bf16 v[66:69], v[18:21], v[194:197], v[30:33]
	v_mfma_f32_16x16x32_bf16 v[30:33], v[150:153], v[190:193], v[58:61]
	v_mfma_f32_16x16x32_bf16 v[62:65], v[202:205], v[194:197], v[30:33]
	v_mfma_f32_16x16x32_bf16 v[30:33], v[14:17], v[206:209], v[54:57]
	v_mfma_f32_16x16x32_bf16 v[50:53], v[18:21], v[210:213], v[30:33]
	v_mfma_f32_16x16x32_bf16 v[30:33], v[150:153], v[206:209], v[218:221]
	v_mfma_f32_16x16x32_bf16 v[46:49], v[202:205], v[210:213], v[30:33]
	v_mfma_f32_16x16x32_bf16 v[30:33], v[14:17], v[214:217], v[238:241]
	v_mfma_f32_16x16x32_bf16 v[14:17], v[14:17], v[242:245], v[38:41]
	v_mfma_f32_16x16x32_bf16 v[34:37], v[18:21], v[234:237], v[30:33]
	v_mfma_f32_16x16x32_bf16 v[30:33], v[150:153], v[214:217], v[42:45]
	v_mfma_f32_16x16x32_bf16 v[18:21], v[18:21], v[142:145], v[14:17]
	v_mfma_f32_16x16x32_bf16 v[14:17], v[150:153], v[242:245], v[136:139]
	v_mfma_f32_16x16x32_bf16 v[30:33], v[202:205], v[234:237], v[30:33]
	v_mfma_f32_16x16x32_bf16 v[14:17], v[202:205], v[142:145], v[14:17]
	v_mfma_f32_16x16x32_bf16 v[22:25], v[222:225], v[206:209], v[22:25]
	v_mfma_f32_16x16x32_bf16 v[38:41], v[222:225], v[190:193], v[166:169]
	v_mfma_f32_16x16x32_bf16 v[42:45], v[226:229], v[210:213], v[22:25]
	v_mfma_f32_16x16x32_bf16 v[22:25], v[230:233], v[206:209], v[170:173]
	v_mfma_f32_16x16x32_bf16 v[58:61], v[226:229], v[194:197], v[38:41]
	v_mfma_f32_16x16x32_bf16 v[26:29], v[230:233], v[190:193], v[26:29]
	v_mfma_f32_16x16x32_bf16 v[38:41], v[146:149], v[210:213], v[22:25]
	v_mfma_f32_16x16x32_bf16 v[22:25], v[222:225], v[214:217], v[198:201]
	v_mfma_f32_16x16x32_bf16 v[10:13], v[230:233], v[214:217], v[10:13]
	v_mfma_f32_16x16x32_bf16 v[6:9], v[222:225], v[242:245], v[6:9]
	v_mfma_f32_16x16x32_bf16 v[2:5], v[230:233], v[242:245], v[2:5]
	v_mfma_f32_16x16x32_bf16 v[54:57], v[146:149], v[194:197], v[26:29]
	v_mfma_f32_16x16x32_bf16 v[26:29], v[226:229], v[234:237], v[22:25]
	v_mfma_f32_16x16x32_bf16 v[22:25], v[146:149], v[234:237], v[10:13]
	v_mfma_f32_16x16x32_bf16 v[10:13], v[226:229], v[142:145], v[6:9]
	v_mfma_f32_16x16x32_bf16 v[6:9], v[146:149], v[142:145], v[2:5]
	v_cmp_gt_u32_e32 vcc, s96, v140
	s_barrier
	s_and_saveexec_b64 s[2:3], vcc
	s_cbranch_execz .LBB0_467
	s_barrier

; #define STAGE_A(P,br,kt) STAGE_G(P,c.A,c.lda,br,(long)(kt)*c.kstr)
; #define STAGE_B(P,br,kt) STAGE_G(P,c.Bt,c.K,br,(long)(kt)*BK)
; #define LDA(dst,b,h) for(int m=0;m<4;++m)for(int k=0;k<2;++k) \
;     dst[m][k]=*reinterpret_cast<const bf16x8*>((char*)SA(b,h)+lds_byte(wr*64+m*16+fr,k*32+fq*8))
; #define LDB(dst,b,h) for(int n=0;n<2;++n)for(int k=0;k<2;++k) \
;     dst[n][k]=*reinterpret_cast<const bf16x8*>((char*)SB(b,h)+lds_byte(wc*32+n*16+fr,k*32+fq*8))
; #define MMA(ai,bj,At,Bt_) do{__builtin_amdgcn_s_setprio(1); \
;     for(int m=0;m<4;++m)for(int n=0;n<2;++n)for(int k=0;k<2;++k) \
;       acc[ai][bj][m][n]=__builtin_amdgcn_mfma_f32_16x16x32_bf16(Bt_[n][k],At[m][k],acc[ai][bj][m][n],0,0,0); \
;     __builtin_amdgcn_s_setprio(0);}while(0)
; #define WAIT_V(n) asm volatile("s_waitcnt vmcnt(" #n ")":::"memory")
; #define WAIT_L(n) asm volatile("s_waitcnt lgkmcnt(" #n ")":::"memory")
; #define BAR __builtin_amdgcn_s_barrier()
; #define SCHED __builtin_amdgcn_sched_barrier(0)
; template <int EPI>
; __device__ __forceinline__ void gemm_run(const GD& c, const bool has_next, const GD& nx, const Ctx& e, bf16* shm, float* rs, float* rs_nxt, float* racc_) {
;     ...
;   for(int t=0;t<nt-2;t+=2){
;     LDB(B0,0,0); SCHED; LDA(At,0,0); STAGE_A(SA(1,1),brow+HALF,t+1);
;     WAIT_L(8); BAR; WAIT_L(0); MMA(0,0,At,B0); BAR; SCHED;
;     LDB(B1,0,1); STAGE_B(SB(0,0),bcol,t+2);
;     BAR; WAIT_L(0); MMA(0,1,At,B1); BAR;
;     LDA(At,0,1); STAGE_A(SA(0,0),brow,t+2);
;     BAR; WAIT_L(0); MMA(1,0,At,B0); BAR; SCHED;
;     STAGE_B(SB(0,1),bcol+HALF,t+2);
;     WAIT_V(6); BAR; MMA(1,1,At,B1); BAR;
.LBB0_689:
	ds_read_b128 v[156:159], v146
	ds_read_b128 v[160:163], v146 offset:1024
	ds_read_b128 v[166:169], v146 offset:2048
	ds_read_b128 v[172:175], v146 offset:3072
	s_lshl_b32 s42, s39, 7
	s_add_u32 s40, s22, s42
	s_addc_u32 s41, s23, 0
	v_add_u32_e32 v147, 0xc000, v133
	v_lshl_add_u64 v[234:235], s[40:41], 0, v[0:1]
	v_readfirstlane_b32 s43, v147
	v_add_u32_e32 v155, 0xe000, v133
	v_lshl_add_u64 v[148:149], v[234:235], 0, s[66:67]
	s_mov_b32 m0, s43
	v_lshl_add_u64 v[236:237], s[40:41], 0, v[130:131]
	v_readfirstlane_b32 s40, v155
	ds_read_b128 v[150:153], v137
	ds_read_b128 v[186:189], v137 offset:1024
	ds_read_b128 v[190:193], v136
	ds_read_b128 v[194:197], v136 offset:1024
	ds_read_b128 v[198:201], v135
	ds_read_b128 v[202:205], v135 offset:1024
	ds_read_b128 v[206:209], v134
	ds_read_b128 v[210:213], v134 offset:1024
	global_load_lds_dwordx4 v[148:149], off
	v_lshl_add_u64 v[148:149], v[236:237], 0, s[66:67]
	s_mov_b32 m0, s40
	s_nop 0
	global_load_lds_dwordx4 v[148:149], off
	s_waitcnt lgkmcnt(8)
	s_barrier
	s_waitcnt lgkmcnt(0)
	v_mfma_f32_16x16x32_bf16 v[126:129], v[156:159], v[150:153], v[126:129]
	v_mfma_f32_16x16x32_bf16 v[122:125], v[166:169], v[150:153], v[122:125]
	v_mfma_f32_16x16x32_bf16 v[118:121], v[156:159], v[190:193], v[118:121]
	v_mfma_f32_16x16x32_bf16 v[114:117], v[166:169], v[190:193], v[114:117]
	v_mfma_f32_16x16x32_bf16 v[110:113], v[156:159], v[198:201], v[110:113]
	v_mfma_f32_16x16x32_bf16 v[106:109], v[166:169], v[198:201], v[106:109]
	v_mfma_f32_16x16x32_bf16 v[102:105], v[156:159], v[206:209], v[102:105]
	v_mfma_f32_16x16x32_bf16 v[98:101], v[166:169], v[206:209], v[98:101]
	v_mfma_f32_16x16x32_bf16 v[126:129], v[160:163], v[186:189], v[126:129]
	v_mfma_f32_16x16x32_bf16 v[122:125], v[172:175], v[186:189], v[122:125]
	v_mfma_f32_16x16x32_bf16 v[118:121], v[160:163], v[194:197], v[118:121]
	v_mfma_f32_16x16x32_bf16 v[114:117], v[172:175], v[194:197], v[114:117]
	v_mfma_f32_16x16x32_bf16 v[110:113], v[160:163], v[202:205], v[110:113]
	v_mfma_f32_16x16x32_bf16 v[106:109], v[172:175], v[202:205], v[106:109]
	v_mfma_f32_16x16x32_bf16 v[102:105], v[160:163], v[210:213], v[102:105]
	v_mfma_f32_16x16x32_bf16 v[98:101], v[172:175], v[210:213], v[98:101]
	s_barrier
	s_add_u32 s40, s2, s42
	s_addc_u32 s41, s3, 0
	v_lshl_add_u64 v[148:149], s[40:41], 0, v[0:1]
	v_lshl_add_u64 v[230:231], v[148:149], 0, s[88:89]
	v_add_u32_e32 v148, s33, v139
	v_add_u32_e32 v149, 0x2000, v148
	v_readfirstlane_b32 s43, v148
	s_mov_b32 m0, s43
	ds_read_b128 v[214:217], v144
	ds_read_b128 v[218:221], v144 offset:1024
	ds_read_b128 v[222:225], v144 offset:2048
	ds_read_b128 v[226:229], v144 offset:3072
	global_load_lds_dwordx4 v[230:231], off
	v_lshl_add_u64 v[230:231], s[40:41], 0, v[130:131]
	v_readfirstlane_b32 s40, v149
	v_lshl_add_u64 v[230:231], v[230:231], 0, s[88:89]
	s_mov_b32 m0, s40
	s_nop 0
	global_load_lds_dwordx4 v[230:231], off
	s_barrier
	s_waitcnt lgkmcnt(0)
	v_mfma_f32_16x16x32_bf16 v[94:97], v[214:217], v[150:153], v[94:97]
	v_mfma_f32_16x16x32_bf16 v[90:93], v[222:225], v[150:153], v[90:93]
	v_mfma_f32_16x16x32_bf16 v[86:89], v[214:217], v[190:193], v[86:89]
	v_mfma_f32_16x16x32_bf16 v[82:85], v[222:225], v[190:193], v[82:85]
	v_mfma_f32_16x16x32_bf16 v[78:81], v[214:217], v[198:201], v[78:81]
	v_mfma_f32_16x16x32_bf16 v[74:77], v[222:225], v[198:201], v[74:77]
	v_mfma_f32_16x16x32_bf16 v[70:73], v[214:217], v[206:209], v[70:73]
	v_mfma_f32_16x16x32_bf16 v[66:69], v[222:225], v[206:209], v[66:69]
	v_mfma_f32_16x16x32_bf16 v[94:97], v[218:221], v[186:189], v[94:97]
	v_mfma_f32_16x16x32_bf16 v[90:93], v[226:229], v[186:189], v[90:93]
	v_mfma_f32_16x16x32_bf16 v[86:89], v[218:221], v[194:197], v[86:89]
	v_mfma_f32_16x16x32_bf16 v[82:85], v[226:229], v[194:197], v[82:85]
	v_mfma_f32_16x16x32_bf16 v[78:81], v[218:221], v[202:205], v[78:81]
	v_mfma_f32_16x16x32_bf16 v[74:77], v[226:229], v[202:205], v[74:77]
	v_mfma_f32_16x16x32_bf16 v[70:73], v[218:221], v[210:213], v[70:73]
	v_mfma_f32_16x16x32_bf16 v[66:69], v[226:229], v[210:213], v[66:69]
	s_add_u32 s40, s14, s42
	s_addc_u32 s41, s15, 0
	v_lshl_add_u64 v[150:151], s[40:41], 0, v[0:1]
	v_readfirstlane_b32 s43, v133
	v_lshl_add_u64 v[150:151], v[150:151], 0, s[88:89]
	s_mov_b32 m0, s43
	s_barrier
	ds_read_b128 v[186:189], v137 offset:16384
	ds_read_b128 v[190:193], v137 offset:17408
	ds_read_b128 v[194:197], v136 offset:16384
	ds_read_b128 v[198:201], v136 offset:17408
	ds_read_b128 v[202:205], v135 offset:16384
	ds_read_b128 v[206:209], v135 offset:17408
	ds_read_b128 v[210:213], v134 offset:16384
	ds_read_b128 v[230:233], v134 offset:17408
	global_load_lds_dwordx4 v[150:151], off
	v_lshl_add_u64 v[150:151], s[40:41], 0, v[130:131]
	v_lshl_add_u64 v[152:153], v[150:151], 0, s[88:89]
	v_add_u32_e32 v150, 0x2000, v133
	s_nop 0
	v_readfirstlane_b32 s40, v150
	s_mov_b32 m0, s40
	s_nop 0
	global_load_lds_dwordx4 v[152:153], off
	s_barrier
	s_waitcnt lgkmcnt(0)
	v_mfma_f32_16x16x32_bf16 v[62:65], v[156:159], v[186:189], v[62:65]
	v_mfma_f32_16x16x32_bf16 v[58:61], v[166:169], v[186:189], v[58:61]
	v_mfma_f32_16x16x32_bf16 v[54:57], v[156:159], v[194:197], v[54:57]
	v_mfma_f32_16x16x32_bf16 v[50:53], v[166:169], v[194:197], v[50:53]
	v_mfma_f32_16x16x32_bf16 v[46:49], v[156:159], v[202:205], v[46:49]
	v_mfma_f32_16x16x32_bf16 v[42:45], v[166:169], v[202:205], v[42:45]
	v_mfma_f32_16x16x32_bf16 v[38:41], v[156:159], v[210:213], v[38:41]
	v_mfma_f32_16x16x32_bf16 v[34:37], v[166:169], v[210:213], v[34:37]
	v_mfma_f32_16x16x32_bf16 v[62:65], v[160:163], v[190:193], v[62:65]
	v_mfma_f32_16x16x32_bf16 v[58:61], v[172:175], v[190:193], v[58:61]
	v_mfma_f32_16x16x32_bf16 v[54:57], v[160:163], v[198:201], v[54:57]
	v_mfma_f32_16x16x32_bf16 v[50:53], v[172:175], v[198:201], v[50:53]
	v_mfma_f32_16x16x32_bf16 v[46:49], v[160:163], v[206:209], v[46:49]
	v_mfma_f32_16x16x32_bf16 v[42:45], v[172:175], v[206:209], v[42:45]
	v_mfma_f32_16x16x32_bf16 v[38:41], v[160:163], v[230:233], v[38:41]
	v_mfma_f32_16x16x32_bf16 v[34:37], v[172:175], v[230:233], v[34:37]
	s_barrier
; #define STAGE_A(P,br,kt) STAGE_G(P,c.A,c.lda,br,(long)(kt)*c.kstr)
; #define STAGE_B(P,br,kt) STAGE_G(P,c.Bt,c.K,br,(long)(kt)*BK)
; #define LDA(dst,b,h) for(int m=0;m<4;++m)for(int k=0;k<2;++k) \
;     dst[m][k]=*reinterpret_cast<const bf16x8*>((char*)SA(b,h)+lds_byte(wr*64+m*16+fr,k*32+fq*8))
; #define LDB(dst,b,h) for(int n=0;n<2;++n)for(int k=0;k<2;++k) \
;     dst[n][k]=*reinterpret_cast<const bf16x8*>((char*)SB(b,h)+lds_byte(wc*32+n*16+fr,k*32+fq*8))
; #define MMA(ai,bj,At,Bt_) do{__builtin_amdgcn_s_setprio(1); \
;     for(int m=0;m<4;++m)for(int n=0;n<2;++n)for(int k=0;k<2;++k) \
;       acc[ai][bj][m][n]=__builtin_amdgcn_mfma_f32_16x16x32_bf16(Bt_[n][k],At[m][k],acc[ai][bj][m][n],0,0,0); \
;     __builtin_amdgcn_s_setprio(0);}while(0)
; #define WAIT_V(n) asm volatile("s_waitcnt vmcnt(" #n ")":::"memory")
; #define WAIT_L(n) asm volatile("s_waitcnt lgkmcnt(" #n ")":::"memory")
; #define BAR __builtin_amdgcn_s_barrier()
; #define SCHED __builtin_amdgcn_sched_barrier(0)
; template <int EPI>
; __device__ __forceinline__ void gemm_run(const GD& c, const bool has_next, const GD& nx, const Ctx& e, bf16* shm, float* rs, float* rs_nxt, float* racc_) {
;     ...
;     WAIT_V(6); BAR; MMA(1,1,At,B1); BAR;
;     LDB(B0,1,0); SCHED; LDA(At,1,0); STAGE_A(SA(0,1),brow+HALF,t+2);
;     WAIT_L(8); BAR; WAIT_L(0); MMA(0,0,At,B0); BAR; SCHED;
;     LDB(B1,1,1); STAGE_B(SB(1,0),bcol,t+3);
;     BAR; WAIT_L(0); MMA(0,1,At,B1); BAR;
;     LDA(At,1,1); STAGE_A(SA(1,0),brow,t+3);
;     BAR; WAIT_L(0); MMA(1,0,At,B0); BAR; SCHED;
;     STAGE_B(SB(1,1),bcol+HALF,t+3);
;     WAIT_V(6); BAR; MMA(1,1,At,B1); BAR;
	s_add_u32 s40, s20, s42
	s_addc_u32 s41, s21, 0
	v_add_u32_e32 v151, s86, v139
	v_lshl_add_u64 v[152:153], s[40:41], 0, v[0:1]
	v_readfirstlane_b32 s42, v151
	v_lshl_add_u64 v[152:153], v[152:153], 0, s[88:89]
	s_mov_b32 m0, s42
	s_nop 0
	global_load_lds_dwordx4 v[152:153], off
	v_lshl_add_u64 v[152:153], s[40:41], 0, v[130:131]
	v_lshl_add_u64 v[156:157], v[152:153], 0, s[88:89]
	v_add_u32_e32 v152, 0x2000, v151
	s_nop 0
	v_readfirstlane_b32 s40, v152
	s_mov_b32 m0, s40
	s_nop 0
	global_load_lds_dwordx4 v[156:157], off
	s_waitcnt vmcnt(6)
	s_barrier
	v_mfma_f32_16x16x32_bf16 v[30:33], v[214:217], v[186:189], v[30:33]
	v_mfma_f32_16x16x32_bf16 v[26:29], v[222:225], v[186:189], v[26:29]
	v_mfma_f32_16x16x32_bf16 v[22:25], v[214:217], v[194:197], v[22:25]
	v_mfma_f32_16x16x32_bf16 v[18:21], v[222:225], v[194:197], v[18:21]
	v_mfma_f32_16x16x32_bf16 v[14:17], v[214:217], v[202:205], v[14:17]
	v_mfma_f32_16x16x32_bf16 v[10:13], v[222:225], v[202:205], v[10:13]
	v_mfma_f32_16x16x32_bf16 v[6:9], v[214:217], v[210:213], v[6:9]
	v_mfma_f32_16x16x32_bf16 v[2:5], v[222:225], v[210:213], v[2:5]
	v_mfma_f32_16x16x32_bf16 v[30:33], v[218:221], v[190:193], v[30:33]
	v_mfma_f32_16x16x32_bf16 v[26:29], v[226:229], v[190:193], v[26:29]
	v_mfma_f32_16x16x32_bf16 v[22:25], v[218:221], v[198:201], v[22:25]
	v_mfma_f32_16x16x32_bf16 v[18:21], v[226:229], v[198:201], v[18:21]
	v_mfma_f32_16x16x32_bf16 v[14:17], v[218:221], v[206:209], v[14:17]
	v_mfma_f32_16x16x32_bf16 v[10:13], v[226:229], v[206:209], v[10:13]
	v_mfma_f32_16x16x32_bf16 v[6:9], v[218:221], v[230:233], v[6:9]
	v_mfma_f32_16x16x32_bf16 v[2:5], v[226:229], v[230:233], v[2:5]
	s_barrier
	ds_read_b128 v[156:159], v140
	ds_read_b128 v[160:163], v140 offset:1024
	ds_read_b128 v[166:169], v140 offset:2048
	ds_read_b128 v[172:175], v140 offset:3072
	v_add_u32_e32 v153, 0x4000, v133
	v_add_u32_e32 v154, 0x6000, v133
	v_readfirstlane_b32 s40, v153
	v_lshl_add_u64 v[218:219], v[234:235], 0, s[88:89]
	s_mov_b32 m0, s40
	v_readfirstlane_b32 s40, v154
	ds_read_b128 v[186:189], v137 offset:32768
	ds_read_b128 v[190:193], v137 offset:33792
	ds_read_b128 v[194:197], v136 offset:32768
	ds_read_b128 v[198:201], v136 offset:33792
	ds_read_b128 v[202:205], v135 offset:32768
	ds_read_b128 v[206:209], v135 offset:33792
	ds_read_b128 v[210:213], v134 offset:32768
	ds_read_b128 v[214:217], v134 offset:33792
	global_load_lds_dwordx4 v[218:219], off
	v_lshl_add_u64 v[218:219], v[236:237], 0, s[88:89]
	s_mov_b32 m0, s40
	s_nop 0
	global_load_lds_dwordx4 v[218:219], off
	s_waitcnt lgkmcnt(8)
	s_barrier
	s_waitcnt lgkmcnt(0)
	v_mfma_f32_16x16x32_bf16 v[126:129], v[156:159], v[186:189], v[126:129]
	v_mfma_f32_16x16x32_bf16 v[122:125], v[166:169], v[186:189], v[122:125]
	v_mfma_f32_16x16x32_bf16 v[118:121], v[156:159], v[194:197], v[118:121]
	v_mfma_f32_16x16x32_bf16 v[114:117], v[166:169], v[194:197], v[114:117]
	v_mfma_f32_16x16x32_bf16 v[110:113], v[156:159], v[202:205], v[110:113]
	v_mfma_f32_16x16x32_bf16 v[106:109], v[166:169], v[202:205], v[106:109]
	v_mfma_f32_16x16x32_bf16 v[102:105], v[156:159], v[210:213], v[102:105]
	v_mfma_f32_16x16x32_bf16 v[98:101], v[166:169], v[210:213], v[98:101]
	v_mfma_f32_16x16x32_bf16 v[126:129], v[160:163], v[190:193], v[126:129]
	v_mfma_f32_16x16x32_bf16 v[122:125], v[172:175], v[190:193], v[122:125]
	v_mfma_f32_16x16x32_bf16 v[118:121], v[160:163], v[198:201], v[118:121]
	v_mfma_f32_16x16x32_bf16 v[114:117], v[172:175], v[198:201], v[114:117]
	v_mfma_f32_16x16x32_bf16 v[110:113], v[160:163], v[206:209], v[110:113]
	v_mfma_f32_16x16x32_bf16 v[106:109], v[172:175], v[206:209], v[106:109]
	v_mfma_f32_16x16x32_bf16 v[102:105], v[160:163], v[214:217], v[102:105]
	v_mfma_f32_16x16x32_bf16 v[98:101], v[172:175], v[214:217], v[98:101]
	s_barrier
	s_add_i32 s82, s39, 3
	s_lshl_b64 s[40:41], s[82:83], 7
	s_add_u32 s42, s2, s40
	s_addc_u32 s43, s3, s41
	v_readfirstlane_b32 s39, v141
	v_add_u32_e32 v170, 0x2000, v141
	v_lshl_add_u64 v[234:235], s[42:43], 0, v[0:1]
	s_mov_b32 m0, s39
	v_readfirstlane_b32 s39, v170
	ds_read_b128 v[218:221], v138
	ds_read_b128 v[222:225], v138 offset:1024
	ds_read_b128 v[226:229], v138 offset:2048
	ds_read_b128 v[230:233], v138 offset:3072
	global_load_lds_dwordx4 v[234:235], off
	v_lshl_add_u64 v[234:235], s[42:43], 0, v[130:131]
	s_mov_b32 m0, s39
	s_nop 0
	global_load_lds_dwordx4 v[234:235], off
	s_barrier
	s_waitcnt lgkmcnt(0)
	v_mfma_f32_16x16x32_bf16 v[94:97], v[218:221], v[186:189], v[94:97]
	v_mfma_f32_16x16x32_bf16 v[90:93], v[226:229], v[186:189], v[90:93]
	v_mfma_f32_16x16x32_bf16 v[86:89], v[218:221], v[194:197], v[86:89]
	v_mfma_f32_16x16x32_bf16 v[82:85], v[226:229], v[194:197], v[82:85]
	s_add_u32 s42, s14, s40
	v_mfma_f32_16x16x32_bf16 v[78:81], v[218:221], v[202:205], v[78:81]
	s_addc_u32 s43, s15, s41
	v_mfma_f32_16x16x32_bf16 v[74:77], v[226:229], v[202:205], v[74:77]
	v_readfirstlane_b32 s39, v142
	v_mfma_f32_16x16x32_bf16 v[70:73], v[218:221], v[210:213], v[70:73]
	v_lshl_add_u64 v[234:235], s[42:43], 0, v[0:1]
	v_mfma_f32_16x16x32_bf16 v[66:69], v[226:229], v[210:213], v[66:69]
	s_mov_b32 m0, s39
	v_mfma_f32_16x16x32_bf16 v[94:97], v[222:225], v[190:193], v[94:97]
	v_readfirstlane_b32 s39, v143
	v_mfma_f32_16x16x32_bf16 v[90:93], v[230:233], v[190:193], v[90:93]
	v_mfma_f32_16x16x32_bf16 v[86:89], v[222:225], v[198:201], v[86:89]
	v_mfma_f32_16x16x32_bf16 v[82:85], v[230:233], v[198:201], v[82:85]
	v_mfma_f32_16x16x32_bf16 v[78:81], v[222:225], v[206:209], v[78:81]
	v_mfma_f32_16x16x32_bf16 v[74:77], v[230:233], v[206:209], v[74:77]
	v_mfma_f32_16x16x32_bf16 v[70:73], v[222:225], v[214:217], v[70:73]
	v_mfma_f32_16x16x32_bf16 v[66:69], v[230:233], v[214:217], v[66:69]
	s_barrier
; #define STAGE_A(P,br,kt) STAGE_G(P,c.A,c.lda,br,(long)(kt)*c.kstr)
; #define STAGE_B(P,br,kt) STAGE_G(P,c.Bt,c.K,br,(long)(kt)*BK)
; #define LDA(dst,b,h) for(int m=0;m<4;++m)for(int k=0;k<2;++k) \
;     dst[m][k]=*reinterpret_cast<const bf16x8*>((char*)SA(b,h)+lds_byte(wr*64+m*16+fr,k*32+fq*8))
; #define LDB(dst,b,h) for(int n=0;n<2;++n)for(int k=0;k<2;++k) \
;     dst[n][k]=*reinterpret_cast<const bf16x8*>((char*)SB(b,h)+lds_byte(wc*32+n*16+fr,k*32+fq*8))
; #define MMA(ai,bj,At,Bt_) do{__builtin_amdgcn_s_setprio(1); \
;     for(int m=0;m<4;++m)for(int n=0;n<2;++n)for(int k=0;k<2;++k) \
;       acc[ai][bj][m][n]=__builtin_amdgcn_mfma_f32_16x16x32_bf16(Bt_[n][k],At[m][k],acc[ai][bj][m][n],0,0,0); \
;     __builtin_amdgcn_s_setprio(0);}while(0)
; #define WAIT_V(n) asm volatile("s_waitcnt vmcnt(" #n ")":::"memory")
; #define WAIT_L(n) asm volatile("s_waitcnt lgkmcnt(" #n ")":::"memory")
; #define BAR __builtin_amdgcn_s_barrier()
; #define SCHED __builtin_amdgcn_sched_barrier(0)
; template <int EPI>
; __device__ __forceinline__ void gemm_run(const GD& c, const bool has_next, const GD& nx, const Ctx& e, bf16* shm, float* rs, float* rs_nxt, float* racc_) {
;     ...
;     BAR; WAIT_L(0); MMA(1,0,At,B0); BAR; SCHED;
;     STAGE_B(SB(1,1),bcol+HALF,t+3);
;     WAIT_V(6); BAR; MMA(1,1,At,B1); BAR;
;   }
;   { LDB(B0,0,0); LDA(At,0,0); STAGE_A(SA(1,1),brow+HALF,nt-1);
;     BAR; WAIT_L(0); MMA(0,0,At,B0); BAR;
	ds_read_b128 v[186:189], v137 offset:49152
	ds_read_b128 v[190:193], v137 offset:50176
	ds_read_b128 v[194:197], v136 offset:49152
	ds_read_b128 v[198:201], v136 offset:50176
	ds_read_b128 v[202:205], v135 offset:49152
	ds_read_b128 v[206:209], v135 offset:50176
	ds_read_b128 v[210:213], v134 offset:49152
	ds_read_b128 v[214:217], v134 offset:50176
	global_load_lds_dwordx4 v[234:235], off
	v_lshl_add_u64 v[234:235], s[42:43], 0, v[130:131]
	s_mov_b32 m0, s39
	s_nop 0
	global_load_lds_dwordx4 v[234:235], off
	s_barrier
	s_waitcnt lgkmcnt(0)
	v_mfma_f32_16x16x32_bf16 v[62:65], v[156:159], v[186:189], v[62:65]
	v_mfma_f32_16x16x32_bf16 v[58:61], v[166:169], v[186:189], v[58:61]
	v_mfma_f32_16x16x32_bf16 v[54:57], v[156:159], v[194:197], v[54:57]
	v_mfma_f32_16x16x32_bf16 v[50:53], v[166:169], v[194:197], v[50:53]
	v_mfma_f32_16x16x32_bf16 v[46:49], v[156:159], v[202:205], v[46:49]
	v_mfma_f32_16x16x32_bf16 v[42:45], v[166:169], v[202:205], v[42:45]
	v_mfma_f32_16x16x32_bf16 v[38:41], v[156:159], v[210:213], v[38:41]
	v_mfma_f32_16x16x32_bf16 v[34:37], v[166:169], v[210:213], v[34:37]
	v_mfma_f32_16x16x32_bf16 v[62:65], v[160:163], v[190:193], v[62:65]
	v_mfma_f32_16x16x32_bf16 v[58:61], v[172:175], v[190:193], v[58:61]
	v_mfma_f32_16x16x32_bf16 v[54:57], v[160:163], v[198:201], v[54:57]
	v_mfma_f32_16x16x32_bf16 v[50:53], v[172:175], v[198:201], v[50:53]
	v_mfma_f32_16x16x32_bf16 v[46:49], v[160:163], v[206:209], v[46:49]
	v_mfma_f32_16x16x32_bf16 v[42:45], v[172:175], v[206:209], v[42:45]
	v_mfma_f32_16x16x32_bf16 v[38:41], v[160:163], v[214:217], v[38:41]
	v_mfma_f32_16x16x32_bf16 v[34:37], v[172:175], v[214:217], v[34:37]
	s_barrier
	s_add_u32 s40, s20, s40
	s_addc_u32 s41, s21, s41
	v_readfirstlane_b32 s39, v145
	v_add_u32_e32 v158, 0x2000, v145
	v_lshl_add_u64 v[156:157], s[40:41], 0, v[0:1]
	s_mov_b32 m0, s39
	v_readfirstlane_b32 s39, v158
	global_load_lds_dwordx4 v[156:157], off
	v_lshl_add_u64 v[156:157], s[40:41], 0, v[130:131]
	s_mov_b32 m0, s39
	s_nop 0
	global_load_lds_dwordx4 v[156:157], off
	s_waitcnt vmcnt(6)
	s_barrier
	v_mfma_f32_16x16x32_bf16 v[30:33], v[218:221], v[186:189], v[30:33]
	v_mfma_f32_16x16x32_bf16 v[26:29], v[226:229], v[186:189], v[26:29]
	v_mfma_f32_16x16x32_bf16 v[22:25], v[218:221], v[194:197], v[22:25]
	v_mfma_f32_16x16x32_bf16 v[18:21], v[226:229], v[194:197], v[18:21]
	v_mfma_f32_16x16x32_bf16 v[14:17], v[218:221], v[202:205], v[14:17]
	v_mfma_f32_16x16x32_bf16 v[10:13], v[226:229], v[202:205], v[10:13]
	v_mfma_f32_16x16x32_bf16 v[6:9], v[218:221], v[210:213], v[6:9]
	v_mfma_f32_16x16x32_bf16 v[2:5], v[226:229], v[210:213], v[2:5]
	v_mfma_f32_16x16x32_bf16 v[30:33], v[222:225], v[190:193], v[30:33]
	v_mfma_f32_16x16x32_bf16 v[26:29], v[230:233], v[190:193], v[26:29]
	v_mfma_f32_16x16x32_bf16 v[22:25], v[222:225], v[198:201], v[22:25]
	v_mfma_f32_16x16x32_bf16 v[18:21], v[230:233], v[198:201], v[18:21]
	v_mfma_f32_16x16x32_bf16 v[14:17], v[222:225], v[206:209], v[14:17]
	v_mfma_f32_16x16x32_bf16 v[10:13], v[230:233], v[206:209], v[10:13]
	v_mfma_f32_16x16x32_bf16 v[6:9], v[222:225], v[214:217], v[6:9]
	v_mfma_f32_16x16x32_bf16 v[2:5], v[230:233], v[214:217], v[2:5]
	s_mov_b32 s39, 2
	s_and_b64 vcc, exec, s[24:25]
	s_mov_b64 s[24:25], 0
	s_barrier
	s_cbranch_vccnz .LBB0_689
	v_lshl_add_u64 v[142:143], s[22:23], 0, v[0:1]
	s_mov_b64 s[14:15], 0x280
	v_readfirstlane_b32 s2, v147
	v_lshl_add_u64 v[142:143], v[142:143], 0, s[14:15]
	s_mov_b32 m0, s2
	ds_read_b128 v[156:159], v146
	ds_read_b128 v[160:163], v146 offset:1024
	ds_read_b128 v[166:169], v146 offset:2048
	ds_read_b128 v[172:175], v146 offset:3072
	ds_read_b128 v[186:189], v137
	ds_read_b128 v[190:193], v137 offset:1024
	ds_read_b128 v[194:197], v136
	ds_read_b128 v[198:201], v136 offset:1024
	ds_read_b128 v[202:205], v135
	ds_read_b128 v[206:209], v135 offset:1024
	ds_read_b128 v[210:213], v134
	ds_read_b128 v[214:217], v134 offset:1024
	global_load_lds_dwordx4 v[142:143], off
	v_lshl_add_u64 v[142:143], s[22:23], 0, v[130:131]
	v_readfirstlane_b32 s2, v155
	v_lshl_add_u64 v[142:143], v[142:143], 0, s[14:15]
	s_mov_b32 m0, s2
	s_nop 0
	global_load_lds_dwordx4 v[142:143], off
	s_barrier
	s_waitcnt lgkmcnt(0)
	v_mfma_f32_16x16x32_bf16 v[126:129], v[156:159], v[186:189], v[126:129]
	v_mfma_f32_16x16x32_bf16 v[122:125], v[166:169], v[186:189], v[122:125]
	v_mfma_f32_16x16x32_bf16 v[118:121], v[156:159], v[194:197], v[118:121]
	v_mfma_f32_16x16x32_bf16 v[110:113], v[156:159], v[202:205], v[110:113]
	v_mfma_f32_16x16x32_bf16 v[106:109], v[166:169], v[202:205], v[106:109]
	v_mfma_f32_16x16x32_bf16 v[126:129], v[160:163], v[190:193], v[126:129]
	v_mfma_f32_16x16x32_bf16 v[122:125], v[172:175], v[190:193], v[122:125]
	v_mfma_f32_16x16x32_bf16 v[118:121], v[160:163], v[198:201], v[118:121]
	v_mfma_f32_16x16x32_bf16 v[114:117], v[166:169], v[194:197], v[114:117]
	v_mfma_f32_16x16x32_bf16 v[110:113], v[160:163], v[206:209], v[110:113]
	v_mfma_f32_16x16x32_bf16 v[106:109], v[172:175], v[206:209], v[106:109]
	v_mfma_f32_16x16x32_bf16 v[102:105], v[156:159], v[210:213], v[102:105]
	v_mfma_f32_16x16x32_bf16 v[98:101], v[166:169], v[210:213], v[98:101]
	v_mfma_f32_16x16x32_bf16 v[218:221], v[172:175], v[198:201], v[114:117]
	v_mfma_f32_16x16x32_bf16 v[222:225], v[160:163], v[214:217], v[102:105]
	v_mfma_f32_16x16x32_bf16 v[226:229], v[172:175], v[214:217], v[98:101]
	s_barrier
	s_nop 2
	ds_read_b128 v[98:101], v144
	ds_read_b128 v[102:105], v144 offset:1024
	ds_read_b128 v[114:117], v144 offset:2048
	ds_read_b128 v[142:145], v144 offset:3072
	s_barrier
; #define LDA(dst,b,h) for(int m=0;m<4;++m)for(int k=0;k<2;++k) \
;     dst[m][k]=*reinterpret_cast<const bf16x8*>((char*)SA(b,h)+lds_byte(wr*64+m*16+fr,k*32+fq*8))
; #define LDB(dst,b,h) for(int n=0;n<2;++n)for(int k=0;k<2;++k) \
;     dst[n][k]=*reinterpret_cast<const bf16x8*>((char*)SB(b,h)+lds_byte(wc*32+n*16+fr,k*32+fq*8))
; #define MMA(ai,bj,At,Bt_) do{__builtin_amdgcn_s_setprio(1); \
;     for(int m=0;m<4;++m)for(int n=0;n<2;++n)for(int k=0;k<2;++k) \
;       acc[ai][bj][m][n]=__builtin_amdgcn_mfma_f32_16x16x32_bf16(Bt_[n][k],At[m][k],acc[ai][bj][m][n],0,0,0); \
;     __builtin_amdgcn_s_setprio(0);}while(0)
; #define WAIT_V(n) asm volatile("s_waitcnt vmcnt(" #n ")":::"memory")
; #define WAIT_L(n) asm volatile("s_waitcnt lgkmcnt(" #n ")":::"memory")
; #define BAR __builtin_amdgcn_s_barrier()
; template <int EPI>
; __device__ __forceinline__ void gemm_run(const GD& c, const bool has_next, const GD& nx, const Ctx& e, bf16* shm, float* rs, float* rs_nxt, float* racc_) {
;     ...
;     BAR; WAIT_L(0); MMA(0,0,At,B0); BAR;
;     LDB(B1,0,1); BAR; WAIT_L(0); MMA(0,1,At,B1); BAR;
;     LDA(At,0,1); WAIT_V(4); BAR; WAIT_L(0); MMA(1,0,At,B0); MMA(1,1,At,B1); BAR; }
;   { LDB(B0,1,0); LDA(At,1,0); WAIT_V(2); BAR; WAIT_L(0); MMA(0,0,At,B0); BAR;
	s_waitcnt lgkmcnt(0)
	v_mfma_f32_16x16x32_bf16 v[94:97], v[98:101], v[186:189], v[94:97]
	v_mfma_f32_16x16x32_bf16 v[90:93], v[114:117], v[186:189], v[90:93]
	v_mfma_f32_16x16x32_bf16 v[82:85], v[114:117], v[194:197], v[82:85]
	v_mfma_f32_16x16x32_bf16 v[78:81], v[98:101], v[202:205], v[78:81]
	v_mfma_f32_16x16x32_bf16 v[94:97], v[102:105], v[190:193], v[94:97]
	v_mfma_f32_16x16x32_bf16 v[90:93], v[142:145], v[190:193], v[90:93]
	v_mfma_f32_16x16x32_bf16 v[86:89], v[98:101], v[194:197], v[86:89]
	v_mfma_f32_16x16x32_bf16 v[82:85], v[142:145], v[198:201], v[82:85]
	v_mfma_f32_16x16x32_bf16 v[78:81], v[102:105], v[206:209], v[78:81]
	v_mfma_f32_16x16x32_bf16 v[74:77], v[114:117], v[202:205], v[74:77]
	v_mfma_f32_16x16x32_bf16 v[70:73], v[98:101], v[210:213], v[70:73]
	v_mfma_f32_16x16x32_bf16 v[66:69], v[114:117], v[210:213], v[66:69]
	v_mfma_f32_16x16x32_bf16 v[186:189], v[102:105], v[198:201], v[86:89]
	v_mfma_f32_16x16x32_bf16 v[190:193], v[142:145], v[206:209], v[74:77]
	v_mfma_f32_16x16x32_bf16 v[194:197], v[102:105], v[214:217], v[70:73]
	v_mfma_f32_16x16x32_bf16 v[198:201], v[142:145], v[214:217], v[66:69]
	s_barrier
	s_nop 1
	ds_read_b128 v[66:69], v137 offset:16384
	ds_read_b128 v[70:73], v137 offset:17408
	ds_read_b128 v[74:77], v136 offset:16384
	ds_read_b128 v[86:89], v136 offset:17408
	ds_read_b128 v[202:205], v135 offset:16384
	ds_read_b128 v[206:209], v135 offset:17408
	ds_read_b128 v[210:213], v134 offset:16384
	ds_read_b128 v[214:217], v134 offset:17408
	s_waitcnt vmcnt(4)
	s_barrier
	s_waitcnt lgkmcnt(0)
	v_mfma_f32_16x16x32_bf16 v[62:65], v[156:159], v[66:69], v[62:65]
	v_mfma_f32_16x16x32_bf16 v[58:61], v[166:169], v[66:69], v[58:61]
	v_mfma_f32_16x16x32_bf16 v[46:49], v[156:159], v[202:205], v[46:49]
	v_mfma_f32_16x16x32_bf16 v[42:45], v[166:169], v[202:205], v[42:45]
	v_mfma_f32_16x16x32_bf16 v[62:65], v[160:163], v[70:73], v[62:65]
	v_mfma_f32_16x16x32_bf16 v[58:61], v[172:175], v[70:73], v[58:61]
	v_mfma_f32_16x16x32_bf16 v[54:57], v[156:159], v[74:77], v[54:57]
	v_mfma_f32_16x16x32_bf16 v[50:53], v[166:169], v[74:77], v[50:53]
	v_mfma_f32_16x16x32_bf16 v[46:49], v[160:163], v[206:209], v[46:49]
	v_mfma_f32_16x16x32_bf16 v[42:45], v[172:175], v[206:209], v[42:45]
	v_mfma_f32_16x16x32_bf16 v[38:41], v[156:159], v[210:213], v[38:41]
	v_mfma_f32_16x16x32_bf16 v[34:37], v[166:169], v[210:213], v[34:37]
	v_mfma_f32_16x16x32_bf16 v[230:233], v[160:163], v[86:89], v[54:57]
	v_mfma_f32_16x16x32_bf16 v[234:237], v[172:175], v[86:89], v[50:53]
	v_mfma_f32_16x16x32_bf16 v[156:159], v[160:163], v[214:217], v[38:41]
	v_mfma_f32_16x16x32_bf16 v[160:163], v[172:175], v[214:217], v[34:37]
	v_mfma_f32_16x16x32_bf16 v[30:33], v[98:101], v[66:69], v[30:33]
	v_mfma_f32_16x16x32_bf16 v[26:29], v[114:117], v[66:69], v[26:29]
	v_mfma_f32_16x16x32_bf16 v[14:17], v[98:101], v[202:205], v[14:17]
	v_mfma_f32_16x16x32_bf16 v[10:13], v[114:117], v[202:205], v[10:13]
	v_mfma_f32_16x16x32_bf16 v[30:33], v[102:105], v[70:73], v[30:33]
	v_mfma_f32_16x16x32_bf16 v[26:29], v[142:145], v[70:73], v[26:29]
	v_mfma_f32_16x16x32_bf16 v[22:25], v[98:101], v[74:77], v[22:25]
	v_mfma_f32_16x16x32_bf16 v[18:21], v[114:117], v[74:77], v[18:21]
	v_mfma_f32_16x16x32_bf16 v[14:17], v[102:105], v[206:209], v[14:17]
	v_mfma_f32_16x16x32_bf16 v[10:13], v[142:145], v[206:209], v[10:13]
	v_mfma_f32_16x16x32_bf16 v[6:9], v[98:101], v[210:213], v[6:9]
	v_mfma_f32_16x16x32_bf16 v[2:5], v[114:117], v[210:213], v[2:5]
	v_mfma_f32_16x16x32_bf16 v[166:169], v[102:105], v[86:89], v[22:25]
	v_mfma_f32_16x16x32_bf16 v[172:175], v[142:145], v[86:89], v[18:21]
	v_mfma_f32_16x16x32_bf16 v[202:205], v[102:105], v[214:217], v[6:9]
	v_mfma_f32_16x16x32_bf16 v[142:145], v[142:145], v[214:217], v[2:5]
	s_barrier
	s_nop 1
	ds_read_b128 v[2:5], v140
	ds_read_b128 v[6:9], v140 offset:1024
	ds_read_b128 v[206:209], v140 offset:2048
	ds_read_b128 v[210:213], v140 offset:3072
	ds_read_b128 v[18:21], v137 offset:32768
	ds_read_b128 v[22:25], v137 offset:33792
	ds_read_b128 v[34:37], v136 offset:32768
	ds_read_b128 v[38:41], v136 offset:33792
	ds_read_b128 v[50:53], v135 offset:32768
	ds_read_b128 v[54:57], v135 offset:33792
	ds_read_b128 v[214:217], v134 offset:32768
	ds_read_b128 v[238:241], v134 offset:33792
	s_waitcnt vmcnt(2)
	s_barrier
; #define LDA(dst,b,h) for(int m=0;m<4;++m)for(int k=0;k<2;++k) \
;     dst[m][k]=*reinterpret_cast<const bf16x8*>((char*)SA(b,h)+lds_byte(wr*64+m*16+fr,k*32+fq*8))
; #define LDB(dst,b,h) for(int n=0;n<2;++n)for(int k=0;k<2;++k) \
;     dst[n][k]=*reinterpret_cast<const bf16x8*>((char*)SB(b,h)+lds_byte(wc*32+n*16+fr,k*32+fq*8))
; #define MMA(ai,bj,At,Bt_) do{__builtin_amdgcn_s_setprio(1); \
;     for(int m=0;m<4;++m)for(int n=0;n<2;++n)for(int k=0;k<2;++k) \
;       acc[ai][bj][m][n]=__builtin_amdgcn_mfma_f32_16x16x32_bf16(Bt_[n][k],At[m][k],acc[ai][bj][m][n],0,0,0); \
;     __builtin_amdgcn_s_setprio(0);}while(0)
; #define WAIT_V(n) asm volatile("s_waitcnt vmcnt(" #n ")":::"memory")
; #define WAIT_L(n) asm volatile("s_waitcnt lgkmcnt(" #n ")":::"memory")
; #define BAR __builtin_amdgcn_s_barrier()
; template <int EPI>
; __device__ __forceinline__ void gemm_run(const GD& c, const bool has_next, const GD& nx, const Ctx& e, bf16* shm, float* rs, float* rs_nxt, float* racc_) {
;     ...
;     LDA(At,0,1); WAIT_V(4); BAR; WAIT_L(0); MMA(1,0,At,B0); MMA(1,1,At,B1); BAR; }
;   { LDB(B0,1,0); LDA(At,1,0); WAIT_V(2); BAR; WAIT_L(0); MMA(0,0,At,B0); BAR;
;     LDB(B1,1,1); WAIT_V(0); BAR; WAIT_L(0); MMA(0,1,At,B1); BAR;
;     LDA(At,1,1); BAR; WAIT_L(0); MMA(1,0,At,B0); MMA(1,1,At,B1); BAR; }
;   if(wr==0)BAR;
	s_waitcnt lgkmcnt(0)
	v_mfma_f32_16x16x32_bf16 v[66:69], v[2:5], v[18:21], v[126:129]
	v_mfma_f32_16x16x32_bf16 v[114:117], v[6:9], v[22:25], v[66:69]
	v_mfma_f32_16x16x32_bf16 v[66:69], v[206:209], v[18:21], v[122:125]
	v_mfma_f32_16x16x32_bf16 v[126:129], v[210:213], v[22:25], v[66:69]
	v_mfma_f32_16x16x32_bf16 v[66:69], v[2:5], v[34:37], v[118:121]
	v_mfma_f32_16x16x32_bf16 v[98:101], v[6:9], v[38:41], v[66:69]
	v_mfma_f32_16x16x32_bf16 v[66:69], v[206:209], v[34:37], v[218:221]
	v_mfma_f32_16x16x32_bf16 v[102:105], v[210:213], v[38:41], v[66:69]
	v_mfma_f32_16x16x32_bf16 v[66:69], v[2:5], v[50:53], v[110:113]
	v_mfma_f32_16x16x32_bf16 v[74:77], v[6:9], v[54:57], v[66:69]
	v_mfma_f32_16x16x32_bf16 v[66:69], v[206:209], v[50:53], v[106:109]
	v_mfma_f32_16x16x32_bf16 v[86:89], v[210:213], v[54:57], v[66:69]
	v_mfma_f32_16x16x32_bf16 v[66:69], v[2:5], v[214:217], v[222:225]
	v_mfma_f32_16x16x32_bf16 v[70:73], v[206:209], v[214:217], v[226:229]
	v_mfma_f32_16x16x32_bf16 v[66:69], v[6:9], v[238:241], v[66:69]
	v_mfma_f32_16x16x32_bf16 v[70:73], v[210:213], v[238:241], v[70:73]
	s_barrier
	ds_read_b128 v[218:221], v138
	ds_read_b128 v[222:225], v138 offset:1024
	ds_read_b128 v[226:229], v138 offset:2048
	ds_read_b128 v[138:141], v138 offset:3072
	s_waitcnt vmcnt(0)
	s_barrier
	s_waitcnt lgkmcnt(0)
	v_mfma_f32_16x16x32_bf16 v[94:97], v[218:221], v[18:21], v[94:97]
	v_mfma_f32_16x16x32_bf16 v[18:21], v[226:229], v[18:21], v[90:93]
	v_mfma_f32_16x16x32_bf16 v[122:125], v[138:141], v[22:25], v[18:21]
	v_mfma_f32_16x16x32_bf16 v[18:21], v[218:221], v[34:37], v[186:189]
	v_mfma_f32_16x16x32_bf16 v[106:109], v[222:225], v[38:41], v[18:21]
	v_mfma_f32_16x16x32_bf16 v[18:21], v[226:229], v[34:37], v[82:85]
	v_mfma_f32_16x16x32_bf16 v[110:113], v[138:141], v[38:41], v[18:21]
	v_mfma_f32_16x16x32_bf16 v[18:21], v[218:221], v[50:53], v[78:81]
	v_mfma_f32_16x16x32_bf16 v[90:93], v[222:225], v[54:57], v[18:21]
	v_mfma_f32_16x16x32_bf16 v[18:21], v[226:229], v[50:53], v[190:193]
	v_mfma_f32_16x16x32_bf16 v[118:121], v[222:225], v[22:25], v[94:97]
	v_mfma_f32_16x16x32_bf16 v[94:97], v[138:141], v[54:57], v[18:21]
	v_mfma_f32_16x16x32_bf16 v[18:21], v[218:221], v[214:217], v[194:197]
	v_mfma_f32_16x16x32_bf16 v[78:81], v[222:225], v[238:241], v[18:21]
	v_mfma_f32_16x16x32_bf16 v[18:21], v[226:229], v[214:217], v[198:201]
	v_mfma_f32_16x16x32_bf16 v[82:85], v[138:141], v[238:241], v[18:21]
	s_barrier
	ds_read_b128 v[186:189], v137 offset:49152
	ds_read_b128 v[190:193], v137 offset:50176
	ds_read_b128 v[194:197], v136 offset:49152
	ds_read_b128 v[198:201], v136 offset:50176
	ds_read_b128 v[214:217], v135 offset:49152
	ds_read_b128 v[238:241], v135 offset:50176
	ds_read_b128 v[242:245], v134 offset:49152
	ds_read_b128 v[134:137], v134 offset:50176
	s_barrier
	s_waitcnt lgkmcnt(0)
	v_mfma_f32_16x16x32_bf16 v[18:21], v[2:5], v[186:189], v[62:65]
	v_mfma_f32_16x16x32_bf16 v[50:53], v[6:9], v[190:193], v[18:21]
	v_mfma_f32_16x16x32_bf16 v[18:21], v[206:209], v[186:189], v[58:61]
	v_mfma_f32_16x16x32_bf16 v[54:57], v[210:213], v[190:193], v[18:21]
	v_mfma_f32_16x16x32_bf16 v[18:21], v[2:5], v[194:197], v[230:233]
	v_mfma_f32_16x16x32_bf16 v[34:37], v[6:9], v[198:201], v[18:21]
	v_mfma_f32_16x16x32_bf16 v[18:21], v[206:209], v[194:197], v[234:237]
	v_mfma_f32_16x16x32_bf16 v[38:41], v[210:213], v[198:201], v[18:21]
	v_mfma_f32_16x16x32_bf16 v[18:21], v[2:5], v[214:217], v[46:49]
	v_mfma_f32_16x16x32_bf16 v[2:5], v[2:5], v[242:245], v[156:159]
	v_mfma_f32_16x16x32_bf16 v[18:21], v[6:9], v[238:241], v[18:21]
	v_mfma_f32_16x16x32_bf16 v[22:25], v[206:209], v[214:217], v[42:45]
	v_mfma_f32_16x16x32_bf16 v[2:5], v[6:9], v[134:137], v[2:5]
	v_mfma_f32_16x16x32_bf16 v[6:9], v[206:209], v[242:245], v[160:163]
	v_mfma_f32_16x16x32_bf16 v[22:25], v[210:213], v[238:241], v[22:25]
	v_mfma_f32_16x16x32_bf16 v[6:9], v[210:213], v[134:137], v[6:9]
	v_mfma_f32_16x16x32_bf16 v[26:29], v[226:229], v[186:189], v[26:29]
	v_mfma_f32_16x16x32_bf16 v[62:65], v[138:141], v[190:193], v[26:29]
	v_mfma_f32_16x16x32_bf16 v[26:29], v[218:221], v[194:197], v[166:169]
	v_mfma_f32_16x16x32_bf16 v[30:33], v[218:221], v[186:189], v[30:33]
	v_mfma_f32_16x16x32_bf16 v[42:45], v[222:225], v[198:201], v[26:29]
	v_mfma_f32_16x16x32_bf16 v[26:29], v[226:229], v[194:197], v[172:175]
	v_mfma_f32_16x16x32_bf16 v[14:17], v[218:221], v[214:217], v[14:17]
	v_mfma_f32_16x16x32_bf16 v[10:13], v[226:229], v[214:217], v[10:13]
	v_mfma_f32_16x16x32_bf16 v[58:61], v[222:225], v[190:193], v[30:33]
	v_mfma_f32_16x16x32_bf16 v[46:49], v[138:141], v[198:201], v[26:29]
	v_mfma_f32_16x16x32_bf16 v[26:29], v[222:225], v[238:241], v[14:17]
	v_mfma_f32_16x16x32_bf16 v[30:33], v[138:141], v[238:241], v[10:13]
	v_mfma_f32_16x16x32_bf16 v[10:13], v[218:221], v[242:245], v[202:205]
	v_mfma_f32_16x16x32_bf16 v[14:17], v[226:229], v[242:245], v[142:145]
	v_mfma_f32_16x16x32_bf16 v[10:13], v[222:225], v[134:137], v[10:13]
	v_mfma_f32_16x16x32_bf16 v[14:17], v[138:141], v[134:137], v[14:17]
	v_cmp_gt_u32_e32 vcc, s96, v132
	s_barrier
	s_and_saveexec_b64 s[2:3], vcc
	s_cbranch_execz .LBB0_692
	s_barrier

; #define STAGE_A(P,br,kt) STAGE_G(P,c.A,c.lda,br,(long)(kt)*c.kstr)
; #define STAGE_B(P,br,kt) STAGE_G(P,c.Bt,c.K,br,(long)(kt)*BK)
; #define LDA(dst,b,h) for(int m=0;m<4;++m)for(int k=0;k<2;++k) \
;     dst[m][k]=*reinterpret_cast<const bf16x8*>((char*)SA(b,h)+lds_byte(wr*64+m*16+fr,k*32+fq*8))
; #define LDB(dst,b,h) for(int n=0;n<2;++n)for(int k=0;k<2;++k) \
;     dst[n][k]=*reinterpret_cast<const bf16x8*>((char*)SB(b,h)+lds_byte(wc*32+n*16+fr,k*32+fq*8))
; #define WAIT_V(n) asm volatile("s_waitcnt vmcnt(" #n ")":::"memory")
; #define BAR __builtin_amdgcn_s_barrier()
; #define SCHED __builtin_amdgcn_sched_barrier(0)
; template <int EPI>
; __device__ __forceinline__ void gemm_run(const GD& c, const bool has_next, const GD& nx, const Ctx& e, bf16* shm, float* rs, float* rs_nxt, float* racc_) {
;     ...
;   WAIT_V(0); BAR;
;   STAGE_B(SB(1,0),bcol,1); STAGE_A(SA(1,0),brow,1); STAGE_B(SB(1,1),bcol+HALF,1);
;   BAR;
;   for(int t=0;t<nt-2;t+=2){
;     LDB(B0,0,0); SCHED; LDA(At,0,0); STAGE_A(SA(1,1),brow+HALF,t+1);
.LBB0_745:
	s_or_b64 exec, exec, s[2:3]
	v_bfe_i32 v2, v92, 27, 1
	v_lshlrev_b32_e32 v20, 4, v92
	v_lshrrev_b32_e32 v2, 22, v2
	v_add_u32_e32 v2, v20, v2
	v_and_b32_e32 v2, 0xfffffc00, v2
	v_sub_u32_e32 v2, v20, v2
	v_lshrrev_b32_e32 v3, 4, v2
	v_bitop3_b32 v2, v3, v2, 32 bitop3:0x6c
	v_ashrrev_i32_e32 v0, 31, v92
	v_ashrrev_i32_e32 v4, 31, v2
	v_lshrrev_b32_e32 v0, 26, v0
	v_lshrrev_b32_e32 v4, 26, v4
	v_add_u32_e32 v0, v92, v0
	v_add_u32_e32 v4, v2, v4
	s_lshl_b32 s2, s31, 8
	v_ashrrev_i32_e32 v0, 6, v0
	v_lshrrev_b32_e32 v5, 6, v4
	v_and_b32_e32 v4, 0xc0, v4
	s_ashr_i32 s3, s2, 31
	v_lshlrev_b32_e32 v3, 3, v0
	v_lshlrev_b32_e32 v0, 5, v0
	v_sub_u32_e32 v2, v2, v4
	s_lshl_b32 s12, s20, 8
	s_lshl_b64 s[20:21], s[2:3], 9
	v_and_b32_e32 v3, 0x7ffff0, v3
	v_and_b32_e32 v0, 32, v0
	v_ashrrev_i16_sdwa v2, v177, sext(v2) dst_sel:DWORD dst_unused:UNUSED_PAD src0_sel:DWORD src1_sel:BYTE_0
	s_add_u32 s34, s25, s20
	v_add_u32_sdwa v0, v0, sext(v2) dst_sel:DWORD dst_unused:UNUSED_PAD src0_sel:DWORD src1_sel:WORD_0
	v_add_lshl_u32 v2, v5, v3, 9
	v_readlane_b32 s38, v254, 23
	s_addc_u32 s35, s26, s21
	v_lshl_add_u32 v0, v0, 1, v2
	v_add_u32_e32 v6, s38, v20
	v_lshl_add_u64 v[2:3], s[34:35], 0, v[0:1]
	v_readfirstlane_b32 s20, v6
	v_lshl_add_u64 v[4:5], v[2:3], 0, s[66:67]
	s_mov_b32 m0, s20
	v_add_u32_e32 v21, 0x2000, v20
	s_waitcnt vmcnt(0)
	s_barrier
	global_load_lds_dwordx4 v[4:5], off
	v_ashrrev_i32_e32 v4, 31, v21
	v_lshrrev_b32_e32 v4, 22, v4
	v_add_u32_e32 v4, v21, v4
	v_ashrrev_i32_e32 v4, 10, v4
	v_mul_i32_i24_e32 v5, 0x400, v4
	v_sub_u32_e32 v5, v21, v5
	v_lshrrev_b32_e32 v6, 4, v5
	v_bitop3_b32 v5, v6, v5, 32 bitop3:0x6c
	v_ashrrev_i32_e32 v7, 31, v5
	v_lshrrev_b32_e32 v7, 26, v7
	v_add_u32_e32 v7, v5, v7
	v_lshrrev_b32_e32 v8, 6, v7
	v_and_b32_e32 v7, 0xc0, v7
	v_lshlrev_b32_e32 v6, 3, v4
	v_lshlrev_b32_e32 v4, 5, v4
	v_sub_u32_e32 v5, v5, v7
	s_ashr_i32 s13, s12, 31
	v_and_b32_e32 v6, 0x7ffff0, v6
	v_and_b32_e32 v4, 32, v4
	v_ashrrev_i16_sdwa v5, v177, sext(v5) dst_sel:DWORD dst_unused:UNUSED_PAD src0_sel:DWORD src1_sel:BYTE_0
	s_lshl_b64 s[36:37], s[12:13], 9
	v_add_u32_sdwa v4, v4, sext(v5) dst_sel:DWORD dst_unused:UNUSED_PAD src0_sel:DWORD src1_sel:WORD_0
	v_add_lshl_u32 v5, v8, v6, 9
	s_add_u32 s36, s23, s36
	v_lshl_add_u32 v90, v4, 1, v5
	v_mov_b32_e32 v91, v1
	v_add_u32_e32 v6, s38, v21
	s_addc_u32 s37, s24, s37
	v_add_u32_e32 v93, 0, v20
	s_bitset1_b32 s2, 7
	v_lshl_add_u64 v[12:13], s[34:35], 0, v[90:91]
	v_readfirstlane_b32 s34, v6
	v_add_u32_e32 v6, 0x8000, v93
	s_ashr_i32 s3, s2, 31
	v_lshl_add_u64 v[4:5], v[12:13], 0, s[66:67]
	s_mov_b32 m0, s34
	v_lshl_add_u64 v[8:9], s[36:37], 0, v[0:1]
	v_readfirstlane_b32 s21, v6
	v_add_u32_e32 v6, 0xa000, v93
	s_lshl_b64 s[2:3], s[2:3], 9
	global_load_lds_dwordx4 v[4:5], off
	v_lshl_add_u64 v[4:5], v[8:9], 0, s[66:67]
	s_mov_b32 m0, s21
	v_lshl_add_u64 v[10:11], s[36:37], 0, v[90:91]
	v_readfirstlane_b32 s13, v6
	s_add_u32 s36, s25, s2
	v_readlane_b32 s35, v254, 24
	global_load_lds_dwordx4 v[4:5], off
	v_lshl_add_u64 v[4:5], v[10:11], 0, s[66:67]
	s_mov_b32 m0, s13
	s_addc_u32 s37, s26, s3
	v_add_u32_e32 v16, s35, v20
	global_load_lds_dwordx4 v[4:5], off
	v_lshl_add_u64 v[4:5], s[36:37], 0, v[0:1]
	v_readfirstlane_b32 s2, v16
	v_lshl_add_u64 v[6:7], v[4:5], 0, s[66:67]
	s_mov_b32 m0, s2
	v_add_u32_e32 v19, s35, v21
	global_load_lds_dwordx4 v[6:7], off
	v_lshl_add_u64 v[6:7], s[36:37], 0, v[90:91]
	v_readfirstlane_b32 s3, v19
	v_lshl_add_u64 v[16:17], v[6:7], 0, s[66:67]
	s_mov_b32 m0, s3
	v_and_b32_e32 v15, 15, v92
	global_load_lds_dwordx4 v[16:17], off
	v_lshlrev_b32_e32 v19, 2, v92
	v_and_b32_e32 v18, 48, v92
	v_lshlrev_b32_e32 v16, 6, v92
	v_lshlrev_b32_e32 v15, 6, v15
	v_and_b32_e32 v22, 32, v19
	v_and_b32_e32 v17, 0x3000, v16
	v_bitop3_b32 v15, v15, v22, v18 bitop3:0x36
	v_add3_u32 v139, s33, v15, v17
	v_and_b32_e32 v16, 0x3c0, v16
	s_barrier
	v_bitop3_b32 v16, v16, v22, v18 bitop3:0x36
	v_add_u32_e32 v138, s33, v20
	v_add_u32_e32 v126, s33, v21
	v_add_u32_e32 v96, s86, v20
	v_add_u32_e32 v176, s86, v21
	ds_read_b128 v[20:23], v139
	ds_read_b128 v[24:27], v139 offset:1024
	ds_read_b128 v[28:31], v139 offset:2048
	ds_read_b128 v[32:35], v139 offset:3072
	v_lshlrev_b32_e32 v14, 13, v14
	s_or_b32 s36, s12, 0x80
	v_add3_u32 v19, 0, v15, v14
	v_add3_u32 v18, 0, v16, v14
	v_add_u32_e32 v68, 0xc000, v93
	v_add_u32_e32 v70, 0xe000, v93
	v_add_u32_e32 v97, 0x2000, v93
	v_add_u32_e32 v95, 0x4000, v93
	v_add_u32_e32 v94, 0x6000, v93
	s_ashr_i32 s37, s36, 31
	v_add3_u32 v170, s86, v15, v17
	v_add3_u32 v182, s38, v15, v17
	v_add3_u32 v183, s35, v15, v17
	s_lshl_b64 s[36:37], s[36:37], 9
	s_add_u32 s38, s23, s36
	s_addc_u32 s39, s24, s37
	v_lshl_add_u64 v[14:15], s[38:39], 0, v[0:1]
	v_readfirstlane_b32 s36, v68
	v_lshl_add_u64 v[16:17], v[14:15], 0, s[66:67]
	s_mov_b32 m0, s36
	ds_read_b128 v[36:39], v19
	ds_read_b128 v[40:43], v19 offset:1024
	ds_read_b128 v[44:47], v18 offset:2048
	ds_read_b128 v[48:51], v18 offset:3072
	ds_read_b128 v[52:55], v18 offset:4096
	ds_read_b128 v[56:59], v18 offset:5120
	ds_read_b128 v[60:63], v18 offset:6144
	ds_read_b128 v[64:67], v18 offset:7168
	global_load_lds_dwordx4 v[16:17], off
	v_lshl_add_u64 v[16:17], s[38:39], 0, v[90:91]
	v_readfirstlane_b32 s35, v70
	v_lshl_add_u64 v[68:69], v[16:17], 0, s[66:67]
	s_mov_b32 m0, s35
	s_nop 0
	global_load_lds_dwordx4 v[68:69], off
	s_waitcnt lgkmcnt(8)
	s_barrier
; #define STAGE_A(P,br,kt) STAGE_G(P,c.A,c.lda,br,(long)(kt)*c.kstr)
; #define STAGE_B(P,br,kt) STAGE_G(P,c.Bt,c.K,br,(long)(kt)*BK)
; #define LDA(dst,b,h) for(int m=0;m<4;++m)for(int k=0;k<2;++k) \
;     dst[m][k]=*reinterpret_cast<const bf16x8*>((char*)SA(b,h)+lds_byte(wr*64+m*16+fr,k*32+fq*8))
; #define LDB(dst,b,h) for(int n=0;n<2;++n)for(int k=0;k<2;++k) \
;     dst[n][k]=*reinterpret_cast<const bf16x8*>((char*)SB(b,h)+lds_byte(wc*32+n*16+fr,k*32+fq*8))
; #define MMA(ai,bj,At,Bt_) do{__builtin_amdgcn_s_setprio(1); \
;     for(int m=0;m<4;++m)for(int n=0;n<2;++n)for(int k=0;k<2;++k) \
;       acc[ai][bj][m][n]=__builtin_amdgcn_mfma_f32_16x16x32_bf16(Bt_[n][k],At[m][k],acc[ai][bj][m][n],0,0,0); \
;     __builtin_amdgcn_s_setprio(0);}while(0)
; #define WAIT_V(n) asm volatile("s_waitcnt vmcnt(" #n ")":::"memory")
; #define WAIT_L(n) asm volatile("s_waitcnt lgkmcnt(" #n ")":::"memory")
; #define BAR __builtin_amdgcn_s_barrier()
; #define SCHED __builtin_amdgcn_sched_barrier(0)
; template <int EPI>
; __device__ __forceinline__ void gemm_run(const GD& c, const bool has_next, const GD& nx, const Ctx& e, bf16* shm, float* rs, float* rs_nxt, float* racc_) {
;     ...
;   for(int t=0;t<nt-2;t+=2){
;     LDB(B0,0,0); SCHED; LDA(At,0,0); STAGE_A(SA(1,1),brow+HALF,t+1);
;     WAIT_L(8); BAR; WAIT_L(0); MMA(0,0,At,B0); BAR; SCHED;
;     LDB(B1,0,1); STAGE_B(SB(0,0),bcol,t+2);
;     BAR; WAIT_L(0); MMA(0,1,At,B1); BAR;
;     LDA(At,0,1); STAGE_A(SA(0,0),brow,t+2);
;     BAR; WAIT_L(0); MMA(1,0,At,B0); BAR; SCHED;
;     STAGE_B(SB(0,1),bcol+HALF,t+2);
;     WAIT_V(6); BAR; MMA(1,1,At,B1); BAR;
	s_waitcnt lgkmcnt(0)
	v_mfma_f32_16x16x32_bf16 v[68:71], v[20:23], v[36:39], 0
	v_mfma_f32_16x16x32_bf16 v[72:75], v[28:31], v[36:39], 0
	v_mfma_f32_16x16x32_bf16 v[76:79], v[20:23], v[44:47], 0
	v_mfma_f32_16x16x32_bf16 v[80:83], v[28:31], v[44:47], 0
	v_mfma_f32_16x16x32_bf16 v[84:87], v[20:23], v[52:55], 0
	v_mfma_f32_16x16x32_bf16 v[98:101], v[28:31], v[52:55], 0
	v_mfma_f32_16x16x32_bf16 v[102:105], v[20:23], v[60:63], 0
	v_mfma_f32_16x16x32_bf16 v[106:109], v[28:31], v[60:63], 0
	v_mfma_f32_16x16x32_bf16 v[68:71], v[24:27], v[40:43], v[68:71]
	v_mfma_f32_16x16x32_bf16 v[72:75], v[32:35], v[40:43], v[72:75]
	v_mfma_f32_16x16x32_bf16 v[76:79], v[24:27], v[48:51], v[76:79]
	v_mfma_f32_16x16x32_bf16 v[80:83], v[32:35], v[48:51], v[80:83]
	v_mfma_f32_16x16x32_bf16 v[84:87], v[24:27], v[56:59], v[84:87]
	v_mfma_f32_16x16x32_bf16 v[98:101], v[32:35], v[56:59], v[98:101]
	v_mfma_f32_16x16x32_bf16 v[102:105], v[24:27], v[64:67], v[102:105]
	v_mfma_f32_16x16x32_bf16 v[106:109], v[32:35], v[64:67], v[106:109]
	s_barrier
	v_readfirstlane_b32 s37, v138
	v_lshl_add_u64 v[88:89], v[2:3], 0, s[88:89]
	s_mov_b32 m0, s37
	v_readfirstlane_b32 s37, v126
	ds_read_b128 v[110:113], v170
	ds_read_b128 v[114:117], v170 offset:1024
	ds_read_b128 v[118:121], v170 offset:2048
	ds_read_b128 v[122:125], v170 offset:3072
	global_load_lds_dwordx4 v[88:89], off
	v_lshl_add_u64 v[88:89], v[12:13], 0, s[88:89]
	s_mov_b32 m0, s37
	s_nop 0
	global_load_lds_dwordx4 v[88:89], off
	s_barrier
	s_waitcnt lgkmcnt(0)
	v_mfma_f32_16x16x32_bf16 v[126:129], v[110:113], v[36:39], 0
	v_mfma_f32_16x16x32_bf16 v[36:39], v[118:121], v[36:39], 0
	v_mfma_f32_16x16x32_bf16 v[126:129], v[114:117], v[40:43], v[126:129]
	v_mfma_f32_16x16x32_bf16 v[36:39], v[122:125], v[40:43], v[36:39]
	v_readfirstlane_b32 s37, v93
	v_mfma_f32_16x16x32_bf16 v[40:43], v[110:113], v[44:47], 0
	v_lshl_add_u64 v[88:89], v[8:9], 0, s[88:89]
	v_mfma_f32_16x16x32_bf16 v[44:47], v[118:121], v[44:47], 0
	s_mov_b32 m0, s37
	v_mfma_f32_16x16x32_bf16 v[40:43], v[114:117], v[48:51], v[40:43]
	v_readfirstlane_b32 s37, v97
	v_mfma_f32_16x16x32_bf16 v[44:47], v[122:125], v[48:51], v[44:47]
	v_mfma_f32_16x16x32_bf16 v[48:51], v[110:113], v[52:55], 0
	v_mfma_f32_16x16x32_bf16 v[52:55], v[118:121], v[52:55], 0
	v_mfma_f32_16x16x32_bf16 v[48:51], v[114:117], v[56:59], v[48:51]
	v_mfma_f32_16x16x32_bf16 v[52:55], v[122:125], v[56:59], v[52:55]
	v_mfma_f32_16x16x32_bf16 v[56:59], v[110:113], v[60:63], 0
	v_mfma_f32_16x16x32_bf16 v[60:63], v[118:121], v[60:63], 0
	v_mfma_f32_16x16x32_bf16 v[56:59], v[114:117], v[64:67], v[56:59]
	v_mfma_f32_16x16x32_bf16 v[60:63], v[122:125], v[64:67], v[60:63]
	s_barrier
	ds_read_b128 v[64:67], v19 offset:16384
	ds_read_b128 v[130:133], v19 offset:17408
	ds_read_b128 v[134:137], v18 offset:18432
	ds_read_b128 v[140:143], v18 offset:19456
	ds_read_b128 v[144:147], v18 offset:20480
	ds_read_b128 v[148:151], v18 offset:21504
	ds_read_b128 v[152:155], v18 offset:22528
	ds_read_b128 v[156:159], v18 offset:23552
	global_load_lds_dwordx4 v[88:89], off
	v_lshl_add_u64 v[88:89], v[10:11], 0, s[88:89]
	s_mov_b32 m0, s37
	s_nop 0
	global_load_lds_dwordx4 v[88:89], off
	s_barrier
	s_waitcnt lgkmcnt(0)
	v_mfma_f32_16x16x32_bf16 v[160:163], v[20:23], v[64:67], 0
	v_mfma_f32_16x16x32_bf16 v[172:175], v[20:23], v[134:137], 0
	v_mfma_f32_16x16x32_bf16 v[190:193], v[20:23], v[144:147], 0
	v_mfma_f32_16x16x32_bf16 v[20:23], v[20:23], v[152:155], 0
	v_mfma_f32_16x16x32_bf16 v[160:163], v[24:27], v[130:133], v[160:163]
	v_mfma_f32_16x16x32_bf16 v[172:175], v[24:27], v[140:143], v[172:175]
	v_mfma_f32_16x16x32_bf16 v[190:193], v[24:27], v[148:151], v[190:193]
	v_mfma_f32_16x16x32_bf16 v[20:23], v[24:27], v[156:159], v[20:23]
	v_mfma_f32_16x16x32_bf16 v[24:27], v[28:31], v[152:155], 0
	v_mfma_f32_16x16x32_bf16 v[166:169], v[28:31], v[64:67], 0
	v_mfma_f32_16x16x32_bf16 v[186:189], v[28:31], v[134:137], 0
	v_mfma_f32_16x16x32_bf16 v[194:197], v[28:31], v[144:147], 0
	v_mfma_f32_16x16x32_bf16 v[24:27], v[32:35], v[156:159], v[24:27]
	v_mfma_f32_16x16x32_bf16 v[166:169], v[32:35], v[130:133], v[166:169]
	v_mfma_f32_16x16x32_bf16 v[186:189], v[32:35], v[140:143], v[186:189]
	v_mfma_f32_16x16x32_bf16 v[194:197], v[32:35], v[148:151], v[194:197]
	s_barrier
	v_readfirstlane_b32 s37, v96
	v_lshl_add_u64 v[28:29], v[4:5], 0, s[88:89]
	s_mov_b32 m0, s37
	v_readfirstlane_b32 s37, v176
	global_load_lds_dwordx4 v[28:29], off
	v_lshl_add_u64 v[28:29], v[6:7], 0, s[88:89]
	s_mov_b32 m0, s37
	s_nop 0
	global_load_lds_dwordx4 v[28:29], off
	s_waitcnt vmcnt(6)
	s_barrier
	v_mfma_f32_16x16x32_bf16 v[28:31], v[110:113], v[64:67], 0
	v_mfma_f32_16x16x32_bf16 v[32:35], v[118:121], v[64:67], 0
	v_mfma_f32_16x16x32_bf16 v[28:31], v[114:117], v[130:133], v[28:31]
	v_mfma_f32_16x16x32_bf16 v[32:35], v[122:125], v[130:133], v[32:35]
	v_mfma_f32_16x16x32_bf16 v[64:67], v[110:113], v[134:137], 0
	v_mfma_f32_16x16x32_bf16 v[130:133], v[118:121], v[134:137], 0
	v_mfma_f32_16x16x32_bf16 v[134:137], v[110:113], v[144:147], 0
	v_mfma_f32_16x16x32_bf16 v[110:113], v[110:113], v[152:155], 0
	v_mfma_f32_16x16x32_bf16 v[64:67], v[114:117], v[140:143], v[64:67]
	v_mfma_f32_16x16x32_bf16 v[134:137], v[114:117], v[148:151], v[134:137]
	v_mfma_f32_16x16x32_bf16 v[110:113], v[114:117], v[156:159], v[110:113]
	v_mfma_f32_16x16x32_bf16 v[114:117], v[118:121], v[152:155], 0
	v_mfma_f32_16x16x32_bf16 v[130:133], v[122:125], v[140:143], v[130:133]
	v_mfma_f32_16x16x32_bf16 v[140:143], v[118:121], v[144:147], 0
	v_mfma_f32_16x16x32_bf16 v[114:117], v[122:125], v[156:159], v[114:117]
	v_mfma_f32_16x16x32_bf16 v[140:143], v[122:125], v[148:151], v[140:143]
	s_barrier
; #define STAGE_A(P,br,kt) STAGE_G(P,c.A,c.lda,br,(long)(kt)*c.kstr)
; #define STAGE_B(P,br,kt) STAGE_G(P,c.Bt,c.K,br,(long)(kt)*BK)
; #define LDA(dst,b,h) for(int m=0;m<4;++m)for(int k=0;k<2;++k) \
;     dst[m][k]=*reinterpret_cast<const bf16x8*>((char*)SA(b,h)+lds_byte(wr*64+m*16+fr,k*32+fq*8))
; #define LDB(dst,b,h) for(int n=0;n<2;++n)for(int k=0;k<2;++k) \
;     dst[n][k]=*reinterpret_cast<const bf16x8*>((char*)SB(b,h)+lds_byte(wc*32+n*16+fr,k*32+fq*8))
; #define MMA(ai,bj,At,Bt_) do{__builtin_amdgcn_s_setprio(1); \
;     for(int m=0;m<4;++m)for(int n=0;n<2;++n)for(int k=0;k<2;++k) \
;       acc[ai][bj][m][n]=__builtin_amdgcn_mfma_f32_16x16x32_bf16(Bt_[n][k],At[m][k],acc[ai][bj][m][n],0,0,0); \
;     __builtin_amdgcn_s_setprio(0);}while(0)
; #define WAIT_V(n) asm volatile("s_waitcnt vmcnt(" #n ")":::"memory")
; #define WAIT_L(n) asm volatile("s_waitcnt lgkmcnt(" #n ")":::"memory")
; #define BAR __builtin_amdgcn_s_barrier()
; #define SCHED __builtin_amdgcn_sched_barrier(0)
; template <int EPI>
; __device__ __forceinline__ void gemm_run(const GD& c, const bool has_next, const GD& nx, const Ctx& e, bf16* shm, float* rs, float* rs_nxt, float* racc_) {
;     ...
;     WAIT_V(6); BAR; MMA(1,1,At,B1); BAR;
;     LDB(B0,1,0); SCHED; LDA(At,1,0); STAGE_A(SA(0,1),brow+HALF,t+2);
;     WAIT_L(8); BAR; WAIT_L(0); MMA(0,0,At,B0); BAR; SCHED;
;     LDB(B1,1,1); STAGE_B(SB(1,0),bcol,t+3);
;     BAR; WAIT_L(0); MMA(0,1,At,B1); BAR;
;     LDA(At,1,1); STAGE_A(SA(1,0),brow,t+3);
;     BAR; WAIT_L(0); MMA(1,0,At,B0); BAR; SCHED;
;     STAGE_B(SB(1,1),bcol+HALF,t+3);
;     WAIT_V(6); BAR; MMA(1,1,At,B1); BAR;
	ds_read_b128 v[118:121], v182
	ds_read_b128 v[122:125], v182 offset:1024
	ds_read_b128 v[144:147], v182 offset:2048
	ds_read_b128 v[148:151], v182 offset:3072
	v_readfirstlane_b32 s37, v95
	v_lshl_add_u64 v[88:89], v[14:15], 0, s[88:89]
	s_mov_b32 m0, s37
	v_readfirstlane_b32 s37, v94
	ds_read_b128 v[152:155], v19 offset:32768
	ds_read_b128 v[156:159], v19 offset:33792
	ds_read_b128 v[198:201], v18 offset:34816
	ds_read_b128 v[202:205], v18 offset:35840
	ds_read_b128 v[206:209], v18 offset:36864
	ds_read_b128 v[210:213], v18 offset:37888
	ds_read_b128 v[214:217], v18 offset:38912
	ds_read_b128 v[218:221], v18 offset:39936
	global_load_lds_dwordx4 v[88:89], off
	v_lshl_add_u64 v[88:89], v[16:17], 0, s[88:89]
	s_mov_b32 m0, s37
	s_nop 0
	global_load_lds_dwordx4 v[88:89], off
	s_waitcnt lgkmcnt(8)
	s_barrier
	s_waitcnt lgkmcnt(0)
	v_mfma_f32_16x16x32_bf16 v[68:71], v[118:121], v[152:155], v[68:71]
	v_mfma_f32_16x16x32_bf16 v[72:75], v[144:147], v[152:155], v[72:75]
	v_mfma_f32_16x16x32_bf16 v[76:79], v[118:121], v[198:201], v[76:79]
	v_mfma_f32_16x16x32_bf16 v[80:83], v[144:147], v[198:201], v[80:83]
	v_mfma_f32_16x16x32_bf16 v[84:87], v[118:121], v[206:209], v[84:87]
	v_mfma_f32_16x16x32_bf16 v[98:101], v[144:147], v[206:209], v[98:101]
	v_mfma_f32_16x16x32_bf16 v[102:105], v[118:121], v[214:217], v[102:105]
	v_mfma_f32_16x16x32_bf16 v[106:109], v[144:147], v[214:217], v[106:109]
	v_mfma_f32_16x16x32_bf16 v[68:71], v[122:125], v[156:159], v[68:71]
	v_mfma_f32_16x16x32_bf16 v[72:75], v[148:151], v[156:159], v[72:75]
	v_mfma_f32_16x16x32_bf16 v[76:79], v[122:125], v[202:205], v[76:79]
	v_mfma_f32_16x16x32_bf16 v[80:83], v[148:151], v[202:205], v[80:83]
	v_mfma_f32_16x16x32_bf16 v[84:87], v[122:125], v[210:213], v[84:87]
	v_mfma_f32_16x16x32_bf16 v[98:101], v[148:151], v[210:213], v[98:101]
	v_mfma_f32_16x16x32_bf16 v[102:105], v[122:125], v[218:221], v[102:105]
	v_mfma_f32_16x16x32_bf16 v[106:109], v[148:151], v[218:221], v[106:109]
	s_barrier
	s_mov_b64 s[38:39], 0x180
	s_mov_b32 m0, s20
	v_lshl_add_u64 v[2:3], v[2:3], 0, s[38:39]
	ds_read_b128 v[222:225], v183
	ds_read_b128 v[226:229], v183 offset:1024
	ds_read_b128 v[230:233], v183 offset:2048
	ds_read_b128 v[234:237], v183 offset:3072
	global_load_lds_dwordx4 v[2:3], off
	v_lshl_add_u64 v[2:3], v[12:13], 0, s[38:39]
	s_mov_b32 m0, s34
	s_nop 0
	global_load_lds_dwordx4 v[2:3], off
	s_barrier
	s_waitcnt lgkmcnt(0)
	v_mfma_f32_16x16x32_bf16 v[126:129], v[222:225], v[152:155], v[126:129]
	v_mfma_f32_16x16x32_bf16 v[36:39], v[230:233], v[152:155], v[36:39]
	v_mfma_f32_16x16x32_bf16 v[40:43], v[222:225], v[198:201], v[40:43]
	v_mfma_f32_16x16x32_bf16 v[44:47], v[230:233], v[198:201], v[44:47]
	s_mov_b32 m0, s21
	v_mfma_f32_16x16x32_bf16 v[48:51], v[222:225], v[206:209], v[48:51]
	v_lshl_add_u64 v[2:3], v[8:9], 0, s[38:39]
	v_mfma_f32_16x16x32_bf16 v[52:55], v[230:233], v[206:209], v[52:55]
	v_mfma_f32_16x16x32_bf16 v[56:59], v[222:225], v[214:217], v[56:59]
	v_mfma_f32_16x16x32_bf16 v[60:63], v[230:233], v[214:217], v[60:63]
	v_mfma_f32_16x16x32_bf16 v[126:129], v[226:229], v[156:159], v[126:129]
	v_mfma_f32_16x16x32_bf16 v[36:39], v[234:237], v[156:159], v[36:39]
	v_mfma_f32_16x16x32_bf16 v[40:43], v[226:229], v[202:205], v[40:43]
	v_mfma_f32_16x16x32_bf16 v[44:47], v[234:237], v[202:205], v[44:47]
	v_mfma_f32_16x16x32_bf16 v[48:51], v[226:229], v[210:213], v[48:51]
	v_mfma_f32_16x16x32_bf16 v[52:55], v[234:237], v[210:213], v[52:55]
	v_mfma_f32_16x16x32_bf16 v[56:59], v[226:229], v[218:221], v[56:59]
	v_mfma_f32_16x16x32_bf16 v[60:63], v[234:237], v[218:221], v[60:63]
	s_barrier
	ds_read_b128 v[152:155], v19 offset:49152
	ds_read_b128 v[156:159], v19 offset:50176
	ds_read_b128 v[198:201], v18 offset:51200
	ds_read_b128 v[202:205], v18 offset:52224
	ds_read_b128 v[206:209], v18 offset:53248
	ds_read_b128 v[210:213], v18 offset:54272
	ds_read_b128 v[214:217], v18 offset:55296
	ds_read_b128 v[218:221], v18 offset:56320
	global_load_lds_dwordx4 v[2:3], off
	v_lshl_add_u64 v[2:3], v[10:11], 0, s[38:39]
	s_mov_b32 m0, s13
	s_nop 0
	global_load_lds_dwordx4 v[2:3], off
	s_barrier
	s_waitcnt lgkmcnt(0)
	v_mfma_f32_16x16x32_bf16 v[8:11], v[118:121], v[152:155], v[160:163]
	v_mfma_f32_16x16x32_bf16 v[20:23], v[118:121], v[214:217], v[20:23]
	v_mfma_f32_16x16x32_bf16 v[24:27], v[144:147], v[214:217], v[24:27]
	v_mfma_f32_16x16x32_bf16 v[8:11], v[122:125], v[156:159], v[8:11]
	v_mfma_f32_16x16x32_bf16 v[160:163], v[144:147], v[152:155], v[166:169]
	v_mfma_f32_16x16x32_bf16 v[166:169], v[118:121], v[198:201], v[172:175]
	v_mfma_f32_16x16x32_bf16 v[172:175], v[144:147], v[198:201], v[186:189]
	v_mfma_f32_16x16x32_bf16 v[186:189], v[118:121], v[206:209], v[190:193]
	v_mfma_f32_16x16x32_bf16 v[190:193], v[144:147], v[206:209], v[194:197]
	v_mfma_f32_16x16x32_bf16 v[20:23], v[122:125], v[218:221], v[20:23]
	v_mfma_f32_16x16x32_bf16 v[24:27], v[148:151], v[218:221], v[24:27]
	v_mfma_f32_16x16x32_bf16 v[160:163], v[148:151], v[156:159], v[160:163]
	v_mfma_f32_16x16x32_bf16 v[166:169], v[122:125], v[202:205], v[166:169]
	v_mfma_f32_16x16x32_bf16 v[172:175], v[148:151], v[202:205], v[172:175]
	v_mfma_f32_16x16x32_bf16 v[186:189], v[122:125], v[210:213], v[186:189]
	v_mfma_f32_16x16x32_bf16 v[190:193], v[148:151], v[210:213], v[190:193]
	s_barrier
	s_mov_b32 m0, s2
	v_lshl_add_u64 v[2:3], v[4:5], 0, s[38:39]
	global_load_lds_dwordx4 v[2:3], off
	v_lshl_add_u64 v[2:3], v[6:7], 0, s[38:39]
	s_mov_b32 m0, s3
	s_nop 0
	global_load_lds_dwordx4 v[2:3], off
	s_waitcnt vmcnt(6)
	s_barrier
; #define STAGE_A(P,br,kt) STAGE_G(P,c.A,c.lda,br,(long)(kt)*c.kstr)
; #define STAGE_B(P,br,kt) STAGE_G(P,c.Bt,c.K,br,(long)(kt)*BK)
; #define LDA(dst,b,h) for(int m=0;m<4;++m)for(int k=0;k<2;++k) \
;     dst[m][k]=*reinterpret_cast<const bf16x8*>((char*)SA(b,h)+lds_byte(wr*64+m*16+fr,k*32+fq*8))
; #define LDB(dst,b,h) for(int n=0;n<2;++n)for(int k=0;k<2;++k) \
;     dst[n][k]=*reinterpret_cast<const bf16x8*>((char*)SB(b,h)+lds_byte(wc*32+n*16+fr,k*32+fq*8))
; #define MMA(ai,bj,At,Bt_) do{__builtin_amdgcn_s_setprio(1); \
;     for(int m=0;m<4;++m)for(int n=0;n<2;++n)for(int k=0;k<2;++k) \
;       acc[ai][bj][m][n]=__builtin_amdgcn_mfma_f32_16x16x32_bf16(Bt_[n][k],At[m][k],acc[ai][bj][m][n],0,0,0); \
;     __builtin_amdgcn_s_setprio(0);}while(0)
; #define WAIT_V(n) asm volatile("s_waitcnt vmcnt(" #n ")":::"memory")
; #define WAIT_L(n) asm volatile("s_waitcnt lgkmcnt(" #n ")":::"memory")
; #define BAR __builtin_amdgcn_s_barrier()
; #define SCHED __builtin_amdgcn_sched_barrier(0)
; template <int EPI>
; __device__ __forceinline__ void gemm_run(const GD& c, const bool has_next, const GD& nx, const Ctx& e, bf16* shm, float* rs, float* rs_nxt, float* racc_) {
;     ...
;     WAIT_V(6); BAR; MMA(1,1,At,B1); BAR;
;     LDB(B0,1,0); SCHED; LDA(At,1,0); STAGE_A(SA(0,1),brow+HALF,t+2);
;     WAIT_L(8); BAR; WAIT_L(0); MMA(0,0,At,B0); BAR; SCHED;
;     LDB(B1,1,1); STAGE_B(SB(1,0),bcol,t+3);
;     BAR; WAIT_L(0); MMA(0,1,At,B1); BAR;
;     LDA(At,1,1); STAGE_A(SA(1,0),brow,t+3);
;     BAR; WAIT_L(0); MMA(1,0,At,B0); BAR; SCHED;
;     STAGE_B(SB(1,1),bcol+HALF,t+3);
;     WAIT_V(6); BAR; MMA(1,1,At,B1); BAR;
;   }
;   { LDB(B0,0,0); LDA(At,0,0); STAGE_A(SA(1,1),brow+HALF,nt-1);
;     BAR; WAIT_L(0); MMA(0,0,At,B0); BAR;
;     LDB(B1,0,1); BAR; WAIT_L(0); MMA(0,1,At,B1); BAR;
;     LDA(At,0,1); WAIT_V(4); BAR; WAIT_L(0); MMA(1,0,At,B0); MMA(1,1,At,B1); BAR; }
	v_mfma_f32_16x16x32_bf16 v[2:5], v[222:225], v[152:155], v[28:31]
	v_mfma_f32_16x16x32_bf16 v[28:31], v[230:233], v[152:155], v[32:35]
	v_mfma_f32_16x16x32_bf16 v[32:35], v[222:225], v[198:201], v[64:67]
	v_mfma_f32_16x16x32_bf16 v[64:67], v[230:233], v[198:201], v[130:133]
	s_mov_b32 m0, s36
	v_mfma_f32_16x16x32_bf16 v[118:121], v[222:225], v[206:209], v[134:137]
	v_lshl_add_u64 v[6:7], v[14:15], 0, s[38:39]
	v_mfma_f32_16x16x32_bf16 v[122:125], v[230:233], v[206:209], v[140:143]
	v_mfma_f32_16x16x32_bf16 v[110:113], v[222:225], v[214:217], v[110:113]
	v_mfma_f32_16x16x32_bf16 v[114:117], v[230:233], v[214:217], v[114:117]
	v_mfma_f32_16x16x32_bf16 v[2:5], v[226:229], v[156:159], v[2:5]
	v_mfma_f32_16x16x32_bf16 v[28:31], v[234:237], v[156:159], v[28:31]
	v_mfma_f32_16x16x32_bf16 v[32:35], v[226:229], v[202:205], v[32:35]
	v_mfma_f32_16x16x32_bf16 v[64:67], v[234:237], v[202:205], v[64:67]
	v_mfma_f32_16x16x32_bf16 v[118:121], v[226:229], v[210:213], v[118:121]
	v_mfma_f32_16x16x32_bf16 v[122:125], v[234:237], v[210:213], v[122:125]
	v_mfma_f32_16x16x32_bf16 v[110:113], v[226:229], v[218:221], v[110:113]
	v_mfma_f32_16x16x32_bf16 v[114:117], v[234:237], v[218:221], v[114:117]
	s_barrier
	ds_read_b128 v[130:133], v139
	ds_read_b128 v[134:137], v139 offset:1024
	ds_read_b128 v[140:143], v139 offset:2048
	ds_read_b128 v[144:147], v139 offset:3072
	ds_read_b128 v[148:151], v19
	ds_read_b128 v[152:155], v19 offset:1024
	ds_read_b128 v[156:159], v18 offset:2048
	ds_read_b128 v[194:197], v18 offset:3072
	ds_read_b128 v[198:201], v18 offset:4096
	ds_read_b128 v[202:205], v18 offset:5120
	ds_read_b128 v[206:209], v18 offset:6144
	ds_read_b128 v[210:213], v18 offset:7168
	global_load_lds_dwordx4 v[6:7], off
	v_lshl_add_u64 v[6:7], v[16:17], 0, s[38:39]
	s_mov_b32 m0, s35
	s_nop 0
	global_load_lds_dwordx4 v[6:7], off
	s_barrier
	s_waitcnt lgkmcnt(0)
	v_mfma_f32_16x16x32_bf16 v[12:15], v[130:133], v[148:151], v[68:71]
	v_mfma_f32_16x16x32_bf16 v[68:71], v[140:143], v[148:151], v[72:75]
	v_mfma_f32_16x16x32_bf16 v[72:75], v[130:133], v[156:159], v[76:79]
	v_mfma_f32_16x16x32_bf16 v[76:79], v[140:143], v[156:159], v[80:83]
	v_mfma_f32_16x16x32_bf16 v[80:83], v[130:133], v[198:201], v[84:87]
	v_mfma_f32_16x16x32_bf16 v[84:87], v[140:143], v[198:201], v[98:101]
	v_mfma_f32_16x16x32_bf16 v[98:101], v[130:133], v[206:209], v[102:105]
	v_mfma_f32_16x16x32_bf16 v[102:105], v[140:143], v[206:209], v[106:109]
	v_mfma_f32_16x16x32_bf16 v[12:15], v[134:137], v[152:155], v[12:15]
	v_mfma_f32_16x16x32_bf16 v[68:71], v[144:147], v[152:155], v[68:71]
	v_mfma_f32_16x16x32_bf16 v[72:75], v[134:137], v[194:197], v[72:75]
	v_mfma_f32_16x16x32_bf16 v[76:79], v[144:147], v[194:197], v[76:79]
	v_mfma_f32_16x16x32_bf16 v[80:83], v[134:137], v[202:205], v[80:83]
	v_mfma_f32_16x16x32_bf16 v[84:87], v[144:147], v[202:205], v[84:87]
	v_mfma_f32_16x16x32_bf16 v[98:101], v[134:137], v[210:213], v[98:101]
	v_mfma_f32_16x16x32_bf16 v[102:105], v[144:147], v[210:213], v[102:105]
	s_barrier
	ds_read_b128 v[106:109], v170
	ds_read_b128 v[214:217], v170 offset:1024
	ds_read_b128 v[218:221], v170 offset:2048
	ds_read_b128 v[222:225], v170 offset:3072
	s_barrier
	s_waitcnt lgkmcnt(0)
	v_mfma_f32_16x16x32_bf16 v[36:39], v[218:221], v[148:151], v[36:39]
	v_mfma_f32_16x16x32_bf16 v[126:129], v[106:109], v[148:151], v[126:129]
	v_mfma_f32_16x16x32_bf16 v[148:151], v[222:225], v[152:155], v[36:39]
	v_mfma_f32_16x16x32_bf16 v[36:39], v[106:109], v[156:159], v[40:43]
	v_mfma_f32_16x16x32_bf16 v[126:129], v[214:217], v[152:155], v[126:129]
	v_mfma_f32_16x16x32_bf16 v[152:155], v[214:217], v[194:197], v[36:39]
	v_mfma_f32_16x16x32_bf16 v[36:39], v[218:221], v[156:159], v[44:47]
	v_mfma_f32_16x16x32_bf16 v[156:159], v[222:225], v[194:197], v[36:39]
	v_mfma_f32_16x16x32_bf16 v[36:39], v[106:109], v[198:201], v[48:51]
	v_mfma_f32_16x16x32_bf16 v[46:49], v[214:217], v[202:205], v[36:39]
	v_mfma_f32_16x16x32_bf16 v[36:39], v[218:221], v[198:201], v[52:55]
	v_mfma_f32_16x16x32_bf16 v[50:53], v[222:225], v[202:205], v[36:39]
	v_mfma_f32_16x16x32_bf16 v[36:39], v[106:109], v[206:209], v[56:59]
	v_mfma_f32_16x16x32_bf16 v[54:57], v[214:217], v[210:213], v[36:39]
	v_mfma_f32_16x16x32_bf16 v[36:39], v[218:221], v[206:209], v[60:63]
	v_mfma_f32_16x16x32_bf16 v[194:197], v[222:225], v[210:213], v[36:39]
	s_barrier
	s_nop 4
	ds_read_b128 v[36:39], v19 offset:16384
	ds_read_b128 v[40:43], v19 offset:17408
	ds_read_b128 v[58:61], v18 offset:18432
	ds_read_b128 v[198:201], v18 offset:19456
	ds_read_b128 v[202:205], v18 offset:20480
	ds_read_b128 v[206:209], v18 offset:21504
	ds_read_b128 v[210:213], v18 offset:22528
	ds_read_b128 v[226:229], v18 offset:23552
	s_waitcnt vmcnt(4)
	s_barrier
; #define LDA(dst,b,h) for(int m=0;m<4;++m)for(int k=0;k<2;++k) \
;     dst[m][k]=*reinterpret_cast<const bf16x8*>((char*)SA(b,h)+lds_byte(wr*64+m*16+fr,k*32+fq*8))
; #define LDB(dst,b,h) for(int n=0;n<2;++n)for(int k=0;k<2;++k) \
;     dst[n][k]=*reinterpret_cast<const bf16x8*>((char*)SB(b,h)+lds_byte(wc*32+n*16+fr,k*32+fq*8))
; #define MMA(ai,bj,At,Bt_) do{__builtin_amdgcn_s_setprio(1); \
;     for(int m=0;m<4;++m)for(int n=0;n<2;++n)for(int k=0;k<2;++k) \
;       acc[ai][bj][m][n]=__builtin_amdgcn_mfma_f32_16x16x32_bf16(Bt_[n][k],At[m][k],acc[ai][bj][m][n],0,0,0); \
;     __builtin_amdgcn_s_setprio(0);}while(0)
; #define WAIT_V(n) asm volatile("s_waitcnt vmcnt(" #n ")":::"memory")
; #define WAIT_L(n) asm volatile("s_waitcnt lgkmcnt(" #n ")":::"memory")
; #define BAR __builtin_amdgcn_s_barrier()
; template <int EPI>
; __device__ __forceinline__ void gemm_run(const GD& c, const bool has_next, const GD& nx, const Ctx& e, bf16* shm, float* rs, float* rs_nxt, float* racc_) {
;     ...
;     LDA(At,0,1); WAIT_V(4); BAR; WAIT_L(0); MMA(1,0,At,B0); MMA(1,1,At,B1); BAR; }
;   { LDB(B0,1,0); LDA(At,1,0); WAIT_V(2); BAR; WAIT_L(0); MMA(0,0,At,B0); BAR;
	s_waitcnt lgkmcnt(0)
	v_mfma_f32_16x16x32_bf16 v[20:23], v[130:133], v[210:213], v[20:23]
	v_mfma_f32_16x16x32_bf16 v[6:9], v[130:133], v[36:39], v[8:11]
	v_mfma_f32_16x16x32_bf16 v[166:169], v[130:133], v[58:61], v[166:169]
	v_mfma_f32_16x16x32_bf16 v[186:189], v[130:133], v[202:205], v[186:189]
	v_mfma_f32_16x16x32_bf16 v[130:133], v[134:137], v[226:229], v[20:23]
	v_mfma_f32_16x16x32_bf16 v[20:23], v[140:143], v[210:213], v[24:27]
	v_mfma_f32_16x16x32_bf16 v[6:9], v[134:137], v[40:43], v[6:9]
	v_mfma_f32_16x16x32_bf16 v[160:163], v[140:143], v[36:39], v[160:163]
	v_mfma_f32_16x16x32_bf16 v[166:169], v[134:137], v[198:201], v[166:169]
	v_mfma_f32_16x16x32_bf16 v[172:175], v[140:143], v[58:61], v[172:175]
	v_mfma_f32_16x16x32_bf16 v[186:189], v[134:137], v[206:209], v[186:189]
	v_mfma_f32_16x16x32_bf16 v[190:193], v[140:143], v[202:205], v[190:193]
	v_mfma_f32_16x16x32_bf16 v[134:137], v[144:147], v[226:229], v[20:23]
	v_mfma_f32_16x16x32_bf16 v[160:163], v[144:147], v[40:43], v[160:163]
	v_mfma_f32_16x16x32_bf16 v[172:175], v[144:147], v[198:201], v[172:175]
	v_mfma_f32_16x16x32_bf16 v[190:193], v[144:147], v[206:209], v[190:193]
	v_mfma_f32_16x16x32_bf16 v[2:5], v[106:109], v[36:39], v[2:5]
	v_mfma_f32_16x16x32_bf16 v[140:143], v[214:217], v[40:43], v[2:5]
	v_mfma_f32_16x16x32_bf16 v[2:5], v[218:221], v[36:39], v[28:31]
	v_mfma_f32_16x16x32_bf16 v[144:147], v[222:225], v[40:43], v[2:5]
	v_mfma_f32_16x16x32_bf16 v[2:5], v[106:109], v[58:61], v[32:35]
	v_mfma_f32_16x16x32_bf16 v[230:233], v[214:217], v[198:201], v[2:5]
	v_mfma_f32_16x16x32_bf16 v[2:5], v[218:221], v[58:61], v[64:67]
	v_mfma_f32_16x16x32_bf16 v[198:201], v[222:225], v[198:201], v[2:5]
	v_mfma_f32_16x16x32_bf16 v[2:5], v[106:109], v[202:205], v[118:121]
	v_mfma_f32_16x16x32_bf16 v[234:237], v[214:217], v[206:209], v[2:5]
	v_mfma_f32_16x16x32_bf16 v[2:5], v[218:221], v[202:205], v[122:125]
	v_mfma_f32_16x16x32_bf16 v[202:205], v[222:225], v[206:209], v[2:5]
	v_mfma_f32_16x16x32_bf16 v[2:5], v[106:109], v[210:213], v[110:113]
	v_mfma_f32_16x16x32_bf16 v[206:209], v[214:217], v[226:229], v[2:5]
	v_mfma_f32_16x16x32_bf16 v[2:5], v[218:221], v[210:213], v[114:117]
	v_mfma_f32_16x16x32_bf16 v[210:213], v[222:225], v[226:229], v[2:5]
	s_barrier
	s_nop 4
	ds_read_b128 v[2:5], v182
	ds_read_b128 v[214:217], v182 offset:1024
	ds_read_b128 v[218:221], v182 offset:2048
	ds_read_b128 v[222:225], v182 offset:3072
	ds_read_b128 v[20:23], v19 offset:32768
	ds_read_b128 v[24:27], v19 offset:33792
	ds_read_b128 v[62:65], v18 offset:34816
	ds_read_b128 v[106:109], v18 offset:35840
	ds_read_b128 v[122:125], v18 offset:36864
	ds_read_b128 v[226:229], v18 offset:37888
	ds_read_b128 v[238:241], v18 offset:38912
	ds_read_b128 v[242:245], v18 offset:39936
	s_waitcnt vmcnt(2)
	s_barrier
	s_waitcnt lgkmcnt(0)
	v_mfma_f32_16x16x32_bf16 v[10:13], v[2:5], v[20:23], v[12:15]
	v_mfma_f32_16x16x32_bf16 v[42:45], v[214:217], v[24:27], v[10:13]
	v_mfma_f32_16x16x32_bf16 v[10:13], v[218:221], v[20:23], v[68:71]
	v_mfma_f32_16x16x32_bf16 v[58:61], v[222:225], v[24:27], v[10:13]
	v_mfma_f32_16x16x32_bf16 v[10:13], v[2:5], v[62:65], v[72:75]
	v_mfma_f32_16x16x32_bf16 v[38:41], v[214:217], v[106:109], v[10:13]
	v_mfma_f32_16x16x32_bf16 v[10:13], v[218:221], v[62:65], v[76:79]
	v_mfma_f32_16x16x32_bf16 v[66:69], v[222:225], v[106:109], v[10:13]
	v_mfma_f32_16x16x32_bf16 v[10:13], v[2:5], v[122:125], v[80:83]
	v_mfma_f32_16x16x32_bf16 v[34:37], v[214:217], v[226:229], v[10:13]
	v_mfma_f32_16x16x32_bf16 v[10:13], v[218:221], v[122:125], v[84:87]
	v_mfma_f32_16x16x32_bf16 v[70:73], v[222:225], v[226:229], v[10:13]
	v_mfma_f32_16x16x32_bf16 v[10:13], v[2:5], v[238:241], v[98:101]
	v_mfma_f32_16x16x32_bf16 v[30:33], v[214:217], v[242:245], v[10:13]
	v_mfma_f32_16x16x32_bf16 v[10:13], v[218:221], v[238:241], v[102:105]
	v_mfma_f32_16x16x32_bf16 v[78:81], v[222:225], v[242:245], v[10:13]
	s_barrier
; #define LDA(dst,b,h) for(int m=0;m<4;++m)for(int k=0;k<2;++k) \
;     dst[m][k]=*reinterpret_cast<const bf16x8*>((char*)SA(b,h)+lds_byte(wr*64+m*16+fr,k*32+fq*8))
; #define LDB(dst,b,h) for(int n=0;n<2;++n)for(int k=0;k<2;++k) \
;     dst[n][k]=*reinterpret_cast<const bf16x8*>((char*)SB(b,h)+lds_byte(wc*32+n*16+fr,k*32+fq*8))
; #define MMA(ai,bj,At,Bt_) do{__builtin_amdgcn_s_setprio(1); \
;     for(int m=0;m<4;++m)for(int n=0;n<2;++n)for(int k=0;k<2;++k) \
;       acc[ai][bj][m][n]=__builtin_amdgcn_mfma_f32_16x16x32_bf16(Bt_[n][k],At[m][k],acc[ai][bj][m][n],0,0,0); \
;     __builtin_amdgcn_s_setprio(0);}while(0)
; #define WAIT_V(n) asm volatile("s_waitcnt vmcnt(" #n ")":::"memory")
; #define WAIT_L(n) asm volatile("s_waitcnt lgkmcnt(" #n ")":::"memory")
; #define BAR __builtin_amdgcn_s_barrier()
; template <int EPI>
; __device__ __forceinline__ void gemm_run(const GD& c, const bool has_next, const GD& nx, const Ctx& e, bf16* shm, float* rs, float* rs_nxt, float* racc_) {
;     ...
;     LDB(B1,1,1); WAIT_V(0); BAR; WAIT_L(0); MMA(0,1,At,B1); BAR;
;     LDA(At,1,1); BAR; WAIT_L(0); MMA(1,0,At,B0); MMA(1,1,At,B1); BAR; }
;   if(wr==0)BAR;
	s_nop 4
	ds_read_b128 v[10:13], v183
	ds_read_b128 v[14:17], v183 offset:1024
	ds_read_b128 v[246:249], v183 offset:2048
	ds_read_b128 v[250:253], v183 offset:3072
	s_waitcnt vmcnt(0)
	s_barrier
	s_waitcnt lgkmcnt(0)
	v_mfma_f32_16x16x32_bf16 v[74:77], v[10:13], v[20:23], v[126:129]
	v_mfma_f32_16x16x32_bf16 v[20:23], v[246:249], v[20:23], v[148:151]
	v_mfma_f32_16x16x32_bf16 v[82:85], v[250:253], v[24:27], v[20:23]
	v_mfma_f32_16x16x32_bf16 v[20:23], v[10:13], v[62:65], v[152:155]
	v_mfma_f32_16x16x32_bf16 v[114:117], v[14:17], v[106:109], v[20:23]
	v_mfma_f32_16x16x32_bf16 v[20:23], v[246:249], v[62:65], v[156:159]
	v_mfma_f32_16x16x32_bf16 v[110:113], v[14:17], v[24:27], v[74:77]
	v_mfma_f32_16x16x32_bf16 v[74:77], v[250:253], v[106:109], v[20:23]
	v_mfma_f32_16x16x32_bf16 v[20:23], v[10:13], v[122:125], v[46:49]
	v_mfma_f32_16x16x32_bf16 v[118:121], v[14:17], v[226:229], v[20:23]
	v_mfma_f32_16x16x32_bf16 v[20:23], v[246:249], v[122:125], v[50:53]
	v_mfma_f32_16x16x32_bf16 v[62:65], v[250:253], v[226:229], v[20:23]
	v_mfma_f32_16x16x32_bf16 v[20:23], v[10:13], v[238:241], v[54:57]
	v_mfma_f32_16x16x32_bf16 v[122:125], v[14:17], v[242:245], v[20:23]
	v_mfma_f32_16x16x32_bf16 v[20:23], v[246:249], v[238:241], v[194:197]
	v_mfma_f32_16x16x32_bf16 v[54:57], v[250:253], v[242:245], v[20:23]
	s_barrier
	ds_read_b128 v[46:49], v19 offset:49152
	ds_read_b128 v[50:53], v19 offset:50176
	ds_read_b128 v[148:151], v18 offset:51200
	ds_read_b128 v[152:155], v18 offset:52224
	ds_read_b128 v[156:159], v18 offset:53248
	ds_read_b128 v[194:197], v18 offset:54272
	ds_read_b128 v[226:229], v18 offset:55296
	ds_read_b128 v[238:241], v18 offset:56320
	s_barrier
	s_waitcnt lgkmcnt(0)
	v_mfma_f32_16x16x32_bf16 v[6:9], v[2:5], v[46:49], v[6:9]
	v_mfma_f32_16x16x32_bf16 v[26:29], v[214:217], v[50:53], v[6:9]
	v_mfma_f32_16x16x32_bf16 v[6:9], v[218:221], v[46:49], v[160:163]
	v_mfma_f32_16x16x32_bf16 v[98:101], v[222:225], v[50:53], v[6:9]
	v_mfma_f32_16x16x32_bf16 v[6:9], v[2:5], v[148:151], v[166:169]
	v_mfma_f32_16x16x32_bf16 v[22:25], v[214:217], v[152:155], v[6:9]
	v_mfma_f32_16x16x32_bf16 v[6:9], v[218:221], v[148:151], v[172:175]
	v_mfma_f32_16x16x32_bf16 v[102:105], v[222:225], v[152:155], v[6:9]
	v_mfma_f32_16x16x32_bf16 v[6:9], v[2:5], v[156:159], v[186:189]
	v_mfma_f32_16x16x32_bf16 v[18:21], v[214:217], v[194:197], v[6:9]
	v_mfma_f32_16x16x32_bf16 v[6:9], v[218:221], v[156:159], v[190:193]
	v_mfma_f32_16x16x32_bf16 v[106:109], v[222:225], v[194:197], v[6:9]
	v_mfma_f32_16x16x32_bf16 v[2:5], v[2:5], v[226:229], v[130:133]
	v_mfma_f32_16x16x32_bf16 v[6:9], v[218:221], v[226:229], v[134:137]
	v_mfma_f32_16x16x32_bf16 v[2:5], v[214:217], v[238:241], v[2:5]
	v_mfma_f32_16x16x32_bf16 v[6:9], v[222:225], v[238:241], v[6:9]
	v_mfma_f32_16x16x32_bf16 v[86:89], v[10:13], v[46:49], v[140:143]
	v_mfma_f32_16x16x32_bf16 v[46:49], v[246:249], v[46:49], v[144:147]
	v_mfma_f32_16x16x32_bf16 v[126:129], v[14:17], v[50:53], v[86:89]
	v_mfma_f32_16x16x32_bf16 v[86:89], v[250:253], v[50:53], v[46:49]
	v_mfma_f32_16x16x32_bf16 v[46:49], v[10:13], v[148:151], v[230:233]
	v_mfma_f32_16x16x32_bf16 v[130:133], v[14:17], v[152:155], v[46:49]
	v_mfma_f32_16x16x32_bf16 v[46:49], v[246:249], v[148:151], v[198:201]
	v_mfma_f32_16x16x32_bf16 v[50:53], v[250:253], v[152:155], v[46:49]
	v_mfma_f32_16x16x32_bf16 v[46:49], v[10:13], v[156:159], v[234:237]
	v_mfma_f32_16x16x32_bf16 v[10:13], v[10:13], v[226:229], v[206:209]
	v_mfma_f32_16x16x32_bf16 v[134:137], v[14:17], v[194:197], v[46:49]
	v_mfma_f32_16x16x32_bf16 v[46:49], v[246:249], v[156:159], v[202:205]
	v_mfma_f32_16x16x32_bf16 v[10:13], v[14:17], v[238:241], v[10:13]
	v_mfma_f32_16x16x32_bf16 v[14:17], v[246:249], v[226:229], v[210:213]
	v_mfma_f32_16x16x32_bf16 v[46:49], v[250:253], v[194:197], v[46:49]
	v_mfma_f32_16x16x32_bf16 v[14:17], v[250:253], v[238:241], v[14:17]
	v_cmp_gt_u32_e32 vcc, s96, v92
	s_barrier
	s_and_saveexec_b64 s[2:3], vcc
	s_cbranch_execz .LBB0_747
	s_barrier

; #define STAGE_A(P,br,kt) STAGE_G(P,c.A,c.lda,br,(long)(kt)*c.kstr)
; #define STAGE_B(P,br,kt) STAGE_G(P,c.Bt,c.K,br,(long)(kt)*BK)
; #define LDA(dst,b,h) for(int m=0;m<4;++m)for(int k=0;k<2;++k) \
;     dst[m][k]=*reinterpret_cast<const bf16x8*>((char*)SA(b,h)+lds_byte(wr*64+m*16+fr,k*32+fq*8))
; #define LDB(dst,b,h) for(int n=0;n<2;++n)for(int k=0;k<2;++k) \
;     dst[n][k]=*reinterpret_cast<const bf16x8*>((char*)SB(b,h)+lds_byte(wc*32+n*16+fr,k*32+fq*8))
; #define MMA(ai,bj,At,Bt_) do{__builtin_amdgcn_s_setprio(1); \
;     for(int m=0;m<4;++m)for(int n=0;n<2;++n)for(int k=0;k<2;++k) \
;       acc[ai][bj][m][n]=__builtin_amdgcn_mfma_f32_16x16x32_bf16(Bt_[n][k],At[m][k],acc[ai][bj][m][n],0,0,0); \
;     __builtin_amdgcn_s_setprio(0);}while(0)
; #define WAIT_L(n) asm volatile("s_waitcnt lgkmcnt(" #n ")":::"memory")
; #define BAR __builtin_amdgcn_s_barrier()
; #define SCHED __builtin_amdgcn_sched_barrier(0)
; template <int EPI>
; __device__ __forceinline__ void gemm_run(const GD& c, const bool has_next, const GD& nx, const Ctx& e, bf16* shm, float* rs, float* rs_nxt, float* racc_) {
;     ...
;     LDB(B0,0,0); SCHED; LDA(At,0,0); STAGE_A(SA(1,1),brow+HALF,t+1);
;     WAIT_L(8); BAR; WAIT_L(0); MMA(0,0,At,B0); BAR; SCHED;
;     LDB(B1,0,1); STAGE_B(SB(0,0),bcol,t+2);
;     BAR; WAIT_L(0); MMA(0,1,At,B1); BAR;
;     LDA(At,0,1); STAGE_A(SA(0,0),brow,t+2);
;     BAR; WAIT_L(0); MMA(1,0,At,B0); BAR; SCHED;
.LBB0_972:
	ds_read_b128 v[172:175], v159
	ds_read_b128 v[186:189], v159 offset:1024
	ds_read_b128 v[190:193], v159 offset:2048
	ds_read_b128 v[194:197], v159 offset:3072
	v_add_u32_e32 v169, 0xc000, v146
	v_lshl_add_u64 v[246:247], s[6:7], 0, v[136:137]
	v_readfirstlane_b32 s19, v169
	v_add_u32_e32 v170, 0xe000, v146
	v_lshl_add_u64 v[160:161], v[246:247], 0, s[22:23]
	s_mov_b32 m0, s19
	v_lshl_add_u64 v[248:249], s[6:7], 0, v[138:139]
	v_readfirstlane_b32 s19, v170
	ds_read_b128 v[198:201], v150
	ds_read_b128 v[202:205], v150 offset:1024
	ds_read_b128 v[206:209], v149
	ds_read_b128 v[210:213], v149 offset:1024
	ds_read_b128 v[214:217], v148
	ds_read_b128 v[218:221], v148 offset:1024
	ds_read_b128 v[222:225], v147
	ds_read_b128 v[226:229], v147 offset:1024
	global_load_lds_dwordx4 v[160:161], off
	v_lshl_add_u64 v[160:161], v[248:249], 0, s[22:23]
	s_mov_b32 m0, s19
	s_nop 0
	global_load_lds_dwordx4 v[160:161], off
	s_waitcnt lgkmcnt(8)
	s_barrier
	s_waitcnt lgkmcnt(0)
	v_mfma_f32_16x16x32_bf16 v[126:129], v[172:175], v[198:201], v[126:129]
	v_mfma_f32_16x16x32_bf16 v[122:125], v[190:193], v[198:201], v[122:125]
	v_mfma_f32_16x16x32_bf16 v[118:121], v[172:175], v[206:209], v[118:121]
	v_mfma_f32_16x16x32_bf16 v[114:117], v[190:193], v[206:209], v[114:117]
	v_mfma_f32_16x16x32_bf16 v[110:113], v[172:175], v[214:217], v[110:113]
	v_mfma_f32_16x16x32_bf16 v[106:109], v[190:193], v[214:217], v[106:109]
	v_mfma_f32_16x16x32_bf16 v[102:105], v[172:175], v[222:225], v[102:105]
	v_mfma_f32_16x16x32_bf16 v[98:101], v[190:193], v[222:225], v[98:101]
	v_mfma_f32_16x16x32_bf16 v[126:129], v[186:189], v[202:205], v[126:129]
	v_mfma_f32_16x16x32_bf16 v[122:125], v[194:197], v[202:205], v[122:125]
	v_mfma_f32_16x16x32_bf16 v[118:121], v[186:189], v[210:213], v[118:121]
	v_mfma_f32_16x16x32_bf16 v[114:117], v[194:197], v[210:213], v[114:117]
	v_mfma_f32_16x16x32_bf16 v[110:113], v[186:189], v[218:221], v[110:113]
	v_mfma_f32_16x16x32_bf16 v[106:109], v[194:197], v[218:221], v[106:109]
	v_mfma_f32_16x16x32_bf16 v[102:105], v[186:189], v[226:229], v[102:105]
	v_mfma_f32_16x16x32_bf16 v[98:101], v[194:197], v[226:229], v[98:101]
	s_barrier
	v_add_u32_e32 v160, s33, v151
	v_lshl_add_u64 v[250:251], s[6:7], 0, v[140:141]
	v_readfirstlane_b32 s19, v160
	v_add_u32_e32 v161, 0x2000, v160
	v_lshl_add_u64 v[162:163], v[250:251], 0, s[24:25]
	s_mov_b32 m0, s19
	v_lshl_add_u64 v[252:253], s[6:7], 0, v[142:143]
	v_readfirstlane_b32 s19, v161
	ds_read_b128 v[230:233], v157
	ds_read_b128 v[234:237], v157 offset:1024
	ds_read_b128 v[238:241], v157 offset:2048
	ds_read_b128 v[242:245], v157 offset:3072
	global_load_lds_dwordx4 v[162:163], off
	v_lshl_add_u64 v[162:163], v[252:253], 0, s[24:25]
	s_mov_b32 m0, s19
	s_nop 0
	global_load_lds_dwordx4 v[162:163], off
	s_barrier
	s_waitcnt lgkmcnt(0)
	v_mfma_f32_16x16x32_bf16 v[94:97], v[230:233], v[198:201], v[94:97]
	v_mfma_f32_16x16x32_bf16 v[90:93], v[238:241], v[198:201], v[90:93]
	v_mfma_f32_16x16x32_bf16 v[86:89], v[230:233], v[206:209], v[86:89]
	v_mfma_f32_16x16x32_bf16 v[82:85], v[238:241], v[206:209], v[82:85]
	v_readfirstlane_b32 s19, v146
	v_mfma_f32_16x16x32_bf16 v[78:81], v[230:233], v[214:217], v[78:81]
	v_lshl_add_u64 v[162:163], v[246:247], 0, s[20:21]
	v_mfma_f32_16x16x32_bf16 v[74:77], v[238:241], v[214:217], v[74:77]
	s_mov_b32 m0, s19
	v_mfma_f32_16x16x32_bf16 v[70:73], v[230:233], v[222:225], v[70:73]
	v_mfma_f32_16x16x32_bf16 v[66:69], v[238:241], v[222:225], v[66:69]
	v_mfma_f32_16x16x32_bf16 v[94:97], v[234:237], v[202:205], v[94:97]
	v_mfma_f32_16x16x32_bf16 v[90:93], v[242:245], v[202:205], v[90:93]
	v_mfma_f32_16x16x32_bf16 v[86:89], v[234:237], v[210:213], v[86:89]
	v_mfma_f32_16x16x32_bf16 v[82:85], v[242:245], v[210:213], v[82:85]
	v_mfma_f32_16x16x32_bf16 v[78:81], v[234:237], v[218:221], v[78:81]
	v_mfma_f32_16x16x32_bf16 v[74:77], v[242:245], v[218:221], v[74:77]
	v_mfma_f32_16x16x32_bf16 v[70:73], v[234:237], v[226:229], v[70:73]
	v_mfma_f32_16x16x32_bf16 v[66:69], v[242:245], v[226:229], v[66:69]
	s_barrier
	ds_read_b128 v[198:201], v150 offset:16384
	ds_read_b128 v[202:205], v150 offset:17408
	ds_read_b128 v[206:209], v149 offset:16384
	ds_read_b128 v[210:213], v149 offset:17408
	ds_read_b128 v[214:217], v148 offset:16384
	ds_read_b128 v[218:221], v148 offset:17408
	ds_read_b128 v[222:225], v147 offset:16384
	ds_read_b128 v[226:229], v147 offset:17408
	global_load_lds_dwordx4 v[162:163], off
	v_add_u32_e32 v162, 0x2000, v146
	v_lshl_add_u64 v[166:167], v[248:249], 0, s[20:21]
	v_readfirstlane_b32 s19, v162
	s_mov_b32 m0, s19
	s_nop 0
	global_load_lds_dwordx4 v[166:167], off
	s_barrier
	s_waitcnt lgkmcnt(0)
	v_mfma_f32_16x16x32_bf16 v[62:65], v[172:175], v[198:201], v[62:65]
	v_mfma_f32_16x16x32_bf16 v[58:61], v[190:193], v[198:201], v[58:61]
	v_mfma_f32_16x16x32_bf16 v[54:57], v[172:175], v[206:209], v[54:57]
	v_mfma_f32_16x16x32_bf16 v[50:53], v[190:193], v[206:209], v[50:53]
	v_mfma_f32_16x16x32_bf16 v[46:49], v[172:175], v[214:217], v[46:49]
	v_mfma_f32_16x16x32_bf16 v[42:45], v[190:193], v[214:217], v[42:45]
	v_mfma_f32_16x16x32_bf16 v[38:41], v[172:175], v[222:225], v[38:41]
	v_mfma_f32_16x16x32_bf16 v[34:37], v[190:193], v[222:225], v[34:37]
	v_mfma_f32_16x16x32_bf16 v[62:65], v[186:189], v[202:205], v[62:65]
	v_mfma_f32_16x16x32_bf16 v[58:61], v[194:197], v[202:205], v[58:61]
	v_mfma_f32_16x16x32_bf16 v[54:57], v[186:189], v[210:213], v[54:57]
	v_mfma_f32_16x16x32_bf16 v[50:53], v[194:197], v[210:213], v[50:53]
	v_mfma_f32_16x16x32_bf16 v[46:49], v[186:189], v[218:221], v[46:49]
	v_mfma_f32_16x16x32_bf16 v[42:45], v[194:197], v[218:221], v[42:45]
	v_mfma_f32_16x16x32_bf16 v[38:41], v[186:189], v[226:229], v[38:41]
	v_mfma_f32_16x16x32_bf16 v[34:37], v[194:197], v[226:229], v[34:37]
	s_barrier
; #define STAGE_A(P,br,kt) STAGE_G(P,c.A,c.lda,br,(long)(kt)*c.kstr)
; #define STAGE_B(P,br,kt) STAGE_G(P,c.Bt,c.K,br,(long)(kt)*BK)
; #define LDA(dst,b,h) for(int m=0;m<4;++m)for(int k=0;k<2;++k) \
;     dst[m][k]=*reinterpret_cast<const bf16x8*>((char*)SA(b,h)+lds_byte(wr*64+m*16+fr,k*32+fq*8))
; #define LDB(dst,b,h) for(int n=0;n<2;++n)for(int k=0;k<2;++k) \
;     dst[n][k]=*reinterpret_cast<const bf16x8*>((char*)SB(b,h)+lds_byte(wc*32+n*16+fr,k*32+fq*8))
; #define MMA(ai,bj,At,Bt_) do{__builtin_amdgcn_s_setprio(1); \
;     for(int m=0;m<4;++m)for(int n=0;n<2;++n)for(int k=0;k<2;++k) \
;       acc[ai][bj][m][n]=__builtin_amdgcn_mfma_f32_16x16x32_bf16(Bt_[n][k],At[m][k],acc[ai][bj][m][n],0,0,0); \
;     __builtin_amdgcn_s_setprio(0);}while(0)
; #define WAIT_V(n) asm volatile("s_waitcnt vmcnt(" #n ")":::"memory")
; #define WAIT_L(n) asm volatile("s_waitcnt lgkmcnt(" #n ")":::"memory")
; #define BAR __builtin_amdgcn_s_barrier()
; #define SCHED __builtin_amdgcn_sched_barrier(0)
; template <int EPI>
; __device__ __forceinline__ void gemm_run(const GD& c, const bool has_next, const GD& nx, const Ctx& e, bf16* shm, float* rs, float* rs_nxt, float* racc_) {
;     ...
;     STAGE_B(SB(0,1),bcol+HALF,t+2);
;     WAIT_V(6); BAR; MMA(1,1,At,B1); BAR;
;     LDB(B0,1,0); SCHED; LDA(At,1,0); STAGE_A(SA(0,1),brow+HALF,t+2);
;     WAIT_L(8); BAR; WAIT_L(0); MMA(0,0,At,B0); BAR; SCHED;
;     LDB(B1,1,1); STAGE_B(SB(1,0),bcol,t+3);
;     BAR; WAIT_L(0); MMA(0,1,At,B1); BAR;
;     LDA(At,1,1); STAGE_A(SA(1,0),brow,t+3);
	v_add_u32_e32 v163, s86, v151
	v_lshl_add_u64 v[166:167], v[250:251], 0, s[26:27]
	v_readfirstlane_b32 s19, v163
	s_mov_b32 m0, s19
	v_lshl_add_u64 v[172:173], v[252:253], 0, s[26:27]
	global_load_lds_dwordx4 v[166:167], off
	v_add_u32_e32 v166, 0x2000, v163
	s_nop 0
	v_readfirstlane_b32 s19, v166
	s_mov_b32 m0, s19
	s_nop 0
	global_load_lds_dwordx4 v[172:173], off
	s_waitcnt vmcnt(6)
	s_barrier
	v_mfma_f32_16x16x32_bf16 v[30:33], v[230:233], v[198:201], v[30:33]
	v_mfma_f32_16x16x32_bf16 v[26:29], v[238:241], v[198:201], v[26:29]
	v_mfma_f32_16x16x32_bf16 v[22:25], v[230:233], v[206:209], v[22:25]
	v_mfma_f32_16x16x32_bf16 v[18:21], v[238:241], v[206:209], v[18:21]
	v_mfma_f32_16x16x32_bf16 v[14:17], v[230:233], v[214:217], v[14:17]
	v_mfma_f32_16x16x32_bf16 v[10:13], v[238:241], v[214:217], v[10:13]
	v_mfma_f32_16x16x32_bf16 v[6:9], v[230:233], v[222:225], v[6:9]
	v_mfma_f32_16x16x32_bf16 v[2:5], v[238:241], v[222:225], v[2:5]
	v_mfma_f32_16x16x32_bf16 v[30:33], v[234:237], v[202:205], v[30:33]
	v_mfma_f32_16x16x32_bf16 v[26:29], v[242:245], v[202:205], v[26:29]
	v_mfma_f32_16x16x32_bf16 v[22:25], v[234:237], v[210:213], v[22:25]
	v_mfma_f32_16x16x32_bf16 v[18:21], v[242:245], v[210:213], v[18:21]
	v_mfma_f32_16x16x32_bf16 v[14:17], v[234:237], v[218:221], v[14:17]
	v_mfma_f32_16x16x32_bf16 v[10:13], v[242:245], v[218:221], v[10:13]
	v_mfma_f32_16x16x32_bf16 v[6:9], v[234:237], v[226:229], v[6:9]
	v_mfma_f32_16x16x32_bf16 v[2:5], v[242:245], v[226:229], v[2:5]
	s_barrier
	ds_read_b128 v[172:175], v154
	ds_read_b128 v[186:189], v154 offset:1024
	ds_read_b128 v[190:193], v154 offset:2048
	ds_read_b128 v[194:197], v154 offset:3072
	v_add_u32_e32 v167, 0x4000, v146
	v_add_u32_e32 v168, 0x6000, v146
	v_readfirstlane_b32 s19, v167
	v_lshl_add_u64 v[230:231], v[246:247], 0, s[28:29]
	s_mov_b32 m0, s19
	v_readfirstlane_b32 s19, v168
	ds_read_b128 v[198:201], v150 offset:32768
	ds_read_b128 v[202:205], v150 offset:33792
	ds_read_b128 v[206:209], v149 offset:32768
	ds_read_b128 v[210:213], v149 offset:33792
	ds_read_b128 v[214:217], v148 offset:32768
	ds_read_b128 v[218:221], v148 offset:33792
	ds_read_b128 v[222:225], v147 offset:32768
	ds_read_b128 v[226:229], v147 offset:33792
	global_load_lds_dwordx4 v[230:231], off
	v_lshl_add_u64 v[230:231], v[248:249], 0, s[28:29]
	s_mov_b32 m0, s19
	s_nop 0
	global_load_lds_dwordx4 v[230:231], off
	s_waitcnt lgkmcnt(8)
	s_barrier
	s_waitcnt lgkmcnt(0)
	v_mfma_f32_16x16x32_bf16 v[126:129], v[172:175], v[198:201], v[126:129]
	v_mfma_f32_16x16x32_bf16 v[122:125], v[190:193], v[198:201], v[122:125]
	v_mfma_f32_16x16x32_bf16 v[118:121], v[172:175], v[206:209], v[118:121]
	v_mfma_f32_16x16x32_bf16 v[114:117], v[190:193], v[206:209], v[114:117]
	v_mfma_f32_16x16x32_bf16 v[110:113], v[172:175], v[214:217], v[110:113]
	v_mfma_f32_16x16x32_bf16 v[106:109], v[190:193], v[214:217], v[106:109]
	v_mfma_f32_16x16x32_bf16 v[102:105], v[172:175], v[222:225], v[102:105]
	v_mfma_f32_16x16x32_bf16 v[98:101], v[190:193], v[222:225], v[98:101]
	v_mfma_f32_16x16x32_bf16 v[126:129], v[186:189], v[202:205], v[126:129]
	v_mfma_f32_16x16x32_bf16 v[122:125], v[194:197], v[202:205], v[122:125]
	v_mfma_f32_16x16x32_bf16 v[118:121], v[186:189], v[210:213], v[118:121]
	v_mfma_f32_16x16x32_bf16 v[114:117], v[194:197], v[210:213], v[114:117]
	v_mfma_f32_16x16x32_bf16 v[110:113], v[186:189], v[218:221], v[110:113]
	v_mfma_f32_16x16x32_bf16 v[106:109], v[194:197], v[218:221], v[106:109]
	v_mfma_f32_16x16x32_bf16 v[102:105], v[186:189], v[226:229], v[102:105]
	v_mfma_f32_16x16x32_bf16 v[98:101], v[194:197], v[226:229], v[98:101]
	s_barrier
	v_readfirstlane_b32 s19, v153
	v_add_u32_e32 v171, 0x2000, v153
	v_lshl_add_u64 v[182:183], v[250:251], 0, s[42:43]
	s_mov_b32 m0, s19
	v_readfirstlane_b32 s19, v171
	ds_read_b128 v[230:233], v152
	ds_read_b128 v[234:237], v152 offset:1024
	ds_read_b128 v[238:241], v152 offset:2048
	ds_read_b128 v[242:245], v152 offset:3072
	global_load_lds_dwordx4 v[182:183], off
	v_lshl_add_u64 v[182:183], v[252:253], 0, s[42:43]
	s_mov_b32 m0, s19
	s_nop 0
	global_load_lds_dwordx4 v[182:183], off
	s_barrier
	s_waitcnt lgkmcnt(0)
	v_mfma_f32_16x16x32_bf16 v[94:97], v[230:233], v[198:201], v[94:97]
	v_mfma_f32_16x16x32_bf16 v[90:93], v[238:241], v[198:201], v[90:93]
	v_mfma_f32_16x16x32_bf16 v[86:89], v[230:233], v[206:209], v[86:89]
	v_mfma_f32_16x16x32_bf16 v[82:85], v[238:241], v[206:209], v[82:85]
	v_readfirstlane_b32 s19, v155
	v_mfma_f32_16x16x32_bf16 v[78:81], v[230:233], v[214:217], v[78:81]
	v_lshl_add_u64 v[182:183], v[246:247], 0, s[44:45]
	v_mfma_f32_16x16x32_bf16 v[74:77], v[238:241], v[214:217], v[74:77]
	s_mov_b32 m0, s19
	v_mfma_f32_16x16x32_bf16 v[70:73], v[230:233], v[222:225], v[70:73]
	v_readfirstlane_b32 s19, v156
	v_mfma_f32_16x16x32_bf16 v[66:69], v[238:241], v[222:225], v[66:69]
	v_mfma_f32_16x16x32_bf16 v[94:97], v[234:237], v[202:205], v[94:97]
	v_mfma_f32_16x16x32_bf16 v[90:93], v[242:245], v[202:205], v[90:93]
	v_mfma_f32_16x16x32_bf16 v[86:89], v[234:237], v[210:213], v[86:89]
	v_mfma_f32_16x16x32_bf16 v[82:85], v[242:245], v[210:213], v[82:85]
	v_mfma_f32_16x16x32_bf16 v[78:81], v[234:237], v[218:221], v[78:81]
	v_mfma_f32_16x16x32_bf16 v[74:77], v[242:245], v[218:221], v[74:77]
	v_mfma_f32_16x16x32_bf16 v[70:73], v[234:237], v[226:229], v[70:73]
	v_mfma_f32_16x16x32_bf16 v[66:69], v[242:245], v[226:229], v[66:69]
	s_barrier
	ds_read_b128 v[198:201], v150 offset:49152
	ds_read_b128 v[202:205], v150 offset:50176
	ds_read_b128 v[206:209], v149 offset:49152
	ds_read_b128 v[210:213], v149 offset:50176
	ds_read_b128 v[214:217], v148 offset:49152
	ds_read_b128 v[218:221], v148 offset:50176
	ds_read_b128 v[222:225], v147 offset:49152
	ds_read_b128 v[226:229], v147 offset:50176
	global_load_lds_dwordx4 v[182:183], off
	v_lshl_add_u64 v[182:183], v[248:249], 0, s[44:45]
	s_mov_b32 m0, s19
	s_nop 0
	global_load_lds_dwordx4 v[182:183], off
	s_barrier
; #define STAGE_A(P,br,kt) STAGE_G(P,c.A,c.lda,br,(long)(kt)*c.kstr)
; #define STAGE_B(P,br,kt) STAGE_G(P,c.Bt,c.K,br,(long)(kt)*BK)
; #define LDA(dst,b,h) for(int m=0;m<4;++m)for(int k=0;k<2;++k) \
;     dst[m][k]=*reinterpret_cast<const bf16x8*>((char*)SA(b,h)+lds_byte(wr*64+m*16+fr,k*32+fq*8))
; #define LDB(dst,b,h) for(int n=0;n<2;++n)for(int k=0;k<2;++k) \
;     dst[n][k]=*reinterpret_cast<const bf16x8*>((char*)SB(b,h)+lds_byte(wc*32+n*16+fr,k*32+fq*8))
; #define MMA(ai,bj,At,Bt_) do{__builtin_amdgcn_s_setprio(1); \
;     for(int m=0;m<4;++m)for(int n=0;n<2;++n)for(int k=0;k<2;++k) \
;       acc[ai][bj][m][n]=__builtin_amdgcn_mfma_f32_16x16x32_bf16(Bt_[n][k],At[m][k],acc[ai][bj][m][n],0,0,0); \
;     __builtin_amdgcn_s_setprio(0);}while(0)
; #define WAIT_V(n) asm volatile("s_waitcnt vmcnt(" #n ")":::"memory")
; #define WAIT_L(n) asm volatile("s_waitcnt lgkmcnt(" #n ")":::"memory")
; #define BAR __builtin_amdgcn_s_barrier()
; #define SCHED __builtin_amdgcn_sched_barrier(0)
; template <int EPI>
; __device__ __forceinline__ void gemm_run(const GD& c, const bool has_next, const GD& nx, const Ctx& e, bf16* shm, float* rs, float* rs_nxt, float* racc_) {
;     ...
;     BAR; WAIT_L(0); MMA(1,0,At,B0); BAR; SCHED;
;     STAGE_B(SB(1,1),bcol+HALF,t+3);
;     WAIT_V(6); BAR; MMA(1,1,At,B1); BAR;
;   }
;   { LDB(B0,0,0); LDA(At,0,0); STAGE_A(SA(1,1),brow+HALF,nt-1);
;     BAR; WAIT_L(0); MMA(0,0,At,B0); BAR;
;     LDB(B1,0,1); BAR; WAIT_L(0); MMA(0,1,At,B1); BAR;
	s_waitcnt lgkmcnt(0)
	v_mfma_f32_16x16x32_bf16 v[62:65], v[172:175], v[198:201], v[62:65]
	v_mfma_f32_16x16x32_bf16 v[58:61], v[190:193], v[198:201], v[58:61]
	v_mfma_f32_16x16x32_bf16 v[54:57], v[172:175], v[206:209], v[54:57]
	v_mfma_f32_16x16x32_bf16 v[50:53], v[190:193], v[206:209], v[50:53]
	v_mfma_f32_16x16x32_bf16 v[46:49], v[172:175], v[214:217], v[46:49]
	v_mfma_f32_16x16x32_bf16 v[42:45], v[190:193], v[214:217], v[42:45]
	v_mfma_f32_16x16x32_bf16 v[38:41], v[172:175], v[222:225], v[38:41]
	v_mfma_f32_16x16x32_bf16 v[34:37], v[190:193], v[222:225], v[34:37]
	v_mfma_f32_16x16x32_bf16 v[62:65], v[186:189], v[202:205], v[62:65]
	v_mfma_f32_16x16x32_bf16 v[58:61], v[194:197], v[202:205], v[58:61]
	v_mfma_f32_16x16x32_bf16 v[54:57], v[186:189], v[210:213], v[54:57]
	v_mfma_f32_16x16x32_bf16 v[50:53], v[194:197], v[210:213], v[50:53]
	v_mfma_f32_16x16x32_bf16 v[46:49], v[186:189], v[218:221], v[46:49]
	v_mfma_f32_16x16x32_bf16 v[42:45], v[194:197], v[218:221], v[42:45]
	v_mfma_f32_16x16x32_bf16 v[38:41], v[186:189], v[226:229], v[38:41]
	v_mfma_f32_16x16x32_bf16 v[34:37], v[194:197], v[226:229], v[34:37]
	s_barrier
	v_readfirstlane_b32 s19, v158
	v_add_u32_e32 v171, 0x2000, v158
	v_lshl_add_u64 v[172:173], v[250:251], 0, s[46:47]
	s_mov_b32 m0, s19
	v_readfirstlane_b32 s19, v171
	global_load_lds_dwordx4 v[172:173], off
	v_lshl_add_u64 v[172:173], v[252:253], 0, s[46:47]
	s_mov_b32 m0, s19
	s_nop 0
	global_load_lds_dwordx4 v[172:173], off
	s_waitcnt vmcnt(6)
	s_barrier
	v_mfma_f32_16x16x32_bf16 v[30:33], v[230:233], v[198:201], v[30:33]
	v_mfma_f32_16x16x32_bf16 v[26:29], v[238:241], v[198:201], v[26:29]
	v_mfma_f32_16x16x32_bf16 v[22:25], v[230:233], v[206:209], v[22:25]
	v_mfma_f32_16x16x32_bf16 v[18:21], v[238:241], v[206:209], v[18:21]
	s_add_i32 s18, s18, 2
	v_mfma_f32_16x16x32_bf16 v[14:17], v[230:233], v[214:217], v[14:17]
	v_lshl_add_u64 v[136:137], v[136:137], 0, s[20:21]
	v_mfma_f32_16x16x32_bf16 v[10:13], v[238:241], v[214:217], v[10:13]
	v_lshl_add_u64 v[138:139], v[138:139], 0, s[20:21]
	v_mfma_f32_16x16x32_bf16 v[6:9], v[230:233], v[222:225], v[6:9]
	v_lshl_add_u64 v[140:141], v[140:141], 0, s[88:89]
	v_mfma_f32_16x16x32_bf16 v[2:5], v[238:241], v[222:225], v[2:5]
	s_cmp_lt_u32 s18, 4
	v_mfma_f32_16x16x32_bf16 v[30:33], v[234:237], v[202:205], v[30:33]
	v_lshl_add_u64 v[142:143], v[142:143], 0, s[88:89]
	v_mfma_f32_16x16x32_bf16 v[26:29], v[242:245], v[202:205], v[26:29]
	v_mfma_f32_16x16x32_bf16 v[22:25], v[234:237], v[210:213], v[22:25]
	v_mfma_f32_16x16x32_bf16 v[18:21], v[242:245], v[210:213], v[18:21]
	v_mfma_f32_16x16x32_bf16 v[14:17], v[234:237], v[218:221], v[14:17]
	v_mfma_f32_16x16x32_bf16 v[10:13], v[242:245], v[218:221], v[10:13]
	v_mfma_f32_16x16x32_bf16 v[6:9], v[234:237], v[226:229], v[6:9]
	v_mfma_f32_16x16x32_bf16 v[2:5], v[242:245], v[226:229], v[2:5]
	s_barrier
	s_cbranch_scc1 .LBB0_972
	s_or_b32 s26, s12, 0x80
	s_ashr_i32 s27, s26, 31
	s_mul_i32 s18, s26, 0x600
	s_mul_hi_i32 s19, s26, 0x600
	s_add_u32 s18, s6, s18
	s_addc_u32 s19, s7, s19
	v_lshl_add_u64 v[132:133], s[18:19], 0, v[132:133]
	s_mov_b64 s[22:23], 0x540
	v_readfirstlane_b32 s20, v169
	v_lshl_add_u64 v[132:133], v[132:133], 0, s[22:23]
	s_mov_b32 m0, s20
	ds_read_b128 v[136:139], v159
	ds_read_b128 v[140:143], v159 offset:1024
	ds_read_b128 v[172:175], v159 offset:2048
	ds_read_b128 v[186:189], v159 offset:3072
	ds_read_b128 v[190:193], v150
	ds_read_b128 v[194:197], v150 offset:1024
	ds_read_b128 v[198:201], v149
	ds_read_b128 v[202:205], v149 offset:1024
	ds_read_b128 v[206:209], v148
	ds_read_b128 v[210:213], v148 offset:1024
	ds_read_b128 v[214:217], v147
	ds_read_b128 v[218:221], v147 offset:1024
	global_load_lds_dwordx4 v[132:133], off
	v_lshl_add_u64 v[132:133], s[18:19], 0, v[134:135]
	v_readfirstlane_b32 s18, v170
	v_lshl_add_u64 v[132:133], v[132:133], 0, s[22:23]
	s_mov_b32 m0, s18
	s_nop 0
	global_load_lds_dwordx4 v[132:133], off
	s_barrier
	s_waitcnt lgkmcnt(0)
	v_mfma_f32_16x16x32_bf16 v[126:129], v[136:139], v[190:193], v[126:129]
	v_mfma_f32_16x16x32_bf16 v[122:125], v[172:175], v[190:193], v[122:125]
	v_mfma_f32_16x16x32_bf16 v[118:121], v[136:139], v[198:201], v[118:121]
	v_mfma_f32_16x16x32_bf16 v[114:117], v[172:175], v[198:201], v[114:117]
	v_mfma_f32_16x16x32_bf16 v[102:105], v[136:139], v[214:217], v[102:105]
	v_mfma_f32_16x16x32_bf16 v[98:101], v[172:175], v[214:217], v[98:101]
	v_mfma_f32_16x16x32_bf16 v[126:129], v[140:143], v[194:197], v[126:129]
	v_mfma_f32_16x16x32_bf16 v[122:125], v[186:189], v[194:197], v[122:125]
	v_mfma_f32_16x16x32_bf16 v[118:121], v[140:143], v[202:205], v[118:121]
	v_mfma_f32_16x16x32_bf16 v[114:117], v[186:189], v[202:205], v[114:117]
	v_mfma_f32_16x16x32_bf16 v[110:113], v[136:139], v[206:209], v[110:113]
	v_mfma_f32_16x16x32_bf16 v[106:109], v[172:175], v[206:209], v[106:109]
	v_mfma_f32_16x16x32_bf16 v[102:105], v[140:143], v[218:221], v[102:105]
	v_mfma_f32_16x16x32_bf16 v[98:101], v[186:189], v[218:221], v[98:101]
	v_mfma_f32_16x16x32_bf16 v[132:135], v[140:143], v[210:213], v[110:113]
	v_mfma_f32_16x16x32_bf16 v[222:225], v[186:189], v[210:213], v[106:109]
	s_barrier
	s_nop 1
	ds_read_b128 v[106:109], v157
	ds_read_b128 v[110:113], v157 offset:1024
	ds_read_b128 v[226:229], v157 offset:2048
	ds_read_b128 v[156:159], v157 offset:3072
	s_barrier
; #define LDA(dst,b,h) for(int m=0;m<4;++m)for(int k=0;k<2;++k) \
;     dst[m][k]=*reinterpret_cast<const bf16x8*>((char*)SA(b,h)+lds_byte(wr*64+m*16+fr,k*32+fq*8))
; #define LDB(dst,b,h) for(int n=0;n<2;++n)for(int k=0;k<2;++k) \
;     dst[n][k]=*reinterpret_cast<const bf16x8*>((char*)SB(b,h)+lds_byte(wc*32+n*16+fr,k*32+fq*8))
; #define MMA(ai,bj,At,Bt_) do{__builtin_amdgcn_s_setprio(1); \
;     for(int m=0;m<4;++m)for(int n=0;n<2;++n)for(int k=0;k<2;++k) \
;       acc[ai][bj][m][n]=__builtin_amdgcn_mfma_f32_16x16x32_bf16(Bt_[n][k],At[m][k],acc[ai][bj][m][n],0,0,0); \
;     __builtin_amdgcn_s_setprio(0);}while(0)
; #define WAIT_V(n) asm volatile("s_waitcnt vmcnt(" #n ")":::"memory")
; #define WAIT_L(n) asm volatile("s_waitcnt lgkmcnt(" #n ")":::"memory")
; #define BAR __builtin_amdgcn_s_barrier()
; template <int EPI>
; __device__ __forceinline__ void gemm_run(const GD& c, const bool has_next, const GD& nx, const Ctx& e, bf16* shm, float* rs, float* rs_nxt, float* racc_) {
;     ...
;     LDB(B1,0,1); BAR; WAIT_L(0); MMA(0,1,At,B1); BAR;
;     LDA(At,0,1); WAIT_V(4); BAR; WAIT_L(0); MMA(1,0,At,B0); MMA(1,1,At,B1); BAR; }
;   { LDB(B0,1,0); LDA(At,1,0); WAIT_V(2); BAR; WAIT_L(0); MMA(0,0,At,B0); BAR;
	s_waitcnt lgkmcnt(0)
	v_mfma_f32_16x16x32_bf16 v[86:89], v[106:109], v[198:201], v[86:89]
	v_mfma_f32_16x16x32_bf16 v[82:85], v[226:229], v[198:201], v[82:85]
	v_mfma_f32_16x16x32_bf16 v[70:73], v[106:109], v[214:217], v[70:73]
	v_mfma_f32_16x16x32_bf16 v[66:69], v[226:229], v[214:217], v[66:69]
	v_mfma_f32_16x16x32_bf16 v[94:97], v[106:109], v[190:193], v[94:97]
	v_mfma_f32_16x16x32_bf16 v[90:93], v[226:229], v[190:193], v[90:93]
	v_mfma_f32_16x16x32_bf16 v[86:89], v[110:113], v[202:205], v[86:89]
	v_mfma_f32_16x16x32_bf16 v[82:85], v[156:159], v[202:205], v[82:85]
	v_mfma_f32_16x16x32_bf16 v[78:81], v[106:109], v[206:209], v[78:81]
	v_mfma_f32_16x16x32_bf16 v[74:77], v[226:229], v[206:209], v[74:77]
	v_mfma_f32_16x16x32_bf16 v[70:73], v[110:113], v[218:221], v[70:73]
	v_mfma_f32_16x16x32_bf16 v[66:69], v[156:159], v[218:221], v[66:69]
	v_mfma_f32_16x16x32_bf16 v[230:233], v[110:113], v[194:197], v[94:97]
	v_mfma_f32_16x16x32_bf16 v[190:193], v[156:159], v[194:197], v[90:93]
	v_mfma_f32_16x16x32_bf16 v[194:197], v[110:113], v[210:213], v[78:81]
	v_mfma_f32_16x16x32_bf16 v[198:201], v[156:159], v[210:213], v[74:77]
	s_barrier
	s_nop 0
	ds_read_b128 v[74:77], v150 offset:16384
	ds_read_b128 v[78:81], v150 offset:17408
	ds_read_b128 v[90:93], v149 offset:16384
	ds_read_b128 v[94:97], v149 offset:17408
	ds_read_b128 v[202:205], v148 offset:16384
	ds_read_b128 v[206:209], v148 offset:17408
	ds_read_b128 v[210:213], v147 offset:16384
	ds_read_b128 v[214:217], v147 offset:17408
	s_waitcnt vmcnt(4)
	s_barrier
	s_waitcnt lgkmcnt(0)
	v_mfma_f32_16x16x32_bf16 v[62:65], v[136:139], v[74:77], v[62:65]
	v_mfma_f32_16x16x32_bf16 v[58:61], v[172:175], v[74:77], v[58:61]
	v_mfma_f32_16x16x32_bf16 v[54:57], v[136:139], v[90:93], v[54:57]
	v_mfma_f32_16x16x32_bf16 v[50:53], v[172:175], v[90:93], v[50:53]
	v_mfma_f32_16x16x32_bf16 v[38:41], v[136:139], v[210:213], v[38:41]
	v_mfma_f32_16x16x32_bf16 v[34:37], v[172:175], v[210:213], v[34:37]
	v_mfma_f32_16x16x32_bf16 v[62:65], v[140:143], v[78:81], v[62:65]
	v_mfma_f32_16x16x32_bf16 v[58:61], v[186:189], v[78:81], v[58:61]
	v_mfma_f32_16x16x32_bf16 v[54:57], v[140:143], v[94:97], v[54:57]
	v_mfma_f32_16x16x32_bf16 v[50:53], v[186:189], v[94:97], v[50:53]
	v_mfma_f32_16x16x32_bf16 v[46:49], v[136:139], v[202:205], v[46:49]
	v_mfma_f32_16x16x32_bf16 v[42:45], v[172:175], v[202:205], v[42:45]
	v_mfma_f32_16x16x32_bf16 v[38:41], v[140:143], v[214:217], v[38:41]
	v_mfma_f32_16x16x32_bf16 v[34:37], v[186:189], v[214:217], v[34:37]
	v_mfma_f32_16x16x32_bf16 v[218:221], v[140:143], v[206:209], v[46:49]
	v_mfma_f32_16x16x32_bf16 v[234:237], v[186:189], v[206:209], v[42:45]
	v_mfma_f32_16x16x32_bf16 v[22:25], v[106:109], v[90:93], v[22:25]
	v_mfma_f32_16x16x32_bf16 v[18:21], v[226:229], v[90:93], v[18:21]
	v_mfma_f32_16x16x32_bf16 v[6:9], v[106:109], v[210:213], v[6:9]
	v_mfma_f32_16x16x32_bf16 v[2:5], v[226:229], v[210:213], v[2:5]
	v_mfma_f32_16x16x32_bf16 v[30:33], v[106:109], v[74:77], v[30:33]
	v_mfma_f32_16x16x32_bf16 v[26:29], v[226:229], v[74:77], v[26:29]
	v_mfma_f32_16x16x32_bf16 v[22:25], v[110:113], v[94:97], v[22:25]
	v_mfma_f32_16x16x32_bf16 v[18:21], v[156:159], v[94:97], v[18:21]
	v_mfma_f32_16x16x32_bf16 v[14:17], v[106:109], v[202:205], v[14:17]
	v_mfma_f32_16x16x32_bf16 v[10:13], v[226:229], v[202:205], v[10:13]
	v_mfma_f32_16x16x32_bf16 v[6:9], v[110:113], v[214:217], v[6:9]
	v_mfma_f32_16x16x32_bf16 v[2:5], v[156:159], v[214:217], v[2:5]
	v_mfma_f32_16x16x32_bf16 v[136:139], v[110:113], v[78:81], v[30:33]
	v_mfma_f32_16x16x32_bf16 v[140:143], v[156:159], v[78:81], v[26:29]
	v_mfma_f32_16x16x32_bf16 v[170:173], v[110:113], v[206:209], v[14:17]
	v_mfma_f32_16x16x32_bf16 v[186:189], v[156:159], v[206:209], v[10:13]
	s_barrier
	s_nop 0
	ds_read_b128 v[10:13], v154
	ds_read_b128 v[14:17], v154 offset:1024
	ds_read_b128 v[156:159], v154 offset:2048
	ds_read_b128 v[202:205], v154 offset:3072
	ds_read_b128 v[26:29], v150 offset:32768
	ds_read_b128 v[30:33], v150 offset:33792
	ds_read_b128 v[42:45], v149 offset:32768
	ds_read_b128 v[46:49], v149 offset:33792
	ds_read_b128 v[206:209], v148 offset:32768
	ds_read_b128 v[210:213], v148 offset:33792
	ds_read_b128 v[214:217], v147 offset:32768
	ds_read_b128 v[226:229], v147 offset:33792
	s_waitcnt vmcnt(2)
	s_barrier
; #define LDA(dst,b,h) for(int m=0;m<4;++m)for(int k=0;k<2;++k) \
;     dst[m][k]=*reinterpret_cast<const bf16x8*>((char*)SA(b,h)+lds_byte(wr*64+m*16+fr,k*32+fq*8))
; #define LDB(dst,b,h) for(int n=0;n<2;++n)for(int k=0;k<2;++k) \
;     dst[n][k]=*reinterpret_cast<const bf16x8*>((char*)SB(b,h)+lds_byte(wc*32+n*16+fr,k*32+fq*8))
; #define MMA(ai,bj,At,Bt_) do{__builtin_amdgcn_s_setprio(1); \
;     for(int m=0;m<4;++m)for(int n=0;n<2;++n)for(int k=0;k<2;++k) \
;       acc[ai][bj][m][n]=__builtin_amdgcn_mfma_f32_16x16x32_bf16(Bt_[n][k],At[m][k],acc[ai][bj][m][n],0,0,0); \
;     __builtin_amdgcn_s_setprio(0);}while(0)
; #define WAIT_V(n) asm volatile("s_waitcnt vmcnt(" #n ")":::"memory")
; #define WAIT_L(n) asm volatile("s_waitcnt lgkmcnt(" #n ")":::"memory")
; #define BAR __builtin_amdgcn_s_barrier()
; template <int EPI>
; __device__ __forceinline__ void gemm_run(const GD& c, const bool has_next, const GD& nx, const Ctx& e, bf16* shm, float* rs, float* rs_nxt, float* racc_) {
;     ...
;   { LDB(B0,1,0); LDA(At,1,0); WAIT_V(2); BAR; WAIT_L(0); MMA(0,0,At,B0); BAR;
;     LDB(B1,1,1); WAIT_V(0); BAR; WAIT_L(0); MMA(0,1,At,B1); BAR;
;     LDA(At,1,1); BAR; WAIT_L(0); MMA(1,0,At,B0); MMA(1,1,At,B1); BAR; }
;   if(wr==0)BAR;
	s_waitcnt lgkmcnt(0)
	v_mfma_f32_16x16x32_bf16 v[74:77], v[10:13], v[26:29], v[126:129]
	v_mfma_f32_16x16x32_bf16 v[126:129], v[14:17], v[30:33], v[74:77]
	v_mfma_f32_16x16x32_bf16 v[74:77], v[156:159], v[26:29], v[122:125]
	v_mfma_f32_16x16x32_bf16 v[122:125], v[202:205], v[30:33], v[74:77]
	v_mfma_f32_16x16x32_bf16 v[74:77], v[10:13], v[42:45], v[118:121]
	v_mfma_f32_16x16x32_bf16 v[110:113], v[14:17], v[46:49], v[74:77]
	v_mfma_f32_16x16x32_bf16 v[74:77], v[156:159], v[42:45], v[114:117]
	v_mfma_f32_16x16x32_bf16 v[106:109], v[202:205], v[46:49], v[74:77]
	v_mfma_f32_16x16x32_bf16 v[74:77], v[10:13], v[206:209], v[132:135]
	v_mfma_f32_16x16x32_bf16 v[94:97], v[14:17], v[210:213], v[74:77]
	v_mfma_f32_16x16x32_bf16 v[74:77], v[156:159], v[206:209], v[222:225]
	v_mfma_f32_16x16x32_bf16 v[90:93], v[202:205], v[210:213], v[74:77]
	v_mfma_f32_16x16x32_bf16 v[74:77], v[10:13], v[214:217], v[102:105]
	v_mfma_f32_16x16x32_bf16 v[78:81], v[14:17], v[226:229], v[74:77]
	v_mfma_f32_16x16x32_bf16 v[74:77], v[156:159], v[214:217], v[98:101]
	v_mfma_f32_16x16x32_bf16 v[74:77], v[202:205], v[226:229], v[74:77]
	s_barrier
	ds_read_b128 v[132:135], v152
	ds_read_b128 v[222:225], v152 offset:1024
	ds_read_b128 v[238:241], v152 offset:2048
	ds_read_b128 v[152:155], v152 offset:3072
	s_waitcnt vmcnt(0)
	s_barrier
	s_waitcnt lgkmcnt(0)
	v_mfma_f32_16x16x32_bf16 v[98:101], v[132:135], v[26:29], v[230:233]
	v_mfma_f32_16x16x32_bf16 v[26:29], v[238:241], v[26:29], v[190:193]
	v_mfma_f32_16x16x32_bf16 v[114:117], v[152:155], v[30:33], v[26:29]
	v_mfma_f32_16x16x32_bf16 v[26:29], v[132:135], v[42:45], v[86:89]
	v_mfma_f32_16x16x32_bf16 v[102:105], v[222:225], v[46:49], v[26:29]
	v_mfma_f32_16x16x32_bf16 v[26:29], v[238:241], v[42:45], v[82:85]
	v_mfma_f32_16x16x32_bf16 v[118:121], v[222:225], v[30:33], v[98:101]
	v_mfma_f32_16x16x32_bf16 v[98:101], v[152:155], v[46:49], v[26:29]
	v_mfma_f32_16x16x32_bf16 v[26:29], v[132:135], v[206:209], v[194:197]
	v_mfma_f32_16x16x32_bf16 v[86:89], v[222:225], v[210:213], v[26:29]
	v_mfma_f32_16x16x32_bf16 v[26:29], v[238:241], v[206:209], v[198:201]
	v_mfma_f32_16x16x32_bf16 v[82:85], v[152:155], v[210:213], v[26:29]
	v_mfma_f32_16x16x32_bf16 v[26:29], v[132:135], v[214:217], v[70:73]
	v_mfma_f32_16x16x32_bf16 v[70:73], v[222:225], v[226:229], v[26:29]
	v_mfma_f32_16x16x32_bf16 v[26:29], v[238:241], v[214:217], v[66:69]
	v_mfma_f32_16x16x32_bf16 v[66:69], v[152:155], v[226:229], v[26:29]
	s_barrier
	ds_read_b128 v[190:193], v150 offset:49152
	ds_read_b128 v[194:197], v150 offset:50176
	ds_read_b128 v[198:201], v149 offset:49152
	ds_read_b128 v[206:209], v149 offset:50176
	ds_read_b128 v[210:213], v148 offset:49152
	ds_read_b128 v[148:151], v148 offset:50176
	ds_read_b128 v[214:217], v147 offset:49152
	ds_read_b128 v[226:229], v147 offset:50176
	s_barrier
	s_waitcnt lgkmcnt(0)
	v_mfma_f32_16x16x32_bf16 v[26:29], v[10:13], v[190:193], v[62:65]
	v_mfma_f32_16x16x32_bf16 v[62:65], v[14:17], v[194:197], v[26:29]
	v_mfma_f32_16x16x32_bf16 v[26:29], v[156:159], v[190:193], v[58:61]
	v_mfma_f32_16x16x32_bf16 v[58:61], v[202:205], v[194:197], v[26:29]
	v_mfma_f32_16x16x32_bf16 v[26:29], v[10:13], v[198:201], v[54:57]
	v_mfma_f32_16x16x32_bf16 v[46:49], v[14:17], v[206:209], v[26:29]
	v_mfma_f32_16x16x32_bf16 v[26:29], v[156:159], v[198:201], v[50:53]
	v_mfma_f32_16x16x32_bf16 v[42:45], v[202:205], v[206:209], v[26:29]
	v_mfma_f32_16x16x32_bf16 v[26:29], v[10:13], v[210:213], v[218:221]
	v_mfma_f32_16x16x32_bf16 v[10:13], v[10:13], v[214:217], v[38:41]
	v_mfma_f32_16x16x32_bf16 v[30:33], v[14:17], v[148:151], v[26:29]
	v_mfma_f32_16x16x32_bf16 v[26:29], v[156:159], v[210:213], v[234:237]
	v_mfma_f32_16x16x32_bf16 v[14:17], v[14:17], v[226:229], v[10:13]
	v_mfma_f32_16x16x32_bf16 v[10:13], v[156:159], v[214:217], v[34:37]
	v_mfma_f32_16x16x32_bf16 v[26:29], v[202:205], v[148:151], v[26:29]
	v_mfma_f32_16x16x32_bf16 v[10:13], v[202:205], v[226:229], v[10:13]
	v_mfma_f32_16x16x32_bf16 v[34:37], v[132:135], v[190:193], v[136:139]
	v_mfma_f32_16x16x32_bf16 v[54:57], v[222:225], v[194:197], v[34:37]
	v_mfma_f32_16x16x32_bf16 v[34:37], v[238:241], v[190:193], v[140:143]
	v_mfma_f32_16x16x32_bf16 v[18:21], v[238:241], v[198:201], v[18:21]
	v_mfma_f32_16x16x32_bf16 v[50:53], v[152:155], v[194:197], v[34:37]
	v_mfma_f32_16x16x32_bf16 v[22:25], v[132:135], v[198:201], v[22:25]
	v_mfma_f32_16x16x32_bf16 v[34:37], v[152:155], v[206:209], v[18:21]
	v_mfma_f32_16x16x32_bf16 v[18:21], v[132:135], v[210:213], v[170:173]
	v_mfma_f32_16x16x32_bf16 v[38:41], v[222:225], v[206:209], v[22:25]
	v_mfma_f32_16x16x32_bf16 v[22:25], v[222:225], v[148:151], v[18:21]
	v_mfma_f32_16x16x32_bf16 v[18:21], v[238:241], v[210:213], v[186:189]
	v_mfma_f32_16x16x32_bf16 v[6:9], v[132:135], v[214:217], v[6:9]
	v_mfma_f32_16x16x32_bf16 v[2:5], v[238:241], v[214:217], v[2:5]
	v_mfma_f32_16x16x32_bf16 v[18:21], v[152:155], v[148:151], v[18:21]
	v_mfma_f32_16x16x32_bf16 v[6:9], v[222:225], v[226:229], v[6:9]
	v_mfma_f32_16x16x32_bf16 v[2:5], v[152:155], v[226:229], v[2:5]
	v_cmp_gt_u32_e32 vcc, s96, v145
	s_barrier
	s_and_saveexec_b64 s[18:19], vcc
	s_cbranch_execz .LBB0_975
	s_barrier

; #define STAGE_A(P,br,kt) STAGE_G(P,c.A,c.lda,br,(long)(kt)*c.kstr)
; #define STAGE_B(P,br,kt) STAGE_G(P,c.Bt,c.K,br,(long)(kt)*BK)
; #define LDA(dst,b,h) for(int m=0;m<4;++m)for(int k=0;k<2;++k) \
;     dst[m][k]=*reinterpret_cast<const bf16x8*>((char*)SA(b,h)+lds_byte(wr*64+m*16+fr,k*32+fq*8))
; #define LDB(dst,b,h) for(int n=0;n<2;++n)for(int k=0;k<2;++k) \
;     dst[n][k]=*reinterpret_cast<const bf16x8*>((char*)SB(b,h)+lds_byte(wc*32+n*16+fr,k*32+fq*8))
; #define MMA(ai,bj,At,Bt_) do{__builtin_amdgcn_s_setprio(1); \
;     for(int m=0;m<4;++m)for(int n=0;n<2;++n)for(int k=0;k<2;++k) \
;       acc[ai][bj][m][n]=__builtin_amdgcn_mfma_f32_16x16x32_bf16(Bt_[n][k],At[m][k],acc[ai][bj][m][n],0,0,0); \
;     __builtin_amdgcn_s_setprio(0);}while(0)
; #define WAIT_L(n) asm volatile("s_waitcnt lgkmcnt(" #n ")":::"memory")
; #define BAR __builtin_amdgcn_s_barrier()
; #define SCHED __builtin_amdgcn_sched_barrier(0)
; template <int EPI>
; __device__ __forceinline__ void gemm_run(const GD& c, const bool has_next, const GD& nx, const Ctx& e, bf16* shm, float* rs, float* rs_nxt, float* racc_) {
;     ...
;     LDB(B0,0,0); SCHED; LDA(At,0,0); STAGE_A(SA(1,1),brow+HALF,t+1);
;     WAIT_L(8); BAR; WAIT_L(0); MMA(0,0,At,B0); BAR; SCHED;
;     LDB(B1,0,1); STAGE_B(SB(0,0),bcol,t+2);
;     BAR; WAIT_L(0); MMA(0,1,At,B1); BAR;
;     LDA(At,0,1); STAGE_A(SA(0,0),brow,t+2);
;     BAR; WAIT_L(0); MMA(1,0,At,B0); BAR; SCHED;
.LBB0_980:
	ds_read_b128 v[172:175], v159
	ds_read_b128 v[186:189], v159 offset:1024
	ds_read_b128 v[190:193], v159 offset:2048
	ds_read_b128 v[194:197], v159 offset:3072
	v_add_u32_e32 v169, 0xc000, v146
	v_lshl_add_u64 v[182:183], s[6:7], 0, v[132:133]
	v_readfirstlane_b32 s3, v169
	v_add_u32_e32 v170, 0xe000, v146
	v_lshl_add_u64 v[160:161], v[182:183], 0, s[18:19]
	s_mov_b32 m0, s3
	v_lshl_add_u64 v[246:247], s[6:7], 0, v[134:135]
	v_readfirstlane_b32 s3, v170
	ds_read_b128 v[198:201], v150
	ds_read_b128 v[202:205], v150 offset:1024
	ds_read_b128 v[206:209], v149
	ds_read_b128 v[210:213], v149 offset:1024
	ds_read_b128 v[214:217], v148
	ds_read_b128 v[218:221], v148 offset:1024
	ds_read_b128 v[222:225], v147
	ds_read_b128 v[226:229], v147 offset:1024
	global_load_lds_dwordx4 v[160:161], off
	v_lshl_add_u64 v[160:161], v[246:247], 0, s[18:19]
	s_mov_b32 m0, s3
	s_nop 0
	global_load_lds_dwordx4 v[160:161], off
	s_waitcnt lgkmcnt(8)
	s_barrier
	s_waitcnt lgkmcnt(0)
	v_mfma_f32_16x16x32_bf16 v[126:129], v[172:175], v[198:201], v[126:129]
	v_mfma_f32_16x16x32_bf16 v[122:125], v[190:193], v[198:201], v[122:125]
	v_mfma_f32_16x16x32_bf16 v[118:121], v[172:175], v[206:209], v[118:121]
	v_mfma_f32_16x16x32_bf16 v[114:117], v[190:193], v[206:209], v[114:117]
	v_mfma_f32_16x16x32_bf16 v[110:113], v[172:175], v[214:217], v[110:113]
	v_mfma_f32_16x16x32_bf16 v[106:109], v[190:193], v[214:217], v[106:109]
	v_mfma_f32_16x16x32_bf16 v[102:105], v[172:175], v[222:225], v[102:105]
	v_mfma_f32_16x16x32_bf16 v[98:101], v[190:193], v[222:225], v[98:101]
	v_mfma_f32_16x16x32_bf16 v[126:129], v[186:189], v[202:205], v[126:129]
	v_mfma_f32_16x16x32_bf16 v[122:125], v[194:197], v[202:205], v[122:125]
	v_mfma_f32_16x16x32_bf16 v[118:121], v[186:189], v[210:213], v[118:121]
	v_mfma_f32_16x16x32_bf16 v[114:117], v[194:197], v[210:213], v[114:117]
	v_mfma_f32_16x16x32_bf16 v[110:113], v[186:189], v[218:221], v[110:113]
	v_mfma_f32_16x16x32_bf16 v[106:109], v[194:197], v[218:221], v[106:109]
	v_mfma_f32_16x16x32_bf16 v[102:105], v[186:189], v[226:229], v[102:105]
	v_mfma_f32_16x16x32_bf16 v[98:101], v[194:197], v[226:229], v[98:101]
	s_barrier
	v_add_u32_e32 v160, s33, v152
	v_lshl_add_u64 v[248:249], s[6:7], 0, v[136:137]
	v_readfirstlane_b32 s3, v160
	v_add_u32_e32 v161, 0x2000, v160
	v_lshl_add_u64 v[162:163], v[248:249], 0, s[20:21]
	s_mov_b32 m0, s3
	v_lshl_add_u64 v[250:251], s[6:7], 0, v[138:139]
	v_readfirstlane_b32 s3, v161
	ds_read_b128 v[230:233], v157
	ds_read_b128 v[234:237], v157 offset:1024
	ds_read_b128 v[238:241], v157 offset:2048
	ds_read_b128 v[242:245], v157 offset:3072
	global_load_lds_dwordx4 v[162:163], off
	v_lshl_add_u64 v[162:163], v[250:251], 0, s[20:21]
	s_mov_b32 m0, s3
	s_nop 0
	global_load_lds_dwordx4 v[162:163], off
	s_barrier
	s_waitcnt lgkmcnt(0)
	v_mfma_f32_16x16x32_bf16 v[94:97], v[230:233], v[198:201], v[94:97]
	v_mfma_f32_16x16x32_bf16 v[90:93], v[238:241], v[198:201], v[90:93]
	v_mfma_f32_16x16x32_bf16 v[86:89], v[230:233], v[206:209], v[86:89]
	v_mfma_f32_16x16x32_bf16 v[82:85], v[238:241], v[206:209], v[82:85]
	v_readfirstlane_b32 s3, v146
	v_mfma_f32_16x16x32_bf16 v[78:81], v[230:233], v[214:217], v[78:81]
	v_lshl_add_u64 v[162:163], v[182:183], 0, s[22:23]
	v_mfma_f32_16x16x32_bf16 v[74:77], v[238:241], v[214:217], v[74:77]
	s_mov_b32 m0, s3
	v_mfma_f32_16x16x32_bf16 v[70:73], v[230:233], v[222:225], v[70:73]
	v_mfma_f32_16x16x32_bf16 v[66:69], v[238:241], v[222:225], v[66:69]
	v_mfma_f32_16x16x32_bf16 v[94:97], v[234:237], v[202:205], v[94:97]
	v_mfma_f32_16x16x32_bf16 v[90:93], v[242:245], v[202:205], v[90:93]
	v_mfma_f32_16x16x32_bf16 v[86:89], v[234:237], v[210:213], v[86:89]
	v_mfma_f32_16x16x32_bf16 v[82:85], v[242:245], v[210:213], v[82:85]
	v_mfma_f32_16x16x32_bf16 v[78:81], v[234:237], v[218:221], v[78:81]
	v_mfma_f32_16x16x32_bf16 v[74:77], v[242:245], v[218:221], v[74:77]
	v_mfma_f32_16x16x32_bf16 v[70:73], v[234:237], v[226:229], v[70:73]
	v_mfma_f32_16x16x32_bf16 v[66:69], v[242:245], v[226:229], v[66:69]
	s_barrier
	ds_read_b128 v[198:201], v150 offset:16384
	ds_read_b128 v[202:205], v150 offset:17408
	ds_read_b128 v[206:209], v149 offset:16384
	ds_read_b128 v[210:213], v149 offset:17408
	ds_read_b128 v[214:217], v148 offset:16384
	ds_read_b128 v[218:221], v148 offset:17408
	ds_read_b128 v[222:225], v147 offset:16384
	ds_read_b128 v[226:229], v147 offset:17408
	global_load_lds_dwordx4 v[162:163], off
	v_add_u32_e32 v162, 0x2000, v146
	v_lshl_add_u64 v[166:167], v[246:247], 0, s[22:23]
	v_readfirstlane_b32 s3, v162
	s_mov_b32 m0, s3
	s_nop 0
	global_load_lds_dwordx4 v[166:167], off
	s_barrier
	s_waitcnt lgkmcnt(0)
	v_mfma_f32_16x16x32_bf16 v[62:65], v[172:175], v[198:201], v[62:65]
	v_mfma_f32_16x16x32_bf16 v[58:61], v[190:193], v[198:201], v[58:61]
	v_mfma_f32_16x16x32_bf16 v[54:57], v[172:175], v[206:209], v[54:57]
	v_mfma_f32_16x16x32_bf16 v[50:53], v[190:193], v[206:209], v[50:53]
	v_mfma_f32_16x16x32_bf16 v[46:49], v[172:175], v[214:217], v[46:49]
	v_mfma_f32_16x16x32_bf16 v[42:45], v[190:193], v[214:217], v[42:45]
	v_mfma_f32_16x16x32_bf16 v[38:41], v[172:175], v[222:225], v[38:41]
	v_mfma_f32_16x16x32_bf16 v[34:37], v[190:193], v[222:225], v[34:37]
	v_mfma_f32_16x16x32_bf16 v[62:65], v[186:189], v[202:205], v[62:65]
	v_mfma_f32_16x16x32_bf16 v[58:61], v[194:197], v[202:205], v[58:61]
	v_mfma_f32_16x16x32_bf16 v[54:57], v[186:189], v[210:213], v[54:57]
	v_mfma_f32_16x16x32_bf16 v[50:53], v[194:197], v[210:213], v[50:53]
	v_mfma_f32_16x16x32_bf16 v[46:49], v[186:189], v[218:221], v[46:49]
	v_mfma_f32_16x16x32_bf16 v[42:45], v[194:197], v[218:221], v[42:45]
	v_mfma_f32_16x16x32_bf16 v[38:41], v[186:189], v[226:229], v[38:41]
	v_mfma_f32_16x16x32_bf16 v[34:37], v[194:197], v[226:229], v[34:37]
	s_barrier
; #define STAGE_A(P,br,kt) STAGE_G(P,c.A,c.lda,br,(long)(kt)*c.kstr)
; #define STAGE_B(P,br,kt) STAGE_G(P,c.Bt,c.K,br,(long)(kt)*BK)
; #define LDA(dst,b,h) for(int m=0;m<4;++m)for(int k=0;k<2;++k) \
;     dst[m][k]=*reinterpret_cast<const bf16x8*>((char*)SA(b,h)+lds_byte(wr*64+m*16+fr,k*32+fq*8))
; #define LDB(dst,b,h) for(int n=0;n<2;++n)for(int k=0;k<2;++k) \
;     dst[n][k]=*reinterpret_cast<const bf16x8*>((char*)SB(b,h)+lds_byte(wc*32+n*16+fr,k*32+fq*8))
; #define MMA(ai,bj,At,Bt_) do{__builtin_amdgcn_s_setprio(1); \
;     for(int m=0;m<4;++m)for(int n=0;n<2;++n)for(int k=0;k<2;++k) \
;       acc[ai][bj][m][n]=__builtin_amdgcn_mfma_f32_16x16x32_bf16(Bt_[n][k],At[m][k],acc[ai][bj][m][n],0,0,0); \
;     __builtin_amdgcn_s_setprio(0);}while(0)
; #define WAIT_V(n) asm volatile("s_waitcnt vmcnt(" #n ")":::"memory")
; #define WAIT_L(n) asm volatile("s_waitcnt lgkmcnt(" #n ")":::"memory")
; #define BAR __builtin_amdgcn_s_barrier()
; #define SCHED __builtin_amdgcn_sched_barrier(0)
; template <int EPI>
; __device__ __forceinline__ void gemm_run(const GD& c, const bool has_next, const GD& nx, const Ctx& e, bf16* shm, float* rs, float* rs_nxt, float* racc_) {
;     ...
;     STAGE_B(SB(0,1),bcol+HALF,t+2);
;     WAIT_V(6); BAR; MMA(1,1,At,B1); BAR;
;     LDB(B0,1,0); SCHED; LDA(At,1,0); STAGE_A(SA(0,1),brow+HALF,t+2);
;     WAIT_L(8); BAR; WAIT_L(0); MMA(0,0,At,B0); BAR; SCHED;
;     LDB(B1,1,1); STAGE_B(SB(1,0),bcol,t+3);
;     BAR; WAIT_L(0); MMA(0,1,At,B1); BAR;
;     LDA(At,1,1); STAGE_A(SA(1,0),brow,t+3);
	v_add_u32_e32 v163, s86, v152
	v_lshl_add_u64 v[166:167], v[248:249], 0, s[24:25]
	v_readfirstlane_b32 s3, v163
	s_mov_b32 m0, s3
	v_lshl_add_u64 v[172:173], v[250:251], 0, s[24:25]
	global_load_lds_dwordx4 v[166:167], off
	v_add_u32_e32 v166, 0x2000, v163
	s_nop 0
	v_readfirstlane_b32 s3, v166
	s_mov_b32 m0, s3
	s_nop 0
	global_load_lds_dwordx4 v[172:173], off
	s_waitcnt vmcnt(6)
	s_barrier
	v_mfma_f32_16x16x32_bf16 v[30:33], v[230:233], v[198:201], v[30:33]
	v_mfma_f32_16x16x32_bf16 v[26:29], v[238:241], v[198:201], v[26:29]
	v_mfma_f32_16x16x32_bf16 v[22:25], v[230:233], v[206:209], v[22:25]
	v_mfma_f32_16x16x32_bf16 v[18:21], v[238:241], v[206:209], v[18:21]
	v_mfma_f32_16x16x32_bf16 v[14:17], v[230:233], v[214:217], v[14:17]
	v_mfma_f32_16x16x32_bf16 v[10:13], v[238:241], v[214:217], v[10:13]
	v_mfma_f32_16x16x32_bf16 v[6:9], v[230:233], v[222:225], v[6:9]
	v_mfma_f32_16x16x32_bf16 v[2:5], v[238:241], v[222:225], v[2:5]
	v_mfma_f32_16x16x32_bf16 v[30:33], v[234:237], v[202:205], v[30:33]
	v_mfma_f32_16x16x32_bf16 v[26:29], v[242:245], v[202:205], v[26:29]
	v_mfma_f32_16x16x32_bf16 v[22:25], v[234:237], v[210:213], v[22:25]
	v_mfma_f32_16x16x32_bf16 v[18:21], v[242:245], v[210:213], v[18:21]
	v_mfma_f32_16x16x32_bf16 v[14:17], v[234:237], v[218:221], v[14:17]
	v_mfma_f32_16x16x32_bf16 v[10:13], v[242:245], v[218:221], v[10:13]
	v_mfma_f32_16x16x32_bf16 v[6:9], v[234:237], v[226:229], v[6:9]
	v_mfma_f32_16x16x32_bf16 v[2:5], v[242:245], v[226:229], v[2:5]
	s_barrier
	ds_read_b128 v[172:175], v153
	ds_read_b128 v[186:189], v153 offset:1024
	ds_read_b128 v[190:193], v153 offset:2048
	ds_read_b128 v[194:197], v153 offset:3072
	v_add_u32_e32 v167, 0x4000, v146
	v_add_u32_e32 v168, 0x6000, v146
	v_readfirstlane_b32 s3, v167
	v_lshl_add_u64 v[230:231], v[182:183], 0, s[28:29]
	s_mov_b32 m0, s3
	v_readfirstlane_b32 s3, v168
	ds_read_b128 v[198:201], v150 offset:32768
	ds_read_b128 v[202:205], v150 offset:33792
	ds_read_b128 v[206:209], v149 offset:32768
	ds_read_b128 v[210:213], v149 offset:33792
	ds_read_b128 v[214:217], v148 offset:32768
	ds_read_b128 v[218:221], v148 offset:33792
	ds_read_b128 v[222:225], v147 offset:32768
	ds_read_b128 v[226:229], v147 offset:33792
	global_load_lds_dwordx4 v[230:231], off
	v_lshl_add_u64 v[230:231], v[246:247], 0, s[28:29]
	s_mov_b32 m0, s3
	s_nop 0
	global_load_lds_dwordx4 v[230:231], off
	s_waitcnt lgkmcnt(8)
	s_barrier
	s_waitcnt lgkmcnt(0)
	v_mfma_f32_16x16x32_bf16 v[126:129], v[172:175], v[198:201], v[126:129]
	v_mfma_f32_16x16x32_bf16 v[122:125], v[190:193], v[198:201], v[122:125]
	v_mfma_f32_16x16x32_bf16 v[118:121], v[172:175], v[206:209], v[118:121]
	v_mfma_f32_16x16x32_bf16 v[114:117], v[190:193], v[206:209], v[114:117]
	v_mfma_f32_16x16x32_bf16 v[110:113], v[172:175], v[214:217], v[110:113]
	v_mfma_f32_16x16x32_bf16 v[106:109], v[190:193], v[214:217], v[106:109]
	v_mfma_f32_16x16x32_bf16 v[102:105], v[172:175], v[222:225], v[102:105]
	v_mfma_f32_16x16x32_bf16 v[98:101], v[190:193], v[222:225], v[98:101]
	v_mfma_f32_16x16x32_bf16 v[126:129], v[186:189], v[202:205], v[126:129]
	v_mfma_f32_16x16x32_bf16 v[122:125], v[194:197], v[202:205], v[122:125]
	v_mfma_f32_16x16x32_bf16 v[118:121], v[186:189], v[210:213], v[118:121]
	v_mfma_f32_16x16x32_bf16 v[114:117], v[194:197], v[210:213], v[114:117]
	v_mfma_f32_16x16x32_bf16 v[110:113], v[186:189], v[218:221], v[110:113]
	v_mfma_f32_16x16x32_bf16 v[106:109], v[194:197], v[218:221], v[106:109]
	v_mfma_f32_16x16x32_bf16 v[102:105], v[186:189], v[226:229], v[102:105]
	v_mfma_f32_16x16x32_bf16 v[98:101], v[194:197], v[226:229], v[98:101]
	s_barrier
	v_readfirstlane_b32 s3, v154
	v_add_u32_e32 v171, 0x2000, v154
	v_lshl_add_u64 v[252:253], v[248:249], 0, s[44:45]
	s_mov_b32 m0, s3
	v_readfirstlane_b32 s3, v171
	ds_read_b128 v[230:233], v151
	ds_read_b128 v[234:237], v151 offset:1024
	ds_read_b128 v[238:241], v151 offset:2048
	ds_read_b128 v[242:245], v151 offset:3072
	global_load_lds_dwordx4 v[252:253], off
	v_lshl_add_u64 v[252:253], v[250:251], 0, s[44:45]
	s_mov_b32 m0, s3
	s_nop 0
	global_load_lds_dwordx4 v[252:253], off
	s_barrier
	s_waitcnt lgkmcnt(0)
	v_mfma_f32_16x16x32_bf16 v[94:97], v[230:233], v[198:201], v[94:97]
	v_mfma_f32_16x16x32_bf16 v[90:93], v[238:241], v[198:201], v[90:93]
	v_mfma_f32_16x16x32_bf16 v[86:89], v[230:233], v[206:209], v[86:89]
	v_mfma_f32_16x16x32_bf16 v[82:85], v[238:241], v[206:209], v[82:85]
	v_readfirstlane_b32 s3, v155
	v_mfma_f32_16x16x32_bf16 v[78:81], v[230:233], v[214:217], v[78:81]
	v_lshl_add_u64 v[182:183], v[182:183], 0, s[46:47]
	v_mfma_f32_16x16x32_bf16 v[74:77], v[238:241], v[214:217], v[74:77]
	s_mov_b32 m0, s3
	v_mfma_f32_16x16x32_bf16 v[70:73], v[230:233], v[222:225], v[70:73]
	v_readfirstlane_b32 s3, v156
	v_mfma_f32_16x16x32_bf16 v[66:69], v[238:241], v[222:225], v[66:69]
	v_mfma_f32_16x16x32_bf16 v[94:97], v[234:237], v[202:205], v[94:97]
	v_mfma_f32_16x16x32_bf16 v[90:93], v[242:245], v[202:205], v[90:93]
	v_mfma_f32_16x16x32_bf16 v[86:89], v[234:237], v[210:213], v[86:89]
	v_mfma_f32_16x16x32_bf16 v[82:85], v[242:245], v[210:213], v[82:85]
	v_mfma_f32_16x16x32_bf16 v[78:81], v[234:237], v[218:221], v[78:81]
	v_mfma_f32_16x16x32_bf16 v[74:77], v[242:245], v[218:221], v[74:77]
	v_mfma_f32_16x16x32_bf16 v[70:73], v[234:237], v[226:229], v[70:73]
	v_mfma_f32_16x16x32_bf16 v[66:69], v[242:245], v[226:229], v[66:69]
	s_barrier
	ds_read_b128 v[198:201], v150 offset:49152
	ds_read_b128 v[202:205], v150 offset:50176
	ds_read_b128 v[206:209], v149 offset:49152
	ds_read_b128 v[210:213], v149 offset:50176
	ds_read_b128 v[214:217], v148 offset:49152
	ds_read_b128 v[218:221], v148 offset:50176
	ds_read_b128 v[222:225], v147 offset:49152
	ds_read_b128 v[226:229], v147 offset:50176
	global_load_lds_dwordx4 v[182:183], off
	v_lshl_add_u64 v[182:183], v[246:247], 0, s[46:47]
	s_mov_b32 m0, s3
	s_nop 0
	global_load_lds_dwordx4 v[182:183], off
	s_barrier
; #define STAGE_A(P,br,kt) STAGE_G(P,c.A,c.lda,br,(long)(kt)*c.kstr)
; #define STAGE_B(P,br,kt) STAGE_G(P,c.Bt,c.K,br,(long)(kt)*BK)
; #define LDA(dst,b,h) for(int m=0;m<4;++m)for(int k=0;k<2;++k) \
;     dst[m][k]=*reinterpret_cast<const bf16x8*>((char*)SA(b,h)+lds_byte(wr*64+m*16+fr,k*32+fq*8))
; #define LDB(dst,b,h) for(int n=0;n<2;++n)for(int k=0;k<2;++k) \
;     dst[n][k]=*reinterpret_cast<const bf16x8*>((char*)SB(b,h)+lds_byte(wc*32+n*16+fr,k*32+fq*8))
; #define MMA(ai,bj,At,Bt_) do{__builtin_amdgcn_s_setprio(1); \
;     for(int m=0;m<4;++m)for(int n=0;n<2;++n)for(int k=0;k<2;++k) \
;       acc[ai][bj][m][n]=__builtin_amdgcn_mfma_f32_16x16x32_bf16(Bt_[n][k],At[m][k],acc[ai][bj][m][n],0,0,0); \
;     __builtin_amdgcn_s_setprio(0);}while(0)
; #define WAIT_V(n) asm volatile("s_waitcnt vmcnt(" #n ")":::"memory")
; #define WAIT_L(n) asm volatile("s_waitcnt lgkmcnt(" #n ")":::"memory")
; #define BAR __builtin_amdgcn_s_barrier()
; #define SCHED __builtin_amdgcn_sched_barrier(0)
; template <int EPI>
; __device__ __forceinline__ void gemm_run(const GD& c, const bool has_next, const GD& nx, const Ctx& e, bf16* shm, float* rs, float* rs_nxt, float* racc_) {
;     ...
;     BAR; WAIT_L(0); MMA(1,0,At,B0); BAR; SCHED;
;     STAGE_B(SB(1,1),bcol+HALF,t+3);
;     WAIT_V(6); BAR; MMA(1,1,At,B1); BAR;
;   }
;   { LDB(B0,0,0); LDA(At,0,0); STAGE_A(SA(1,1),brow+HALF,nt-1);
;     BAR; WAIT_L(0); MMA(0,0,At,B0); BAR;
;     LDB(B1,0,1); BAR; WAIT_L(0); MMA(0,1,At,B1); BAR;
	s_waitcnt lgkmcnt(0)
	v_mfma_f32_16x16x32_bf16 v[62:65], v[172:175], v[198:201], v[62:65]
	v_mfma_f32_16x16x32_bf16 v[58:61], v[190:193], v[198:201], v[58:61]
	v_mfma_f32_16x16x32_bf16 v[54:57], v[172:175], v[206:209], v[54:57]
	v_mfma_f32_16x16x32_bf16 v[50:53], v[190:193], v[206:209], v[50:53]
	v_mfma_f32_16x16x32_bf16 v[46:49], v[172:175], v[214:217], v[46:49]
	v_mfma_f32_16x16x32_bf16 v[42:45], v[190:193], v[214:217], v[42:45]
	v_mfma_f32_16x16x32_bf16 v[38:41], v[172:175], v[222:225], v[38:41]
	v_mfma_f32_16x16x32_bf16 v[34:37], v[190:193], v[222:225], v[34:37]
	v_mfma_f32_16x16x32_bf16 v[62:65], v[186:189], v[202:205], v[62:65]
	v_mfma_f32_16x16x32_bf16 v[58:61], v[194:197], v[202:205], v[58:61]
	v_mfma_f32_16x16x32_bf16 v[54:57], v[186:189], v[210:213], v[54:57]
	v_mfma_f32_16x16x32_bf16 v[50:53], v[194:197], v[210:213], v[50:53]
	v_mfma_f32_16x16x32_bf16 v[46:49], v[186:189], v[218:221], v[46:49]
	v_mfma_f32_16x16x32_bf16 v[42:45], v[194:197], v[218:221], v[42:45]
	v_mfma_f32_16x16x32_bf16 v[38:41], v[186:189], v[226:229], v[38:41]
	v_mfma_f32_16x16x32_bf16 v[34:37], v[194:197], v[226:229], v[34:37]
	s_barrier
	v_readfirstlane_b32 s3, v158
	v_add_u32_e32 v171, 0x2000, v158
	v_lshl_add_u64 v[172:173], v[248:249], 0, s[48:49]
	s_mov_b32 m0, s3
	v_readfirstlane_b32 s3, v171
	global_load_lds_dwordx4 v[172:173], off
	v_lshl_add_u64 v[172:173], v[250:251], 0, s[48:49]
	s_mov_b32 m0, s3
	s_nop 0
	global_load_lds_dwordx4 v[172:173], off
	s_waitcnt vmcnt(6)
	s_barrier
	v_mfma_f32_16x16x32_bf16 v[30:33], v[230:233], v[198:201], v[30:33]
	v_mfma_f32_16x16x32_bf16 v[26:29], v[238:241], v[198:201], v[26:29]
	v_mfma_f32_16x16x32_bf16 v[22:25], v[230:233], v[206:209], v[22:25]
	v_mfma_f32_16x16x32_bf16 v[18:21], v[238:241], v[206:209], v[18:21]
	s_add_i32 s2, s2, 2
	v_mfma_f32_16x16x32_bf16 v[14:17], v[230:233], v[214:217], v[14:17]
	v_lshl_add_u64 v[132:133], v[132:133], 0, s[88:89]
	v_mfma_f32_16x16x32_bf16 v[10:13], v[238:241], v[214:217], v[10:13]
	v_lshl_add_u64 v[134:135], v[134:135], 0, s[88:89]
	v_mfma_f32_16x16x32_bf16 v[6:9], v[230:233], v[222:225], v[6:9]
	v_lshl_add_u64 v[136:137], v[136:137], 0, s[88:89]
	v_mfma_f32_16x16x32_bf16 v[2:5], v[238:241], v[222:225], v[2:5]
	s_cmp_lt_u32 s2, 4
	v_mfma_f32_16x16x32_bf16 v[30:33], v[234:237], v[202:205], v[30:33]
	v_lshl_add_u64 v[138:139], v[138:139], 0, s[88:89]
	v_mfma_f32_16x16x32_bf16 v[26:29], v[242:245], v[202:205], v[26:29]
	v_mfma_f32_16x16x32_bf16 v[22:25], v[234:237], v[210:213], v[22:25]
	v_mfma_f32_16x16x32_bf16 v[18:21], v[242:245], v[210:213], v[18:21]
	v_mfma_f32_16x16x32_bf16 v[14:17], v[234:237], v[218:221], v[14:17]
	v_mfma_f32_16x16x32_bf16 v[10:13], v[242:245], v[218:221], v[10:13]
	v_mfma_f32_16x16x32_bf16 v[6:9], v[234:237], v[226:229], v[6:9]
	v_mfma_f32_16x16x32_bf16 v[2:5], v[242:245], v[226:229], v[2:5]
	s_barrier
	s_cbranch_scc1 .LBB0_980
	v_lshl_add_u64 v[154:155], s[16:17], 0, v[0:1]
	s_mov_b64 s[18:19], 0x380
	v_readfirstlane_b32 s2, v169
	v_lshl_add_u64 v[154:155], v[154:155], 0, s[18:19]
	s_mov_b32 m0, s2
	ds_read_b128 v[132:135], v159
	ds_read_b128 v[136:139], v159 offset:1024
	ds_read_b128 v[172:175], v159 offset:2048
	ds_read_b128 v[186:189], v159 offset:3072
	ds_read_b128 v[190:193], v150
	ds_read_b128 v[194:197], v150 offset:1024
	ds_read_b128 v[198:201], v149
	ds_read_b128 v[202:205], v149 offset:1024
	ds_read_b128 v[206:209], v148
	ds_read_b128 v[210:213], v148 offset:1024
	ds_read_b128 v[214:217], v147
	ds_read_b128 v[218:221], v147 offset:1024
	global_load_lds_dwordx4 v[154:155], off
	v_lshl_add_u64 v[154:155], s[16:17], 0, v[130:131]
	v_readfirstlane_b32 s2, v170
	v_lshl_add_u64 v[154:155], v[154:155], 0, s[18:19]
	s_mov_b32 m0, s2
	s_nop 0
	global_load_lds_dwordx4 v[154:155], off
	s_barrier
	s_waitcnt lgkmcnt(0)
	v_mfma_f32_16x16x32_bf16 v[126:129], v[132:135], v[190:193], v[126:129]
	v_mfma_f32_16x16x32_bf16 v[122:125], v[172:175], v[190:193], v[122:125]
	v_mfma_f32_16x16x32_bf16 v[118:121], v[132:135], v[198:201], v[118:121]
	v_mfma_f32_16x16x32_bf16 v[114:117], v[172:175], v[198:201], v[114:117]
	v_mfma_f32_16x16x32_bf16 v[102:105], v[132:135], v[214:217], v[102:105]
	v_mfma_f32_16x16x32_bf16 v[98:101], v[172:175], v[214:217], v[98:101]
	v_mfma_f32_16x16x32_bf16 v[126:129], v[136:139], v[194:197], v[126:129]
	v_mfma_f32_16x16x32_bf16 v[122:125], v[186:189], v[194:197], v[122:125]
	v_mfma_f32_16x16x32_bf16 v[118:121], v[136:139], v[202:205], v[118:121]
	v_mfma_f32_16x16x32_bf16 v[114:117], v[186:189], v[202:205], v[114:117]
	v_mfma_f32_16x16x32_bf16 v[110:113], v[132:135], v[206:209], v[110:113]
	v_mfma_f32_16x16x32_bf16 v[106:109], v[172:175], v[206:209], v[106:109]
	v_mfma_f32_16x16x32_bf16 v[102:105], v[136:139], v[218:221], v[102:105]
	v_mfma_f32_16x16x32_bf16 v[98:101], v[186:189], v[218:221], v[98:101]
	v_mfma_f32_16x16x32_bf16 v[222:225], v[136:139], v[210:213], v[110:113]
	v_mfma_f32_16x16x32_bf16 v[226:229], v[186:189], v[210:213], v[106:109]
	s_barrier
	s_nop 1
	ds_read_b128 v[106:109], v157
	ds_read_b128 v[110:113], v157 offset:1024
	ds_read_b128 v[230:233], v157 offset:2048
	ds_read_b128 v[154:157], v157 offset:3072
	s_barrier
; #define LDA(dst,b,h) for(int m=0;m<4;++m)for(int k=0;k<2;++k) \
;     dst[m][k]=*reinterpret_cast<const bf16x8*>((char*)SA(b,h)+lds_byte(wr*64+m*16+fr,k*32+fq*8))
; #define LDB(dst,b,h) for(int n=0;n<2;++n)for(int k=0;k<2;++k) \
;     dst[n][k]=*reinterpret_cast<const bf16x8*>((char*)SB(b,h)+lds_byte(wc*32+n*16+fr,k*32+fq*8))
; #define MMA(ai,bj,At,Bt_) do{__builtin_amdgcn_s_setprio(1); \
;     for(int m=0;m<4;++m)for(int n=0;n<2;++n)for(int k=0;k<2;++k) \
;       acc[ai][bj][m][n]=__builtin_amdgcn_mfma_f32_16x16x32_bf16(Bt_[n][k],At[m][k],acc[ai][bj][m][n],0,0,0); \
;     __builtin_amdgcn_s_setprio(0);}while(0)
; #define WAIT_V(n) asm volatile("s_waitcnt vmcnt(" #n ")":::"memory")
; #define WAIT_L(n) asm volatile("s_waitcnt lgkmcnt(" #n ")":::"memory")
; #define BAR __builtin_amdgcn_s_barrier()
; template <int EPI>
; __device__ __forceinline__ void gemm_run(const GD& c, const bool has_next, const GD& nx, const Ctx& e, bf16* shm, float* rs, float* rs_nxt, float* racc_) {
;     ...
;     LDB(B1,0,1); BAR; WAIT_L(0); MMA(0,1,At,B1); BAR;
;     LDA(At,0,1); WAIT_V(4); BAR; WAIT_L(0); MMA(1,0,At,B0); MMA(1,1,At,B1); BAR; }
;   { LDB(B0,1,0); LDA(At,1,0); WAIT_V(2); BAR; WAIT_L(0); MMA(0,0,At,B0); BAR;
	s_waitcnt lgkmcnt(0)
	v_mfma_f32_16x16x32_bf16 v[86:89], v[106:109], v[198:201], v[86:89]
	v_mfma_f32_16x16x32_bf16 v[82:85], v[230:233], v[198:201], v[82:85]
	v_mfma_f32_16x16x32_bf16 v[70:73], v[106:109], v[214:217], v[70:73]
	v_mfma_f32_16x16x32_bf16 v[66:69], v[230:233], v[214:217], v[66:69]
	v_mfma_f32_16x16x32_bf16 v[94:97], v[106:109], v[190:193], v[94:97]
	v_mfma_f32_16x16x32_bf16 v[90:93], v[230:233], v[190:193], v[90:93]
	v_mfma_f32_16x16x32_bf16 v[86:89], v[110:113], v[202:205], v[86:89]
	v_mfma_f32_16x16x32_bf16 v[82:85], v[154:157], v[202:205], v[82:85]
	v_mfma_f32_16x16x32_bf16 v[78:81], v[106:109], v[206:209], v[78:81]
	v_mfma_f32_16x16x32_bf16 v[74:77], v[230:233], v[206:209], v[74:77]
	v_mfma_f32_16x16x32_bf16 v[70:73], v[110:113], v[218:221], v[70:73]
	v_mfma_f32_16x16x32_bf16 v[66:69], v[154:157], v[218:221], v[66:69]
	v_mfma_f32_16x16x32_bf16 v[234:237], v[110:113], v[194:197], v[94:97]
	v_mfma_f32_16x16x32_bf16 v[190:193], v[154:157], v[194:197], v[90:93]
	v_mfma_f32_16x16x32_bf16 v[194:197], v[110:113], v[210:213], v[78:81]
	v_mfma_f32_16x16x32_bf16 v[198:201], v[154:157], v[210:213], v[74:77]
	s_barrier
	s_nop 0
	ds_read_b128 v[74:77], v150 offset:16384
	ds_read_b128 v[78:81], v150 offset:17408
	ds_read_b128 v[90:93], v149 offset:16384
	ds_read_b128 v[94:97], v149 offset:17408
	ds_read_b128 v[202:205], v148 offset:16384
	ds_read_b128 v[206:209], v148 offset:17408
	ds_read_b128 v[210:213], v147 offset:16384
	ds_read_b128 v[214:217], v147 offset:17408
	s_waitcnt vmcnt(4)
	s_barrier
	s_waitcnt lgkmcnt(0)
	v_mfma_f32_16x16x32_bf16 v[62:65], v[132:135], v[74:77], v[62:65]
	v_mfma_f32_16x16x32_bf16 v[58:61], v[172:175], v[74:77], v[58:61]
	v_mfma_f32_16x16x32_bf16 v[54:57], v[132:135], v[90:93], v[54:57]
	v_mfma_f32_16x16x32_bf16 v[50:53], v[172:175], v[90:93], v[50:53]
	v_mfma_f32_16x16x32_bf16 v[38:41], v[132:135], v[210:213], v[38:41]
	v_mfma_f32_16x16x32_bf16 v[34:37], v[172:175], v[210:213], v[34:37]
	v_mfma_f32_16x16x32_bf16 v[62:65], v[136:139], v[78:81], v[62:65]
	v_mfma_f32_16x16x32_bf16 v[58:61], v[186:189], v[78:81], v[58:61]
	v_mfma_f32_16x16x32_bf16 v[54:57], v[136:139], v[94:97], v[54:57]
	v_mfma_f32_16x16x32_bf16 v[50:53], v[186:189], v[94:97], v[50:53]
	v_mfma_f32_16x16x32_bf16 v[46:49], v[132:135], v[202:205], v[46:49]
	v_mfma_f32_16x16x32_bf16 v[42:45], v[172:175], v[202:205], v[42:45]
	v_mfma_f32_16x16x32_bf16 v[38:41], v[136:139], v[214:217], v[38:41]
	v_mfma_f32_16x16x32_bf16 v[34:37], v[186:189], v[214:217], v[34:37]
	v_mfma_f32_16x16x32_bf16 v[218:221], v[136:139], v[206:209], v[46:49]
	v_mfma_f32_16x16x32_bf16 v[238:241], v[186:189], v[206:209], v[42:45]
	v_mfma_f32_16x16x32_bf16 v[22:25], v[106:109], v[90:93], v[22:25]
	v_mfma_f32_16x16x32_bf16 v[18:21], v[230:233], v[90:93], v[18:21]
	v_mfma_f32_16x16x32_bf16 v[6:9], v[106:109], v[210:213], v[6:9]
	v_mfma_f32_16x16x32_bf16 v[2:5], v[230:233], v[210:213], v[2:5]
	v_mfma_f32_16x16x32_bf16 v[30:33], v[106:109], v[74:77], v[30:33]
	v_mfma_f32_16x16x32_bf16 v[26:29], v[230:233], v[74:77], v[26:29]
	v_mfma_f32_16x16x32_bf16 v[22:25], v[110:113], v[94:97], v[22:25]
	v_mfma_f32_16x16x32_bf16 v[18:21], v[154:157], v[94:97], v[18:21]
	v_mfma_f32_16x16x32_bf16 v[14:17], v[106:109], v[202:205], v[14:17]
	v_mfma_f32_16x16x32_bf16 v[10:13], v[230:233], v[202:205], v[10:13]
	v_mfma_f32_16x16x32_bf16 v[6:9], v[110:113], v[214:217], v[6:9]
	v_mfma_f32_16x16x32_bf16 v[2:5], v[154:157], v[214:217], v[2:5]
	v_mfma_f32_16x16x32_bf16 v[132:135], v[110:113], v[78:81], v[30:33]
	v_mfma_f32_16x16x32_bf16 v[136:139], v[154:157], v[78:81], v[26:29]
	v_mfma_f32_16x16x32_bf16 v[170:173], v[110:113], v[206:209], v[14:17]
	v_mfma_f32_16x16x32_bf16 v[186:189], v[154:157], v[206:209], v[10:13]
	s_barrier
	s_nop 0
	ds_read_b128 v[10:13], v153
	ds_read_b128 v[14:17], v153 offset:1024
	ds_read_b128 v[154:157], v153 offset:2048
	ds_read_b128 v[202:205], v153 offset:3072
	ds_read_b128 v[26:29], v150 offset:32768
	ds_read_b128 v[30:33], v150 offset:33792
	ds_read_b128 v[42:45], v149 offset:32768
	ds_read_b128 v[46:49], v149 offset:33792
	ds_read_b128 v[206:209], v148 offset:32768
	ds_read_b128 v[210:213], v148 offset:33792
	ds_read_b128 v[214:217], v147 offset:32768
	ds_read_b128 v[230:233], v147 offset:33792
	s_waitcnt vmcnt(2)
	s_barrier
; #define LDA(dst,b,h) for(int m=0;m<4;++m)for(int k=0;k<2;++k) \
;     dst[m][k]=*reinterpret_cast<const bf16x8*>((char*)SA(b,h)+lds_byte(wr*64+m*16+fr,k*32+fq*8))
; #define LDB(dst,b,h) for(int n=0;n<2;++n)for(int k=0;k<2;++k) \
;     dst[n][k]=*reinterpret_cast<const bf16x8*>((char*)SB(b,h)+lds_byte(wc*32+n*16+fr,k*32+fq*8))
; #define MMA(ai,bj,At,Bt_) do{__builtin_amdgcn_s_setprio(1); \
;     for(int m=0;m<4;++m)for(int n=0;n<2;++n)for(int k=0;k<2;++k) \
;       acc[ai][bj][m][n]=__builtin_amdgcn_mfma_f32_16x16x32_bf16(Bt_[n][k],At[m][k],acc[ai][bj][m][n],0,0,0); \
;     __builtin_amdgcn_s_setprio(0);}while(0)
; #define WAIT_V(n) asm volatile("s_waitcnt vmcnt(" #n ")":::"memory")
; #define WAIT_L(n) asm volatile("s_waitcnt lgkmcnt(" #n ")":::"memory")
; #define BAR __builtin_amdgcn_s_barrier()
; template <int EPI>
; __device__ __forceinline__ void gemm_run(const GD& c, const bool has_next, const GD& nx, const Ctx& e, bf16* shm, float* rs, float* rs_nxt, float* racc_) {
;     ...
;   { LDB(B0,1,0); LDA(At,1,0); WAIT_V(2); BAR; WAIT_L(0); MMA(0,0,At,B0); BAR;
;     LDB(B1,1,1); WAIT_V(0); BAR; WAIT_L(0); MMA(0,1,At,B1); BAR;
;     LDA(At,1,1); BAR; WAIT_L(0); MMA(1,0,At,B0); MMA(1,1,At,B1); BAR; }
;   if(wr==0)BAR;
	s_waitcnt lgkmcnt(0)
	v_mfma_f32_16x16x32_bf16 v[74:77], v[10:13], v[26:29], v[126:129]
	v_mfma_f32_16x16x32_bf16 v[126:129], v[14:17], v[30:33], v[74:77]
	v_mfma_f32_16x16x32_bf16 v[74:77], v[154:157], v[26:29], v[122:125]
	v_mfma_f32_16x16x32_bf16 v[122:125], v[202:205], v[30:33], v[74:77]
	v_mfma_f32_16x16x32_bf16 v[74:77], v[10:13], v[42:45], v[118:121]
	v_mfma_f32_16x16x32_bf16 v[110:113], v[14:17], v[46:49], v[74:77]
	v_mfma_f32_16x16x32_bf16 v[74:77], v[154:157], v[42:45], v[114:117]
	v_mfma_f32_16x16x32_bf16 v[106:109], v[202:205], v[46:49], v[74:77]
	v_mfma_f32_16x16x32_bf16 v[74:77], v[10:13], v[206:209], v[222:225]
	v_mfma_f32_16x16x32_bf16 v[94:97], v[14:17], v[210:213], v[74:77]
	v_mfma_f32_16x16x32_bf16 v[74:77], v[154:157], v[206:209], v[226:229]
	v_mfma_f32_16x16x32_bf16 v[90:93], v[202:205], v[210:213], v[74:77]
	v_mfma_f32_16x16x32_bf16 v[74:77], v[10:13], v[214:217], v[102:105]
	v_mfma_f32_16x16x32_bf16 v[78:81], v[14:17], v[230:233], v[74:77]
	v_mfma_f32_16x16x32_bf16 v[74:77], v[154:157], v[214:217], v[98:101]
	v_mfma_f32_16x16x32_bf16 v[74:77], v[202:205], v[230:233], v[74:77]
	s_barrier
	ds_read_b128 v[222:225], v151
	ds_read_b128 v[226:229], v151 offset:1024
	ds_read_b128 v[242:245], v151 offset:2048
	ds_read_b128 v[246:249], v151 offset:3072
	s_waitcnt vmcnt(0)
	s_barrier
	s_waitcnt lgkmcnt(0)
	v_mfma_f32_16x16x32_bf16 v[98:101], v[222:225], v[26:29], v[234:237]
	v_mfma_f32_16x16x32_bf16 v[26:29], v[242:245], v[26:29], v[190:193]
	v_mfma_f32_16x16x32_bf16 v[114:117], v[246:249], v[30:33], v[26:29]
	v_mfma_f32_16x16x32_bf16 v[26:29], v[222:225], v[42:45], v[86:89]
	v_mfma_f32_16x16x32_bf16 v[102:105], v[226:229], v[46:49], v[26:29]
	v_mfma_f32_16x16x32_bf16 v[26:29], v[242:245], v[42:45], v[82:85]
	v_mfma_f32_16x16x32_bf16 v[118:121], v[226:229], v[30:33], v[98:101]
	v_mfma_f32_16x16x32_bf16 v[98:101], v[246:249], v[46:49], v[26:29]
	v_mfma_f32_16x16x32_bf16 v[26:29], v[222:225], v[206:209], v[194:197]
	v_mfma_f32_16x16x32_bf16 v[86:89], v[226:229], v[210:213], v[26:29]
	v_mfma_f32_16x16x32_bf16 v[26:29], v[242:245], v[206:209], v[198:201]
	v_mfma_f32_16x16x32_bf16 v[82:85], v[246:249], v[210:213], v[26:29]
	v_mfma_f32_16x16x32_bf16 v[26:29], v[222:225], v[214:217], v[70:73]
	v_mfma_f32_16x16x32_bf16 v[70:73], v[226:229], v[230:233], v[26:29]
	v_mfma_f32_16x16x32_bf16 v[26:29], v[242:245], v[214:217], v[66:69]
	v_mfma_f32_16x16x32_bf16 v[66:69], v[246:249], v[230:233], v[26:29]
	s_barrier
	ds_read_b128 v[190:193], v150 offset:49152
	ds_read_b128 v[150:153], v150 offset:50176
	ds_read_b128 v[194:197], v149 offset:49152
	ds_read_b128 v[198:201], v149 offset:50176
	ds_read_b128 v[206:209], v148 offset:49152
	ds_read_b128 v[210:213], v148 offset:50176
	ds_read_b128 v[214:217], v147 offset:49152
	ds_read_b128 v[230:233], v147 offset:50176
	s_barrier
	s_waitcnt lgkmcnt(0)
	v_mfma_f32_16x16x32_bf16 v[26:29], v[10:13], v[190:193], v[62:65]
	v_mfma_f32_16x16x32_bf16 v[62:65], v[14:17], v[150:153], v[26:29]
	v_mfma_f32_16x16x32_bf16 v[26:29], v[154:157], v[190:193], v[58:61]
	v_mfma_f32_16x16x32_bf16 v[58:61], v[202:205], v[150:153], v[26:29]
	v_mfma_f32_16x16x32_bf16 v[26:29], v[10:13], v[194:197], v[54:57]
	v_mfma_f32_16x16x32_bf16 v[46:49], v[14:17], v[198:201], v[26:29]
	v_mfma_f32_16x16x32_bf16 v[26:29], v[154:157], v[194:197], v[50:53]
	v_mfma_f32_16x16x32_bf16 v[42:45], v[202:205], v[198:201], v[26:29]
	v_mfma_f32_16x16x32_bf16 v[26:29], v[10:13], v[206:209], v[218:221]
	v_mfma_f32_16x16x32_bf16 v[10:13], v[10:13], v[214:217], v[38:41]
	v_mfma_f32_16x16x32_bf16 v[30:33], v[14:17], v[210:213], v[26:29]
	v_mfma_f32_16x16x32_bf16 v[26:29], v[154:157], v[206:209], v[238:241]
	v_mfma_f32_16x16x32_bf16 v[14:17], v[14:17], v[230:233], v[10:13]
	v_mfma_f32_16x16x32_bf16 v[10:13], v[154:157], v[214:217], v[34:37]
	v_mfma_f32_16x16x32_bf16 v[26:29], v[202:205], v[210:213], v[26:29]
	v_mfma_f32_16x16x32_bf16 v[10:13], v[202:205], v[230:233], v[10:13]
	v_mfma_f32_16x16x32_bf16 v[34:37], v[222:225], v[190:193], v[132:135]
	v_mfma_f32_16x16x32_bf16 v[54:57], v[226:229], v[150:153], v[34:37]
	v_mfma_f32_16x16x32_bf16 v[34:37], v[242:245], v[190:193], v[136:139]
	v_mfma_f32_16x16x32_bf16 v[18:21], v[242:245], v[194:197], v[18:21]
	v_mfma_f32_16x16x32_bf16 v[50:53], v[246:249], v[150:153], v[34:37]
	v_mfma_f32_16x16x32_bf16 v[22:25], v[222:225], v[194:197], v[22:25]
	v_mfma_f32_16x16x32_bf16 v[34:37], v[246:249], v[198:201], v[18:21]
	v_mfma_f32_16x16x32_bf16 v[18:21], v[222:225], v[206:209], v[170:173]
	v_mfma_f32_16x16x32_bf16 v[38:41], v[226:229], v[198:201], v[22:25]
	v_mfma_f32_16x16x32_bf16 v[22:25], v[226:229], v[210:213], v[18:21]
	v_mfma_f32_16x16x32_bf16 v[18:21], v[242:245], v[206:209], v[186:189]
	v_mfma_f32_16x16x32_bf16 v[6:9], v[222:225], v[214:217], v[6:9]
	v_mfma_f32_16x16x32_bf16 v[2:5], v[242:245], v[214:217], v[2:5]
	v_mfma_f32_16x16x32_bf16 v[18:21], v[246:249], v[210:213], v[18:21]
	v_mfma_f32_16x16x32_bf16 v[6:9], v[226:229], v[230:233], v[6:9]
	v_mfma_f32_16x16x32_bf16 v[2:5], v[246:249], v[230:233], v[2:5]
	v_cmp_gt_u32_e32 vcc, s96, v142
	s_barrier
	s_and_saveexec_b64 s[2:3], vcc
	s_cbranch_execz .LBB0_983
	s_barrier

; #define STAGE_A(P,br,kt) STAGE_G(P,c.A,c.lda,br,(long)(kt)*c.kstr)
; #define STAGE_B(P,br,kt) STAGE_G(P,c.Bt,c.K,br,(long)(kt)*BK)
; #define LDA(dst,b,h) for(int m=0;m<4;++m)for(int k=0;k<2;++k) \
;     dst[m][k]=*reinterpret_cast<const bf16x8*>((char*)SA(b,h)+lds_byte(wr*64+m*16+fr,k*32+fq*8))
; #define LDB(dst,b,h) for(int n=0;n<2;++n)for(int k=0;k<2;++k) \
;     dst[n][k]=*reinterpret_cast<const bf16x8*>((char*)SB(b,h)+lds_byte(wc*32+n*16+fr,k*32+fq*8))
; #define MMA(ai,bj,At,Bt_) do{__builtin_amdgcn_s_setprio(1); \
;     for(int m=0;m<4;++m)for(int n=0;n<2;++n)for(int k=0;k<2;++k) \
;       acc[ai][bj][m][n]=__builtin_amdgcn_mfma_f32_16x16x32_bf16(Bt_[n][k],At[m][k],acc[ai][bj][m][n],0,0,0); \
;     __builtin_amdgcn_s_setprio(0);}while(0)
; #define WAIT_L(n) asm volatile("s_waitcnt lgkmcnt(" #n ")":::"memory")
; #define BAR __builtin_amdgcn_s_barrier()
; #define SCHED __builtin_amdgcn_sched_barrier(0)
; template <int EPI>
; __device__ __forceinline__ void gemm_run(const GD& c, const bool has_next, const GD& nx, const Ctx& e, bf16* shm, float* rs, float* rs_nxt, float* racc_) {
;     ...
;     LDB(B0,0,0); SCHED; LDA(At,0,0); STAGE_A(SA(1,1),brow+HALF,t+1);
;     WAIT_L(8); BAR; WAIT_L(0); MMA(0,0,At,B0); BAR; SCHED;
;     LDB(B1,0,1); STAGE_B(SB(0,0),bcol,t+2);
;     BAR; WAIT_L(0); MMA(0,1,At,B1); BAR;
;     LDA(At,0,1); STAGE_A(SA(0,0),brow,t+2);
;     BAR; WAIT_L(0); MMA(1,0,At,B0); BAR; SCHED;
.LBB0_1035:
	ds_read_b128 v[168:171], v155
	ds_read_b128 v[172:175], v155 offset:1024
	ds_read_b128 v[186:189], v155 offset:2048
	ds_read_b128 v[190:193], v155 offset:3072
	v_add_u32_e32 v163, 0xc000, v142
	v_lshl_add_u64 v[182:183], s[6:7], 0, v[132:133]
	v_readfirstlane_b32 s3, v163
	v_add_u32_e32 v166, 0xe000, v142
	v_lshl_add_u64 v[156:157], v[182:183], 0, s[28:29]
	s_mov_b32 m0, s3
	v_lshl_add_u64 v[242:243], s[6:7], 0, v[134:135]
	v_readfirstlane_b32 s3, v166
	ds_read_b128 v[158:161], v146
	ds_read_b128 v[194:197], v146 offset:1024
	ds_read_b128 v[198:201], v145
	ds_read_b128 v[202:205], v145 offset:1024
	ds_read_b128 v[206:209], v144
	ds_read_b128 v[210:213], v144 offset:1024
	ds_read_b128 v[214:217], v143
	ds_read_b128 v[218:221], v143 offset:1024
	global_load_lds_dwordx4 v[156:157], off
	v_lshl_add_u64 v[156:157], v[242:243], 0, s[28:29]
	s_mov_b32 m0, s3
	s_nop 0
	global_load_lds_dwordx4 v[156:157], off
	s_waitcnt lgkmcnt(8)
	s_barrier
	s_waitcnt lgkmcnt(0)
	v_mfma_f32_16x16x32_bf16 v[126:129], v[168:171], v[158:161], v[126:129]
	v_mfma_f32_16x16x32_bf16 v[122:125], v[186:189], v[158:161], v[122:125]
	v_mfma_f32_16x16x32_bf16 v[118:121], v[168:171], v[198:201], v[118:121]
	v_mfma_f32_16x16x32_bf16 v[114:117], v[186:189], v[198:201], v[114:117]
	v_mfma_f32_16x16x32_bf16 v[110:113], v[168:171], v[206:209], v[110:113]
	v_mfma_f32_16x16x32_bf16 v[106:109], v[186:189], v[206:209], v[106:109]
	v_mfma_f32_16x16x32_bf16 v[102:105], v[168:171], v[214:217], v[102:105]
	v_mfma_f32_16x16x32_bf16 v[98:101], v[186:189], v[214:217], v[98:101]
	v_mfma_f32_16x16x32_bf16 v[126:129], v[172:175], v[194:197], v[126:129]
	v_mfma_f32_16x16x32_bf16 v[122:125], v[190:193], v[194:197], v[122:125]
	v_mfma_f32_16x16x32_bf16 v[118:121], v[172:175], v[202:205], v[118:121]
	v_mfma_f32_16x16x32_bf16 v[114:117], v[190:193], v[202:205], v[114:117]
	v_mfma_f32_16x16x32_bf16 v[110:113], v[172:175], v[210:213], v[110:113]
	v_mfma_f32_16x16x32_bf16 v[106:109], v[190:193], v[210:213], v[106:109]
	v_mfma_f32_16x16x32_bf16 v[102:105], v[172:175], v[218:221], v[102:105]
	v_mfma_f32_16x16x32_bf16 v[98:101], v[190:193], v[218:221], v[98:101]
	s_barrier
	v_add_u32_e32 v156, s33, v148
	v_lshl_add_u64 v[244:245], s[6:7], 0, v[136:137]
	v_readfirstlane_b32 s3, v156
	v_add_u32_e32 v157, 0x2000, v156
	v_lshl_add_u64 v[238:239], v[244:245], 0, s[30:31]
	s_mov_b32 m0, s3
	v_lshl_add_u64 v[246:247], s[6:7], 0, v[138:139]
	v_readfirstlane_b32 s3, v157
	ds_read_b128 v[222:225], v154
	ds_read_b128 v[226:229], v154 offset:1024
	ds_read_b128 v[230:233], v154 offset:2048
	ds_read_b128 v[234:237], v154 offset:3072
	global_load_lds_dwordx4 v[238:239], off
	v_lshl_add_u64 v[238:239], v[246:247], 0, s[30:31]
	s_mov_b32 m0, s3
	s_nop 0
	global_load_lds_dwordx4 v[238:239], off
	s_barrier
	s_waitcnt lgkmcnt(0)
	v_mfma_f32_16x16x32_bf16 v[94:97], v[222:225], v[158:161], v[94:97]
	v_mfma_f32_16x16x32_bf16 v[90:93], v[230:233], v[158:161], v[90:93]
	v_mfma_f32_16x16x32_bf16 v[86:89], v[222:225], v[198:201], v[86:89]
	v_mfma_f32_16x16x32_bf16 v[82:85], v[230:233], v[198:201], v[82:85]
	v_mfma_f32_16x16x32_bf16 v[78:81], v[222:225], v[206:209], v[78:81]
	v_mfma_f32_16x16x32_bf16 v[74:77], v[230:233], v[206:209], v[74:77]
	v_mfma_f32_16x16x32_bf16 v[70:73], v[222:225], v[214:217], v[70:73]
	v_mfma_f32_16x16x32_bf16 v[66:69], v[230:233], v[214:217], v[66:69]
	v_mfma_f32_16x16x32_bf16 v[94:97], v[226:229], v[194:197], v[94:97]
	v_mfma_f32_16x16x32_bf16 v[90:93], v[234:237], v[194:197], v[90:93]
	v_mfma_f32_16x16x32_bf16 v[86:89], v[226:229], v[202:205], v[86:89]
	v_mfma_f32_16x16x32_bf16 v[82:85], v[234:237], v[202:205], v[82:85]
	v_mfma_f32_16x16x32_bf16 v[78:81], v[226:229], v[210:213], v[78:81]
	v_mfma_f32_16x16x32_bf16 v[74:77], v[234:237], v[210:213], v[74:77]
	v_mfma_f32_16x16x32_bf16 v[70:73], v[226:229], v[218:221], v[70:73]
	v_mfma_f32_16x16x32_bf16 v[66:69], v[234:237], v[218:221], v[66:69]
	v_readfirstlane_b32 s3, v142
	v_lshl_add_u64 v[158:159], v[182:183], 0, s[34:35]
	s_mov_b32 m0, s3
	s_barrier
	ds_read_b128 v[194:197], v146 offset:16384
	ds_read_b128 v[198:201], v146 offset:17408
	ds_read_b128 v[202:205], v145 offset:16384
	ds_read_b128 v[206:209], v145 offset:17408
	ds_read_b128 v[210:213], v144 offset:16384
	ds_read_b128 v[214:217], v144 offset:17408
	ds_read_b128 v[218:221], v143 offset:16384
	ds_read_b128 v[238:241], v143 offset:17408
	global_load_lds_dwordx4 v[158:159], off
	v_add_u32_e32 v158, 0x2000, v142
	v_lshl_add_u64 v[160:161], v[242:243], 0, s[34:35]
	v_readfirstlane_b32 s3, v158
	s_mov_b32 m0, s3
	s_nop 0
	global_load_lds_dwordx4 v[160:161], off
	s_barrier
	s_waitcnt lgkmcnt(0)
	v_mfma_f32_16x16x32_bf16 v[62:65], v[168:171], v[194:197], v[62:65]
	v_mfma_f32_16x16x32_bf16 v[58:61], v[186:189], v[194:197], v[58:61]
	v_mfma_f32_16x16x32_bf16 v[54:57], v[168:171], v[202:205], v[54:57]
	v_mfma_f32_16x16x32_bf16 v[50:53], v[186:189], v[202:205], v[50:53]
	v_mfma_f32_16x16x32_bf16 v[46:49], v[168:171], v[210:213], v[46:49]
	v_mfma_f32_16x16x32_bf16 v[42:45], v[186:189], v[210:213], v[42:45]
	v_mfma_f32_16x16x32_bf16 v[38:41], v[168:171], v[218:221], v[38:41]
	v_mfma_f32_16x16x32_bf16 v[34:37], v[186:189], v[218:221], v[34:37]
	v_mfma_f32_16x16x32_bf16 v[62:65], v[172:175], v[198:201], v[62:65]
	v_mfma_f32_16x16x32_bf16 v[58:61], v[190:193], v[198:201], v[58:61]
	v_mfma_f32_16x16x32_bf16 v[54:57], v[172:175], v[206:209], v[54:57]
	v_mfma_f32_16x16x32_bf16 v[50:53], v[190:193], v[206:209], v[50:53]
	v_mfma_f32_16x16x32_bf16 v[46:49], v[172:175], v[214:217], v[46:49]
	v_mfma_f32_16x16x32_bf16 v[42:45], v[190:193], v[214:217], v[42:45]
	v_mfma_f32_16x16x32_bf16 v[38:41], v[172:175], v[238:241], v[38:41]
	v_mfma_f32_16x16x32_bf16 v[34:37], v[190:193], v[238:241], v[34:37]
	s_barrier
; #define STAGE_A(P,br,kt) STAGE_G(P,c.A,c.lda,br,(long)(kt)*c.kstr)
; #define STAGE_B(P,br,kt) STAGE_G(P,c.Bt,c.K,br,(long)(kt)*BK)
; #define LDA(dst,b,h) for(int m=0;m<4;++m)for(int k=0;k<2;++k) \
;     dst[m][k]=*reinterpret_cast<const bf16x8*>((char*)SA(b,h)+lds_byte(wr*64+m*16+fr,k*32+fq*8))
; #define LDB(dst,b,h) for(int n=0;n<2;++n)for(int k=0;k<2;++k) \
;     dst[n][k]=*reinterpret_cast<const bf16x8*>((char*)SB(b,h)+lds_byte(wc*32+n*16+fr,k*32+fq*8))
; #define MMA(ai,bj,At,Bt_) do{__builtin_amdgcn_s_setprio(1); \
;     for(int m=0;m<4;++m)for(int n=0;n<2;++n)for(int k=0;k<2;++k) \
;       acc[ai][bj][m][n]=__builtin_amdgcn_mfma_f32_16x16x32_bf16(Bt_[n][k],At[m][k],acc[ai][bj][m][n],0,0,0); \
;     __builtin_amdgcn_s_setprio(0);}while(0)
; #define WAIT_V(n) asm volatile("s_waitcnt vmcnt(" #n ")":::"memory")
; #define WAIT_L(n) asm volatile("s_waitcnt lgkmcnt(" #n ")":::"memory")
; #define BAR __builtin_amdgcn_s_barrier()
; #define SCHED __builtin_amdgcn_sched_barrier(0)
; template <int EPI>
; __device__ __forceinline__ void gemm_run(const GD& c, const bool has_next, const GD& nx, const Ctx& e, bf16* shm, float* rs, float* rs_nxt, float* racc_) {
;     ...
;     STAGE_B(SB(0,1),bcol+HALF,t+2);
;     WAIT_V(6); BAR; MMA(1,1,At,B1); BAR;
;     LDB(B0,1,0); SCHED; LDA(At,1,0); STAGE_A(SA(0,1),brow+HALF,t+2);
;     WAIT_L(8); BAR; WAIT_L(0); MMA(0,0,At,B0); BAR; SCHED;
;     LDB(B1,1,1); STAGE_B(SB(1,0),bcol,t+3);
;     BAR; WAIT_L(0); MMA(0,1,At,B1); BAR;
;     LDA(At,1,1); STAGE_A(SA(1,0),brow,t+3);
	v_add_u32_e32 v159, s86, v148
	v_lshl_add_u64 v[160:161], v[244:245], 0, s[36:37]
	v_readfirstlane_b32 s3, v159
	s_mov_b32 m0, s3
	v_lshl_add_u64 v[168:169], v[246:247], 0, s[36:37]
	global_load_lds_dwordx4 v[160:161], off
	v_add_u32_e32 v160, 0x2000, v159
	s_nop 0
	v_readfirstlane_b32 s3, v160
	s_mov_b32 m0, s3
	s_nop 0
	global_load_lds_dwordx4 v[168:169], off
	s_waitcnt vmcnt(6)
	s_barrier
	v_mfma_f32_16x16x32_bf16 v[30:33], v[222:225], v[194:197], v[30:33]
	v_mfma_f32_16x16x32_bf16 v[26:29], v[230:233], v[194:197], v[26:29]
	v_mfma_f32_16x16x32_bf16 v[22:25], v[222:225], v[202:205], v[22:25]
	v_mfma_f32_16x16x32_bf16 v[18:21], v[230:233], v[202:205], v[18:21]
	v_mfma_f32_16x16x32_bf16 v[14:17], v[222:225], v[210:213], v[14:17]
	v_mfma_f32_16x16x32_bf16 v[10:13], v[230:233], v[210:213], v[10:13]
	v_mfma_f32_16x16x32_bf16 v[6:9], v[222:225], v[218:221], v[6:9]
	v_mfma_f32_16x16x32_bf16 v[2:5], v[230:233], v[218:221], v[2:5]
	v_mfma_f32_16x16x32_bf16 v[30:33], v[226:229], v[198:201], v[30:33]
	v_mfma_f32_16x16x32_bf16 v[26:29], v[234:237], v[198:201], v[26:29]
	v_mfma_f32_16x16x32_bf16 v[22:25], v[226:229], v[206:209], v[22:25]
	v_mfma_f32_16x16x32_bf16 v[18:21], v[234:237], v[206:209], v[18:21]
	v_mfma_f32_16x16x32_bf16 v[14:17], v[226:229], v[214:217], v[14:17]
	v_mfma_f32_16x16x32_bf16 v[10:13], v[234:237], v[214:217], v[10:13]
	v_mfma_f32_16x16x32_bf16 v[6:9], v[226:229], v[238:241], v[6:9]
	v_mfma_f32_16x16x32_bf16 v[2:5], v[234:237], v[238:241], v[2:5]
	s_barrier
	ds_read_b128 v[168:171], v149
	ds_read_b128 v[172:175], v149 offset:1024
	ds_read_b128 v[186:189], v149 offset:2048
	ds_read_b128 v[190:193], v149 offset:3072
	v_add_u32_e32 v161, 0x4000, v142
	v_add_u32_e32 v162, 0x6000, v142
	v_readfirstlane_b32 s3, v161
	v_lshl_add_u64 v[226:227], v[182:183], 0, s[38:39]
	s_mov_b32 m0, s3
	v_readfirstlane_b32 s3, v162
	ds_read_b128 v[194:197], v146 offset:32768
	ds_read_b128 v[198:201], v146 offset:33792
	ds_read_b128 v[202:205], v145 offset:32768
	ds_read_b128 v[206:209], v145 offset:33792
	ds_read_b128 v[210:213], v144 offset:32768
	ds_read_b128 v[214:217], v144 offset:33792
	ds_read_b128 v[218:221], v143 offset:32768
	ds_read_b128 v[222:225], v143 offset:33792
	global_load_lds_dwordx4 v[226:227], off
	v_lshl_add_u64 v[226:227], v[242:243], 0, s[38:39]
	s_mov_b32 m0, s3
	s_nop 0
	global_load_lds_dwordx4 v[226:227], off
	s_waitcnt lgkmcnt(8)
	s_barrier
	s_waitcnt lgkmcnt(0)
	v_mfma_f32_16x16x32_bf16 v[126:129], v[168:171], v[194:197], v[126:129]
	v_mfma_f32_16x16x32_bf16 v[122:125], v[186:189], v[194:197], v[122:125]
	v_mfma_f32_16x16x32_bf16 v[118:121], v[168:171], v[202:205], v[118:121]
	v_mfma_f32_16x16x32_bf16 v[114:117], v[186:189], v[202:205], v[114:117]
	v_mfma_f32_16x16x32_bf16 v[110:113], v[168:171], v[210:213], v[110:113]
	v_mfma_f32_16x16x32_bf16 v[106:109], v[186:189], v[210:213], v[106:109]
	v_mfma_f32_16x16x32_bf16 v[102:105], v[168:171], v[218:221], v[102:105]
	v_mfma_f32_16x16x32_bf16 v[98:101], v[186:189], v[218:221], v[98:101]
	v_mfma_f32_16x16x32_bf16 v[126:129], v[172:175], v[198:201], v[126:129]
	v_mfma_f32_16x16x32_bf16 v[122:125], v[190:193], v[198:201], v[122:125]
	v_mfma_f32_16x16x32_bf16 v[118:121], v[172:175], v[206:209], v[118:121]
	v_mfma_f32_16x16x32_bf16 v[114:117], v[190:193], v[206:209], v[114:117]
	v_mfma_f32_16x16x32_bf16 v[110:113], v[172:175], v[214:217], v[110:113]
	v_mfma_f32_16x16x32_bf16 v[106:109], v[190:193], v[214:217], v[106:109]
	v_mfma_f32_16x16x32_bf16 v[102:105], v[172:175], v[222:225], v[102:105]
	v_mfma_f32_16x16x32_bf16 v[98:101], v[190:193], v[222:225], v[98:101]
	s_barrier
	v_readfirstlane_b32 s3, v150
	v_add_u32_e32 v167, 0x2000, v150
	v_lshl_add_u64 v[248:249], v[244:245], 0, s[40:41]
	s_mov_b32 m0, s3
	v_readfirstlane_b32 s3, v167
	ds_read_b128 v[226:229], v147
	ds_read_b128 v[230:233], v147 offset:1024
	ds_read_b128 v[234:237], v147 offset:2048
	ds_read_b128 v[238:241], v147 offset:3072
	global_load_lds_dwordx4 v[248:249], off
	v_lshl_add_u64 v[248:249], v[246:247], 0, s[40:41]
	s_mov_b32 m0, s3
	s_nop 0
	global_load_lds_dwordx4 v[248:249], off
	s_barrier
	s_waitcnt lgkmcnt(0)
	v_mfma_f32_16x16x32_bf16 v[94:97], v[226:229], v[194:197], v[94:97]
	v_mfma_f32_16x16x32_bf16 v[90:93], v[234:237], v[194:197], v[90:93]
	v_mfma_f32_16x16x32_bf16 v[86:89], v[226:229], v[202:205], v[86:89]
	v_mfma_f32_16x16x32_bf16 v[82:85], v[234:237], v[202:205], v[82:85]
	v_readfirstlane_b32 s3, v151
	v_mfma_f32_16x16x32_bf16 v[78:81], v[226:229], v[210:213], v[78:81]
	v_lshl_add_u64 v[182:183], v[182:183], 0, s[42:43]
	v_mfma_f32_16x16x32_bf16 v[74:77], v[234:237], v[210:213], v[74:77]
	s_mov_b32 m0, s3
	v_mfma_f32_16x16x32_bf16 v[70:73], v[226:229], v[218:221], v[70:73]
	v_readfirstlane_b32 s3, v152
	v_mfma_f32_16x16x32_bf16 v[66:69], v[234:237], v[218:221], v[66:69]
	v_mfma_f32_16x16x32_bf16 v[94:97], v[230:233], v[198:201], v[94:97]
	v_mfma_f32_16x16x32_bf16 v[90:93], v[238:241], v[198:201], v[90:93]
	v_mfma_f32_16x16x32_bf16 v[86:89], v[230:233], v[206:209], v[86:89]
	v_mfma_f32_16x16x32_bf16 v[82:85], v[238:241], v[206:209], v[82:85]
	v_mfma_f32_16x16x32_bf16 v[78:81], v[230:233], v[214:217], v[78:81]
	v_mfma_f32_16x16x32_bf16 v[74:77], v[238:241], v[214:217], v[74:77]
	v_mfma_f32_16x16x32_bf16 v[70:73], v[230:233], v[222:225], v[70:73]
	v_mfma_f32_16x16x32_bf16 v[66:69], v[238:241], v[222:225], v[66:69]
	s_barrier
	ds_read_b128 v[194:197], v146 offset:49152
	ds_read_b128 v[198:201], v146 offset:50176
	ds_read_b128 v[202:205], v145 offset:49152
	ds_read_b128 v[206:209], v145 offset:50176
	ds_read_b128 v[210:213], v144 offset:49152
	ds_read_b128 v[214:217], v144 offset:50176
	ds_read_b128 v[218:221], v143 offset:49152
	ds_read_b128 v[222:225], v143 offset:50176
	global_load_lds_dwordx4 v[182:183], off
	v_lshl_add_u64 v[182:183], v[242:243], 0, s[42:43]
	s_mov_b32 m0, s3
	s_nop 0
	global_load_lds_dwordx4 v[182:183], off
	s_barrier
; #define STAGE_A(P,br,kt) STAGE_G(P,c.A,c.lda,br,(long)(kt)*c.kstr)
; #define STAGE_B(P,br,kt) STAGE_G(P,c.Bt,c.K,br,(long)(kt)*BK)
; #define LDA(dst,b,h) for(int m=0;m<4;++m)for(int k=0;k<2;++k) \
;     dst[m][k]=*reinterpret_cast<const bf16x8*>((char*)SA(b,h)+lds_byte(wr*64+m*16+fr,k*32+fq*8))
; #define LDB(dst,b,h) for(int n=0;n<2;++n)for(int k=0;k<2;++k) \
;     dst[n][k]=*reinterpret_cast<const bf16x8*>((char*)SB(b,h)+lds_byte(wc*32+n*16+fr,k*32+fq*8))
; #define MMA(ai,bj,At,Bt_) do{__builtin_amdgcn_s_setprio(1); \
;     for(int m=0;m<4;++m)for(int n=0;n<2;++n)for(int k=0;k<2;++k) \
;       acc[ai][bj][m][n]=__builtin_amdgcn_mfma_f32_16x16x32_bf16(Bt_[n][k],At[m][k],acc[ai][bj][m][n],0,0,0); \
;     __builtin_amdgcn_s_setprio(0);}while(0)
; #define WAIT_V(n) asm volatile("s_waitcnt vmcnt(" #n ")":::"memory")
; #define WAIT_L(n) asm volatile("s_waitcnt lgkmcnt(" #n ")":::"memory")
; #define BAR __builtin_amdgcn_s_barrier()
; #define SCHED __builtin_amdgcn_sched_barrier(0)
; template <int EPI>
; __device__ __forceinline__ void gemm_run(const GD& c, const bool has_next, const GD& nx, const Ctx& e, bf16* shm, float* rs, float* rs_nxt, float* racc_) {
;     ...
;     BAR; WAIT_L(0); MMA(1,0,At,B0); BAR; SCHED;
;     STAGE_B(SB(1,1),bcol+HALF,t+3);
;     WAIT_V(6); BAR; MMA(1,1,At,B1); BAR;
;   }
;   { LDB(B0,0,0); LDA(At,0,0); STAGE_A(SA(1,1),brow+HALF,nt-1);
;     BAR; WAIT_L(0); MMA(0,0,At,B0); BAR;
;     LDB(B1,0,1); BAR; WAIT_L(0); MMA(0,1,At,B1); BAR;
	s_waitcnt lgkmcnt(0)
	v_mfma_f32_16x16x32_bf16 v[62:65], v[168:171], v[194:197], v[62:65]
	v_mfma_f32_16x16x32_bf16 v[58:61], v[186:189], v[194:197], v[58:61]
	v_mfma_f32_16x16x32_bf16 v[54:57], v[168:171], v[202:205], v[54:57]
	v_mfma_f32_16x16x32_bf16 v[50:53], v[186:189], v[202:205], v[50:53]
	v_mfma_f32_16x16x32_bf16 v[46:49], v[168:171], v[210:213], v[46:49]
	v_mfma_f32_16x16x32_bf16 v[42:45], v[186:189], v[210:213], v[42:45]
	v_mfma_f32_16x16x32_bf16 v[38:41], v[168:171], v[218:221], v[38:41]
	v_mfma_f32_16x16x32_bf16 v[34:37], v[186:189], v[218:221], v[34:37]
	v_mfma_f32_16x16x32_bf16 v[62:65], v[172:175], v[198:201], v[62:65]
	v_mfma_f32_16x16x32_bf16 v[58:61], v[190:193], v[198:201], v[58:61]
	v_mfma_f32_16x16x32_bf16 v[54:57], v[172:175], v[206:209], v[54:57]
	v_mfma_f32_16x16x32_bf16 v[50:53], v[190:193], v[206:209], v[50:53]
	v_mfma_f32_16x16x32_bf16 v[46:49], v[172:175], v[214:217], v[46:49]
	v_mfma_f32_16x16x32_bf16 v[42:45], v[190:193], v[214:217], v[42:45]
	v_mfma_f32_16x16x32_bf16 v[38:41], v[172:175], v[222:225], v[38:41]
	v_mfma_f32_16x16x32_bf16 v[34:37], v[190:193], v[222:225], v[34:37]
	s_barrier
	v_readfirstlane_b32 s3, v153
	v_add_u32_e32 v167, 0x2000, v153
	v_lshl_add_u64 v[168:169], v[244:245], 0, s[44:45]
	s_mov_b32 m0, s3
	v_readfirstlane_b32 s3, v167
	global_load_lds_dwordx4 v[168:169], off
	v_lshl_add_u64 v[168:169], v[246:247], 0, s[44:45]
	s_mov_b32 m0, s3
	s_nop 0
	global_load_lds_dwordx4 v[168:169], off
	s_waitcnt vmcnt(6)
	s_barrier
	v_mfma_f32_16x16x32_bf16 v[30:33], v[226:229], v[194:197], v[30:33]
	v_mfma_f32_16x16x32_bf16 v[26:29], v[234:237], v[194:197], v[26:29]
	v_mfma_f32_16x16x32_bf16 v[22:25], v[226:229], v[202:205], v[22:25]
	v_mfma_f32_16x16x32_bf16 v[18:21], v[234:237], v[202:205], v[18:21]
	s_add_i32 s2, s2, 2
	v_mfma_f32_16x16x32_bf16 v[14:17], v[226:229], v[210:213], v[14:17]
	v_lshl_add_u64 v[132:133], v[132:133], 0, s[88:89]
	v_mfma_f32_16x16x32_bf16 v[10:13], v[234:237], v[210:213], v[10:13]
	v_lshl_add_u64 v[134:135], v[134:135], 0, s[88:89]
	v_mfma_f32_16x16x32_bf16 v[6:9], v[226:229], v[218:221], v[6:9]
	v_lshl_add_u64 v[136:137], v[136:137], 0, s[88:89]
	v_mfma_f32_16x16x32_bf16 v[2:5], v[234:237], v[218:221], v[2:5]
	s_cmp_lt_u32 s2, 12
	v_mfma_f32_16x16x32_bf16 v[30:33], v[230:233], v[198:201], v[30:33]
	v_lshl_add_u64 v[138:139], v[138:139], 0, s[88:89]
	v_mfma_f32_16x16x32_bf16 v[26:29], v[238:241], v[198:201], v[26:29]
	v_mfma_f32_16x16x32_bf16 v[22:25], v[230:233], v[206:209], v[22:25]
	v_mfma_f32_16x16x32_bf16 v[18:21], v[238:241], v[206:209], v[18:21]
	v_mfma_f32_16x16x32_bf16 v[14:17], v[230:233], v[214:217], v[14:17]
	v_mfma_f32_16x16x32_bf16 v[10:13], v[238:241], v[214:217], v[10:13]
	v_mfma_f32_16x16x32_bf16 v[6:9], v[230:233], v[222:225], v[6:9]
	v_mfma_f32_16x16x32_bf16 v[2:5], v[238:241], v[222:225], v[2:5]
	s_barrier
	s_cbranch_scc1 .LBB0_1035
	s_or_b32 s2, s14, 0x80
	s_ashr_i32 s3, s2, 31
	s_lshl_b64 s[2:3], s[2:3], 11
	s_add_u32 s2, s24, s2
	s_addc_u32 s3, s25, s3
	v_readfirstlane_b32 s5, v163
	v_lshl_add_u64 v[182:183], s[2:3], 0, v[0:1]
	s_mov_b32 m0, s5
	ds_read_b128 v[132:135], v155
	ds_read_b128 v[136:139], v155 offset:1024
	ds_read_b128 v[150:153], v155 offset:2048
	ds_read_b128 v[168:171], v155 offset:3072
	ds_read_b128 v[172:175], v146
	ds_read_b128 v[186:189], v146 offset:1024
	ds_read_b128 v[190:193], v145
	ds_read_b128 v[194:197], v145 offset:1024
	ds_read_b128 v[198:201], v144
	ds_read_b128 v[202:205], v144 offset:1024
	ds_read_b128 v[206:209], v143
	ds_read_b128 v[210:213], v143 offset:1024
	global_load_lds_dwordx4 v[182:183], off
	v_lshl_add_u64 v[182:183], s[2:3], 0, v[130:131]
	v_readfirstlane_b32 s2, v166
	s_mov_b32 m0, s2
	s_nop 0
	global_load_lds_dwordx4 v[182:183], off
	s_barrier
	s_waitcnt lgkmcnt(0)
	v_mfma_f32_16x16x32_bf16 v[126:129], v[132:135], v[172:175], v[126:129]
	v_mfma_f32_16x16x32_bf16 v[122:125], v[150:153], v[172:175], v[122:125]
	v_mfma_f32_16x16x32_bf16 v[118:121], v[132:135], v[190:193], v[118:121]
	v_mfma_f32_16x16x32_bf16 v[114:117], v[150:153], v[190:193], v[114:117]
	v_mfma_f32_16x16x32_bf16 v[102:105], v[132:135], v[206:209], v[102:105]
	v_mfma_f32_16x16x32_bf16 v[98:101], v[150:153], v[206:209], v[98:101]
	v_mfma_f32_16x16x32_bf16 v[126:129], v[136:139], v[186:189], v[126:129]
	v_mfma_f32_16x16x32_bf16 v[122:125], v[168:171], v[186:189], v[122:125]
	v_mfma_f32_16x16x32_bf16 v[118:121], v[136:139], v[194:197], v[118:121]
	v_mfma_f32_16x16x32_bf16 v[114:117], v[168:171], v[194:197], v[114:117]
	v_mfma_f32_16x16x32_bf16 v[110:113], v[132:135], v[198:201], v[110:113]
	v_mfma_f32_16x16x32_bf16 v[106:109], v[150:153], v[198:201], v[106:109]
	v_mfma_f32_16x16x32_bf16 v[102:105], v[136:139], v[210:213], v[102:105]
	v_mfma_f32_16x16x32_bf16 v[98:101], v[168:171], v[210:213], v[98:101]
	v_mfma_f32_16x16x32_bf16 v[214:217], v[136:139], v[202:205], v[110:113]
	v_mfma_f32_16x16x32_bf16 v[218:221], v[168:171], v[202:205], v[106:109]
	s_barrier
	s_nop 1
	ds_read_b128 v[106:109], v154
	ds_read_b128 v[110:113], v154 offset:1024
	ds_read_b128 v[222:225], v154 offset:2048
	ds_read_b128 v[226:229], v154 offset:3072
	s_barrier
; #define LDA(dst,b,h) for(int m=0;m<4;++m)for(int k=0;k<2;++k) \
;     dst[m][k]=*reinterpret_cast<const bf16x8*>((char*)SA(b,h)+lds_byte(wr*64+m*16+fr,k*32+fq*8))
; #define LDB(dst,b,h) for(int n=0;n<2;++n)for(int k=0;k<2;++k) \
;     dst[n][k]=*reinterpret_cast<const bf16x8*>((char*)SB(b,h)+lds_byte(wc*32+n*16+fr,k*32+fq*8))
; #define MMA(ai,bj,At,Bt_) do{__builtin_amdgcn_s_setprio(1); \
;     for(int m=0;m<4;++m)for(int n=0;n<2;++n)for(int k=0;k<2;++k) \
;       acc[ai][bj][m][n]=__builtin_amdgcn_mfma_f32_16x16x32_bf16(Bt_[n][k],At[m][k],acc[ai][bj][m][n],0,0,0); \
;     __builtin_amdgcn_s_setprio(0);}while(0)
; #define WAIT_V(n) asm volatile("s_waitcnt vmcnt(" #n ")":::"memory")
; #define WAIT_L(n) asm volatile("s_waitcnt lgkmcnt(" #n ")":::"memory")
; #define BAR __builtin_amdgcn_s_barrier()
; template <int EPI>
; __device__ __forceinline__ void gemm_run(const GD& c, const bool has_next, const GD& nx, const Ctx& e, bf16* shm, float* rs, float* rs_nxt, float* racc_) {
;     ...
;     LDB(B1,0,1); BAR; WAIT_L(0); MMA(0,1,At,B1); BAR;
;     LDA(At,0,1); WAIT_V(4); BAR; WAIT_L(0); MMA(1,0,At,B0); MMA(1,1,At,B1); BAR; }
;   { LDB(B0,1,0); LDA(At,1,0); WAIT_V(2); BAR; WAIT_L(0); MMA(0,0,At,B0); BAR;
	s_waitcnt lgkmcnt(0)
	v_mfma_f32_16x16x32_bf16 v[86:89], v[106:109], v[190:193], v[86:89]
	v_mfma_f32_16x16x32_bf16 v[82:85], v[222:225], v[190:193], v[82:85]
	v_mfma_f32_16x16x32_bf16 v[70:73], v[106:109], v[206:209], v[70:73]
	v_mfma_f32_16x16x32_bf16 v[66:69], v[222:225], v[206:209], v[66:69]
	v_mfma_f32_16x16x32_bf16 v[94:97], v[106:109], v[172:175], v[94:97]
	v_mfma_f32_16x16x32_bf16 v[90:93], v[222:225], v[172:175], v[90:93]
	v_mfma_f32_16x16x32_bf16 v[86:89], v[110:113], v[194:197], v[86:89]
	v_mfma_f32_16x16x32_bf16 v[82:85], v[226:229], v[194:197], v[82:85]
	v_mfma_f32_16x16x32_bf16 v[78:81], v[106:109], v[198:201], v[78:81]
	v_mfma_f32_16x16x32_bf16 v[74:77], v[222:225], v[198:201], v[74:77]
	v_mfma_f32_16x16x32_bf16 v[70:73], v[110:113], v[210:213], v[70:73]
	v_mfma_f32_16x16x32_bf16 v[66:69], v[226:229], v[210:213], v[66:69]
	v_mfma_f32_16x16x32_bf16 v[230:233], v[110:113], v[186:189], v[94:97]
	v_mfma_f32_16x16x32_bf16 v[172:175], v[226:229], v[186:189], v[90:93]
	v_mfma_f32_16x16x32_bf16 v[186:189], v[110:113], v[202:205], v[78:81]
	v_mfma_f32_16x16x32_bf16 v[190:193], v[226:229], v[202:205], v[74:77]
	s_barrier
	s_nop 0
	ds_read_b128 v[74:77], v146 offset:16384
	ds_read_b128 v[78:81], v146 offset:17408
	ds_read_b128 v[90:93], v145 offset:16384
	ds_read_b128 v[94:97], v145 offset:17408
	ds_read_b128 v[194:197], v144 offset:16384
	ds_read_b128 v[198:201], v144 offset:17408
	ds_read_b128 v[202:205], v143 offset:16384
	ds_read_b128 v[206:209], v143 offset:17408
	s_waitcnt vmcnt(4)
	s_barrier
	s_waitcnt lgkmcnt(0)
	v_mfma_f32_16x16x32_bf16 v[62:65], v[132:135], v[74:77], v[62:65]
	v_mfma_f32_16x16x32_bf16 v[58:61], v[150:153], v[74:77], v[58:61]
	v_mfma_f32_16x16x32_bf16 v[54:57], v[132:135], v[90:93], v[54:57]
	v_mfma_f32_16x16x32_bf16 v[50:53], v[150:153], v[90:93], v[50:53]
	v_mfma_f32_16x16x32_bf16 v[38:41], v[132:135], v[202:205], v[38:41]
	v_mfma_f32_16x16x32_bf16 v[34:37], v[150:153], v[202:205], v[34:37]
	v_mfma_f32_16x16x32_bf16 v[62:65], v[136:139], v[78:81], v[62:65]
	v_mfma_f32_16x16x32_bf16 v[58:61], v[168:171], v[78:81], v[58:61]
	v_mfma_f32_16x16x32_bf16 v[54:57], v[136:139], v[94:97], v[54:57]
	v_mfma_f32_16x16x32_bf16 v[50:53], v[168:171], v[94:97], v[50:53]
	v_mfma_f32_16x16x32_bf16 v[46:49], v[132:135], v[194:197], v[46:49]
	v_mfma_f32_16x16x32_bf16 v[42:45], v[150:153], v[194:197], v[42:45]
	v_mfma_f32_16x16x32_bf16 v[38:41], v[136:139], v[206:209], v[38:41]
	v_mfma_f32_16x16x32_bf16 v[34:37], v[168:171], v[206:209], v[34:37]
	v_mfma_f32_16x16x32_bf16 v[210:213], v[136:139], v[198:201], v[46:49]
	v_mfma_f32_16x16x32_bf16 v[234:237], v[168:171], v[198:201], v[42:45]
	v_mfma_f32_16x16x32_bf16 v[22:25], v[106:109], v[90:93], v[22:25]
	v_mfma_f32_16x16x32_bf16 v[18:21], v[222:225], v[90:93], v[18:21]
	v_mfma_f32_16x16x32_bf16 v[6:9], v[106:109], v[202:205], v[6:9]
	v_mfma_f32_16x16x32_bf16 v[2:5], v[222:225], v[202:205], v[2:5]
	v_mfma_f32_16x16x32_bf16 v[30:33], v[106:109], v[74:77], v[30:33]
	v_mfma_f32_16x16x32_bf16 v[26:29], v[222:225], v[74:77], v[26:29]
	v_mfma_f32_16x16x32_bf16 v[22:25], v[110:113], v[94:97], v[22:25]
	v_mfma_f32_16x16x32_bf16 v[18:21], v[226:229], v[94:97], v[18:21]
	v_mfma_f32_16x16x32_bf16 v[14:17], v[106:109], v[194:197], v[14:17]
	v_mfma_f32_16x16x32_bf16 v[10:13], v[222:225], v[194:197], v[10:13]
	v_mfma_f32_16x16x32_bf16 v[6:9], v[110:113], v[206:209], v[6:9]
	v_mfma_f32_16x16x32_bf16 v[2:5], v[226:229], v[206:209], v[2:5]
	v_mfma_f32_16x16x32_bf16 v[132:135], v[110:113], v[78:81], v[30:33]
	v_mfma_f32_16x16x32_bf16 v[136:139], v[226:229], v[78:81], v[26:29]
	v_mfma_f32_16x16x32_bf16 v[150:153], v[110:113], v[198:201], v[14:17]
	v_mfma_f32_16x16x32_bf16 v[166:169], v[226:229], v[198:201], v[10:13]
	s_barrier
	s_nop 0
	ds_read_b128 v[10:13], v149
	ds_read_b128 v[14:17], v149 offset:1024
	ds_read_b128 v[194:197], v149 offset:2048
	ds_read_b128 v[198:201], v149 offset:3072
	ds_read_b128 v[26:29], v146 offset:32768
	ds_read_b128 v[30:33], v146 offset:33792
	ds_read_b128 v[42:45], v145 offset:32768
	ds_read_b128 v[46:49], v145 offset:33792
	ds_read_b128 v[202:205], v144 offset:32768
	ds_read_b128 v[206:209], v144 offset:33792
	ds_read_b128 v[222:225], v143 offset:32768
	ds_read_b128 v[226:229], v143 offset:33792
	s_waitcnt vmcnt(2)
	s_barrier
; #define LDA(dst,b,h) for(int m=0;m<4;++m)for(int k=0;k<2;++k) \
;     dst[m][k]=*reinterpret_cast<const bf16x8*>((char*)SA(b,h)+lds_byte(wr*64+m*16+fr,k*32+fq*8))
; #define LDB(dst,b,h) for(int n=0;n<2;++n)for(int k=0;k<2;++k) \
;     dst[n][k]=*reinterpret_cast<const bf16x8*>((char*)SB(b,h)+lds_byte(wc*32+n*16+fr,k*32+fq*8))
; #define MMA(ai,bj,At,Bt_) do{__builtin_amdgcn_s_setprio(1); \
;     for(int m=0;m<4;++m)for(int n=0;n<2;++n)for(int k=0;k<2;++k) \
;       acc[ai][bj][m][n]=__builtin_amdgcn_mfma_f32_16x16x32_bf16(Bt_[n][k],At[m][k],acc[ai][bj][m][n],0,0,0); \
;     __builtin_amdgcn_s_setprio(0);}while(0)
; #define WAIT_V(n) asm volatile("s_waitcnt vmcnt(" #n ")":::"memory")
; #define WAIT_L(n) asm volatile("s_waitcnt lgkmcnt(" #n ")":::"memory")
; #define BAR __builtin_amdgcn_s_barrier()
; template <int EPI>
; __device__ __forceinline__ void gemm_run(const GD& c, const bool has_next, const GD& nx, const Ctx& e, bf16* shm, float* rs, float* rs_nxt, float* racc_) {
;     ...
;   { LDB(B0,1,0); LDA(At,1,0); WAIT_V(2); BAR; WAIT_L(0); MMA(0,0,At,B0); BAR;
;     LDB(B1,1,1); WAIT_V(0); BAR; WAIT_L(0); MMA(0,1,At,B1); BAR;
;     LDA(At,1,1); BAR; WAIT_L(0); MMA(1,0,At,B0); MMA(1,1,At,B1); BAR; }
;   if(wr==0)BAR;
	s_waitcnt lgkmcnt(0)
	v_mfma_f32_16x16x32_bf16 v[74:77], v[10:13], v[26:29], v[126:129]
	v_mfma_f32_16x16x32_bf16 v[126:129], v[14:17], v[30:33], v[74:77]
	v_mfma_f32_16x16x32_bf16 v[74:77], v[194:197], v[26:29], v[122:125]
	v_mfma_f32_16x16x32_bf16 v[122:125], v[198:201], v[30:33], v[74:77]
	v_mfma_f32_16x16x32_bf16 v[74:77], v[10:13], v[42:45], v[118:121]
	v_mfma_f32_16x16x32_bf16 v[110:113], v[14:17], v[46:49], v[74:77]
	v_mfma_f32_16x16x32_bf16 v[74:77], v[194:197], v[42:45], v[114:117]
	v_mfma_f32_16x16x32_bf16 v[106:109], v[198:201], v[46:49], v[74:77]
	v_mfma_f32_16x16x32_bf16 v[74:77], v[10:13], v[202:205], v[214:217]
	v_mfma_f32_16x16x32_bf16 v[94:97], v[14:17], v[206:209], v[74:77]
	v_mfma_f32_16x16x32_bf16 v[74:77], v[194:197], v[202:205], v[218:221]
	v_mfma_f32_16x16x32_bf16 v[90:93], v[198:201], v[206:209], v[74:77]
	v_mfma_f32_16x16x32_bf16 v[74:77], v[10:13], v[222:225], v[102:105]
	v_mfma_f32_16x16x32_bf16 v[78:81], v[14:17], v[226:229], v[74:77]
	v_mfma_f32_16x16x32_bf16 v[74:77], v[194:197], v[222:225], v[98:101]
	v_mfma_f32_16x16x32_bf16 v[74:77], v[198:201], v[226:229], v[74:77]
	s_barrier
	ds_read_b128 v[214:217], v147
	ds_read_b128 v[218:221], v147 offset:1024
	ds_read_b128 v[238:241], v147 offset:2048
	ds_read_b128 v[242:245], v147 offset:3072
	s_waitcnt vmcnt(0)
	s_barrier
	s_waitcnt lgkmcnt(0)
	v_mfma_f32_16x16x32_bf16 v[98:101], v[214:217], v[26:29], v[230:233]
	v_mfma_f32_16x16x32_bf16 v[26:29], v[238:241], v[26:29], v[172:175]
	v_mfma_f32_16x16x32_bf16 v[114:117], v[242:245], v[30:33], v[26:29]
	v_mfma_f32_16x16x32_bf16 v[26:29], v[214:217], v[42:45], v[86:89]
	v_mfma_f32_16x16x32_bf16 v[102:105], v[218:221], v[46:49], v[26:29]
	v_mfma_f32_16x16x32_bf16 v[26:29], v[238:241], v[42:45], v[82:85]
	v_mfma_f32_16x16x32_bf16 v[118:121], v[218:221], v[30:33], v[98:101]
	v_mfma_f32_16x16x32_bf16 v[98:101], v[242:245], v[46:49], v[26:29]
	v_mfma_f32_16x16x32_bf16 v[26:29], v[214:217], v[202:205], v[186:189]
	v_mfma_f32_16x16x32_bf16 v[86:89], v[218:221], v[206:209], v[26:29]
	v_mfma_f32_16x16x32_bf16 v[26:29], v[238:241], v[202:205], v[190:193]
	v_mfma_f32_16x16x32_bf16 v[82:85], v[242:245], v[206:209], v[26:29]
	v_mfma_f32_16x16x32_bf16 v[26:29], v[214:217], v[222:225], v[70:73]
	v_mfma_f32_16x16x32_bf16 v[70:73], v[218:221], v[226:229], v[26:29]
	v_mfma_f32_16x16x32_bf16 v[26:29], v[238:241], v[222:225], v[66:69]
	v_mfma_f32_16x16x32_bf16 v[66:69], v[242:245], v[226:229], v[26:29]
	s_barrier
	ds_read_b128 v[170:173], v146 offset:49152
	ds_read_b128 v[146:149], v146 offset:50176
	ds_read_b128 v[186:189], v145 offset:49152
	ds_read_b128 v[190:193], v145 offset:50176
	ds_read_b128 v[202:205], v144 offset:49152
	ds_read_b128 v[206:209], v144 offset:50176
	ds_read_b128 v[222:225], v143 offset:49152
	ds_read_b128 v[226:229], v143 offset:50176
	s_barrier
	s_waitcnt lgkmcnt(0)
	v_mfma_f32_16x16x32_bf16 v[26:29], v[10:13], v[170:173], v[62:65]
	v_mfma_f32_16x16x32_bf16 v[62:65], v[14:17], v[146:149], v[26:29]
	v_mfma_f32_16x16x32_bf16 v[26:29], v[194:197], v[170:173], v[58:61]
	v_mfma_f32_16x16x32_bf16 v[58:61], v[198:201], v[146:149], v[26:29]
	v_mfma_f32_16x16x32_bf16 v[26:29], v[10:13], v[186:189], v[54:57]
	v_mfma_f32_16x16x32_bf16 v[46:49], v[14:17], v[190:193], v[26:29]
	v_mfma_f32_16x16x32_bf16 v[26:29], v[194:197], v[186:189], v[50:53]
	v_mfma_f32_16x16x32_bf16 v[42:45], v[198:201], v[190:193], v[26:29]
	v_mfma_f32_16x16x32_bf16 v[26:29], v[10:13], v[202:205], v[210:213]
	v_mfma_f32_16x16x32_bf16 v[10:13], v[10:13], v[222:225], v[38:41]
	v_mfma_f32_16x16x32_bf16 v[30:33], v[14:17], v[206:209], v[26:29]
	v_mfma_f32_16x16x32_bf16 v[26:29], v[194:197], v[202:205], v[234:237]
	v_mfma_f32_16x16x32_bf16 v[14:17], v[14:17], v[226:229], v[10:13]
	v_mfma_f32_16x16x32_bf16 v[10:13], v[194:197], v[222:225], v[34:37]
	v_mfma_f32_16x16x32_bf16 v[26:29], v[198:201], v[206:209], v[26:29]
	v_mfma_f32_16x16x32_bf16 v[10:13], v[198:201], v[226:229], v[10:13]
	v_mfma_f32_16x16x32_bf16 v[34:37], v[214:217], v[170:173], v[132:135]
	v_mfma_f32_16x16x32_bf16 v[54:57], v[218:221], v[146:149], v[34:37]
	v_mfma_f32_16x16x32_bf16 v[34:37], v[238:241], v[170:173], v[136:139]
	v_mfma_f32_16x16x32_bf16 v[18:21], v[238:241], v[186:189], v[18:21]
	v_mfma_f32_16x16x32_bf16 v[50:53], v[242:245], v[146:149], v[34:37]
	v_mfma_f32_16x16x32_bf16 v[22:25], v[214:217], v[186:189], v[22:25]
	v_mfma_f32_16x16x32_bf16 v[34:37], v[242:245], v[190:193], v[18:21]
	v_mfma_f32_16x16x32_bf16 v[18:21], v[214:217], v[202:205], v[150:153]
	v_mfma_f32_16x16x32_bf16 v[38:41], v[218:221], v[190:193], v[22:25]
	v_mfma_f32_16x16x32_bf16 v[22:25], v[218:221], v[206:209], v[18:21]
	v_mfma_f32_16x16x32_bf16 v[18:21], v[238:241], v[202:205], v[166:169]
	v_mfma_f32_16x16x32_bf16 v[6:9], v[214:217], v[222:225], v[6:9]
	v_mfma_f32_16x16x32_bf16 v[2:5], v[238:241], v[222:225], v[2:5]
	v_mfma_f32_16x16x32_bf16 v[18:21], v[242:245], v[206:209], v[18:21]
	v_mfma_f32_16x16x32_bf16 v[6:9], v[218:221], v[226:229], v[6:9]
	v_mfma_f32_16x16x32_bf16 v[2:5], v[242:245], v[226:229], v[2:5]
	v_cmp_gt_u32_e32 vcc, s96, v141
	s_barrier
	s_and_saveexec_b64 s[2:3], vcc
	s_cbranch_execz .LBB0_1038
	s_barrier

; #define STAGE_A(P,br,kt) STAGE_G(P,c.A,c.lda,br,(long)(kt)*c.kstr)
; #define STAGE_B(P,br,kt) STAGE_G(P,c.Bt,c.K,br,(long)(kt)*BK)
; #define LDA(dst,b,h) for(int m=0;m<4;++m)for(int k=0;k<2;++k) \
;     dst[m][k]=*reinterpret_cast<const bf16x8*>((char*)SA(b,h)+lds_byte(wr*64+m*16+fr,k*32+fq*8))
; #define LDB(dst,b,h) for(int n=0;n<2;++n)for(int k=0;k<2;++k) \
;     dst[n][k]=*reinterpret_cast<const bf16x8*>((char*)SB(b,h)+lds_byte(wc*32+n*16+fr,k*32+fq*8))
; #define MMA(ai,bj,At,Bt_) do{__builtin_amdgcn_s_setprio(1); \
;     for(int m=0;m<4;++m)for(int n=0;n<2;++n)for(int k=0;k<2;++k) \
;       acc[ai][bj][m][n]=__builtin_amdgcn_mfma_f32_16x16x32_bf16(Bt_[n][k],At[m][k],acc[ai][bj][m][n],0,0,0); \
;     __builtin_amdgcn_s_setprio(0);}while(0)
; #define WAIT_L(n) asm volatile("s_waitcnt lgkmcnt(" #n ")":::"memory")
; #define BAR __builtin_amdgcn_s_barrier()
; #define SCHED __builtin_amdgcn_sched_barrier(0)
; template <int EPI>
; __device__ __forceinline__ void gemm_run(const GD& c, const bool has_next, const GD& nx, const Ctx& e, bf16* shm, float* rs, float* rs_nxt, float* racc_) {
;     ...
;     LDB(B0,0,0); SCHED; LDA(At,0,0); STAGE_A(SA(1,1),brow+HALF,t+1);
;     WAIT_L(8); BAR; WAIT_L(0); MMA(0,0,At,B0); BAR; SCHED;
;     LDB(B1,0,1); STAGE_B(SB(0,0),bcol,t+2);
;     BAR; WAIT_L(0); MMA(0,1,At,B1); BAR;
;     LDA(At,0,1); STAGE_A(SA(0,0),brow,t+2);
;     BAR; WAIT_L(0); MMA(1,0,At,B0); BAR; SCHED;
.LBB0_1119:
	ds_read_b128 v[168:171], v155
	ds_read_b128 v[172:175], v155 offset:1024
	ds_read_b128 v[186:189], v155 offset:2048
	ds_read_b128 v[190:193], v155 offset:3072
	v_add_u32_e32 v163, 0xc000, v142
	v_lshl_add_u64 v[182:183], s[4:5], 0, v[130:131]
	v_readfirstlane_b32 s3, v163
	v_add_u32_e32 v166, 0xe000, v142
	v_lshl_add_u64 v[156:157], v[182:183], 0, s[94:95]
	s_mov_b32 m0, s3
	v_lshl_add_u64 v[242:243], s[4:5], 0, v[132:133]
	v_readfirstlane_b32 s3, v166
	ds_read_b128 v[158:161], v146
	ds_read_b128 v[194:197], v146 offset:1024
	ds_read_b128 v[198:201], v145
	ds_read_b128 v[202:205], v145 offset:1024
	ds_read_b128 v[206:209], v144
	ds_read_b128 v[210:213], v144 offset:1024
	ds_read_b128 v[214:217], v143
	ds_read_b128 v[218:221], v143 offset:1024
	global_load_lds_dwordx4 v[156:157], off
	v_lshl_add_u64 v[156:157], v[242:243], 0, s[94:95]
	s_mov_b32 m0, s3
	s_nop 0
	global_load_lds_dwordx4 v[156:157], off
	s_waitcnt lgkmcnt(8)
	s_barrier
	s_waitcnt lgkmcnt(0)
	v_mfma_f32_16x16x32_bf16 v[126:129], v[168:171], v[158:161], v[126:129]
	v_mfma_f32_16x16x32_bf16 v[122:125], v[186:189], v[158:161], v[122:125]
	v_mfma_f32_16x16x32_bf16 v[118:121], v[168:171], v[198:201], v[118:121]
	v_mfma_f32_16x16x32_bf16 v[114:117], v[186:189], v[198:201], v[114:117]
	v_mfma_f32_16x16x32_bf16 v[110:113], v[168:171], v[206:209], v[110:113]
	v_mfma_f32_16x16x32_bf16 v[106:109], v[186:189], v[206:209], v[106:109]
	v_mfma_f32_16x16x32_bf16 v[102:105], v[168:171], v[214:217], v[102:105]
	v_mfma_f32_16x16x32_bf16 v[98:101], v[186:189], v[214:217], v[98:101]
	v_mfma_f32_16x16x32_bf16 v[126:129], v[172:175], v[194:197], v[126:129]
	v_mfma_f32_16x16x32_bf16 v[122:125], v[190:193], v[194:197], v[122:125]
	v_mfma_f32_16x16x32_bf16 v[118:121], v[172:175], v[202:205], v[118:121]
	v_mfma_f32_16x16x32_bf16 v[114:117], v[190:193], v[202:205], v[114:117]
	v_mfma_f32_16x16x32_bf16 v[110:113], v[172:175], v[210:213], v[110:113]
	v_mfma_f32_16x16x32_bf16 v[106:109], v[190:193], v[210:213], v[106:109]
	v_mfma_f32_16x16x32_bf16 v[102:105], v[172:175], v[218:221], v[102:105]
	v_mfma_f32_16x16x32_bf16 v[98:101], v[190:193], v[218:221], v[98:101]
	s_barrier
	v_add_u32_e32 v156, s33, v148
	v_lshl_add_u64 v[244:245], s[4:5], 0, v[136:137]
	v_readfirstlane_b32 s3, v156
	v_add_u32_e32 v157, 0x2000, v156
	v_lshl_add_u64 v[238:239], v[244:245], 0, s[14:15]
	s_mov_b32 m0, s3
	v_lshl_add_u64 v[246:247], s[4:5], 0, v[138:139]
	v_readfirstlane_b32 s3, v157
	ds_read_b128 v[222:225], v154
	ds_read_b128 v[226:229], v154 offset:1024
	ds_read_b128 v[230:233], v154 offset:2048
	ds_read_b128 v[234:237], v154 offset:3072
	global_load_lds_dwordx4 v[238:239], off
	v_lshl_add_u64 v[238:239], v[246:247], 0, s[14:15]
	s_mov_b32 m0, s3
	s_nop 0
	global_load_lds_dwordx4 v[238:239], off
	s_barrier
	s_waitcnt lgkmcnt(0)
	v_mfma_f32_16x16x32_bf16 v[94:97], v[222:225], v[158:161], v[94:97]
	v_mfma_f32_16x16x32_bf16 v[90:93], v[230:233], v[158:161], v[90:93]
	v_mfma_f32_16x16x32_bf16 v[86:89], v[222:225], v[198:201], v[86:89]
	v_mfma_f32_16x16x32_bf16 v[82:85], v[230:233], v[198:201], v[82:85]
	v_mfma_f32_16x16x32_bf16 v[78:81], v[222:225], v[206:209], v[78:81]
	v_mfma_f32_16x16x32_bf16 v[74:77], v[230:233], v[206:209], v[74:77]
	v_mfma_f32_16x16x32_bf16 v[70:73], v[222:225], v[214:217], v[70:73]
	v_mfma_f32_16x16x32_bf16 v[66:69], v[230:233], v[214:217], v[66:69]
	v_mfma_f32_16x16x32_bf16 v[94:97], v[226:229], v[194:197], v[94:97]
	v_mfma_f32_16x16x32_bf16 v[90:93], v[234:237], v[194:197], v[90:93]
	v_mfma_f32_16x16x32_bf16 v[86:89], v[226:229], v[202:205], v[86:89]
	v_mfma_f32_16x16x32_bf16 v[82:85], v[234:237], v[202:205], v[82:85]
	v_mfma_f32_16x16x32_bf16 v[78:81], v[226:229], v[210:213], v[78:81]
	v_mfma_f32_16x16x32_bf16 v[74:77], v[234:237], v[210:213], v[74:77]
	v_mfma_f32_16x16x32_bf16 v[70:73], v[226:229], v[218:221], v[70:73]
	v_mfma_f32_16x16x32_bf16 v[66:69], v[234:237], v[218:221], v[66:69]
	v_readfirstlane_b32 s3, v142
	v_lshl_add_u64 v[158:159], v[182:183], 0, s[84:85]
	s_mov_b32 m0, s3
	s_barrier
	ds_read_b128 v[194:197], v146 offset:16384
	ds_read_b128 v[198:201], v146 offset:17408
	ds_read_b128 v[202:205], v145 offset:16384
	ds_read_b128 v[206:209], v145 offset:17408
	ds_read_b128 v[210:213], v144 offset:16384
	ds_read_b128 v[214:217], v144 offset:17408
	ds_read_b128 v[218:221], v143 offset:16384
	ds_read_b128 v[238:241], v143 offset:17408
	global_load_lds_dwordx4 v[158:159], off
	v_add_u32_e32 v158, 0x2000, v142
	v_lshl_add_u64 v[160:161], v[242:243], 0, s[84:85]
	v_readfirstlane_b32 s3, v158
	s_mov_b32 m0, s3
	s_nop 0
	global_load_lds_dwordx4 v[160:161], off
	s_barrier
	s_waitcnt lgkmcnt(0)
	v_mfma_f32_16x16x32_bf16 v[62:65], v[168:171], v[194:197], v[62:65]
	v_mfma_f32_16x16x32_bf16 v[58:61], v[186:189], v[194:197], v[58:61]
	v_mfma_f32_16x16x32_bf16 v[54:57], v[168:171], v[202:205], v[54:57]
	v_mfma_f32_16x16x32_bf16 v[50:53], v[186:189], v[202:205], v[50:53]
	v_mfma_f32_16x16x32_bf16 v[46:49], v[168:171], v[210:213], v[46:49]
	v_mfma_f32_16x16x32_bf16 v[42:45], v[186:189], v[210:213], v[42:45]
	v_mfma_f32_16x16x32_bf16 v[38:41], v[168:171], v[218:221], v[38:41]
	v_mfma_f32_16x16x32_bf16 v[34:37], v[186:189], v[218:221], v[34:37]
	v_mfma_f32_16x16x32_bf16 v[62:65], v[172:175], v[198:201], v[62:65]
	v_mfma_f32_16x16x32_bf16 v[58:61], v[190:193], v[198:201], v[58:61]
	v_mfma_f32_16x16x32_bf16 v[54:57], v[172:175], v[206:209], v[54:57]
	v_mfma_f32_16x16x32_bf16 v[50:53], v[190:193], v[206:209], v[50:53]
	v_mfma_f32_16x16x32_bf16 v[46:49], v[172:175], v[214:217], v[46:49]
	v_mfma_f32_16x16x32_bf16 v[42:45], v[190:193], v[214:217], v[42:45]
	v_mfma_f32_16x16x32_bf16 v[38:41], v[172:175], v[238:241], v[38:41]
	v_mfma_f32_16x16x32_bf16 v[34:37], v[190:193], v[238:241], v[34:37]
	s_barrier
; #define STAGE_A(P,br,kt) STAGE_G(P,c.A,c.lda,br,(long)(kt)*c.kstr)
; #define STAGE_B(P,br,kt) STAGE_G(P,c.Bt,c.K,br,(long)(kt)*BK)
; #define LDA(dst,b,h) for(int m=0;m<4;++m)for(int k=0;k<2;++k) \
;     dst[m][k]=*reinterpret_cast<const bf16x8*>((char*)SA(b,h)+lds_byte(wr*64+m*16+fr,k*32+fq*8))
; #define LDB(dst,b,h) for(int n=0;n<2;++n)for(int k=0;k<2;++k) \
;     dst[n][k]=*reinterpret_cast<const bf16x8*>((char*)SB(b,h)+lds_byte(wc*32+n*16+fr,k*32+fq*8))
; #define MMA(ai,bj,At,Bt_) do{__builtin_amdgcn_s_setprio(1); \
;     for(int m=0;m<4;++m)for(int n=0;n<2;++n)for(int k=0;k<2;++k) \
;       acc[ai][bj][m][n]=__builtin_amdgcn_mfma_f32_16x16x32_bf16(Bt_[n][k],At[m][k],acc[ai][bj][m][n],0,0,0); \
;     __builtin_amdgcn_s_setprio(0);}while(0)
; #define WAIT_V(n) asm volatile("s_waitcnt vmcnt(" #n ")":::"memory")
; #define WAIT_L(n) asm volatile("s_waitcnt lgkmcnt(" #n ")":::"memory")
; #define BAR __builtin_amdgcn_s_barrier()
; #define SCHED __builtin_amdgcn_sched_barrier(0)
; template <int EPI>
; __device__ __forceinline__ void gemm_run(const GD& c, const bool has_next, const GD& nx, const Ctx& e, bf16* shm, float* rs, float* rs_nxt, float* racc_) {
;     ...
;     STAGE_B(SB(0,1),bcol+HALF,t+2);
;     WAIT_V(6); BAR; MMA(1,1,At,B1); BAR;
;     LDB(B0,1,0); SCHED; LDA(At,1,0); STAGE_A(SA(0,1),brow+HALF,t+2);
;     WAIT_L(8); BAR; WAIT_L(0); MMA(0,0,At,B0); BAR; SCHED;
;     LDB(B1,1,1); STAGE_B(SB(1,0),bcol,t+3);
;     BAR; WAIT_L(0); MMA(0,1,At,B1); BAR;
;     LDA(At,1,1); STAGE_A(SA(1,0),brow,t+3);
	v_add_u32_e32 v159, s86, v148
	v_lshl_add_u64 v[160:161], v[244:245], 0, s[26:27]
	v_readfirstlane_b32 s3, v159
	s_mov_b32 m0, s3
	v_lshl_add_u64 v[168:169], v[246:247], 0, s[26:27]
	global_load_lds_dwordx4 v[160:161], off
	v_add_u32_e32 v160, 0x2000, v159
	s_nop 0
	v_readfirstlane_b32 s3, v160
	s_mov_b32 m0, s3
	s_nop 0
	global_load_lds_dwordx4 v[168:169], off
	s_waitcnt vmcnt(6)
	s_barrier
	v_mfma_f32_16x16x32_bf16 v[30:33], v[222:225], v[194:197], v[30:33]
	v_mfma_f32_16x16x32_bf16 v[26:29], v[230:233], v[194:197], v[26:29]
	v_mfma_f32_16x16x32_bf16 v[22:25], v[222:225], v[202:205], v[22:25]
	v_mfma_f32_16x16x32_bf16 v[18:21], v[230:233], v[202:205], v[18:21]
	v_mfma_f32_16x16x32_bf16 v[14:17], v[222:225], v[210:213], v[14:17]
	v_mfma_f32_16x16x32_bf16 v[10:13], v[230:233], v[210:213], v[10:13]
	v_mfma_f32_16x16x32_bf16 v[6:9], v[222:225], v[218:221], v[6:9]
	v_mfma_f32_16x16x32_bf16 v[2:5], v[230:233], v[218:221], v[2:5]
	v_mfma_f32_16x16x32_bf16 v[30:33], v[226:229], v[198:201], v[30:33]
	v_mfma_f32_16x16x32_bf16 v[26:29], v[234:237], v[198:201], v[26:29]
	v_mfma_f32_16x16x32_bf16 v[22:25], v[226:229], v[206:209], v[22:25]
	v_mfma_f32_16x16x32_bf16 v[18:21], v[234:237], v[206:209], v[18:21]
	v_mfma_f32_16x16x32_bf16 v[14:17], v[226:229], v[214:217], v[14:17]
	v_mfma_f32_16x16x32_bf16 v[10:13], v[234:237], v[214:217], v[10:13]
	v_mfma_f32_16x16x32_bf16 v[6:9], v[226:229], v[238:241], v[6:9]
	v_mfma_f32_16x16x32_bf16 v[2:5], v[234:237], v[238:241], v[2:5]
	s_barrier
	ds_read_b128 v[168:171], v149
	ds_read_b128 v[172:175], v149 offset:1024
	ds_read_b128 v[186:189], v149 offset:2048
	ds_read_b128 v[190:193], v149 offset:3072
	v_add_u32_e32 v161, 0x4000, v142
	v_add_u32_e32 v162, 0x6000, v142
	v_readfirstlane_b32 s3, v161
	v_lshl_add_u64 v[226:227], v[182:183], 0, s[92:93]
	s_mov_b32 m0, s3
	v_readfirstlane_b32 s3, v162
	ds_read_b128 v[194:197], v146 offset:32768
	ds_read_b128 v[198:201], v146 offset:33792
	ds_read_b128 v[202:205], v145 offset:32768
	ds_read_b128 v[206:209], v145 offset:33792
	ds_read_b128 v[210:213], v144 offset:32768
	ds_read_b128 v[214:217], v144 offset:33792
	ds_read_b128 v[218:221], v143 offset:32768
	ds_read_b128 v[222:225], v143 offset:33792
	global_load_lds_dwordx4 v[226:227], off
	v_lshl_add_u64 v[226:227], v[242:243], 0, s[92:93]
	s_mov_b32 m0, s3
	s_nop 0
	global_load_lds_dwordx4 v[226:227], off
	s_waitcnt lgkmcnt(8)
	s_barrier
	s_waitcnt lgkmcnt(0)
	v_mfma_f32_16x16x32_bf16 v[126:129], v[168:171], v[194:197], v[126:129]
	v_mfma_f32_16x16x32_bf16 v[122:125], v[186:189], v[194:197], v[122:125]
	v_mfma_f32_16x16x32_bf16 v[118:121], v[168:171], v[202:205], v[118:121]
	v_mfma_f32_16x16x32_bf16 v[114:117], v[186:189], v[202:205], v[114:117]
	v_mfma_f32_16x16x32_bf16 v[110:113], v[168:171], v[210:213], v[110:113]
	v_mfma_f32_16x16x32_bf16 v[106:109], v[186:189], v[210:213], v[106:109]
	v_mfma_f32_16x16x32_bf16 v[102:105], v[168:171], v[218:221], v[102:105]
	v_mfma_f32_16x16x32_bf16 v[98:101], v[186:189], v[218:221], v[98:101]
	v_mfma_f32_16x16x32_bf16 v[126:129], v[172:175], v[198:201], v[126:129]
	v_mfma_f32_16x16x32_bf16 v[122:125], v[190:193], v[198:201], v[122:125]
	v_mfma_f32_16x16x32_bf16 v[118:121], v[172:175], v[206:209], v[118:121]
	v_mfma_f32_16x16x32_bf16 v[114:117], v[190:193], v[206:209], v[114:117]
	v_mfma_f32_16x16x32_bf16 v[110:113], v[172:175], v[214:217], v[110:113]
	v_mfma_f32_16x16x32_bf16 v[106:109], v[190:193], v[214:217], v[106:109]
	v_mfma_f32_16x16x32_bf16 v[102:105], v[172:175], v[222:225], v[102:105]
	v_mfma_f32_16x16x32_bf16 v[98:101], v[190:193], v[222:225], v[98:101]
	s_barrier
	v_readfirstlane_b32 s3, v150
	v_add_u32_e32 v167, 0x2000, v150
	v_lshl_add_u64 v[248:249], v[244:245], 0, s[28:29]
	s_mov_b32 m0, s3
	v_readfirstlane_b32 s3, v167
	ds_read_b128 v[226:229], v147
	ds_read_b128 v[230:233], v147 offset:1024
	ds_read_b128 v[234:237], v147 offset:2048
	ds_read_b128 v[238:241], v147 offset:3072
	global_load_lds_dwordx4 v[248:249], off
	v_lshl_add_u64 v[248:249], v[246:247], 0, s[28:29]
	s_mov_b32 m0, s3
	s_nop 0
	global_load_lds_dwordx4 v[248:249], off
	s_barrier
	s_waitcnt lgkmcnt(0)
	v_mfma_f32_16x16x32_bf16 v[94:97], v[226:229], v[194:197], v[94:97]
	v_mfma_f32_16x16x32_bf16 v[90:93], v[234:237], v[194:197], v[90:93]
	v_mfma_f32_16x16x32_bf16 v[86:89], v[226:229], v[202:205], v[86:89]
	v_mfma_f32_16x16x32_bf16 v[82:85], v[234:237], v[202:205], v[82:85]
	v_readfirstlane_b32 s3, v151
	v_mfma_f32_16x16x32_bf16 v[78:81], v[226:229], v[210:213], v[78:81]
	v_lshl_add_u64 v[182:183], v[182:183], 0, s[80:81]
	v_mfma_f32_16x16x32_bf16 v[74:77], v[234:237], v[210:213], v[74:77]
	s_mov_b32 m0, s3
	v_mfma_f32_16x16x32_bf16 v[70:73], v[226:229], v[218:221], v[70:73]
	v_readfirstlane_b32 s3, v152
	v_mfma_f32_16x16x32_bf16 v[66:69], v[234:237], v[218:221], v[66:69]
	v_mfma_f32_16x16x32_bf16 v[94:97], v[230:233], v[198:201], v[94:97]
	v_mfma_f32_16x16x32_bf16 v[90:93], v[238:241], v[198:201], v[90:93]
	v_mfma_f32_16x16x32_bf16 v[86:89], v[230:233], v[206:209], v[86:89]
	v_mfma_f32_16x16x32_bf16 v[82:85], v[238:241], v[206:209], v[82:85]
	v_mfma_f32_16x16x32_bf16 v[78:81], v[230:233], v[214:217], v[78:81]
	v_mfma_f32_16x16x32_bf16 v[74:77], v[238:241], v[214:217], v[74:77]
	v_mfma_f32_16x16x32_bf16 v[70:73], v[230:233], v[222:225], v[70:73]
	v_mfma_f32_16x16x32_bf16 v[66:69], v[238:241], v[222:225], v[66:69]
	s_barrier
	ds_read_b128 v[194:197], v146 offset:49152
	ds_read_b128 v[198:201], v146 offset:50176
	ds_read_b128 v[202:205], v145 offset:49152
	ds_read_b128 v[206:209], v145 offset:50176
	ds_read_b128 v[210:213], v144 offset:49152
	ds_read_b128 v[214:217], v144 offset:50176
	ds_read_b128 v[218:221], v143 offset:49152
	ds_read_b128 v[222:225], v143 offset:50176
	global_load_lds_dwordx4 v[182:183], off
	v_lshl_add_u64 v[182:183], v[242:243], 0, s[80:81]
	s_mov_b32 m0, s3
	s_nop 0
	global_load_lds_dwordx4 v[182:183], off
	s_barrier
; #define STAGE_A(P,br,kt) STAGE_G(P,c.A,c.lda,br,(long)(kt)*c.kstr)
; #define STAGE_B(P,br,kt) STAGE_G(P,c.Bt,c.K,br,(long)(kt)*BK)
; #define LDA(dst,b,h) for(int m=0;m<4;++m)for(int k=0;k<2;++k) \
;     dst[m][k]=*reinterpret_cast<const bf16x8*>((char*)SA(b,h)+lds_byte(wr*64+m*16+fr,k*32+fq*8))
; #define LDB(dst,b,h) for(int n=0;n<2;++n)for(int k=0;k<2;++k) \
;     dst[n][k]=*reinterpret_cast<const bf16x8*>((char*)SB(b,h)+lds_byte(wc*32+n*16+fr,k*32+fq*8))
; #define MMA(ai,bj,At,Bt_) do{__builtin_amdgcn_s_setprio(1); \
;     for(int m=0;m<4;++m)for(int n=0;n<2;++n)for(int k=0;k<2;++k) \
;       acc[ai][bj][m][n]=__builtin_amdgcn_mfma_f32_16x16x32_bf16(Bt_[n][k],At[m][k],acc[ai][bj][m][n],0,0,0); \
;     __builtin_amdgcn_s_setprio(0);}while(0)
; #define WAIT_V(n) asm volatile("s_waitcnt vmcnt(" #n ")":::"memory")
; #define WAIT_L(n) asm volatile("s_waitcnt lgkmcnt(" #n ")":::"memory")
; #define BAR __builtin_amdgcn_s_barrier()
; #define SCHED __builtin_amdgcn_sched_barrier(0)
; template <int EPI>
; __device__ __forceinline__ void gemm_run(const GD& c, const bool has_next, const GD& nx, const Ctx& e, bf16* shm, float* rs, float* rs_nxt, float* racc_) {
;     ...
;     BAR; WAIT_L(0); MMA(1,0,At,B0); BAR; SCHED;
;     STAGE_B(SB(1,1),bcol+HALF,t+3);
;     WAIT_V(6); BAR; MMA(1,1,At,B1); BAR;
;   }
;   { LDB(B0,0,0); LDA(At,0,0); STAGE_A(SA(1,1),brow+HALF,nt-1);
;     BAR; WAIT_L(0); MMA(0,0,At,B0); BAR;
;     LDB(B1,0,1); BAR; WAIT_L(0); MMA(0,1,At,B1); BAR;
	s_waitcnt lgkmcnt(0)
	v_mfma_f32_16x16x32_bf16 v[62:65], v[168:171], v[194:197], v[62:65]
	v_mfma_f32_16x16x32_bf16 v[58:61], v[186:189], v[194:197], v[58:61]
	v_mfma_f32_16x16x32_bf16 v[54:57], v[168:171], v[202:205], v[54:57]
	v_mfma_f32_16x16x32_bf16 v[50:53], v[186:189], v[202:205], v[50:53]
	v_mfma_f32_16x16x32_bf16 v[46:49], v[168:171], v[210:213], v[46:49]
	v_mfma_f32_16x16x32_bf16 v[42:45], v[186:189], v[210:213], v[42:45]
	v_mfma_f32_16x16x32_bf16 v[38:41], v[168:171], v[218:221], v[38:41]
	v_mfma_f32_16x16x32_bf16 v[34:37], v[186:189], v[218:221], v[34:37]
	v_mfma_f32_16x16x32_bf16 v[62:65], v[172:175], v[198:201], v[62:65]
	v_mfma_f32_16x16x32_bf16 v[58:61], v[190:193], v[198:201], v[58:61]
	v_mfma_f32_16x16x32_bf16 v[54:57], v[172:175], v[206:209], v[54:57]
	v_mfma_f32_16x16x32_bf16 v[50:53], v[190:193], v[206:209], v[50:53]
	v_mfma_f32_16x16x32_bf16 v[46:49], v[172:175], v[214:217], v[46:49]
	v_mfma_f32_16x16x32_bf16 v[42:45], v[190:193], v[214:217], v[42:45]
	v_mfma_f32_16x16x32_bf16 v[38:41], v[172:175], v[222:225], v[38:41]
	v_mfma_f32_16x16x32_bf16 v[34:37], v[190:193], v[222:225], v[34:37]
	s_barrier
	v_readfirstlane_b32 s3, v153
	v_add_u32_e32 v167, 0x2000, v153
	v_lshl_add_u64 v[168:169], v[244:245], 0, s[30:31]
	s_mov_b32 m0, s3
	v_readfirstlane_b32 s3, v167
	global_load_lds_dwordx4 v[168:169], off
	v_lshl_add_u64 v[168:169], v[246:247], 0, s[30:31]
	s_mov_b32 m0, s3
	s_nop 0
	global_load_lds_dwordx4 v[168:169], off
	s_waitcnt vmcnt(6)
	s_barrier
	v_mfma_f32_16x16x32_bf16 v[30:33], v[226:229], v[194:197], v[30:33]
	v_mfma_f32_16x16x32_bf16 v[26:29], v[234:237], v[194:197], v[26:29]
	v_mfma_f32_16x16x32_bf16 v[22:25], v[226:229], v[202:205], v[22:25]
	v_mfma_f32_16x16x32_bf16 v[18:21], v[234:237], v[202:205], v[18:21]
	s_add_i32 s2, s2, 2
	v_mfma_f32_16x16x32_bf16 v[14:17], v[226:229], v[210:213], v[14:17]
	v_lshl_add_u64 v[130:131], v[130:131], 0, s[88:89]
	v_mfma_f32_16x16x32_bf16 v[10:13], v[234:237], v[210:213], v[10:13]
	v_lshl_add_u64 v[132:133], v[132:133], 0, s[88:89]
	v_mfma_f32_16x16x32_bf16 v[6:9], v[226:229], v[218:221], v[6:9]
	v_lshl_add_u64 v[136:137], v[136:137], 0, s[88:89]
	v_mfma_f32_16x16x32_bf16 v[2:5], v[234:237], v[218:221], v[2:5]
	s_cmp_lt_u32 s2, 12
	v_mfma_f32_16x16x32_bf16 v[30:33], v[230:233], v[198:201], v[30:33]
	v_lshl_add_u64 v[138:139], v[138:139], 0, s[88:89]
	v_mfma_f32_16x16x32_bf16 v[26:29], v[238:241], v[198:201], v[26:29]
	v_mfma_f32_16x16x32_bf16 v[22:25], v[230:233], v[206:209], v[22:25]
	v_mfma_f32_16x16x32_bf16 v[18:21], v[238:241], v[206:209], v[18:21]
	v_mfma_f32_16x16x32_bf16 v[14:17], v[230:233], v[214:217], v[14:17]
	v_mfma_f32_16x16x32_bf16 v[10:13], v[238:241], v[214:217], v[10:13]
	v_mfma_f32_16x16x32_bf16 v[6:9], v[230:233], v[222:225], v[6:9]
	v_mfma_f32_16x16x32_bf16 v[2:5], v[238:241], v[222:225], v[2:5]
	s_barrier
	s_cbranch_scc1 .LBB0_1119
	s_or_b32 s2, s10, 0x80
	s_ashr_i32 s3, s2, 31
	s_lshl_b64 s[2:3], s[2:3], 11
	s_add_u32 s2, s18, s2
	s_addc_u32 s3, s19, s3
	v_lshl_add_u64 v[182:183], s[2:3], 0, v[0:1]
	s_mov_b64 s[14:15], 0x780
	v_readfirstlane_b32 s11, v163
	v_lshl_add_u64 v[182:183], v[182:183], 0, s[14:15]
	s_mov_b32 m0, s11
	ds_read_b128 v[130:133], v155
	ds_read_b128 v[136:139], v155 offset:1024
	ds_read_b128 v[150:153], v155 offset:2048
	ds_read_b128 v[168:171], v155 offset:3072
	ds_read_b128 v[172:175], v146
	ds_read_b128 v[186:189], v146 offset:1024
	ds_read_b128 v[190:193], v145
	ds_read_b128 v[194:197], v145 offset:1024
	ds_read_b128 v[198:201], v144
	ds_read_b128 v[202:205], v144 offset:1024
	ds_read_b128 v[206:209], v143
	ds_read_b128 v[210:213], v143 offset:1024
	global_load_lds_dwordx4 v[182:183], off
	v_lshl_add_u64 v[182:183], s[2:3], 0, v[134:135]
	v_readfirstlane_b32 s2, v166
	v_lshl_add_u64 v[182:183], v[182:183], 0, s[14:15]
	s_mov_b32 m0, s2
	s_nop 0
	global_load_lds_dwordx4 v[182:183], off
	s_barrier
	s_waitcnt lgkmcnt(0)
	v_mfma_f32_16x16x32_bf16 v[126:129], v[130:133], v[172:175], v[126:129]
	v_mfma_f32_16x16x32_bf16 v[122:125], v[150:153], v[172:175], v[122:125]
	v_mfma_f32_16x16x32_bf16 v[118:121], v[130:133], v[190:193], v[118:121]
	v_mfma_f32_16x16x32_bf16 v[106:109], v[150:153], v[198:201], v[106:109]
	v_mfma_f32_16x16x32_bf16 v[102:105], v[130:133], v[206:209], v[102:105]
	v_mfma_f32_16x16x32_bf16 v[126:129], v[136:139], v[186:189], v[126:129]
	v_mfma_f32_16x16x32_bf16 v[122:125], v[168:171], v[186:189], v[122:125]
	v_mfma_f32_16x16x32_bf16 v[118:121], v[136:139], v[194:197], v[118:121]
	v_mfma_f32_16x16x32_bf16 v[114:117], v[150:153], v[190:193], v[114:117]
	v_mfma_f32_16x16x32_bf16 v[110:113], v[130:133], v[198:201], v[110:113]
	v_mfma_f32_16x16x32_bf16 v[106:109], v[168:171], v[202:205], v[106:109]
	v_mfma_f32_16x16x32_bf16 v[102:105], v[136:139], v[210:213], v[102:105]
	v_mfma_f32_16x16x32_bf16 v[98:101], v[150:153], v[206:209], v[98:101]
	v_mfma_f32_16x16x32_bf16 v[214:217], v[168:171], v[194:197], v[114:117]
	v_mfma_f32_16x16x32_bf16 v[218:221], v[136:139], v[202:205], v[110:113]
	v_mfma_f32_16x16x32_bf16 v[222:225], v[168:171], v[210:213], v[98:101]
	s_barrier
	s_nop 2
	ds_read_b128 v[98:101], v154
	ds_read_b128 v[110:113], v154 offset:1024
	ds_read_b128 v[114:117], v154 offset:2048
	ds_read_b128 v[226:229], v154 offset:3072
	s_barrier
; #define LDA(dst,b,h) for(int m=0;m<4;++m)for(int k=0;k<2;++k) \
;     dst[m][k]=*reinterpret_cast<const bf16x8*>((char*)SA(b,h)+lds_byte(wr*64+m*16+fr,k*32+fq*8))
; #define LDB(dst,b,h) for(int n=0;n<2;++n)for(int k=0;k<2;++k) \
;     dst[n][k]=*reinterpret_cast<const bf16x8*>((char*)SB(b,h)+lds_byte(wc*32+n*16+fr,k*32+fq*8))
; #define MMA(ai,bj,At,Bt_) do{__builtin_amdgcn_s_setprio(1); \
;     for(int m=0;m<4;++m)for(int n=0;n<2;++n)for(int k=0;k<2;++k) \
;       acc[ai][bj][m][n]=__builtin_amdgcn_mfma_f32_16x16x32_bf16(Bt_[n][k],At[m][k],acc[ai][bj][m][n],0,0,0); \
;     __builtin_amdgcn_s_setprio(0);}while(0)
; #define WAIT_V(n) asm volatile("s_waitcnt vmcnt(" #n ")":::"memory")
; #define WAIT_L(n) asm volatile("s_waitcnt lgkmcnt(" #n ")":::"memory")
; #define BAR __builtin_amdgcn_s_barrier()
; template <int EPI>
; __device__ __forceinline__ void gemm_run(const GD& c, const bool has_next, const GD& nx, const Ctx& e, bf16* shm, float* rs, float* rs_nxt, float* racc_) {
;     ...
;     LDB(B1,0,1); BAR; WAIT_L(0); MMA(0,1,At,B1); BAR;
;     LDA(At,0,1); WAIT_V(4); BAR; WAIT_L(0); MMA(1,0,At,B0); MMA(1,1,At,B1); BAR; }
;   { LDB(B0,1,0); LDA(At,1,0); WAIT_V(2); BAR; WAIT_L(0); MMA(0,0,At,B0); BAR;
	s_waitcnt lgkmcnt(0)
	v_mfma_f32_16x16x32_bf16 v[90:93], v[114:117], v[172:175], v[90:93]
	v_mfma_f32_16x16x32_bf16 v[86:89], v[98:101], v[190:193], v[86:89]
	v_mfma_f32_16x16x32_bf16 v[74:77], v[114:117], v[198:201], v[74:77]
	v_mfma_f32_16x16x32_bf16 v[70:73], v[98:101], v[206:209], v[70:73]
	v_mfma_f32_16x16x32_bf16 v[66:69], v[114:117], v[206:209], v[66:69]
	v_mfma_f32_16x16x32_bf16 v[94:97], v[98:101], v[172:175], v[94:97]
	v_mfma_f32_16x16x32_bf16 v[90:93], v[226:229], v[186:189], v[90:93]
	v_mfma_f32_16x16x32_bf16 v[86:89], v[110:113], v[194:197], v[86:89]
	v_mfma_f32_16x16x32_bf16 v[82:85], v[114:117], v[190:193], v[82:85]
	v_mfma_f32_16x16x32_bf16 v[78:81], v[98:101], v[198:201], v[78:81]
	v_mfma_f32_16x16x32_bf16 v[74:77], v[226:229], v[202:205], v[74:77]
	v_mfma_f32_16x16x32_bf16 v[70:73], v[110:113], v[210:213], v[70:73]
	v_mfma_f32_16x16x32_bf16 v[66:69], v[226:229], v[210:213], v[66:69]
	v_mfma_f32_16x16x32_bf16 v[230:233], v[110:113], v[186:189], v[94:97]
	v_mfma_f32_16x16x32_bf16 v[172:175], v[226:229], v[194:197], v[82:85]
	v_mfma_f32_16x16x32_bf16 v[186:189], v[110:113], v[202:205], v[78:81]
	s_barrier
	s_nop 0
	ds_read_b128 v[78:81], v146 offset:16384
	ds_read_b128 v[82:85], v146 offset:17408
	ds_read_b128 v[94:97], v145 offset:16384
	ds_read_b128 v[190:193], v145 offset:17408
	ds_read_b128 v[194:197], v144 offset:16384
	ds_read_b128 v[198:201], v144 offset:17408
	ds_read_b128 v[202:205], v143 offset:16384
	ds_read_b128 v[206:209], v143 offset:17408
	s_waitcnt vmcnt(4)
	s_barrier
	s_waitcnt lgkmcnt(0)
	v_mfma_f32_16x16x32_bf16 v[62:65], v[130:133], v[78:81], v[62:65]
	v_mfma_f32_16x16x32_bf16 v[58:61], v[150:153], v[78:81], v[58:61]
	v_mfma_f32_16x16x32_bf16 v[54:57], v[130:133], v[94:97], v[54:57]
	v_mfma_f32_16x16x32_bf16 v[42:45], v[150:153], v[194:197], v[42:45]
	v_mfma_f32_16x16x32_bf16 v[38:41], v[130:133], v[202:205], v[38:41]
	v_mfma_f32_16x16x32_bf16 v[62:65], v[136:139], v[82:85], v[62:65]
	v_mfma_f32_16x16x32_bf16 v[58:61], v[168:171], v[82:85], v[58:61]
	v_mfma_f32_16x16x32_bf16 v[54:57], v[136:139], v[190:193], v[54:57]
	v_mfma_f32_16x16x32_bf16 v[50:53], v[150:153], v[94:97], v[50:53]
	v_mfma_f32_16x16x32_bf16 v[46:49], v[130:133], v[194:197], v[46:49]
	v_mfma_f32_16x16x32_bf16 v[42:45], v[168:171], v[198:201], v[42:45]
	v_mfma_f32_16x16x32_bf16 v[38:41], v[136:139], v[206:209], v[38:41]
	v_mfma_f32_16x16x32_bf16 v[34:37], v[150:153], v[202:205], v[34:37]
	v_mfma_f32_16x16x32_bf16 v[210:213], v[168:171], v[190:193], v[50:53]
	v_mfma_f32_16x16x32_bf16 v[234:237], v[136:139], v[198:201], v[46:49]
	v_mfma_f32_16x16x32_bf16 v[136:139], v[168:171], v[206:209], v[34:37]
	v_mfma_f32_16x16x32_bf16 v[26:29], v[114:117], v[78:81], v[26:29]
	v_mfma_f32_16x16x32_bf16 v[22:25], v[98:101], v[94:97], v[22:25]
	v_mfma_f32_16x16x32_bf16 v[10:13], v[114:117], v[194:197], v[10:13]
	v_mfma_f32_16x16x32_bf16 v[6:9], v[98:101], v[202:205], v[6:9]
	v_mfma_f32_16x16x32_bf16 v[30:33], v[98:101], v[78:81], v[30:33]
	v_mfma_f32_16x16x32_bf16 v[26:29], v[226:229], v[82:85], v[26:29]
	v_mfma_f32_16x16x32_bf16 v[22:25], v[110:113], v[190:193], v[22:25]
	v_mfma_f32_16x16x32_bf16 v[18:21], v[114:117], v[94:97], v[18:21]
	v_mfma_f32_16x16x32_bf16 v[14:17], v[98:101], v[194:197], v[14:17]
	v_mfma_f32_16x16x32_bf16 v[10:13], v[226:229], v[198:201], v[10:13]
	v_mfma_f32_16x16x32_bf16 v[6:9], v[110:113], v[206:209], v[6:9]
	v_mfma_f32_16x16x32_bf16 v[2:5], v[114:117], v[202:205], v[2:5]
	v_mfma_f32_16x16x32_bf16 v[150:153], v[110:113], v[82:85], v[30:33]
	v_mfma_f32_16x16x32_bf16 v[166:169], v[226:229], v[190:193], v[18:21]
	v_mfma_f32_16x16x32_bf16 v[190:193], v[110:113], v[198:201], v[14:17]
	v_mfma_f32_16x16x32_bf16 v[2:5], v[226:229], v[206:209], v[2:5]
	s_barrier
	ds_read_b128 v[14:17], v149
	ds_read_b128 v[18:21], v149 offset:1024
	ds_read_b128 v[194:197], v149 offset:2048
	ds_read_b128 v[198:201], v149 offset:3072
	ds_read_b128 v[30:33], v146 offset:32768
	ds_read_b128 v[34:37], v146 offset:33792
	ds_read_b128 v[46:49], v145 offset:32768
	ds_read_b128 v[50:53], v145 offset:33792
	ds_read_b128 v[202:205], v144 offset:32768
	ds_read_b128 v[206:209], v144 offset:33792
	ds_read_b128 v[226:229], v143 offset:32768
	ds_read_b128 v[238:241], v143 offset:33792
	s_waitcnt vmcnt(2)
	s_barrier
; #define LDA(dst,b,h) for(int m=0;m<4;++m)for(int k=0;k<2;++k) \
;     dst[m][k]=*reinterpret_cast<const bf16x8*>((char*)SA(b,h)+lds_byte(wr*64+m*16+fr,k*32+fq*8))
; #define LDB(dst,b,h) for(int n=0;n<2;++n)for(int k=0;k<2;++k) \
;     dst[n][k]=*reinterpret_cast<const bf16x8*>((char*)SB(b,h)+lds_byte(wc*32+n*16+fr,k*32+fq*8))
; #define MMA(ai,bj,At,Bt_) do{__builtin_amdgcn_s_setprio(1); \
;     for(int m=0;m<4;++m)for(int n=0;n<2;++n)for(int k=0;k<2;++k) \
;       acc[ai][bj][m][n]=__builtin_amdgcn_mfma_f32_16x16x32_bf16(Bt_[n][k],At[m][k],acc[ai][bj][m][n],0,0,0); \
;     __builtin_amdgcn_s_setprio(0);}while(0)
; #define WAIT_V(n) asm volatile("s_waitcnt vmcnt(" #n ")":::"memory")
; #define WAIT_L(n) asm volatile("s_waitcnt lgkmcnt(" #n ")":::"memory")
; #define BAR __builtin_amdgcn_s_barrier()
; template <int EPI>
; __device__ __forceinline__ void gemm_run(const GD& c, const bool has_next, const GD& nx, const Ctx& e, bf16* shm, float* rs, float* rs_nxt, float* racc_) {
;     ...
;   { LDB(B0,1,0); LDA(At,1,0); WAIT_V(2); BAR; WAIT_L(0); MMA(0,0,At,B0); BAR;
;     LDB(B1,1,1); WAIT_V(0); BAR; WAIT_L(0); MMA(0,1,At,B1); BAR;
;     LDA(At,1,1); BAR; WAIT_L(0); MMA(1,0,At,B0); MMA(1,1,At,B1); BAR; }
;   if(wr==0)BAR;
	s_waitcnt lgkmcnt(0)
	v_mfma_f32_16x16x32_bf16 v[78:81], v[14:17], v[30:33], v[126:129]
	v_mfma_f32_16x16x32_bf16 v[130:133], v[18:21], v[34:37], v[78:81]
	v_mfma_f32_16x16x32_bf16 v[78:81], v[194:197], v[30:33], v[122:125]
	v_mfma_f32_16x16x32_bf16 v[126:129], v[198:201], v[34:37], v[78:81]
	v_mfma_f32_16x16x32_bf16 v[78:81], v[14:17], v[46:49], v[118:121]
	v_mfma_f32_16x16x32_bf16 v[114:117], v[18:21], v[50:53], v[78:81]
	v_mfma_f32_16x16x32_bf16 v[78:81], v[194:197], v[46:49], v[214:217]
	v_mfma_f32_16x16x32_bf16 v[110:113], v[198:201], v[50:53], v[78:81]
	v_mfma_f32_16x16x32_bf16 v[78:81], v[14:17], v[202:205], v[218:221]
	v_mfma_f32_16x16x32_bf16 v[98:101], v[18:21], v[206:209], v[78:81]
	v_mfma_f32_16x16x32_bf16 v[78:81], v[194:197], v[202:205], v[106:109]
	v_mfma_f32_16x16x32_bf16 v[94:97], v[198:201], v[206:209], v[78:81]
	v_mfma_f32_16x16x32_bf16 v[78:81], v[14:17], v[226:229], v[102:105]
	v_mfma_f32_16x16x32_bf16 v[82:85], v[18:21], v[238:241], v[78:81]
	v_mfma_f32_16x16x32_bf16 v[78:81], v[194:197], v[226:229], v[222:225]
	v_mfma_f32_16x16x32_bf16 v[78:81], v[198:201], v[238:241], v[78:81]
	s_barrier
	ds_read_b128 v[214:217], v147
	ds_read_b128 v[218:221], v147 offset:1024
	ds_read_b128 v[222:225], v147 offset:2048
	ds_read_b128 v[242:245], v147 offset:3072
	s_waitcnt vmcnt(0)
	s_barrier
	s_waitcnt lgkmcnt(0)
	v_mfma_f32_16x16x32_bf16 v[102:105], v[214:217], v[30:33], v[230:233]
	v_mfma_f32_16x16x32_bf16 v[30:33], v[222:225], v[30:33], v[90:93]
	v_mfma_f32_16x16x32_bf16 v[118:121], v[242:245], v[34:37], v[30:33]
	v_mfma_f32_16x16x32_bf16 v[30:33], v[214:217], v[46:49], v[86:89]
	v_mfma_f32_16x16x32_bf16 v[106:109], v[218:221], v[50:53], v[30:33]
	v_mfma_f32_16x16x32_bf16 v[30:33], v[222:225], v[46:49], v[172:175]
	v_mfma_f32_16x16x32_bf16 v[122:125], v[218:221], v[34:37], v[102:105]
	v_mfma_f32_16x16x32_bf16 v[102:105], v[242:245], v[50:53], v[30:33]
	v_mfma_f32_16x16x32_bf16 v[30:33], v[214:217], v[202:205], v[186:189]
	v_mfma_f32_16x16x32_bf16 v[90:93], v[218:221], v[206:209], v[30:33]
	v_mfma_f32_16x16x32_bf16 v[30:33], v[222:225], v[202:205], v[74:77]
	v_mfma_f32_16x16x32_bf16 v[86:89], v[242:245], v[206:209], v[30:33]
	v_mfma_f32_16x16x32_bf16 v[30:33], v[214:217], v[226:229], v[70:73]
	v_mfma_f32_16x16x32_bf16 v[74:77], v[218:221], v[238:241], v[30:33]
	v_mfma_f32_16x16x32_bf16 v[30:33], v[222:225], v[226:229], v[66:69]
	v_mfma_f32_16x16x32_bf16 v[70:73], v[242:245], v[238:241], v[30:33]
	s_barrier
	ds_read_b128 v[170:173], v146 offset:49152
	ds_read_b128 v[146:149], v146 offset:50176
	ds_read_b128 v[186:189], v145 offset:49152
	ds_read_b128 v[202:205], v145 offset:50176
	ds_read_b128 v[206:209], v144 offset:49152
	ds_read_b128 v[226:229], v144 offset:50176
	ds_read_b128 v[230:233], v143 offset:49152
	ds_read_b128 v[238:241], v143 offset:50176
	s_barrier
	s_waitcnt lgkmcnt(0)
	v_mfma_f32_16x16x32_bf16 v[30:33], v[14:17], v[170:173], v[62:65]
	v_mfma_f32_16x16x32_bf16 v[66:69], v[18:21], v[146:149], v[30:33]
	v_mfma_f32_16x16x32_bf16 v[30:33], v[194:197], v[170:173], v[58:61]
	v_mfma_f32_16x16x32_bf16 v[62:65], v[198:201], v[146:149], v[30:33]
	v_mfma_f32_16x16x32_bf16 v[30:33], v[14:17], v[186:189], v[54:57]
	v_mfma_f32_16x16x32_bf16 v[50:53], v[18:21], v[202:205], v[30:33]
	v_mfma_f32_16x16x32_bf16 v[30:33], v[194:197], v[186:189], v[210:213]
	v_mfma_f32_16x16x32_bf16 v[46:49], v[198:201], v[202:205], v[30:33]
	v_mfma_f32_16x16x32_bf16 v[30:33], v[14:17], v[206:209], v[234:237]
	v_mfma_f32_16x16x32_bf16 v[14:17], v[14:17], v[230:233], v[38:41]
	v_mfma_f32_16x16x32_bf16 v[34:37], v[18:21], v[226:229], v[30:33]
	v_mfma_f32_16x16x32_bf16 v[30:33], v[194:197], v[206:209], v[42:45]
	v_mfma_f32_16x16x32_bf16 v[18:21], v[18:21], v[238:241], v[14:17]
	v_mfma_f32_16x16x32_bf16 v[14:17], v[194:197], v[230:233], v[136:139]
	v_mfma_f32_16x16x32_bf16 v[30:33], v[198:201], v[226:229], v[30:33]
	v_mfma_f32_16x16x32_bf16 v[14:17], v[198:201], v[238:241], v[14:17]
	v_mfma_f32_16x16x32_bf16 v[22:25], v[214:217], v[186:189], v[22:25]
	v_mfma_f32_16x16x32_bf16 v[38:41], v[214:217], v[170:173], v[150:153]
	v_mfma_f32_16x16x32_bf16 v[42:45], v[218:221], v[202:205], v[22:25]
	v_mfma_f32_16x16x32_bf16 v[22:25], v[222:225], v[186:189], v[166:169]
	v_mfma_f32_16x16x32_bf16 v[58:61], v[218:221], v[146:149], v[38:41]
	v_mfma_f32_16x16x32_bf16 v[26:29], v[222:225], v[170:173], v[26:29]
	v_mfma_f32_16x16x32_bf16 v[38:41], v[242:245], v[202:205], v[22:25]
	v_mfma_f32_16x16x32_bf16 v[22:25], v[214:217], v[206:209], v[190:193]
	v_mfma_f32_16x16x32_bf16 v[10:13], v[222:225], v[206:209], v[10:13]
	v_mfma_f32_16x16x32_bf16 v[6:9], v[214:217], v[230:233], v[6:9]
	v_mfma_f32_16x16x32_bf16 v[2:5], v[222:225], v[230:233], v[2:5]
	v_mfma_f32_16x16x32_bf16 v[54:57], v[242:245], v[146:149], v[26:29]
	v_mfma_f32_16x16x32_bf16 v[26:29], v[218:221], v[226:229], v[22:25]
	v_mfma_f32_16x16x32_bf16 v[22:25], v[242:245], v[226:229], v[10:13]
	v_mfma_f32_16x16x32_bf16 v[10:13], v[218:221], v[238:241], v[6:9]
	v_mfma_f32_16x16x32_bf16 v[6:9], v[242:245], v[238:241], v[2:5]
	v_cmp_gt_u32_e32 vcc, s96, v140
	s_barrier
	s_and_saveexec_b64 s[2:3], vcc
	s_cbranch_execz .LBB0_1122
	s_barrier

; #define STAGE_A(P,br,kt) STAGE_G(P,c.A,c.lda,br,(long)(kt)*c.kstr)
; #define STAGE_B(P,br,kt) STAGE_G(P,c.Bt,c.K,br,(long)(kt)*BK)
; #define LDA(dst,b,h) for(int m=0;m<4;++m)for(int k=0;k<2;++k) \
;     dst[m][k]=*reinterpret_cast<const bf16x8*>((char*)SA(b,h)+lds_byte(wr*64+m*16+fr,k*32+fq*8))
; #define LDB(dst,b,h) for(int n=0;n<2;++n)for(int k=0;k<2;++k) \
;     dst[n][k]=*reinterpret_cast<const bf16x8*>((char*)SB(b,h)+lds_byte(wc*32+n*16+fr,k*32+fq*8))
; #define MMA(ai,bj,At,Bt_) do{__builtin_amdgcn_s_setprio(1); \
;     for(int m=0;m<4;++m)for(int n=0;n<2;++n)for(int k=0;k<2;++k) \
;       acc[ai][bj][m][n]=__builtin_amdgcn_mfma_f32_16x16x32_bf16(Bt_[n][k],At[m][k],acc[ai][bj][m][n],0,0,0); \
;     __builtin_amdgcn_s_setprio(0);}while(0)
; #define WAIT_V(n) asm volatile("s_waitcnt vmcnt(" #n ")":::"memory")
; #define WAIT_L(n) asm volatile("s_waitcnt lgkmcnt(" #n ")":::"memory")
; #define BAR __builtin_amdgcn_s_barrier()
; #define SCHED __builtin_amdgcn_sched_barrier(0)
; template <int EPI>
; __device__ __forceinline__ void gemm_run(const GD& c, const bool has_next, const GD& nx, const Ctx& e, bf16* shm, float* rs, float* rs_nxt, float* racc_) {
;     ...
;   for(int t=0;t<nt-2;t+=2){
;     LDB(B0,0,0); SCHED; LDA(At,0,0); STAGE_A(SA(1,1),brow+HALF,t+1);
;     WAIT_L(8); BAR; WAIT_L(0); MMA(0,0,At,B0); BAR; SCHED;
;     LDB(B1,0,1); STAGE_B(SB(0,0),bcol,t+2);
;     BAR; WAIT_L(0); MMA(0,1,At,B1); BAR;
;     LDA(At,0,1); STAGE_A(SA(0,0),brow,t+2);
;     BAR; WAIT_L(0); MMA(1,0,At,B0); BAR; SCHED;
;     STAGE_B(SB(0,1),bcol+HALF,t+2);
;     WAIT_V(6); BAR; MMA(1,1,At,B1); BAR;
.LBB0_1178:
	ds_read_b128 v[168:171], v155
	ds_read_b128 v[172:175], v155 offset:1024
	ds_read_b128 v[186:189], v155 offset:2048
	ds_read_b128 v[190:193], v155 offset:3072
	v_add_u32_e32 v163, 0xc000, v142
	v_lshl_add_u64 v[182:183], s[6:7], 0, v[132:133]
	v_readfirstlane_b32 s3, v163
	v_add_u32_e32 v166, 0xe000, v142
	v_lshl_add_u64 v[156:157], v[182:183], 0, s[90:91]
	s_mov_b32 m0, s3
	v_lshl_add_u64 v[242:243], s[6:7], 0, v[134:135]
	v_readfirstlane_b32 s3, v166
	ds_read_b128 v[158:161], v146
	ds_read_b128 v[194:197], v146 offset:1024
	ds_read_b128 v[198:201], v145
	ds_read_b128 v[202:205], v145 offset:1024
	ds_read_b128 v[206:209], v144
	ds_read_b128 v[210:213], v144 offset:1024
	ds_read_b128 v[214:217], v143
	ds_read_b128 v[218:221], v143 offset:1024
	global_load_lds_dwordx4 v[156:157], off
	v_lshl_add_u64 v[156:157], v[242:243], 0, s[90:91]
	s_mov_b32 m0, s3
	s_nop 0
	global_load_lds_dwordx4 v[156:157], off
	s_waitcnt lgkmcnt(8)
	s_barrier
	s_waitcnt lgkmcnt(0)
	v_mfma_f32_16x16x32_bf16 v[126:129], v[168:171], v[158:161], v[126:129]
	v_mfma_f32_16x16x32_bf16 v[122:125], v[186:189], v[158:161], v[122:125]
	v_mfma_f32_16x16x32_bf16 v[118:121], v[168:171], v[198:201], v[118:121]
	v_mfma_f32_16x16x32_bf16 v[114:117], v[186:189], v[198:201], v[114:117]
	v_mfma_f32_16x16x32_bf16 v[110:113], v[168:171], v[206:209], v[110:113]
	v_mfma_f32_16x16x32_bf16 v[106:109], v[186:189], v[206:209], v[106:109]
	v_mfma_f32_16x16x32_bf16 v[102:105], v[168:171], v[214:217], v[102:105]
	v_mfma_f32_16x16x32_bf16 v[98:101], v[186:189], v[214:217], v[98:101]
	v_mfma_f32_16x16x32_bf16 v[126:129], v[172:175], v[194:197], v[126:129]
	v_mfma_f32_16x16x32_bf16 v[122:125], v[190:193], v[194:197], v[122:125]
	v_mfma_f32_16x16x32_bf16 v[118:121], v[172:175], v[202:205], v[118:121]
	v_mfma_f32_16x16x32_bf16 v[114:117], v[190:193], v[202:205], v[114:117]
	v_mfma_f32_16x16x32_bf16 v[110:113], v[172:175], v[210:213], v[110:113]
	v_mfma_f32_16x16x32_bf16 v[106:109], v[190:193], v[210:213], v[106:109]
	v_mfma_f32_16x16x32_bf16 v[102:105], v[172:175], v[218:221], v[102:105]
	v_mfma_f32_16x16x32_bf16 v[98:101], v[190:193], v[218:221], v[98:101]
	s_barrier
	v_add_u32_e32 v156, s33, v147
	v_lshl_add_u64 v[244:245], s[6:7], 0, v[136:137]
	v_readfirstlane_b32 s3, v156
	v_add_u32_e32 v157, 0x2000, v156
	v_lshl_add_u64 v[238:239], v[244:245], 0, s[28:29]
	s_mov_b32 m0, s3
	v_lshl_add_u64 v[246:247], s[6:7], 0, v[138:139]
	v_readfirstlane_b32 s3, v157
	ds_read_b128 v[222:225], v154
	ds_read_b128 v[226:229], v154 offset:1024
	ds_read_b128 v[230:233], v154 offset:2048
	ds_read_b128 v[234:237], v154 offset:3072
	global_load_lds_dwordx4 v[238:239], off
	v_lshl_add_u64 v[238:239], v[246:247], 0, s[28:29]
	s_mov_b32 m0, s3
	s_nop 0
	global_load_lds_dwordx4 v[238:239], off
	s_barrier
	s_waitcnt lgkmcnt(0)
	v_mfma_f32_16x16x32_bf16 v[94:97], v[222:225], v[158:161], v[94:97]
	v_mfma_f32_16x16x32_bf16 v[90:93], v[230:233], v[158:161], v[90:93]
	v_mfma_f32_16x16x32_bf16 v[86:89], v[222:225], v[198:201], v[86:89]
	v_mfma_f32_16x16x32_bf16 v[82:85], v[230:233], v[198:201], v[82:85]
	v_mfma_f32_16x16x32_bf16 v[78:81], v[222:225], v[206:209], v[78:81]
	v_mfma_f32_16x16x32_bf16 v[74:77], v[230:233], v[206:209], v[74:77]
	v_mfma_f32_16x16x32_bf16 v[70:73], v[222:225], v[214:217], v[70:73]
	v_mfma_f32_16x16x32_bf16 v[66:69], v[230:233], v[214:217], v[66:69]
	v_mfma_f32_16x16x32_bf16 v[94:97], v[226:229], v[194:197], v[94:97]
	v_mfma_f32_16x16x32_bf16 v[90:93], v[234:237], v[194:197], v[90:93]
	v_mfma_f32_16x16x32_bf16 v[86:89], v[226:229], v[202:205], v[86:89]
	v_mfma_f32_16x16x32_bf16 v[82:85], v[234:237], v[202:205], v[82:85]
	v_mfma_f32_16x16x32_bf16 v[78:81], v[226:229], v[210:213], v[78:81]
	v_mfma_f32_16x16x32_bf16 v[74:77], v[234:237], v[210:213], v[74:77]
	v_mfma_f32_16x16x32_bf16 v[70:73], v[226:229], v[218:221], v[70:73]
	v_mfma_f32_16x16x32_bf16 v[66:69], v[234:237], v[218:221], v[66:69]
	v_readfirstlane_b32 s3, v142
	v_lshl_add_u64 v[158:159], v[182:183], 0, s[0:1]
	s_mov_b32 m0, s3
	s_barrier
	ds_read_b128 v[194:197], v146 offset:16384
	ds_read_b128 v[198:201], v146 offset:17408
	ds_read_b128 v[202:205], v145 offset:16384
	ds_read_b128 v[206:209], v145 offset:17408
	ds_read_b128 v[210:213], v144 offset:16384
	ds_read_b128 v[214:217], v144 offset:17408
	ds_read_b128 v[218:221], v143 offset:16384
	ds_read_b128 v[238:241], v143 offset:17408
	global_load_lds_dwordx4 v[158:159], off
	v_add_u32_e32 v158, 0x2000, v142
	v_lshl_add_u64 v[160:161], v[242:243], 0, s[0:1]
	v_readfirstlane_b32 s3, v158
	s_mov_b32 m0, s3
	s_nop 0
	global_load_lds_dwordx4 v[160:161], off
	s_barrier
	s_waitcnt lgkmcnt(0)
	v_mfma_f32_16x16x32_bf16 v[62:65], v[168:171], v[194:197], v[62:65]
	v_mfma_f32_16x16x32_bf16 v[58:61], v[186:189], v[194:197], v[58:61]
	v_mfma_f32_16x16x32_bf16 v[54:57], v[168:171], v[202:205], v[54:57]
	v_mfma_f32_16x16x32_bf16 v[50:53], v[186:189], v[202:205], v[50:53]
	v_mfma_f32_16x16x32_bf16 v[46:49], v[168:171], v[210:213], v[46:49]
	v_mfma_f32_16x16x32_bf16 v[42:45], v[186:189], v[210:213], v[42:45]
	v_mfma_f32_16x16x32_bf16 v[38:41], v[168:171], v[218:221], v[38:41]
	v_mfma_f32_16x16x32_bf16 v[34:37], v[186:189], v[218:221], v[34:37]
	v_mfma_f32_16x16x32_bf16 v[62:65], v[172:175], v[198:201], v[62:65]
	v_mfma_f32_16x16x32_bf16 v[58:61], v[190:193], v[198:201], v[58:61]
	v_mfma_f32_16x16x32_bf16 v[54:57], v[172:175], v[206:209], v[54:57]
	v_mfma_f32_16x16x32_bf16 v[50:53], v[190:193], v[206:209], v[50:53]
	v_mfma_f32_16x16x32_bf16 v[46:49], v[172:175], v[214:217], v[46:49]
	v_mfma_f32_16x16x32_bf16 v[42:45], v[190:193], v[214:217], v[42:45]
	v_mfma_f32_16x16x32_bf16 v[38:41], v[172:175], v[238:241], v[38:41]
	v_mfma_f32_16x16x32_bf16 v[34:37], v[190:193], v[238:241], v[34:37]
	s_barrier
; #define STAGE_A(P,br,kt) STAGE_G(P,c.A,c.lda,br,(long)(kt)*c.kstr)
; #define STAGE_B(P,br,kt) STAGE_G(P,c.Bt,c.K,br,(long)(kt)*BK)
; #define LDA(dst,b,h) for(int m=0;m<4;++m)for(int k=0;k<2;++k) \
;     dst[m][k]=*reinterpret_cast<const bf16x8*>((char*)SA(b,h)+lds_byte(wr*64+m*16+fr,k*32+fq*8))
; #define LDB(dst,b,h) for(int n=0;n<2;++n)for(int k=0;k<2;++k) \
;     dst[n][k]=*reinterpret_cast<const bf16x8*>((char*)SB(b,h)+lds_byte(wc*32+n*16+fr,k*32+fq*8))
; #define MMA(ai,bj,At,Bt_) do{__builtin_amdgcn_s_setprio(1); \
;     for(int m=0;m<4;++m)for(int n=0;n<2;++n)for(int k=0;k<2;++k) \
;       acc[ai][bj][m][n]=__builtin_amdgcn_mfma_f32_16x16x32_bf16(Bt_[n][k],At[m][k],acc[ai][bj][m][n],0,0,0); \
;     __builtin_amdgcn_s_setprio(0);}while(0)
; #define WAIT_V(n) asm volatile("s_waitcnt vmcnt(" #n ")":::"memory")
; #define WAIT_L(n) asm volatile("s_waitcnt lgkmcnt(" #n ")":::"memory")
; #define BAR __builtin_amdgcn_s_barrier()
; #define SCHED __builtin_amdgcn_sched_barrier(0)
; template <int EPI>
; __device__ __forceinline__ void gemm_run(const GD& c, const bool has_next, const GD& nx, const Ctx& e, bf16* shm, float* rs, float* rs_nxt, float* racc_) {
;     ...
;     STAGE_B(SB(0,1),bcol+HALF,t+2);
;     WAIT_V(6); BAR; MMA(1,1,At,B1); BAR;
;     LDB(B0,1,0); SCHED; LDA(At,1,0); STAGE_A(SA(0,1),brow+HALF,t+2);
;     WAIT_L(8); BAR; WAIT_L(0); MMA(0,0,At,B0); BAR; SCHED;
;     LDB(B1,1,1); STAGE_B(SB(1,0),bcol,t+3);
;     BAR; WAIT_L(0); MMA(0,1,At,B1); BAR;
;     LDA(At,1,1); STAGE_A(SA(1,0),brow,t+3);
;     BAR; WAIT_L(0); MMA(1,0,At,B0); BAR; SCHED;
;     STAGE_B(SB(1,1),bcol+HALF,t+3);
;     WAIT_V(6); BAR; MMA(1,1,At,B1); BAR;
	v_add_u32_e32 v159, s86, v147
	v_lshl_add_u64 v[160:161], v[244:245], 0, s[30:31]
	v_readfirstlane_b32 s3, v159
	s_mov_b32 m0, s3
	v_lshl_add_u64 v[168:169], v[246:247], 0, s[30:31]
	global_load_lds_dwordx4 v[160:161], off
	v_add_u32_e32 v160, 0x2000, v159
	s_nop 0
	v_readfirstlane_b32 s3, v160
	s_mov_b32 m0, s3
	s_nop 0
	global_load_lds_dwordx4 v[168:169], off
	s_waitcnt vmcnt(6)
	s_barrier
	v_mfma_f32_16x16x32_bf16 v[30:33], v[222:225], v[194:197], v[30:33]
	v_mfma_f32_16x16x32_bf16 v[26:29], v[230:233], v[194:197], v[26:29]
	v_mfma_f32_16x16x32_bf16 v[22:25], v[222:225], v[202:205], v[22:25]
	v_mfma_f32_16x16x32_bf16 v[18:21], v[230:233], v[202:205], v[18:21]
	v_mfma_f32_16x16x32_bf16 v[14:17], v[222:225], v[210:213], v[14:17]
	v_mfma_f32_16x16x32_bf16 v[10:13], v[230:233], v[210:213], v[10:13]
	v_mfma_f32_16x16x32_bf16 v[6:9], v[222:225], v[218:221], v[6:9]
	v_mfma_f32_16x16x32_bf16 v[2:5], v[230:233], v[218:221], v[2:5]
	v_mfma_f32_16x16x32_bf16 v[30:33], v[226:229], v[198:201], v[30:33]
	v_mfma_f32_16x16x32_bf16 v[26:29], v[234:237], v[198:201], v[26:29]
	v_mfma_f32_16x16x32_bf16 v[22:25], v[226:229], v[206:209], v[22:25]
	v_mfma_f32_16x16x32_bf16 v[18:21], v[234:237], v[206:209], v[18:21]
	v_mfma_f32_16x16x32_bf16 v[14:17], v[226:229], v[214:217], v[14:17]
	v_mfma_f32_16x16x32_bf16 v[10:13], v[234:237], v[214:217], v[10:13]
	v_mfma_f32_16x16x32_bf16 v[6:9], v[226:229], v[238:241], v[6:9]
	v_mfma_f32_16x16x32_bf16 v[2:5], v[234:237], v[238:241], v[2:5]
	s_barrier
	ds_read_b128 v[168:171], v150
	ds_read_b128 v[172:175], v150 offset:1024
	ds_read_b128 v[186:189], v150 offset:2048
	ds_read_b128 v[190:193], v150 offset:3072
	v_add_u32_e32 v161, 0x4000, v142
	v_add_u32_e32 v162, 0x6000, v142
	v_readfirstlane_b32 s3, v161
	v_lshl_add_u64 v[226:227], v[182:183], 0, s[76:77]
	s_mov_b32 m0, s3
	v_readfirstlane_b32 s3, v162
	ds_read_b128 v[194:197], v146 offset:32768
	ds_read_b128 v[198:201], v146 offset:33792
	ds_read_b128 v[202:205], v145 offset:32768
	ds_read_b128 v[206:209], v145 offset:33792
	ds_read_b128 v[210:213], v144 offset:32768
	ds_read_b128 v[214:217], v144 offset:33792
	ds_read_b128 v[218:221], v143 offset:32768
	ds_read_b128 v[222:225], v143 offset:33792
	global_load_lds_dwordx4 v[226:227], off
	v_lshl_add_u64 v[226:227], v[242:243], 0, s[76:77]
	s_mov_b32 m0, s3
	s_nop 0
	global_load_lds_dwordx4 v[226:227], off
	s_waitcnt lgkmcnt(8)
	s_barrier
	s_waitcnt lgkmcnt(0)
	v_mfma_f32_16x16x32_bf16 v[126:129], v[168:171], v[194:197], v[126:129]
	v_mfma_f32_16x16x32_bf16 v[122:125], v[186:189], v[194:197], v[122:125]
	v_mfma_f32_16x16x32_bf16 v[118:121], v[168:171], v[202:205], v[118:121]
	v_mfma_f32_16x16x32_bf16 v[114:117], v[186:189], v[202:205], v[114:117]
	v_mfma_f32_16x16x32_bf16 v[110:113], v[168:171], v[210:213], v[110:113]
	v_mfma_f32_16x16x32_bf16 v[106:109], v[186:189], v[210:213], v[106:109]
	v_mfma_f32_16x16x32_bf16 v[102:105], v[168:171], v[218:221], v[102:105]
	v_mfma_f32_16x16x32_bf16 v[98:101], v[186:189], v[218:221], v[98:101]
	v_mfma_f32_16x16x32_bf16 v[126:129], v[172:175], v[198:201], v[126:129]
	v_mfma_f32_16x16x32_bf16 v[122:125], v[190:193], v[198:201], v[122:125]
	v_mfma_f32_16x16x32_bf16 v[118:121], v[172:175], v[206:209], v[118:121]
	v_mfma_f32_16x16x32_bf16 v[114:117], v[190:193], v[206:209], v[114:117]
	v_mfma_f32_16x16x32_bf16 v[110:113], v[172:175], v[214:217], v[110:113]
	v_mfma_f32_16x16x32_bf16 v[106:109], v[190:193], v[214:217], v[106:109]
	v_mfma_f32_16x16x32_bf16 v[102:105], v[172:175], v[222:225], v[102:105]
	v_mfma_f32_16x16x32_bf16 v[98:101], v[190:193], v[222:225], v[98:101]
	s_barrier
	v_readfirstlane_b32 s3, v149
	v_add_u32_e32 v167, 0x2000, v149
	v_lshl_add_u64 v[248:249], v[244:245], 0, s[34:35]
	s_mov_b32 m0, s3
	v_readfirstlane_b32 s3, v167
	ds_read_b128 v[226:229], v148
	ds_read_b128 v[230:233], v148 offset:1024
	ds_read_b128 v[234:237], v148 offset:2048
	ds_read_b128 v[238:241], v148 offset:3072
	global_load_lds_dwordx4 v[248:249], off
	v_lshl_add_u64 v[248:249], v[246:247], 0, s[34:35]
	s_mov_b32 m0, s3
	s_nop 0
	global_load_lds_dwordx4 v[248:249], off
	s_barrier
	s_waitcnt lgkmcnt(0)
	v_mfma_f32_16x16x32_bf16 v[94:97], v[226:229], v[194:197], v[94:97]
	v_mfma_f32_16x16x32_bf16 v[90:93], v[234:237], v[194:197], v[90:93]
	v_mfma_f32_16x16x32_bf16 v[86:89], v[226:229], v[202:205], v[86:89]
	v_mfma_f32_16x16x32_bf16 v[82:85], v[234:237], v[202:205], v[82:85]
	v_readfirstlane_b32 s3, v151
	v_mfma_f32_16x16x32_bf16 v[78:81], v[226:229], v[210:213], v[78:81]
	v_lshl_add_u64 v[182:183], v[182:183], 0, s[74:75]
	v_mfma_f32_16x16x32_bf16 v[74:77], v[234:237], v[210:213], v[74:77]
	s_mov_b32 m0, s3
	v_mfma_f32_16x16x32_bf16 v[70:73], v[226:229], v[218:221], v[70:73]
	v_readfirstlane_b32 s3, v152
	v_mfma_f32_16x16x32_bf16 v[66:69], v[234:237], v[218:221], v[66:69]
	v_mfma_f32_16x16x32_bf16 v[94:97], v[230:233], v[198:201], v[94:97]
	v_mfma_f32_16x16x32_bf16 v[90:93], v[238:241], v[198:201], v[90:93]
	v_mfma_f32_16x16x32_bf16 v[86:89], v[230:233], v[206:209], v[86:89]
	v_mfma_f32_16x16x32_bf16 v[82:85], v[238:241], v[206:209], v[82:85]
	v_mfma_f32_16x16x32_bf16 v[78:81], v[230:233], v[214:217], v[78:81]
	v_mfma_f32_16x16x32_bf16 v[74:77], v[238:241], v[214:217], v[74:77]
	v_mfma_f32_16x16x32_bf16 v[70:73], v[230:233], v[222:225], v[70:73]
	v_mfma_f32_16x16x32_bf16 v[66:69], v[238:241], v[222:225], v[66:69]
	s_barrier
	ds_read_b128 v[194:197], v146 offset:49152
	ds_read_b128 v[198:201], v146 offset:50176
	ds_read_b128 v[202:205], v145 offset:49152
	ds_read_b128 v[206:209], v145 offset:50176
	ds_read_b128 v[210:213], v144 offset:49152
	ds_read_b128 v[214:217], v144 offset:50176
	ds_read_b128 v[218:221], v143 offset:49152
	ds_read_b128 v[222:225], v143 offset:50176
	global_load_lds_dwordx4 v[182:183], off
	v_lshl_add_u64 v[182:183], v[242:243], 0, s[74:75]
	s_mov_b32 m0, s3
	s_nop 0
	global_load_lds_dwordx4 v[182:183], off
	s_barrier
; #define STAGE_A(P,br,kt) STAGE_G(P,c.A,c.lda,br,(long)(kt)*c.kstr)
; #define STAGE_B(P,br,kt) STAGE_G(P,c.Bt,c.K,br,(long)(kt)*BK)
; #define LDA(dst,b,h) for(int m=0;m<4;++m)for(int k=0;k<2;++k) \
;     dst[m][k]=*reinterpret_cast<const bf16x8*>((char*)SA(b,h)+lds_byte(wr*64+m*16+fr,k*32+fq*8))
; #define LDB(dst,b,h) for(int n=0;n<2;++n)for(int k=0;k<2;++k) \
;     dst[n][k]=*reinterpret_cast<const bf16x8*>((char*)SB(b,h)+lds_byte(wc*32+n*16+fr,k*32+fq*8))
; #define MMA(ai,bj,At,Bt_) do{__builtin_amdgcn_s_setprio(1); \
;     for(int m=0;m<4;++m)for(int n=0;n<2;++n)for(int k=0;k<2;++k) \
;       acc[ai][bj][m][n]=__builtin_amdgcn_mfma_f32_16x16x32_bf16(Bt_[n][k],At[m][k],acc[ai][bj][m][n],0,0,0); \
;     __builtin_amdgcn_s_setprio(0);}while(0)
; #define WAIT_V(n) asm volatile("s_waitcnt vmcnt(" #n ")":::"memory")
; #define WAIT_L(n) asm volatile("s_waitcnt lgkmcnt(" #n ")":::"memory")
; #define BAR __builtin_amdgcn_s_barrier()
; #define SCHED __builtin_amdgcn_sched_barrier(0)
; template <int EPI>
; __device__ __forceinline__ void gemm_run(const GD& c, const bool has_next, const GD& nx, const Ctx& e, bf16* shm, float* rs, float* rs_nxt, float* racc_) {
;     ...
;     WAIT_V(6); BAR; MMA(1,1,At,B1); BAR;
;     LDB(B0,1,0); SCHED; LDA(At,1,0); STAGE_A(SA(0,1),brow+HALF,t+2);
;     WAIT_L(8); BAR; WAIT_L(0); MMA(0,0,At,B0); BAR; SCHED;
;     LDB(B1,1,1); STAGE_B(SB(1,0),bcol,t+3);
;     BAR; WAIT_L(0); MMA(0,1,At,B1); BAR;
;     LDA(At,1,1); STAGE_A(SA(1,0),brow,t+3);
;     BAR; WAIT_L(0); MMA(1,0,At,B0); BAR; SCHED;
;     STAGE_B(SB(1,1),bcol+HALF,t+3);
;     WAIT_V(6); BAR; MMA(1,1,At,B1); BAR;
;   }
;   { LDB(B0,0,0); LDA(At,0,0); STAGE_A(SA(1,1),brow+HALF,nt-1);
;     BAR; WAIT_L(0); MMA(0,0,At,B0); BAR;
;     LDB(B1,0,1); BAR; WAIT_L(0); MMA(0,1,At,B1); BAR;
	s_waitcnt lgkmcnt(0)
	v_mfma_f32_16x16x32_bf16 v[62:65], v[168:171], v[194:197], v[62:65]
	v_mfma_f32_16x16x32_bf16 v[58:61], v[186:189], v[194:197], v[58:61]
	v_mfma_f32_16x16x32_bf16 v[54:57], v[168:171], v[202:205], v[54:57]
	v_mfma_f32_16x16x32_bf16 v[50:53], v[186:189], v[202:205], v[50:53]
	v_mfma_f32_16x16x32_bf16 v[46:49], v[168:171], v[210:213], v[46:49]
	v_mfma_f32_16x16x32_bf16 v[42:45], v[186:189], v[210:213], v[42:45]
	v_mfma_f32_16x16x32_bf16 v[38:41], v[168:171], v[218:221], v[38:41]
	v_mfma_f32_16x16x32_bf16 v[34:37], v[186:189], v[218:221], v[34:37]
	v_mfma_f32_16x16x32_bf16 v[62:65], v[172:175], v[198:201], v[62:65]
	v_mfma_f32_16x16x32_bf16 v[58:61], v[190:193], v[198:201], v[58:61]
	v_mfma_f32_16x16x32_bf16 v[54:57], v[172:175], v[206:209], v[54:57]
	v_mfma_f32_16x16x32_bf16 v[50:53], v[190:193], v[206:209], v[50:53]
	v_mfma_f32_16x16x32_bf16 v[46:49], v[172:175], v[214:217], v[46:49]
	v_mfma_f32_16x16x32_bf16 v[42:45], v[190:193], v[214:217], v[42:45]
	v_mfma_f32_16x16x32_bf16 v[38:41], v[172:175], v[222:225], v[38:41]
	v_mfma_f32_16x16x32_bf16 v[34:37], v[190:193], v[222:225], v[34:37]
	s_barrier
	v_readfirstlane_b32 s3, v153
	v_add_u32_e32 v167, 0x2000, v153
	v_lshl_add_u64 v[168:169], v[244:245], 0, s[36:37]
	s_mov_b32 m0, s3
	v_readfirstlane_b32 s3, v167
	global_load_lds_dwordx4 v[168:169], off
	v_lshl_add_u64 v[168:169], v[246:247], 0, s[36:37]
	s_mov_b32 m0, s3
	s_nop 0
	global_load_lds_dwordx4 v[168:169], off
	s_waitcnt vmcnt(6)
	s_barrier
	v_mfma_f32_16x16x32_bf16 v[30:33], v[226:229], v[194:197], v[30:33]
	v_mfma_f32_16x16x32_bf16 v[26:29], v[234:237], v[194:197], v[26:29]
	v_mfma_f32_16x16x32_bf16 v[22:25], v[226:229], v[202:205], v[22:25]
	v_mfma_f32_16x16x32_bf16 v[18:21], v[234:237], v[202:205], v[18:21]
	s_add_i32 s2, s2, 2
	v_mfma_f32_16x16x32_bf16 v[14:17], v[226:229], v[210:213], v[14:17]
	v_lshl_add_u64 v[132:133], v[132:133], 0, s[88:89]
	v_mfma_f32_16x16x32_bf16 v[10:13], v[234:237], v[210:213], v[10:13]
	v_lshl_add_u64 v[134:135], v[134:135], 0, s[88:89]
	v_mfma_f32_16x16x32_bf16 v[6:9], v[226:229], v[218:221], v[6:9]
	v_lshl_add_u64 v[136:137], v[136:137], 0, s[88:89]
	v_mfma_f32_16x16x32_bf16 v[2:5], v[234:237], v[218:221], v[2:5]
	s_cmp_lt_u32 s2, 38
	v_mfma_f32_16x16x32_bf16 v[30:33], v[230:233], v[198:201], v[30:33]
	v_lshl_add_u64 v[138:139], v[138:139], 0, s[88:89]
	v_mfma_f32_16x16x32_bf16 v[26:29], v[238:241], v[198:201], v[26:29]
	v_mfma_f32_16x16x32_bf16 v[22:25], v[230:233], v[206:209], v[22:25]
	v_mfma_f32_16x16x32_bf16 v[18:21], v[238:241], v[206:209], v[18:21]
	v_mfma_f32_16x16x32_bf16 v[14:17], v[230:233], v[214:217], v[14:17]
	v_mfma_f32_16x16x32_bf16 v[10:13], v[238:241], v[214:217], v[10:13]
	v_mfma_f32_16x16x32_bf16 v[6:9], v[230:233], v[222:225], v[6:9]
	v_mfma_f32_16x16x32_bf16 v[2:5], v[238:241], v[222:225], v[2:5]
	s_barrier
	s_cbranch_scc1 .LBB0_1178
	s_or_b32 s2, s15, 0x80
	s_mul_hi_i32 s3, s2, 0x1500
	s_mulk_i32 s2, 0x1500
	s_add_u32 s2, s23, s2
	s_addc_u32 s3, s24, s3
	v_readfirstlane_b32 s28, v163
	v_lshl_add_u64 v[152:153], s[2:3], 0, v[0:1]
	s_mov_b32 m0, s28
	ds_read_b128 v[132:135], v155
	ds_read_b128 v[136:139], v155 offset:1024
	ds_read_b128 v[168:171], v155 offset:2048
	ds_read_b128 v[172:175], v155 offset:3072
	ds_read_b128 v[186:189], v146
	ds_read_b128 v[190:193], v146 offset:1024
	ds_read_b128 v[194:197], v145
	ds_read_b128 v[198:201], v145 offset:1024
	ds_read_b128 v[202:205], v144
	ds_read_b128 v[206:209], v144 offset:1024
	ds_read_b128 v[210:213], v143
	ds_read_b128 v[214:217], v143 offset:1024
	global_load_lds_dwordx4 v[152:153], off
	v_lshl_add_u64 v[152:153], s[2:3], 0, v[130:131]
	v_readfirstlane_b32 s2, v166
	s_mov_b32 m0, s2
	s_nop 0
	global_load_lds_dwordx4 v[152:153], off
	s_barrier
	s_waitcnt lgkmcnt(0)
	v_mfma_f32_16x16x32_bf16 v[126:129], v[132:135], v[186:189], v[126:129]
	v_mfma_f32_16x16x32_bf16 v[122:125], v[168:171], v[186:189], v[122:125]
	v_mfma_f32_16x16x32_bf16 v[118:121], v[132:135], v[194:197], v[118:121]
	v_mfma_f32_16x16x32_bf16 v[114:117], v[168:171], v[194:197], v[114:117]
	v_mfma_f32_16x16x32_bf16 v[102:105], v[132:135], v[210:213], v[102:105]
	v_mfma_f32_16x16x32_bf16 v[98:101], v[168:171], v[210:213], v[98:101]
	v_mfma_f32_16x16x32_bf16 v[126:129], v[136:139], v[190:193], v[126:129]
	v_mfma_f32_16x16x32_bf16 v[122:125], v[172:175], v[190:193], v[122:125]
	v_mfma_f32_16x16x32_bf16 v[118:121], v[136:139], v[198:201], v[118:121]
	v_mfma_f32_16x16x32_bf16 v[114:117], v[172:175], v[198:201], v[114:117]
	v_mfma_f32_16x16x32_bf16 v[110:113], v[132:135], v[202:205], v[110:113]
	v_mfma_f32_16x16x32_bf16 v[106:109], v[168:171], v[202:205], v[106:109]
	v_mfma_f32_16x16x32_bf16 v[102:105], v[136:139], v[214:217], v[102:105]
	v_mfma_f32_16x16x32_bf16 v[98:101], v[172:175], v[214:217], v[98:101]
	v_mfma_f32_16x16x32_bf16 v[218:221], v[136:139], v[206:209], v[110:113]
	v_mfma_f32_16x16x32_bf16 v[222:225], v[172:175], v[206:209], v[106:109]
	s_barrier
	s_nop 1
	ds_read_b128 v[106:109], v154
	ds_read_b128 v[110:113], v154 offset:1024
	ds_read_b128 v[226:229], v154 offset:2048
	ds_read_b128 v[152:155], v154 offset:3072
	s_barrier
; #define LDA(dst,b,h) for(int m=0;m<4;++m)for(int k=0;k<2;++k) \
;     dst[m][k]=*reinterpret_cast<const bf16x8*>((char*)SA(b,h)+lds_byte(wr*64+m*16+fr,k*32+fq*8))
; #define LDB(dst,b,h) for(int n=0;n<2;++n)for(int k=0;k<2;++k) \
;     dst[n][k]=*reinterpret_cast<const bf16x8*>((char*)SB(b,h)+lds_byte(wc*32+n*16+fr,k*32+fq*8))
; #define MMA(ai,bj,At,Bt_) do{__builtin_amdgcn_s_setprio(1); \
;     for(int m=0;m<4;++m)for(int n=0;n<2;++n)for(int k=0;k<2;++k) \
;       acc[ai][bj][m][n]=__builtin_amdgcn_mfma_f32_16x16x32_bf16(Bt_[n][k],At[m][k],acc[ai][bj][m][n],0,0,0); \
;     __builtin_amdgcn_s_setprio(0);}while(0)
; #define WAIT_V(n) asm volatile("s_waitcnt vmcnt(" #n ")":::"memory")
; #define WAIT_L(n) asm volatile("s_waitcnt lgkmcnt(" #n ")":::"memory")
; #define BAR __builtin_amdgcn_s_barrier()
; template <int EPI>
; __device__ __forceinline__ void gemm_run(const GD& c, const bool has_next, const GD& nx, const Ctx& e, bf16* shm, float* rs, float* rs_nxt, float* racc_) {
;     ...
;     BAR; WAIT_L(0); MMA(0,0,At,B0); BAR;
;     LDB(B1,0,1); BAR; WAIT_L(0); MMA(0,1,At,B1); BAR;
;     LDA(At,0,1); WAIT_V(4); BAR; WAIT_L(0); MMA(1,0,At,B0); MMA(1,1,At,B1); BAR; }
;   { LDB(B0,1,0); LDA(At,1,0); WAIT_V(2); BAR; WAIT_L(0); MMA(0,0,At,B0); BAR;
;     LDB(B1,1,1); WAIT_V(0); BAR; WAIT_L(0); MMA(0,1,At,B1); BAR;
;     LDA(At,1,1); BAR; WAIT_L(0); MMA(1,0,At,B0); MMA(1,1,At,B1); BAR; }
	s_waitcnt lgkmcnt(0)
	v_mfma_f32_16x16x32_bf16 v[86:89], v[106:109], v[194:197], v[86:89]
	v_mfma_f32_16x16x32_bf16 v[82:85], v[226:229], v[194:197], v[82:85]
	v_mfma_f32_16x16x32_bf16 v[70:73], v[106:109], v[210:213], v[70:73]
	v_mfma_f32_16x16x32_bf16 v[66:69], v[226:229], v[210:213], v[66:69]
	v_mfma_f32_16x16x32_bf16 v[94:97], v[106:109], v[186:189], v[94:97]
	v_mfma_f32_16x16x32_bf16 v[90:93], v[226:229], v[186:189], v[90:93]
	v_mfma_f32_16x16x32_bf16 v[86:89], v[110:113], v[198:201], v[86:89]
	v_mfma_f32_16x16x32_bf16 v[82:85], v[152:155], v[198:201], v[82:85]
	v_mfma_f32_16x16x32_bf16 v[78:81], v[106:109], v[202:205], v[78:81]
	v_mfma_f32_16x16x32_bf16 v[74:77], v[226:229], v[202:205], v[74:77]
	v_mfma_f32_16x16x32_bf16 v[70:73], v[110:113], v[214:217], v[70:73]
	v_mfma_f32_16x16x32_bf16 v[66:69], v[152:155], v[214:217], v[66:69]
	v_mfma_f32_16x16x32_bf16 v[230:233], v[110:113], v[190:193], v[94:97]
	v_mfma_f32_16x16x32_bf16 v[186:189], v[152:155], v[190:193], v[90:93]
	v_mfma_f32_16x16x32_bf16 v[190:193], v[110:113], v[206:209], v[78:81]
	v_mfma_f32_16x16x32_bf16 v[194:197], v[152:155], v[206:209], v[74:77]
	s_barrier
	s_nop 0
	ds_read_b128 v[74:77], v146 offset:16384
	ds_read_b128 v[78:81], v146 offset:17408
	ds_read_b128 v[90:93], v145 offset:16384
	ds_read_b128 v[94:97], v145 offset:17408
	ds_read_b128 v[198:201], v144 offset:16384
	ds_read_b128 v[202:205], v144 offset:17408
	ds_read_b128 v[206:209], v143 offset:16384
	ds_read_b128 v[210:213], v143 offset:17408
	s_waitcnt vmcnt(4)
	s_barrier
	s_waitcnt lgkmcnt(0)
	v_mfma_f32_16x16x32_bf16 v[62:65], v[132:135], v[74:77], v[62:65]
	v_mfma_f32_16x16x32_bf16 v[58:61], v[168:171], v[74:77], v[58:61]
	v_mfma_f32_16x16x32_bf16 v[54:57], v[132:135], v[90:93], v[54:57]
	v_mfma_f32_16x16x32_bf16 v[50:53], v[168:171], v[90:93], v[50:53]
	v_mfma_f32_16x16x32_bf16 v[38:41], v[132:135], v[206:209], v[38:41]
	v_mfma_f32_16x16x32_bf16 v[34:37], v[168:171], v[206:209], v[34:37]
	v_mfma_f32_16x16x32_bf16 v[62:65], v[136:139], v[78:81], v[62:65]
	v_mfma_f32_16x16x32_bf16 v[58:61], v[172:175], v[78:81], v[58:61]
	v_mfma_f32_16x16x32_bf16 v[54:57], v[136:139], v[94:97], v[54:57]
	v_mfma_f32_16x16x32_bf16 v[50:53], v[172:175], v[94:97], v[50:53]
	v_mfma_f32_16x16x32_bf16 v[46:49], v[132:135], v[198:201], v[46:49]
	v_mfma_f32_16x16x32_bf16 v[42:45], v[168:171], v[198:201], v[42:45]
	v_mfma_f32_16x16x32_bf16 v[38:41], v[136:139], v[210:213], v[38:41]
	v_mfma_f32_16x16x32_bf16 v[34:37], v[172:175], v[210:213], v[34:37]
	v_mfma_f32_16x16x32_bf16 v[214:217], v[136:139], v[202:205], v[46:49]
	v_mfma_f32_16x16x32_bf16 v[234:237], v[172:175], v[202:205], v[42:45]
	v_mfma_f32_16x16x32_bf16 v[22:25], v[106:109], v[90:93], v[22:25]
	v_mfma_f32_16x16x32_bf16 v[18:21], v[226:229], v[90:93], v[18:21]
	v_mfma_f32_16x16x32_bf16 v[6:9], v[106:109], v[206:209], v[6:9]
	v_mfma_f32_16x16x32_bf16 v[2:5], v[226:229], v[206:209], v[2:5]
	v_mfma_f32_16x16x32_bf16 v[30:33], v[106:109], v[74:77], v[30:33]
	v_mfma_f32_16x16x32_bf16 v[26:29], v[226:229], v[74:77], v[26:29]
	v_mfma_f32_16x16x32_bf16 v[22:25], v[110:113], v[94:97], v[22:25]
	v_mfma_f32_16x16x32_bf16 v[18:21], v[152:155], v[94:97], v[18:21]
	v_mfma_f32_16x16x32_bf16 v[14:17], v[106:109], v[198:201], v[14:17]
	v_mfma_f32_16x16x32_bf16 v[10:13], v[226:229], v[198:201], v[10:13]
	v_mfma_f32_16x16x32_bf16 v[6:9], v[110:113], v[210:213], v[6:9]
	v_mfma_f32_16x16x32_bf16 v[2:5], v[152:155], v[210:213], v[2:5]
	v_mfma_f32_16x16x32_bf16 v[132:135], v[110:113], v[78:81], v[30:33]
	v_mfma_f32_16x16x32_bf16 v[136:139], v[152:155], v[78:81], v[26:29]
	v_mfma_f32_16x16x32_bf16 v[166:169], v[110:113], v[202:205], v[14:17]
	v_mfma_f32_16x16x32_bf16 v[170:173], v[152:155], v[202:205], v[10:13]
	s_barrier
	s_nop 0
	ds_read_b128 v[10:13], v150
	ds_read_b128 v[14:17], v150 offset:1024
	ds_read_b128 v[152:155], v150 offset:2048
	ds_read_b128 v[198:201], v150 offset:3072
	ds_read_b128 v[26:29], v146 offset:32768
	ds_read_b128 v[30:33], v146 offset:33792
	ds_read_b128 v[42:45], v145 offset:32768
	ds_read_b128 v[46:49], v145 offset:33792
	ds_read_b128 v[202:205], v144 offset:32768
	ds_read_b128 v[206:209], v144 offset:33792
	ds_read_b128 v[210:213], v143 offset:32768
	ds_read_b128 v[226:229], v143 offset:33792
	s_waitcnt vmcnt(2)
	s_barrier
; #define LDA(dst,b,h) for(int m=0;m<4;++m)for(int k=0;k<2;++k) \
;     dst[m][k]=*reinterpret_cast<const bf16x8*>((char*)SA(b,h)+lds_byte(wr*64+m*16+fr,k*32+fq*8))
; #define LDB(dst,b,h) for(int n=0;n<2;++n)for(int k=0;k<2;++k) \
;     dst[n][k]=*reinterpret_cast<const bf16x8*>((char*)SB(b,h)+lds_byte(wc*32+n*16+fr,k*32+fq*8))
; #define MMA(ai,bj,At,Bt_) do{__builtin_amdgcn_s_setprio(1); \
;     for(int m=0;m<4;++m)for(int n=0;n<2;++n)for(int k=0;k<2;++k) \
;       acc[ai][bj][m][n]=__builtin_amdgcn_mfma_f32_16x16x32_bf16(Bt_[n][k],At[m][k],acc[ai][bj][m][n],0,0,0); \
;     __builtin_amdgcn_s_setprio(0);}while(0)
; #define WAIT_V(n) asm volatile("s_waitcnt vmcnt(" #n ")":::"memory")
; #define WAIT_L(n) asm volatile("s_waitcnt lgkmcnt(" #n ")":::"memory")
; #define BAR __builtin_amdgcn_s_barrier()
; template <int EPI>
; __device__ __forceinline__ void gemm_run(const GD& c, const bool has_next, const GD& nx, const Ctx& e, bf16* shm, float* rs, float* rs_nxt, float* racc_) {
;     ...
;     LDA(At,0,1); WAIT_V(4); BAR; WAIT_L(0); MMA(1,0,At,B0); MMA(1,1,At,B1); BAR; }
;   { LDB(B0,1,0); LDA(At,1,0); WAIT_V(2); BAR; WAIT_L(0); MMA(0,0,At,B0); BAR;
;     LDB(B1,1,1); WAIT_V(0); BAR; WAIT_L(0); MMA(0,1,At,B1); BAR;
;     LDA(At,1,1); BAR; WAIT_L(0); MMA(1,0,At,B0); MMA(1,1,At,B1); BAR; }
;   if(wr==0)BAR;
	s_waitcnt lgkmcnt(0)
	v_mfma_f32_16x16x32_bf16 v[74:77], v[10:13], v[26:29], v[126:129]
	v_mfma_f32_16x16x32_bf16 v[126:129], v[14:17], v[30:33], v[74:77]
	v_mfma_f32_16x16x32_bf16 v[74:77], v[152:155], v[26:29], v[122:125]
	v_mfma_f32_16x16x32_bf16 v[122:125], v[198:201], v[30:33], v[74:77]
	v_mfma_f32_16x16x32_bf16 v[74:77], v[10:13], v[42:45], v[118:121]
	v_mfma_f32_16x16x32_bf16 v[110:113], v[14:17], v[46:49], v[74:77]
	v_mfma_f32_16x16x32_bf16 v[74:77], v[152:155], v[42:45], v[114:117]
	v_mfma_f32_16x16x32_bf16 v[106:109], v[198:201], v[46:49], v[74:77]
	v_mfma_f32_16x16x32_bf16 v[74:77], v[10:13], v[202:205], v[218:221]
	v_mfma_f32_16x16x32_bf16 v[94:97], v[14:17], v[206:209], v[74:77]
	v_mfma_f32_16x16x32_bf16 v[74:77], v[152:155], v[202:205], v[222:225]
	v_mfma_f32_16x16x32_bf16 v[90:93], v[198:201], v[206:209], v[74:77]
	v_mfma_f32_16x16x32_bf16 v[74:77], v[10:13], v[210:213], v[102:105]
	v_mfma_f32_16x16x32_bf16 v[78:81], v[14:17], v[226:229], v[74:77]
	v_mfma_f32_16x16x32_bf16 v[74:77], v[152:155], v[210:213], v[98:101]
	v_mfma_f32_16x16x32_bf16 v[74:77], v[198:201], v[226:229], v[74:77]
	s_barrier
	ds_read_b128 v[218:221], v148
	ds_read_b128 v[222:225], v148 offset:1024
	ds_read_b128 v[238:241], v148 offset:2048
	ds_read_b128 v[148:151], v148 offset:3072
	s_waitcnt vmcnt(0)
	s_barrier
	s_waitcnt lgkmcnt(0)
	v_mfma_f32_16x16x32_bf16 v[98:101], v[218:221], v[26:29], v[230:233]
	v_mfma_f32_16x16x32_bf16 v[26:29], v[238:241], v[26:29], v[186:189]
	v_mfma_f32_16x16x32_bf16 v[114:117], v[148:151], v[30:33], v[26:29]
	v_mfma_f32_16x16x32_bf16 v[26:29], v[218:221], v[42:45], v[86:89]
	v_mfma_f32_16x16x32_bf16 v[102:105], v[222:225], v[46:49], v[26:29]
	v_mfma_f32_16x16x32_bf16 v[26:29], v[238:241], v[42:45], v[82:85]
	v_mfma_f32_16x16x32_bf16 v[118:121], v[222:225], v[30:33], v[98:101]
	v_mfma_f32_16x16x32_bf16 v[98:101], v[148:151], v[46:49], v[26:29]
	v_mfma_f32_16x16x32_bf16 v[26:29], v[218:221], v[202:205], v[190:193]
	v_mfma_f32_16x16x32_bf16 v[86:89], v[222:225], v[206:209], v[26:29]
	v_mfma_f32_16x16x32_bf16 v[26:29], v[238:241], v[202:205], v[194:197]
	v_mfma_f32_16x16x32_bf16 v[82:85], v[148:151], v[206:209], v[26:29]
	v_mfma_f32_16x16x32_bf16 v[26:29], v[218:221], v[210:213], v[70:73]
	v_mfma_f32_16x16x32_bf16 v[70:73], v[222:225], v[226:229], v[26:29]
	v_mfma_f32_16x16x32_bf16 v[26:29], v[238:241], v[210:213], v[66:69]
	v_mfma_f32_16x16x32_bf16 v[66:69], v[148:151], v[226:229], v[26:29]
	s_barrier
	ds_read_b128 v[186:189], v146 offset:49152
	ds_read_b128 v[190:193], v146 offset:50176
	ds_read_b128 v[194:197], v145 offset:49152
	ds_read_b128 v[202:205], v145 offset:50176
	ds_read_b128 v[206:209], v144 offset:49152
	ds_read_b128 v[144:147], v144 offset:50176
	ds_read_b128 v[210:213], v143 offset:49152
	ds_read_b128 v[226:229], v143 offset:50176
	s_barrier
	s_waitcnt lgkmcnt(0)
	v_mfma_f32_16x16x32_bf16 v[26:29], v[10:13], v[186:189], v[62:65]
	v_mfma_f32_16x16x32_bf16 v[62:65], v[14:17], v[190:193], v[26:29]
	v_mfma_f32_16x16x32_bf16 v[26:29], v[152:155], v[186:189], v[58:61]
	v_mfma_f32_16x16x32_bf16 v[58:61], v[198:201], v[190:193], v[26:29]
	v_mfma_f32_16x16x32_bf16 v[26:29], v[10:13], v[194:197], v[54:57]
	v_mfma_f32_16x16x32_bf16 v[46:49], v[14:17], v[202:205], v[26:29]
	v_mfma_f32_16x16x32_bf16 v[26:29], v[152:155], v[194:197], v[50:53]
	v_mfma_f32_16x16x32_bf16 v[42:45], v[198:201], v[202:205], v[26:29]
	v_mfma_f32_16x16x32_bf16 v[26:29], v[10:13], v[206:209], v[214:217]
	v_mfma_f32_16x16x32_bf16 v[10:13], v[10:13], v[210:213], v[38:41]
	v_mfma_f32_16x16x32_bf16 v[30:33], v[14:17], v[144:147], v[26:29]
	v_mfma_f32_16x16x32_bf16 v[26:29], v[152:155], v[206:209], v[234:237]
	v_mfma_f32_16x16x32_bf16 v[14:17], v[14:17], v[226:229], v[10:13]
	v_mfma_f32_16x16x32_bf16 v[10:13], v[152:155], v[210:213], v[34:37]
	v_mfma_f32_16x16x32_bf16 v[26:29], v[198:201], v[144:147], v[26:29]
	v_mfma_f32_16x16x32_bf16 v[10:13], v[198:201], v[226:229], v[10:13]
	v_mfma_f32_16x16x32_bf16 v[34:37], v[218:221], v[186:189], v[132:135]
	v_mfma_f32_16x16x32_bf16 v[54:57], v[222:225], v[190:193], v[34:37]
	v_mfma_f32_16x16x32_bf16 v[34:37], v[238:241], v[186:189], v[136:139]
	v_mfma_f32_16x16x32_bf16 v[18:21], v[238:241], v[194:197], v[18:21]
	v_mfma_f32_16x16x32_bf16 v[50:53], v[148:151], v[190:193], v[34:37]
	v_mfma_f32_16x16x32_bf16 v[22:25], v[218:221], v[194:197], v[22:25]
	v_mfma_f32_16x16x32_bf16 v[34:37], v[148:151], v[202:205], v[18:21]
	v_mfma_f32_16x16x32_bf16 v[18:21], v[218:221], v[206:209], v[166:169]
	v_mfma_f32_16x16x32_bf16 v[38:41], v[222:225], v[202:205], v[22:25]
	v_mfma_f32_16x16x32_bf16 v[22:25], v[222:225], v[144:147], v[18:21]
	v_mfma_f32_16x16x32_bf16 v[18:21], v[238:241], v[206:209], v[170:173]
	v_mfma_f32_16x16x32_bf16 v[6:9], v[218:221], v[210:213], v[6:9]
	v_mfma_f32_16x16x32_bf16 v[2:5], v[238:241], v[210:213], v[2:5]
	v_mfma_f32_16x16x32_bf16 v[18:21], v[148:151], v[144:147], v[18:21]
	v_mfma_f32_16x16x32_bf16 v[6:9], v[222:225], v[226:229], v[6:9]
	v_mfma_f32_16x16x32_bf16 v[2:5], v[148:151], v[226:229], v[2:5]
	v_cmp_gt_u32_e32 vcc, s96, v141
	s_barrier
	s_and_saveexec_b64 s[2:3], vcc
	s_cbranch_execz .LBB0_1181
	s_barrier

; #define STAGE_A(P,br,kt) STAGE_G(P,c.A,c.lda,br,(long)(kt)*c.kstr)
; #define STAGE_B(P,br,kt) STAGE_G(P,c.Bt,c.K,br,(long)(kt)*BK)
; #define LDA(dst,b,h) for(int m=0;m<4;++m)for(int k=0;k<2;++k) \
;     dst[m][k]=*reinterpret_cast<const bf16x8*>((char*)SA(b,h)+lds_byte(wr*64+m*16+fr,k*32+fq*8))
; #define LDB(dst,b,h) for(int n=0;n<2;++n)for(int k=0;k<2;++k) \
;     dst[n][k]=*reinterpret_cast<const bf16x8*>((char*)SB(b,h)+lds_byte(wc*32+n*16+fr,k*32+fq*8))
; #define MMA(ai,bj,At,Bt_) do{__builtin_amdgcn_s_setprio(1); \
;     for(int m=0;m<4;++m)for(int n=0;n<2;++n)for(int k=0;k<2;++k) \
;       acc[ai][bj][m][n]=__builtin_amdgcn_mfma_f32_16x16x32_bf16(Bt_[n][k],At[m][k],acc[ai][bj][m][n],0,0,0); \
;     __builtin_amdgcn_s_setprio(0);}while(0)
; #define WAIT_V(n) asm volatile("s_waitcnt vmcnt(" #n ")":::"memory")
; #define WAIT_L(n) asm volatile("s_waitcnt lgkmcnt(" #n ")":::"memory")
; #define BAR __builtin_amdgcn_s_barrier()
; #define SCHED __builtin_amdgcn_sched_barrier(0)
; template <int EPI>
; __device__ __forceinline__ void gemm_run(const GD& c, const bool has_next, const GD& nx, const Ctx& e, bf16* shm, float* rs, float* rs_nxt, float* racc_) {
;     ...
;   for(int t=0;t<nt-2;t+=2){
;     LDB(B0,0,0); SCHED; LDA(At,0,0); STAGE_A(SA(1,1),brow+HALF,t+1);
;     WAIT_L(8); BAR; WAIT_L(0); MMA(0,0,At,B0); BAR; SCHED;
;     LDB(B1,0,1); STAGE_B(SB(0,0),bcol,t+2);
;     BAR; WAIT_L(0); MMA(0,1,At,B1); BAR;
;     LDA(At,0,1); STAGE_A(SA(0,0),brow,t+2);
;     BAR; WAIT_L(0); MMA(1,0,At,B0); BAR; SCHED;
;     STAGE_B(SB(0,1),bcol+HALF,t+2);
;     WAIT_V(6); BAR; MMA(1,1,At,B1); BAR;
.LBB0_1426:
	ds_read_b128 v[168:171], v155
	ds_read_b128 v[172:175], v155 offset:1024
	ds_read_b128 v[186:189], v155 offset:2048
	ds_read_b128 v[190:193], v155 offset:3072
	v_add_u32_e32 v163, 0xc000, v142
	v_lshl_add_u64 v[182:183], s[2:3], 0, v[132:133]
	v_readfirstlane_b32 s15, v163
	v_add_u32_e32 v166, 0xe000, v142
	v_lshl_add_u64 v[156:157], v[182:183], 0, s[90:91]
	s_mov_b32 m0, s15
	v_lshl_add_u64 v[242:243], s[2:3], 0, v[134:135]
	v_readfirstlane_b32 s15, v166
	ds_read_b128 v[158:161], v146
	ds_read_b128 v[194:197], v146 offset:1024
	ds_read_b128 v[198:201], v145
	ds_read_b128 v[202:205], v145 offset:1024
	ds_read_b128 v[206:209], v144
	ds_read_b128 v[210:213], v144 offset:1024
	ds_read_b128 v[214:217], v143
	ds_read_b128 v[218:221], v143 offset:1024
	global_load_lds_dwordx4 v[156:157], off
	v_lshl_add_u64 v[156:157], v[242:243], 0, s[90:91]
	s_mov_b32 m0, s15
	s_nop 0
	global_load_lds_dwordx4 v[156:157], off
	s_waitcnt lgkmcnt(8)
	s_barrier
	s_waitcnt lgkmcnt(0)
	v_mfma_f32_16x16x32_bf16 v[126:129], v[168:171], v[158:161], v[126:129]
	v_mfma_f32_16x16x32_bf16 v[122:125], v[186:189], v[158:161], v[122:125]
	v_mfma_f32_16x16x32_bf16 v[118:121], v[168:171], v[198:201], v[118:121]
	v_mfma_f32_16x16x32_bf16 v[114:117], v[186:189], v[198:201], v[114:117]
	v_mfma_f32_16x16x32_bf16 v[110:113], v[168:171], v[206:209], v[110:113]
	v_mfma_f32_16x16x32_bf16 v[106:109], v[186:189], v[206:209], v[106:109]
	v_mfma_f32_16x16x32_bf16 v[102:105], v[168:171], v[214:217], v[102:105]
	v_mfma_f32_16x16x32_bf16 v[98:101], v[186:189], v[214:217], v[98:101]
	v_mfma_f32_16x16x32_bf16 v[126:129], v[172:175], v[194:197], v[126:129]
	v_mfma_f32_16x16x32_bf16 v[122:125], v[190:193], v[194:197], v[122:125]
	v_mfma_f32_16x16x32_bf16 v[118:121], v[172:175], v[202:205], v[118:121]
	v_mfma_f32_16x16x32_bf16 v[114:117], v[190:193], v[202:205], v[114:117]
	v_mfma_f32_16x16x32_bf16 v[110:113], v[172:175], v[210:213], v[110:113]
	v_mfma_f32_16x16x32_bf16 v[106:109], v[190:193], v[210:213], v[106:109]
	v_mfma_f32_16x16x32_bf16 v[102:105], v[172:175], v[218:221], v[102:105]
	v_mfma_f32_16x16x32_bf16 v[98:101], v[190:193], v[218:221], v[98:101]
	s_barrier
	v_add_u32_e32 v156, s33, v148
	v_lshl_add_u64 v[244:245], s[2:3], 0, v[136:137]
	v_readfirstlane_b32 s15, v156
	v_add_u32_e32 v157, 0x2000, v156
	v_lshl_add_u64 v[238:239], v[244:245], 0, s[28:29]
	s_mov_b32 m0, s15
	v_lshl_add_u64 v[246:247], s[2:3], 0, v[138:139]
	v_readfirstlane_b32 s15, v157
	ds_read_b128 v[222:225], v154
	ds_read_b128 v[226:229], v154 offset:1024
	ds_read_b128 v[230:233], v154 offset:2048
	ds_read_b128 v[234:237], v154 offset:3072
	global_load_lds_dwordx4 v[238:239], off
	v_lshl_add_u64 v[238:239], v[246:247], 0, s[28:29]
	s_mov_b32 m0, s15
	s_nop 0
	global_load_lds_dwordx4 v[238:239], off
	s_barrier
	s_waitcnt lgkmcnt(0)
	v_mfma_f32_16x16x32_bf16 v[94:97], v[222:225], v[158:161], v[94:97]
	v_mfma_f32_16x16x32_bf16 v[90:93], v[230:233], v[158:161], v[90:93]
	v_mfma_f32_16x16x32_bf16 v[86:89], v[222:225], v[198:201], v[86:89]
	v_mfma_f32_16x16x32_bf16 v[82:85], v[230:233], v[198:201], v[82:85]
	v_mfma_f32_16x16x32_bf16 v[78:81], v[222:225], v[206:209], v[78:81]
	v_mfma_f32_16x16x32_bf16 v[74:77], v[230:233], v[206:209], v[74:77]
	v_mfma_f32_16x16x32_bf16 v[70:73], v[222:225], v[214:217], v[70:73]
	v_mfma_f32_16x16x32_bf16 v[66:69], v[230:233], v[214:217], v[66:69]
	v_mfma_f32_16x16x32_bf16 v[94:97], v[226:229], v[194:197], v[94:97]
	v_mfma_f32_16x16x32_bf16 v[90:93], v[234:237], v[194:197], v[90:93]
	v_mfma_f32_16x16x32_bf16 v[86:89], v[226:229], v[202:205], v[86:89]
	v_mfma_f32_16x16x32_bf16 v[82:85], v[234:237], v[202:205], v[82:85]
	v_mfma_f32_16x16x32_bf16 v[78:81], v[226:229], v[210:213], v[78:81]
	v_mfma_f32_16x16x32_bf16 v[74:77], v[234:237], v[210:213], v[74:77]
	v_mfma_f32_16x16x32_bf16 v[70:73], v[226:229], v[218:221], v[70:73]
	v_mfma_f32_16x16x32_bf16 v[66:69], v[234:237], v[218:221], v[66:69]
	v_readfirstlane_b32 s15, v142
	v_lshl_add_u64 v[158:159], v[182:183], 0, s[0:1]
	s_mov_b32 m0, s15
	s_barrier
	ds_read_b128 v[194:197], v146 offset:16384
	ds_read_b128 v[198:201], v146 offset:17408
	ds_read_b128 v[202:205], v145 offset:16384
	ds_read_b128 v[206:209], v145 offset:17408
	ds_read_b128 v[210:213], v144 offset:16384
	ds_read_b128 v[214:217], v144 offset:17408
	ds_read_b128 v[218:221], v143 offset:16384
	ds_read_b128 v[238:241], v143 offset:17408
	global_load_lds_dwordx4 v[158:159], off
	v_add_u32_e32 v158, 0x2000, v142
	v_lshl_add_u64 v[160:161], v[242:243], 0, s[0:1]
	v_readfirstlane_b32 s15, v158
	s_mov_b32 m0, s15
	s_nop 0
	global_load_lds_dwordx4 v[160:161], off
	s_barrier
	s_waitcnt lgkmcnt(0)
	v_mfma_f32_16x16x32_bf16 v[62:65], v[168:171], v[194:197], v[62:65]
	v_mfma_f32_16x16x32_bf16 v[58:61], v[186:189], v[194:197], v[58:61]
	v_mfma_f32_16x16x32_bf16 v[54:57], v[168:171], v[202:205], v[54:57]
	v_mfma_f32_16x16x32_bf16 v[50:53], v[186:189], v[202:205], v[50:53]
	v_mfma_f32_16x16x32_bf16 v[46:49], v[168:171], v[210:213], v[46:49]
	v_mfma_f32_16x16x32_bf16 v[42:45], v[186:189], v[210:213], v[42:45]
	v_mfma_f32_16x16x32_bf16 v[38:41], v[168:171], v[218:221], v[38:41]
	v_mfma_f32_16x16x32_bf16 v[34:37], v[186:189], v[218:221], v[34:37]
	v_mfma_f32_16x16x32_bf16 v[62:65], v[172:175], v[198:201], v[62:65]
	v_mfma_f32_16x16x32_bf16 v[58:61], v[190:193], v[198:201], v[58:61]
	v_mfma_f32_16x16x32_bf16 v[54:57], v[172:175], v[206:209], v[54:57]
	v_mfma_f32_16x16x32_bf16 v[50:53], v[190:193], v[206:209], v[50:53]
	v_mfma_f32_16x16x32_bf16 v[46:49], v[172:175], v[214:217], v[46:49]
	v_mfma_f32_16x16x32_bf16 v[42:45], v[190:193], v[214:217], v[42:45]
	v_mfma_f32_16x16x32_bf16 v[38:41], v[172:175], v[238:241], v[38:41]
	v_mfma_f32_16x16x32_bf16 v[34:37], v[190:193], v[238:241], v[34:37]
	s_barrier
; #define STAGE_A(P,br,kt) STAGE_G(P,c.A,c.lda,br,(long)(kt)*c.kstr)
; #define STAGE_B(P,br,kt) STAGE_G(P,c.Bt,c.K,br,(long)(kt)*BK)
; #define LDA(dst,b,h) for(int m=0;m<4;++m)for(int k=0;k<2;++k) \
;     dst[m][k]=*reinterpret_cast<const bf16x8*>((char*)SA(b,h)+lds_byte(wr*64+m*16+fr,k*32+fq*8))
; #define LDB(dst,b,h) for(int n=0;n<2;++n)for(int k=0;k<2;++k) \
;     dst[n][k]=*reinterpret_cast<const bf16x8*>((char*)SB(b,h)+lds_byte(wc*32+n*16+fr,k*32+fq*8))
; #define MMA(ai,bj,At,Bt_) do{__builtin_amdgcn_s_setprio(1); \
;     for(int m=0;m<4;++m)for(int n=0;n<2;++n)for(int k=0;k<2;++k) \
;       acc[ai][bj][m][n]=__builtin_amdgcn_mfma_f32_16x16x32_bf16(Bt_[n][k],At[m][k],acc[ai][bj][m][n],0,0,0); \
;     __builtin_amdgcn_s_setprio(0);}while(0)
; #define WAIT_V(n) asm volatile("s_waitcnt vmcnt(" #n ")":::"memory")
; #define WAIT_L(n) asm volatile("s_waitcnt lgkmcnt(" #n ")":::"memory")
; #define BAR __builtin_amdgcn_s_barrier()
; #define SCHED __builtin_amdgcn_sched_barrier(0)
; template <int EPI>
; __device__ __forceinline__ void gemm_run(const GD& c, const bool has_next, const GD& nx, const Ctx& e, bf16* shm, float* rs, float* rs_nxt, float* racc_) {
;     ...
;     STAGE_B(SB(0,1),bcol+HALF,t+2);
;     WAIT_V(6); BAR; MMA(1,1,At,B1); BAR;
;     LDB(B0,1,0); SCHED; LDA(At,1,0); STAGE_A(SA(0,1),brow+HALF,t+2);
;     WAIT_L(8); BAR; WAIT_L(0); MMA(0,0,At,B0); BAR; SCHED;
;     LDB(B1,1,1); STAGE_B(SB(1,0),bcol,t+3);
;     BAR; WAIT_L(0); MMA(0,1,At,B1); BAR;
;     LDA(At,1,1); STAGE_A(SA(1,0),brow,t+3);
;     BAR; WAIT_L(0); MMA(1,0,At,B0); BAR; SCHED;
;     STAGE_B(SB(1,1),bcol+HALF,t+3);
;     WAIT_V(6); BAR; MMA(1,1,At,B1); BAR;
	v_add_u32_e32 v159, s86, v148
	v_lshl_add_u64 v[160:161], v[244:245], 0, s[30:31]
	v_readfirstlane_b32 s15, v159
	s_mov_b32 m0, s15
	v_lshl_add_u64 v[168:169], v[246:247], 0, s[30:31]
	global_load_lds_dwordx4 v[160:161], off
	v_add_u32_e32 v160, 0x2000, v159
	s_nop 0
	v_readfirstlane_b32 s15, v160
	s_mov_b32 m0, s15
	s_nop 0
	global_load_lds_dwordx4 v[168:169], off
	s_waitcnt vmcnt(6)
	s_barrier
	v_mfma_f32_16x16x32_bf16 v[30:33], v[222:225], v[194:197], v[30:33]
	v_mfma_f32_16x16x32_bf16 v[26:29], v[230:233], v[194:197], v[26:29]
	v_mfma_f32_16x16x32_bf16 v[22:25], v[222:225], v[202:205], v[22:25]
	v_mfma_f32_16x16x32_bf16 v[18:21], v[230:233], v[202:205], v[18:21]
	v_mfma_f32_16x16x32_bf16 v[14:17], v[222:225], v[210:213], v[14:17]
	v_mfma_f32_16x16x32_bf16 v[10:13], v[230:233], v[210:213], v[10:13]
	v_mfma_f32_16x16x32_bf16 v[6:9], v[222:225], v[218:221], v[6:9]
	v_mfma_f32_16x16x32_bf16 v[2:5], v[230:233], v[218:221], v[2:5]
	v_mfma_f32_16x16x32_bf16 v[30:33], v[226:229], v[198:201], v[30:33]
	v_mfma_f32_16x16x32_bf16 v[26:29], v[234:237], v[198:201], v[26:29]
	v_mfma_f32_16x16x32_bf16 v[22:25], v[226:229], v[206:209], v[22:25]
	v_mfma_f32_16x16x32_bf16 v[18:21], v[234:237], v[206:209], v[18:21]
	v_mfma_f32_16x16x32_bf16 v[14:17], v[226:229], v[214:217], v[14:17]
	v_mfma_f32_16x16x32_bf16 v[10:13], v[234:237], v[214:217], v[10:13]
	v_mfma_f32_16x16x32_bf16 v[6:9], v[226:229], v[238:241], v[6:9]
	v_mfma_f32_16x16x32_bf16 v[2:5], v[234:237], v[238:241], v[2:5]
	s_barrier
	ds_read_b128 v[168:171], v149
	ds_read_b128 v[172:175], v149 offset:1024
	ds_read_b128 v[186:189], v149 offset:2048
	ds_read_b128 v[190:193], v149 offset:3072
	v_add_u32_e32 v161, 0x4000, v142
	v_add_u32_e32 v162, 0x6000, v142
	v_readfirstlane_b32 s15, v161
	v_lshl_add_u64 v[226:227], v[182:183], 0, s[76:77]
	s_mov_b32 m0, s15
	v_readfirstlane_b32 s15, v162
	ds_read_b128 v[194:197], v146 offset:32768
	ds_read_b128 v[198:201], v146 offset:33792
	ds_read_b128 v[202:205], v145 offset:32768
	ds_read_b128 v[206:209], v145 offset:33792
	ds_read_b128 v[210:213], v144 offset:32768
	ds_read_b128 v[214:217], v144 offset:33792
	ds_read_b128 v[218:221], v143 offset:32768
	ds_read_b128 v[222:225], v143 offset:33792
	global_load_lds_dwordx4 v[226:227], off
	v_lshl_add_u64 v[226:227], v[242:243], 0, s[76:77]
	s_mov_b32 m0, s15
	s_nop 0
	global_load_lds_dwordx4 v[226:227], off
	s_waitcnt lgkmcnt(8)
	s_barrier
	s_waitcnt lgkmcnt(0)
	v_mfma_f32_16x16x32_bf16 v[126:129], v[168:171], v[194:197], v[126:129]
	v_mfma_f32_16x16x32_bf16 v[122:125], v[186:189], v[194:197], v[122:125]
	v_mfma_f32_16x16x32_bf16 v[118:121], v[168:171], v[202:205], v[118:121]
	v_mfma_f32_16x16x32_bf16 v[114:117], v[186:189], v[202:205], v[114:117]
	v_mfma_f32_16x16x32_bf16 v[110:113], v[168:171], v[210:213], v[110:113]
	v_mfma_f32_16x16x32_bf16 v[106:109], v[186:189], v[210:213], v[106:109]
	v_mfma_f32_16x16x32_bf16 v[102:105], v[168:171], v[218:221], v[102:105]
	v_mfma_f32_16x16x32_bf16 v[98:101], v[186:189], v[218:221], v[98:101]
	v_mfma_f32_16x16x32_bf16 v[126:129], v[172:175], v[198:201], v[126:129]
	v_mfma_f32_16x16x32_bf16 v[122:125], v[190:193], v[198:201], v[122:125]
	v_mfma_f32_16x16x32_bf16 v[118:121], v[172:175], v[206:209], v[118:121]
	v_mfma_f32_16x16x32_bf16 v[114:117], v[190:193], v[206:209], v[114:117]
	v_mfma_f32_16x16x32_bf16 v[110:113], v[172:175], v[214:217], v[110:113]
	v_mfma_f32_16x16x32_bf16 v[106:109], v[190:193], v[214:217], v[106:109]
	v_mfma_f32_16x16x32_bf16 v[102:105], v[172:175], v[222:225], v[102:105]
	v_mfma_f32_16x16x32_bf16 v[98:101], v[190:193], v[222:225], v[98:101]
	s_barrier
	v_readfirstlane_b32 s15, v150
	v_add_u32_e32 v167, 0x2000, v150
	v_lshl_add_u64 v[248:249], v[244:245], 0, s[34:35]
	s_mov_b32 m0, s15
	v_readfirstlane_b32 s15, v167
	ds_read_b128 v[226:229], v147
	ds_read_b128 v[230:233], v147 offset:1024
	ds_read_b128 v[234:237], v147 offset:2048
	ds_read_b128 v[238:241], v147 offset:3072
	global_load_lds_dwordx4 v[248:249], off
	v_lshl_add_u64 v[248:249], v[246:247], 0, s[34:35]
	s_mov_b32 m0, s15
	s_nop 0
	global_load_lds_dwordx4 v[248:249], off
	s_barrier
	s_waitcnt lgkmcnt(0)
	v_mfma_f32_16x16x32_bf16 v[94:97], v[226:229], v[194:197], v[94:97]
	v_mfma_f32_16x16x32_bf16 v[90:93], v[234:237], v[194:197], v[90:93]
	v_mfma_f32_16x16x32_bf16 v[86:89], v[226:229], v[202:205], v[86:89]
	v_mfma_f32_16x16x32_bf16 v[82:85], v[234:237], v[202:205], v[82:85]
	v_readfirstlane_b32 s15, v151
	v_mfma_f32_16x16x32_bf16 v[78:81], v[226:229], v[210:213], v[78:81]
	v_lshl_add_u64 v[182:183], v[182:183], 0, s[74:75]
	v_mfma_f32_16x16x32_bf16 v[74:77], v[234:237], v[210:213], v[74:77]
	s_mov_b32 m0, s15
	v_mfma_f32_16x16x32_bf16 v[70:73], v[226:229], v[218:221], v[70:73]
	v_readfirstlane_b32 s15, v152
	v_mfma_f32_16x16x32_bf16 v[66:69], v[234:237], v[218:221], v[66:69]
	v_mfma_f32_16x16x32_bf16 v[94:97], v[230:233], v[198:201], v[94:97]
	v_mfma_f32_16x16x32_bf16 v[90:93], v[238:241], v[198:201], v[90:93]
	v_mfma_f32_16x16x32_bf16 v[86:89], v[230:233], v[206:209], v[86:89]
	v_mfma_f32_16x16x32_bf16 v[82:85], v[238:241], v[206:209], v[82:85]
	v_mfma_f32_16x16x32_bf16 v[78:81], v[230:233], v[214:217], v[78:81]
	v_mfma_f32_16x16x32_bf16 v[74:77], v[238:241], v[214:217], v[74:77]
	v_mfma_f32_16x16x32_bf16 v[70:73], v[230:233], v[222:225], v[70:73]
	v_mfma_f32_16x16x32_bf16 v[66:69], v[238:241], v[222:225], v[66:69]
	s_barrier
	ds_read_b128 v[194:197], v146 offset:49152
	ds_read_b128 v[198:201], v146 offset:50176
	ds_read_b128 v[202:205], v145 offset:49152
	ds_read_b128 v[206:209], v145 offset:50176
	ds_read_b128 v[210:213], v144 offset:49152
	ds_read_b128 v[214:217], v144 offset:50176
	ds_read_b128 v[218:221], v143 offset:49152
	ds_read_b128 v[222:225], v143 offset:50176
	global_load_lds_dwordx4 v[182:183], off
	v_lshl_add_u64 v[182:183], v[242:243], 0, s[74:75]
	s_mov_b32 m0, s15
	s_nop 0
	global_load_lds_dwordx4 v[182:183], off
	s_barrier
; #define STAGE_A(P,br,kt) STAGE_G(P,c.A,c.lda,br,(long)(kt)*c.kstr)
; #define STAGE_B(P,br,kt) STAGE_G(P,c.Bt,c.K,br,(long)(kt)*BK)
; #define LDA(dst,b,h) for(int m=0;m<4;++m)for(int k=0;k<2;++k) \
;     dst[m][k]=*reinterpret_cast<const bf16x8*>((char*)SA(b,h)+lds_byte(wr*64+m*16+fr,k*32+fq*8))
; #define LDB(dst,b,h) for(int n=0;n<2;++n)for(int k=0;k<2;++k) \
;     dst[n][k]=*reinterpret_cast<const bf16x8*>((char*)SB(b,h)+lds_byte(wc*32+n*16+fr,k*32+fq*8))
; #define MMA(ai,bj,At,Bt_) do{__builtin_amdgcn_s_setprio(1); \
;     for(int m=0;m<4;++m)for(int n=0;n<2;++n)for(int k=0;k<2;++k) \
;       acc[ai][bj][m][n]=__builtin_amdgcn_mfma_f32_16x16x32_bf16(Bt_[n][k],At[m][k],acc[ai][bj][m][n],0,0,0); \
;     __builtin_amdgcn_s_setprio(0);}while(0)
; #define WAIT_V(n) asm volatile("s_waitcnt vmcnt(" #n ")":::"memory")
; #define WAIT_L(n) asm volatile("s_waitcnt lgkmcnt(" #n ")":::"memory")
; #define BAR __builtin_amdgcn_s_barrier()
; #define SCHED __builtin_amdgcn_sched_barrier(0)
; template <int EPI>
; __device__ __forceinline__ void gemm_run(const GD& c, const bool has_next, const GD& nx, const Ctx& e, bf16* shm, float* rs, float* rs_nxt, float* racc_) {
;     ...
;     WAIT_V(6); BAR; MMA(1,1,At,B1); BAR;
;     LDB(B0,1,0); SCHED; LDA(At,1,0); STAGE_A(SA(0,1),brow+HALF,t+2);
;     WAIT_L(8); BAR; WAIT_L(0); MMA(0,0,At,B0); BAR; SCHED;
;     LDB(B1,1,1); STAGE_B(SB(1,0),bcol,t+3);
;     BAR; WAIT_L(0); MMA(0,1,At,B1); BAR;
;     LDA(At,1,1); STAGE_A(SA(1,0),brow,t+3);
;     BAR; WAIT_L(0); MMA(1,0,At,B0); BAR; SCHED;
;     STAGE_B(SB(1,1),bcol+HALF,t+3);
;     WAIT_V(6); BAR; MMA(1,1,At,B1); BAR;
;   }
;   { LDB(B0,0,0); LDA(At,0,0); STAGE_A(SA(1,1),brow+HALF,nt-1);
;     BAR; WAIT_L(0); MMA(0,0,At,B0); BAR;
;     LDB(B1,0,1); BAR; WAIT_L(0); MMA(0,1,At,B1); BAR;
;     LDA(At,0,1); WAIT_V(4); BAR; WAIT_L(0); MMA(1,0,At,B0); MMA(1,1,At,B1); BAR; }
	s_waitcnt lgkmcnt(0)
	v_mfma_f32_16x16x32_bf16 v[62:65], v[168:171], v[194:197], v[62:65]
	v_mfma_f32_16x16x32_bf16 v[58:61], v[186:189], v[194:197], v[58:61]
	v_mfma_f32_16x16x32_bf16 v[54:57], v[168:171], v[202:205], v[54:57]
	v_mfma_f32_16x16x32_bf16 v[50:53], v[186:189], v[202:205], v[50:53]
	v_mfma_f32_16x16x32_bf16 v[46:49], v[168:171], v[210:213], v[46:49]
	v_mfma_f32_16x16x32_bf16 v[42:45], v[186:189], v[210:213], v[42:45]
	v_mfma_f32_16x16x32_bf16 v[38:41], v[168:171], v[218:221], v[38:41]
	v_mfma_f32_16x16x32_bf16 v[34:37], v[186:189], v[218:221], v[34:37]
	v_mfma_f32_16x16x32_bf16 v[62:65], v[172:175], v[198:201], v[62:65]
	v_mfma_f32_16x16x32_bf16 v[58:61], v[190:193], v[198:201], v[58:61]
	v_mfma_f32_16x16x32_bf16 v[54:57], v[172:175], v[206:209], v[54:57]
	v_mfma_f32_16x16x32_bf16 v[50:53], v[190:193], v[206:209], v[50:53]
	v_mfma_f32_16x16x32_bf16 v[46:49], v[172:175], v[214:217], v[46:49]
	v_mfma_f32_16x16x32_bf16 v[42:45], v[190:193], v[214:217], v[42:45]
	v_mfma_f32_16x16x32_bf16 v[38:41], v[172:175], v[222:225], v[38:41]
	v_mfma_f32_16x16x32_bf16 v[34:37], v[190:193], v[222:225], v[34:37]
	s_barrier
	v_readfirstlane_b32 s15, v153
	v_add_u32_e32 v167, 0x2000, v153
	v_lshl_add_u64 v[168:169], v[244:245], 0, s[36:37]
	s_mov_b32 m0, s15
	v_readfirstlane_b32 s15, v167
	global_load_lds_dwordx4 v[168:169], off
	v_lshl_add_u64 v[168:169], v[246:247], 0, s[36:37]
	s_mov_b32 m0, s15
	s_nop 0
	global_load_lds_dwordx4 v[168:169], off
	s_waitcnt vmcnt(6)
	s_barrier
	v_mfma_f32_16x16x32_bf16 v[30:33], v[226:229], v[194:197], v[30:33]
	v_mfma_f32_16x16x32_bf16 v[26:29], v[234:237], v[194:197], v[26:29]
	v_mfma_f32_16x16x32_bf16 v[22:25], v[226:229], v[202:205], v[22:25]
	v_mfma_f32_16x16x32_bf16 v[18:21], v[234:237], v[202:205], v[18:21]
	s_add_i32 s14, s14, 2
	v_mfma_f32_16x16x32_bf16 v[14:17], v[226:229], v[210:213], v[14:17]
	s_add_u32 s2, s2, 0x100
	v_mfma_f32_16x16x32_bf16 v[10:13], v[234:237], v[210:213], v[10:13]
	s_addc_u32 s3, s3, 0
	v_mfma_f32_16x16x32_bf16 v[6:9], v[226:229], v[218:221], v[6:9]
	s_cmp_lt_u32 s14, 38
	v_mfma_f32_16x16x32_bf16 v[2:5], v[234:237], v[218:221], v[2:5]
	v_mfma_f32_16x16x32_bf16 v[30:33], v[230:233], v[198:201], v[30:33]
	v_mfma_f32_16x16x32_bf16 v[26:29], v[238:241], v[198:201], v[26:29]
	v_mfma_f32_16x16x32_bf16 v[22:25], v[230:233], v[206:209], v[22:25]
	v_mfma_f32_16x16x32_bf16 v[18:21], v[238:241], v[206:209], v[18:21]
	v_mfma_f32_16x16x32_bf16 v[14:17], v[230:233], v[214:217], v[14:17]
	v_mfma_f32_16x16x32_bf16 v[10:13], v[238:241], v[214:217], v[10:13]
	v_mfma_f32_16x16x32_bf16 v[6:9], v[230:233], v[222:225], v[6:9]
	v_mfma_f32_16x16x32_bf16 v[2:5], v[238:241], v[222:225], v[2:5]
	s_barrier
	s_cbranch_scc1 .LBB0_1426
	s_or_b32 s27, s25, 0x80
	s_mul_i32 s2, s27, 0x1500
	s_mul_hi_i32 s3, s27, 0x1500
	s_add_u32 s2, s21, s2
	s_addc_u32 s3, s22, s3
	v_readfirstlane_b32 s14, v163
	v_lshl_add_u64 v[182:183], s[2:3], 0, v[0:1]
	s_mov_b32 m0, s14
	ds_read_b128 v[132:135], v155
	ds_read_b128 v[136:139], v155 offset:1024
	ds_read_b128 v[150:153], v155 offset:2048
	ds_read_b128 v[168:171], v155 offset:3072
	ds_read_b128 v[172:175], v146
	ds_read_b128 v[186:189], v146 offset:1024
	ds_read_b128 v[190:193], v145
	ds_read_b128 v[194:197], v145 offset:1024
	ds_read_b128 v[198:201], v144
	ds_read_b128 v[202:205], v144 offset:1024
	ds_read_b128 v[206:209], v143
	ds_read_b128 v[210:213], v143 offset:1024
	global_load_lds_dwordx4 v[182:183], off
	v_lshl_add_u64 v[182:183], s[2:3], 0, v[130:131]
	v_readfirstlane_b32 s2, v166
	s_mov_b32 m0, s2
	s_nop 0
	global_load_lds_dwordx4 v[182:183], off
	s_barrier
	s_waitcnt lgkmcnt(0)
	v_mfma_f32_16x16x32_bf16 v[126:129], v[132:135], v[172:175], v[126:129]
	v_mfma_f32_16x16x32_bf16 v[122:125], v[150:153], v[172:175], v[122:125]
	v_mfma_f32_16x16x32_bf16 v[118:121], v[132:135], v[190:193], v[118:121]
	v_mfma_f32_16x16x32_bf16 v[114:117], v[150:153], v[190:193], v[114:117]
	v_mfma_f32_16x16x32_bf16 v[106:109], v[150:153], v[198:201], v[106:109]
	v_mfma_f32_16x16x32_bf16 v[98:101], v[150:153], v[206:209], v[98:101]
	v_mfma_f32_16x16x32_bf16 v[126:129], v[136:139], v[186:189], v[126:129]
	v_mfma_f32_16x16x32_bf16 v[122:125], v[168:171], v[186:189], v[122:125]
	v_mfma_f32_16x16x32_bf16 v[118:121], v[136:139], v[194:197], v[118:121]
	v_mfma_f32_16x16x32_bf16 v[114:117], v[168:171], v[194:197], v[114:117]
	v_mfma_f32_16x16x32_bf16 v[110:113], v[132:135], v[198:201], v[110:113]
	v_mfma_f32_16x16x32_bf16 v[106:109], v[168:171], v[202:205], v[106:109]
	v_mfma_f32_16x16x32_bf16 v[102:105], v[132:135], v[206:209], v[102:105]
	v_mfma_f32_16x16x32_bf16 v[98:101], v[168:171], v[210:213], v[98:101]
	v_mfma_f32_16x16x32_bf16 v[214:217], v[136:139], v[202:205], v[110:113]
	v_mfma_f32_16x16x32_bf16 v[218:221], v[136:139], v[210:213], v[102:105]
	s_barrier
	s_nop 2
	ds_read_b128 v[102:105], v154
	ds_read_b128 v[110:113], v154 offset:1024
	ds_read_b128 v[222:225], v154 offset:2048
	ds_read_b128 v[226:229], v154 offset:3072
	s_barrier
	s_waitcnt lgkmcnt(0)
	v_mfma_f32_16x16x32_bf16 v[90:93], v[222:225], v[172:175], v[90:93]
	v_mfma_f32_16x16x32_bf16 v[82:85], v[222:225], v[190:193], v[82:85]
	v_mfma_f32_16x16x32_bf16 v[74:77], v[222:225], v[198:201], v[74:77]
	v_mfma_f32_16x16x32_bf16 v[66:69], v[222:225], v[206:209], v[66:69]
	v_mfma_f32_16x16x32_bf16 v[94:97], v[102:105], v[172:175], v[94:97]
	v_mfma_f32_16x16x32_bf16 v[90:93], v[226:229], v[186:189], v[90:93]
	v_mfma_f32_16x16x32_bf16 v[86:89], v[102:105], v[190:193], v[86:89]
	v_mfma_f32_16x16x32_bf16 v[82:85], v[226:229], v[194:197], v[82:85]
	v_mfma_f32_16x16x32_bf16 v[78:81], v[102:105], v[198:201], v[78:81]
	v_mfma_f32_16x16x32_bf16 v[74:77], v[226:229], v[202:205], v[74:77]
	v_mfma_f32_16x16x32_bf16 v[70:73], v[102:105], v[206:209], v[70:73]
	v_mfma_f32_16x16x32_bf16 v[66:69], v[226:229], v[210:213], v[66:69]
	v_mfma_f32_16x16x32_bf16 v[230:233], v[110:113], v[186:189], v[94:97]
	v_mfma_f32_16x16x32_bf16 v[172:175], v[110:113], v[194:197], v[86:89]
	v_mfma_f32_16x16x32_bf16 v[186:189], v[110:113], v[202:205], v[78:81]
	v_mfma_f32_16x16x32_bf16 v[190:193], v[110:113], v[210:213], v[70:73]
	s_barrier
; #define LDA(dst,b,h) for(int m=0;m<4;++m)for(int k=0;k<2;++k) \
;     dst[m][k]=*reinterpret_cast<const bf16x8*>((char*)SA(b,h)+lds_byte(wr*64+m*16+fr,k*32+fq*8))
; #define LDB(dst,b,h) for(int n=0;n<2;++n)for(int k=0;k<2;++k) \
;     dst[n][k]=*reinterpret_cast<const bf16x8*>((char*)SB(b,h)+lds_byte(wc*32+n*16+fr,k*32+fq*8))
; #define MMA(ai,bj,At,Bt_) do{__builtin_amdgcn_s_setprio(1); \
;     for(int m=0;m<4;++m)for(int n=0;n<2;++n)for(int k=0;k<2;++k) \
;       acc[ai][bj][m][n]=__builtin_amdgcn_mfma_f32_16x16x32_bf16(Bt_[n][k],At[m][k],acc[ai][bj][m][n],0,0,0); \
;     __builtin_amdgcn_s_setprio(0);}while(0)
; #define WAIT_V(n) asm volatile("s_waitcnt vmcnt(" #n ")":::"memory")
; #define WAIT_L(n) asm volatile("s_waitcnt lgkmcnt(" #n ")":::"memory")
; #define BAR __builtin_amdgcn_s_barrier()
; template <int EPI>
; __device__ __forceinline__ void gemm_run(const GD& c, const bool has_next, const GD& nx, const Ctx& e, bf16* shm, float* rs, float* rs_nxt, float* racc_) {
;     ...
;     LDA(At,0,1); WAIT_V(4); BAR; WAIT_L(0); MMA(1,0,At,B0); MMA(1,1,At,B1); BAR; }
;   { LDB(B0,1,0); LDA(At,1,0); WAIT_V(2); BAR; WAIT_L(0); MMA(0,0,At,B0); BAR;
;     LDB(B1,1,1); WAIT_V(0); BAR; WAIT_L(0); MMA(0,1,At,B1); BAR;
;     LDA(At,1,1); BAR; WAIT_L(0); MMA(1,0,At,B0); MMA(1,1,At,B1); BAR; }
	s_nop 0
	ds_read_b128 v[70:73], v146 offset:16384
	ds_read_b128 v[78:81], v146 offset:17408
	ds_read_b128 v[86:89], v145 offset:16384
	ds_read_b128 v[94:97], v145 offset:17408
	ds_read_b128 v[194:197], v144 offset:16384
	ds_read_b128 v[198:201], v144 offset:17408
	ds_read_b128 v[202:205], v143 offset:16384
	ds_read_b128 v[206:209], v143 offset:17408
	s_waitcnt vmcnt(4)
	s_barrier
	s_waitcnt lgkmcnt(0)
	v_mfma_f32_16x16x32_bf16 v[62:65], v[132:135], v[70:73], v[62:65]
	v_mfma_f32_16x16x32_bf16 v[58:61], v[150:153], v[70:73], v[58:61]
	v_mfma_f32_16x16x32_bf16 v[54:57], v[132:135], v[86:89], v[54:57]
	v_mfma_f32_16x16x32_bf16 v[50:53], v[150:153], v[86:89], v[50:53]
	v_mfma_f32_16x16x32_bf16 v[38:41], v[132:135], v[202:205], v[38:41]
	v_mfma_f32_16x16x32_bf16 v[34:37], v[150:153], v[202:205], v[34:37]
	v_mfma_f32_16x16x32_bf16 v[62:65], v[136:139], v[78:81], v[62:65]
	v_mfma_f32_16x16x32_bf16 v[58:61], v[168:171], v[78:81], v[58:61]
	v_mfma_f32_16x16x32_bf16 v[54:57], v[136:139], v[94:97], v[54:57]
	v_mfma_f32_16x16x32_bf16 v[50:53], v[168:171], v[94:97], v[50:53]
	v_mfma_f32_16x16x32_bf16 v[46:49], v[132:135], v[194:197], v[46:49]
	v_mfma_f32_16x16x32_bf16 v[42:45], v[150:153], v[194:197], v[42:45]
	v_mfma_f32_16x16x32_bf16 v[38:41], v[136:139], v[206:209], v[38:41]
	v_mfma_f32_16x16x32_bf16 v[34:37], v[168:171], v[206:209], v[34:37]
	v_mfma_f32_16x16x32_bf16 v[210:213], v[136:139], v[198:201], v[46:49]
	v_mfma_f32_16x16x32_bf16 v[234:237], v[168:171], v[198:201], v[42:45]
	v_mfma_f32_16x16x32_bf16 v[22:25], v[102:105], v[86:89], v[22:25]
	v_mfma_f32_16x16x32_bf16 v[18:21], v[222:225], v[86:89], v[18:21]
	v_mfma_f32_16x16x32_bf16 v[6:9], v[102:105], v[202:205], v[6:9]
	v_mfma_f32_16x16x32_bf16 v[2:5], v[222:225], v[202:205], v[2:5]
	v_mfma_f32_16x16x32_bf16 v[30:33], v[102:105], v[70:73], v[30:33]
	v_mfma_f32_16x16x32_bf16 v[26:29], v[222:225], v[70:73], v[26:29]
	v_mfma_f32_16x16x32_bf16 v[22:25], v[110:113], v[94:97], v[22:25]
	v_mfma_f32_16x16x32_bf16 v[18:21], v[226:229], v[94:97], v[18:21]
	v_mfma_f32_16x16x32_bf16 v[14:17], v[102:105], v[194:197], v[14:17]
	v_mfma_f32_16x16x32_bf16 v[10:13], v[222:225], v[194:197], v[10:13]
	v_mfma_f32_16x16x32_bf16 v[6:9], v[110:113], v[206:209], v[6:9]
	v_mfma_f32_16x16x32_bf16 v[2:5], v[226:229], v[206:209], v[2:5]
	v_mfma_f32_16x16x32_bf16 v[132:135], v[110:113], v[78:81], v[30:33]
	v_mfma_f32_16x16x32_bf16 v[136:139], v[226:229], v[78:81], v[26:29]
	v_mfma_f32_16x16x32_bf16 v[150:153], v[110:113], v[198:201], v[14:17]
	v_mfma_f32_16x16x32_bf16 v[166:169], v[226:229], v[198:201], v[10:13]
	s_barrier
	s_nop 0
	ds_read_b128 v[10:13], v149
	ds_read_b128 v[14:17], v149 offset:1024
	ds_read_b128 v[194:197], v149 offset:2048
	ds_read_b128 v[198:201], v149 offset:3072
	ds_read_b128 v[26:29], v146 offset:32768
	ds_read_b128 v[30:33], v146 offset:33792
	ds_read_b128 v[42:45], v145 offset:32768
	ds_read_b128 v[46:49], v145 offset:33792
	ds_read_b128 v[202:205], v144 offset:32768
	ds_read_b128 v[206:209], v144 offset:33792
	ds_read_b128 v[222:225], v143 offset:32768
	ds_read_b128 v[226:229], v143 offset:33792
	s_waitcnt vmcnt(2)
	s_barrier
	s_waitcnt lgkmcnt(0)
	v_mfma_f32_16x16x32_bf16 v[70:73], v[10:13], v[26:29], v[126:129]
	v_mfma_f32_16x16x32_bf16 v[126:129], v[14:17], v[30:33], v[70:73]
	v_mfma_f32_16x16x32_bf16 v[70:73], v[194:197], v[26:29], v[122:125]
	v_mfma_f32_16x16x32_bf16 v[122:125], v[198:201], v[30:33], v[70:73]
	v_mfma_f32_16x16x32_bf16 v[70:73], v[10:13], v[42:45], v[118:121]
	v_mfma_f32_16x16x32_bf16 v[110:113], v[14:17], v[46:49], v[70:73]
	v_mfma_f32_16x16x32_bf16 v[70:73], v[194:197], v[42:45], v[114:117]
	v_mfma_f32_16x16x32_bf16 v[102:105], v[198:201], v[46:49], v[70:73]
	v_mfma_f32_16x16x32_bf16 v[70:73], v[10:13], v[202:205], v[214:217]
	v_mfma_f32_16x16x32_bf16 v[94:97], v[14:17], v[206:209], v[70:73]
	v_mfma_f32_16x16x32_bf16 v[70:73], v[194:197], v[202:205], v[106:109]
	v_mfma_f32_16x16x32_bf16 v[86:89], v[198:201], v[206:209], v[70:73]
	v_mfma_f32_16x16x32_bf16 v[70:73], v[10:13], v[222:225], v[218:221]
	v_mfma_f32_16x16x32_bf16 v[78:81], v[14:17], v[226:229], v[70:73]
	v_mfma_f32_16x16x32_bf16 v[70:73], v[194:197], v[222:225], v[98:101]
	v_mfma_f32_16x16x32_bf16 v[70:73], v[198:201], v[226:229], v[70:73]
	s_barrier
; #define LDA(dst,b,h) for(int m=0;m<4;++m)for(int k=0;k<2;++k) \
;     dst[m][k]=*reinterpret_cast<const bf16x8*>((char*)SA(b,h)+lds_byte(wr*64+m*16+fr,k*32+fq*8))
; #define LDB(dst,b,h) for(int n=0;n<2;++n)for(int k=0;k<2;++k) \
;     dst[n][k]=*reinterpret_cast<const bf16x8*>((char*)SB(b,h)+lds_byte(wc*32+n*16+fr,k*32+fq*8))
; #define MMA(ai,bj,At,Bt_) do{__builtin_amdgcn_s_setprio(1); \
;     for(int m=0;m<4;++m)for(int n=0;n<2;++n)for(int k=0;k<2;++k) \
;       acc[ai][bj][m][n]=__builtin_amdgcn_mfma_f32_16x16x32_bf16(Bt_[n][k],At[m][k],acc[ai][bj][m][n],0,0,0); \
;     __builtin_amdgcn_s_setprio(0);}while(0)
; #define WAIT_V(n) asm volatile("s_waitcnt vmcnt(" #n ")":::"memory")
; #define WAIT_L(n) asm volatile("s_waitcnt lgkmcnt(" #n ")":::"memory")
; #define BAR __builtin_amdgcn_s_barrier()
; template <int EPI>
; __device__ __forceinline__ void gemm_run(const GD& c, const bool has_next, const GD& nx, const Ctx& e, bf16* shm, float* rs, float* rs_nxt, float* racc_) {
;     ...
;     LDB(B1,1,1); WAIT_V(0); BAR; WAIT_L(0); MMA(0,1,At,B1); BAR;
;     LDA(At,1,1); BAR; WAIT_L(0); MMA(1,0,At,B0); MMA(1,1,At,B1); BAR; }
;   if(wr==0)BAR;
	ds_read_b128 v[214:217], v147
	ds_read_b128 v[218:221], v147 offset:1024
	ds_read_b128 v[238:241], v147 offset:2048
	ds_read_b128 v[242:245], v147 offset:3072
	s_waitcnt vmcnt(0)
	s_barrier
	s_waitcnt lgkmcnt(0)
	v_mfma_f32_16x16x32_bf16 v[98:101], v[214:217], v[26:29], v[230:233]
	v_mfma_f32_16x16x32_bf16 v[26:29], v[238:241], v[26:29], v[90:93]
	v_mfma_f32_16x16x32_bf16 v[114:117], v[242:245], v[30:33], v[26:29]
	v_mfma_f32_16x16x32_bf16 v[26:29], v[214:217], v[42:45], v[172:175]
	v_mfma_f32_16x16x32_bf16 v[106:109], v[218:221], v[46:49], v[26:29]
	v_mfma_f32_16x16x32_bf16 v[26:29], v[238:241], v[42:45], v[82:85]
	v_mfma_f32_16x16x32_bf16 v[118:121], v[218:221], v[30:33], v[98:101]
	v_mfma_f32_16x16x32_bf16 v[98:101], v[242:245], v[46:49], v[26:29]
	v_mfma_f32_16x16x32_bf16 v[26:29], v[214:217], v[202:205], v[186:189]
	v_mfma_f32_16x16x32_bf16 v[90:93], v[218:221], v[206:209], v[26:29]
	v_mfma_f32_16x16x32_bf16 v[26:29], v[238:241], v[202:205], v[74:77]
	v_mfma_f32_16x16x32_bf16 v[82:85], v[242:245], v[206:209], v[26:29]
	v_mfma_f32_16x16x32_bf16 v[26:29], v[214:217], v[222:225], v[190:193]
	v_mfma_f32_16x16x32_bf16 v[74:77], v[218:221], v[226:229], v[26:29]
	v_mfma_f32_16x16x32_bf16 v[26:29], v[238:241], v[222:225], v[66:69]
	v_mfma_f32_16x16x32_bf16 v[66:69], v[242:245], v[226:229], v[26:29]
	s_barrier
	ds_read_b128 v[170:173], v146 offset:49152
	ds_read_b128 v[146:149], v146 offset:50176
	ds_read_b128 v[186:189], v145 offset:49152
	ds_read_b128 v[190:193], v145 offset:50176
	ds_read_b128 v[202:205], v144 offset:49152
	ds_read_b128 v[206:209], v144 offset:50176
	ds_read_b128 v[222:225], v143 offset:49152
	ds_read_b128 v[226:229], v143 offset:50176
	s_barrier
	s_waitcnt lgkmcnt(0)
	v_mfma_f32_16x16x32_bf16 v[26:29], v[10:13], v[170:173], v[62:65]
	v_mfma_f32_16x16x32_bf16 v[62:65], v[14:17], v[146:149], v[26:29]
	v_mfma_f32_16x16x32_bf16 v[26:29], v[194:197], v[170:173], v[58:61]
	v_mfma_f32_16x16x32_bf16 v[58:61], v[198:201], v[146:149], v[26:29]
	v_mfma_f32_16x16x32_bf16 v[26:29], v[10:13], v[186:189], v[54:57]
	v_mfma_f32_16x16x32_bf16 v[46:49], v[14:17], v[190:193], v[26:29]
	v_mfma_f32_16x16x32_bf16 v[26:29], v[194:197], v[186:189], v[50:53]
	v_mfma_f32_16x16x32_bf16 v[42:45], v[198:201], v[190:193], v[26:29]
	v_mfma_f32_16x16x32_bf16 v[26:29], v[10:13], v[202:205], v[210:213]
	v_mfma_f32_16x16x32_bf16 v[10:13], v[10:13], v[222:225], v[38:41]
	v_mfma_f32_16x16x32_bf16 v[30:33], v[14:17], v[206:209], v[26:29]
	v_mfma_f32_16x16x32_bf16 v[26:29], v[194:197], v[202:205], v[234:237]
	v_mfma_f32_16x16x32_bf16 v[14:17], v[14:17], v[226:229], v[10:13]
	v_mfma_f32_16x16x32_bf16 v[10:13], v[194:197], v[222:225], v[34:37]
	v_mfma_f32_16x16x32_bf16 v[26:29], v[198:201], v[206:209], v[26:29]
	v_mfma_f32_16x16x32_bf16 v[10:13], v[198:201], v[226:229], v[10:13]
	v_mfma_f32_16x16x32_bf16 v[34:37], v[214:217], v[170:173], v[132:135]
	v_mfma_f32_16x16x32_bf16 v[54:57], v[218:221], v[146:149], v[34:37]
	v_mfma_f32_16x16x32_bf16 v[34:37], v[238:241], v[170:173], v[136:139]
	v_mfma_f32_16x16x32_bf16 v[18:21], v[238:241], v[186:189], v[18:21]
	v_mfma_f32_16x16x32_bf16 v[50:53], v[242:245], v[146:149], v[34:37]
	v_mfma_f32_16x16x32_bf16 v[22:25], v[214:217], v[186:189], v[22:25]
	v_mfma_f32_16x16x32_bf16 v[34:37], v[242:245], v[190:193], v[18:21]
	v_mfma_f32_16x16x32_bf16 v[18:21], v[214:217], v[202:205], v[150:153]
	v_mfma_f32_16x16x32_bf16 v[38:41], v[218:221], v[190:193], v[22:25]
	v_mfma_f32_16x16x32_bf16 v[22:25], v[218:221], v[206:209], v[18:21]
	v_mfma_f32_16x16x32_bf16 v[18:21], v[238:241], v[202:205], v[166:169]
	v_mfma_f32_16x16x32_bf16 v[6:9], v[214:217], v[222:225], v[6:9]
	v_mfma_f32_16x16x32_bf16 v[2:5], v[238:241], v[222:225], v[2:5]
	v_mfma_f32_16x16x32_bf16 v[18:21], v[242:245], v[206:209], v[18:21]
	v_mfma_f32_16x16x32_bf16 v[6:9], v[218:221], v[226:229], v[6:9]
	v_mfma_f32_16x16x32_bf16 v[2:5], v[242:245], v[226:229], v[2:5]
	v_cmp_gt_u32_e32 vcc, s96, v141
	s_barrier
	s_and_saveexec_b64 s[2:3], vcc
	s_cbranch_execz .LBB0_1429
	s_barrier

; #define STAGE_A(P,br,kt) STAGE_G(P,c.A,c.lda,br,(long)(kt)*c.kstr)
; #define STAGE_B(P,br,kt) STAGE_G(P,c.Bt,c.K,br,(long)(kt)*BK)
; #define LDA(dst,b,h) for(int m=0;m<4;++m)for(int k=0;k<2;++k) \
;     dst[m][k]=*reinterpret_cast<const bf16x8*>((char*)SA(b,h)+lds_byte(wr*64+m*16+fr,k*32+fq*8))
; #define LDB(dst,b,h) for(int n=0;n<2;++n)for(int k=0;k<2;++k) \
;     dst[n][k]=*reinterpret_cast<const bf16x8*>((char*)SB(b,h)+lds_byte(wc*32+n*16+fr,k*32+fq*8))
; #define MMA(ai,bj,At,Bt_) do{__builtin_amdgcn_s_setprio(1); \
;     for(int m=0;m<4;++m)for(int n=0;n<2;++n)for(int k=0;k<2;++k) \
;       acc[ai][bj][m][n]=__builtin_amdgcn_mfma_f32_16x16x32_bf16(Bt_[n][k],At[m][k],acc[ai][bj][m][n],0,0,0); \
;     __builtin_amdgcn_s_setprio(0);}while(0)
; #define WAIT_V(n) asm volatile("s_waitcnt vmcnt(" #n ")":::"memory")
; #define WAIT_L(n) asm volatile("s_waitcnt lgkmcnt(" #n ")":::"memory")
; #define BAR __builtin_amdgcn_s_barrier()
; #define SCHED __builtin_amdgcn_sched_barrier(0)
; template <int EPI>
; __device__ __forceinline__ void gemm_run(const GD& c, const bool has_next, const GD& nx, const Ctx& e, bf16* shm, float* rs, float* rs_nxt, float* racc_) {
;     ...
;   for(int t=0;t<nt-2;t+=2){
;     LDB(B0,0,0); SCHED; LDA(At,0,0); STAGE_A(SA(1,1),brow+HALF,t+1);
;     WAIT_L(8); BAR; WAIT_L(0); MMA(0,0,At,B0); BAR; SCHED;
;     LDB(B1,0,1); STAGE_B(SB(0,0),bcol,t+2);
;     BAR; WAIT_L(0); MMA(0,1,At,B1); BAR;
;     LDA(At,0,1); STAGE_A(SA(0,0),brow,t+2);
;     BAR; WAIT_L(0); MMA(1,0,At,B0); BAR; SCHED;
;     STAGE_B(SB(0,1),bcol+HALF,t+2);
;     WAIT_V(6); BAR; MMA(1,1,At,B1); BAR;
.LBB0_1505:
	ds_read_b128 v[158:161], v155
	ds_read_b128 v[166:169], v155 offset:1024
	ds_read_b128 v[170:173], v155 offset:2048
	ds_read_b128 v[186:189], v155 offset:3072
	v_add_u32_e32 v156, 0xc000, v150
	v_lshl_add_u64 v[162:163], v[132:133], 0, s[8:9]
	v_readfirstlane_b32 s12, v156
	v_lshl_add_u64 v[174:175], v[162:163], 0, s[90:91]
	s_mov_b32 m0, s12
	v_add_u32_e32 v157, 0xe000, v150
	ds_read_b128 v[190:193], v145
	ds_read_b128 v[194:197], v145 offset:1024
	ds_read_b128 v[198:201], v144
	ds_read_b128 v[202:205], v144 offset:1024
	ds_read_b128 v[206:209], v143
	ds_read_b128 v[210:213], v143 offset:1024
	ds_read_b128 v[214:217], v142
	ds_read_b128 v[218:221], v142 offset:1024
	global_load_lds_dwordx4 v[174:175], off
	v_lshl_add_u64 v[174:175], v[134:135], 0, s[8:9]
	v_readfirstlane_b32 s12, v157
	v_lshl_add_u64 v[182:183], v[174:175], 0, s[90:91]
	s_mov_b32 m0, s12
	s_nop 0
	global_load_lds_dwordx4 v[182:183], off
	s_waitcnt lgkmcnt(8)
	s_barrier
	s_waitcnt lgkmcnt(0)
	v_mfma_f32_16x16x32_bf16 v[126:129], v[158:161], v[190:193], v[126:129]
	v_mfma_f32_16x16x32_bf16 v[122:125], v[170:173], v[190:193], v[122:125]
	v_mfma_f32_16x16x32_bf16 v[118:121], v[158:161], v[198:201], v[118:121]
	v_mfma_f32_16x16x32_bf16 v[114:117], v[170:173], v[198:201], v[114:117]
	v_mfma_f32_16x16x32_bf16 v[110:113], v[158:161], v[206:209], v[110:113]
	v_mfma_f32_16x16x32_bf16 v[106:109], v[170:173], v[206:209], v[106:109]
	v_mfma_f32_16x16x32_bf16 v[102:105], v[158:161], v[214:217], v[102:105]
	v_mfma_f32_16x16x32_bf16 v[98:101], v[170:173], v[214:217], v[98:101]
	v_mfma_f32_16x16x32_bf16 v[126:129], v[166:169], v[194:197], v[126:129]
	v_mfma_f32_16x16x32_bf16 v[122:125], v[186:189], v[194:197], v[122:125]
	v_mfma_f32_16x16x32_bf16 v[118:121], v[166:169], v[202:205], v[118:121]
	v_mfma_f32_16x16x32_bf16 v[114:117], v[186:189], v[202:205], v[114:117]
	v_mfma_f32_16x16x32_bf16 v[110:113], v[166:169], v[210:213], v[110:113]
	v_mfma_f32_16x16x32_bf16 v[106:109], v[186:189], v[210:213], v[106:109]
	v_mfma_f32_16x16x32_bf16 v[102:105], v[166:169], v[218:221], v[102:105]
	v_mfma_f32_16x16x32_bf16 v[98:101], v[186:189], v[218:221], v[98:101]
	s_barrier
	v_add_u32_e32 v176, s33, v146
	v_lshl_add_u64 v[182:183], v[136:137], 0, s[8:9]
	v_readfirstlane_b32 s12, v176
	v_lshl_add_u64 v[238:239], v[182:183], 0, s[24:25]
	s_mov_b32 m0, s12
	v_add_u32_e32 v176, 0x2000, v176
	ds_read_b128 v[222:225], v154
	ds_read_b128 v[226:229], v154 offset:1024
	ds_read_b128 v[230:233], v154 offset:2048
	ds_read_b128 v[234:237], v154 offset:3072
	global_load_lds_dwordx4 v[238:239], off
	v_lshl_add_u64 v[238:239], v[138:139], 0, s[8:9]
	v_readfirstlane_b32 s12, v176
	v_lshl_add_u64 v[240:241], v[238:239], 0, s[24:25]
	s_mov_b32 m0, s12
	s_add_i32 s11, s11, 2
	global_load_lds_dwordx4 v[240:241], off
	s_barrier
	s_waitcnt lgkmcnt(0)
	v_mfma_f32_16x16x32_bf16 v[94:97], v[222:225], v[190:193], v[94:97]
	v_mfma_f32_16x16x32_bf16 v[90:93], v[230:233], v[190:193], v[90:93]
	v_mfma_f32_16x16x32_bf16 v[86:89], v[222:225], v[198:201], v[86:89]
	v_mfma_f32_16x16x32_bf16 v[82:85], v[230:233], v[198:201], v[82:85]
	v_readfirstlane_b32 s12, v150
	v_mfma_f32_16x16x32_bf16 v[78:81], v[222:225], v[206:209], v[78:81]
	v_add_u32_e32 v176, 0x2000, v150
	v_mfma_f32_16x16x32_bf16 v[74:77], v[230:233], v[206:209], v[74:77]
	v_lshl_add_u64 v[240:241], v[162:163], 0, s[0:1]
	v_mfma_f32_16x16x32_bf16 v[70:73], v[222:225], v[214:217], v[70:73]
	s_mov_b32 m0, s12
	v_mfma_f32_16x16x32_bf16 v[66:69], v[230:233], v[214:217], v[66:69]
	v_readfirstlane_b32 s12, v176
	v_mfma_f32_16x16x32_bf16 v[94:97], v[226:229], v[194:197], v[94:97]
	v_mfma_f32_16x16x32_bf16 v[90:93], v[234:237], v[194:197], v[90:93]
	v_mfma_f32_16x16x32_bf16 v[86:89], v[226:229], v[202:205], v[86:89]
	v_mfma_f32_16x16x32_bf16 v[82:85], v[234:237], v[202:205], v[82:85]
	v_mfma_f32_16x16x32_bf16 v[78:81], v[226:229], v[210:213], v[78:81]
	v_mfma_f32_16x16x32_bf16 v[74:77], v[234:237], v[210:213], v[74:77]
	v_mfma_f32_16x16x32_bf16 v[70:73], v[226:229], v[218:221], v[70:73]
	v_mfma_f32_16x16x32_bf16 v[66:69], v[234:237], v[218:221], v[66:69]
	s_barrier
	ds_read_b128 v[190:193], v145 offset:16384
	ds_read_b128 v[194:197], v145 offset:17408
	ds_read_b128 v[198:201], v144 offset:16384
	ds_read_b128 v[202:205], v144 offset:17408
	ds_read_b128 v[206:209], v143 offset:16384
	ds_read_b128 v[210:213], v143 offset:17408
	ds_read_b128 v[214:217], v142 offset:16384
	ds_read_b128 v[218:221], v142 offset:17408
	global_load_lds_dwordx4 v[240:241], off
	v_lshl_add_u64 v[240:241], v[174:175], 0, s[0:1]
	s_mov_b32 m0, s12
	s_nop 0
	global_load_lds_dwordx4 v[240:241], off
	s_barrier
	s_waitcnt lgkmcnt(0)
	v_mfma_f32_16x16x32_bf16 v[62:65], v[158:161], v[190:193], v[62:65]
	v_mfma_f32_16x16x32_bf16 v[58:61], v[170:173], v[190:193], v[58:61]
	v_mfma_f32_16x16x32_bf16 v[54:57], v[158:161], v[198:201], v[54:57]
	v_mfma_f32_16x16x32_bf16 v[50:53], v[170:173], v[198:201], v[50:53]
	v_mfma_f32_16x16x32_bf16 v[46:49], v[158:161], v[206:209], v[46:49]
	v_mfma_f32_16x16x32_bf16 v[42:45], v[170:173], v[206:209], v[42:45]
	v_mfma_f32_16x16x32_bf16 v[38:41], v[158:161], v[214:217], v[38:41]
	v_mfma_f32_16x16x32_bf16 v[34:37], v[170:173], v[214:217], v[34:37]
	v_mfma_f32_16x16x32_bf16 v[62:65], v[166:169], v[194:197], v[62:65]
	v_mfma_f32_16x16x32_bf16 v[58:61], v[186:189], v[194:197], v[58:61]
	v_mfma_f32_16x16x32_bf16 v[54:57], v[166:169], v[202:205], v[54:57]
	v_mfma_f32_16x16x32_bf16 v[50:53], v[186:189], v[202:205], v[50:53]
	v_mfma_f32_16x16x32_bf16 v[46:49], v[166:169], v[210:213], v[46:49]
	v_mfma_f32_16x16x32_bf16 v[42:45], v[186:189], v[210:213], v[42:45]
	v_mfma_f32_16x16x32_bf16 v[38:41], v[166:169], v[218:221], v[38:41]
	v_mfma_f32_16x16x32_bf16 v[34:37], v[186:189], v[218:221], v[34:37]
	s_barrier
; #define STAGE_A(P,br,kt) STAGE_G(P,c.A,c.lda,br,(long)(kt)*c.kstr)
; #define STAGE_B(P,br,kt) STAGE_G(P,c.Bt,c.K,br,(long)(kt)*BK)
; #define LDA(dst,b,h) for(int m=0;m<4;++m)for(int k=0;k<2;++k) \
;     dst[m][k]=*reinterpret_cast<const bf16x8*>((char*)SA(b,h)+lds_byte(wr*64+m*16+fr,k*32+fq*8))
; #define LDB(dst,b,h) for(int n=0;n<2;++n)for(int k=0;k<2;++k) \
;     dst[n][k]=*reinterpret_cast<const bf16x8*>((char*)SB(b,h)+lds_byte(wc*32+n*16+fr,k*32+fq*8))
; #define MMA(ai,bj,At,Bt_) do{__builtin_amdgcn_s_setprio(1); \
;     for(int m=0;m<4;++m)for(int n=0;n<2;++n)for(int k=0;k<2;++k) \
;       acc[ai][bj][m][n]=__builtin_amdgcn_mfma_f32_16x16x32_bf16(Bt_[n][k],At[m][k],acc[ai][bj][m][n],0,0,0); \
;     __builtin_amdgcn_s_setprio(0);}while(0)
; #define WAIT_V(n) asm volatile("s_waitcnt vmcnt(" #n ")":::"memory")
; #define WAIT_L(n) asm volatile("s_waitcnt lgkmcnt(" #n ")":::"memory")
; #define BAR __builtin_amdgcn_s_barrier()
; #define SCHED __builtin_amdgcn_sched_barrier(0)
; template <int EPI>
; __device__ __forceinline__ void gemm_run(const GD& c, const bool has_next, const GD& nx, const Ctx& e, bf16* shm, float* rs, float* rs_nxt, float* racc_) {
;     ...
;     STAGE_B(SB(0,1),bcol+HALF,t+2);
;     WAIT_V(6); BAR; MMA(1,1,At,B1); BAR;
;     LDB(B0,1,0); SCHED; LDA(At,1,0); STAGE_A(SA(0,1),brow+HALF,t+2);
;     WAIT_L(8); BAR; WAIT_L(0); MMA(0,0,At,B0); BAR; SCHED;
;     LDB(B1,1,1); STAGE_B(SB(1,0),bcol,t+3);
;     BAR; WAIT_L(0); MMA(0,1,At,B1); BAR;
;     LDA(At,1,1); STAGE_A(SA(1,0),brow,t+3);
;     BAR; WAIT_L(0); MMA(1,0,At,B0); BAR; SCHED;
;     STAGE_B(SB(1,1),bcol+HALF,t+3);
;     WAIT_V(6); BAR; MMA(1,1,At,B1); BAR;
	v_add_u32_e32 v160, s86, v146
	v_lshl_add_u64 v[158:159], v[182:183], 0, s[26:27]
	v_readfirstlane_b32 s12, v160
	v_add_u32_e32 v160, 0x2000, v160
	s_mov_b32 m0, s12
	v_readfirstlane_b32 s12, v160
	global_load_lds_dwordx4 v[158:159], off
	v_lshl_add_u64 v[158:159], v[238:239], 0, s[26:27]
	s_mov_b32 m0, s12
	s_nop 0
	global_load_lds_dwordx4 v[158:159], off
	s_waitcnt vmcnt(6)
	s_barrier
	v_mfma_f32_16x16x32_bf16 v[30:33], v[222:225], v[190:193], v[30:33]
	v_mfma_f32_16x16x32_bf16 v[26:29], v[230:233], v[190:193], v[26:29]
	v_mfma_f32_16x16x32_bf16 v[22:25], v[222:225], v[198:201], v[22:25]
	v_mfma_f32_16x16x32_bf16 v[18:21], v[230:233], v[198:201], v[18:21]
	v_mfma_f32_16x16x32_bf16 v[14:17], v[222:225], v[206:209], v[14:17]
	v_mfma_f32_16x16x32_bf16 v[10:13], v[230:233], v[206:209], v[10:13]
	v_mfma_f32_16x16x32_bf16 v[6:9], v[222:225], v[214:217], v[6:9]
	v_mfma_f32_16x16x32_bf16 v[2:5], v[230:233], v[214:217], v[2:5]
	v_mfma_f32_16x16x32_bf16 v[30:33], v[226:229], v[194:197], v[30:33]
	v_mfma_f32_16x16x32_bf16 v[26:29], v[234:237], v[194:197], v[26:29]
	v_mfma_f32_16x16x32_bf16 v[22:25], v[226:229], v[202:205], v[22:25]
	v_mfma_f32_16x16x32_bf16 v[18:21], v[234:237], v[202:205], v[18:21]
	v_mfma_f32_16x16x32_bf16 v[14:17], v[226:229], v[210:213], v[14:17]
	v_mfma_f32_16x16x32_bf16 v[10:13], v[234:237], v[210:213], v[10:13]
	v_mfma_f32_16x16x32_bf16 v[6:9], v[226:229], v[218:221], v[6:9]
	v_mfma_f32_16x16x32_bf16 v[2:5], v[234:237], v[218:221], v[2:5]
	s_barrier
	ds_read_b128 v[158:161], v149
	ds_read_b128 v[166:169], v149 offset:1024
	ds_read_b128 v[170:173], v149 offset:2048
	ds_read_b128 v[186:189], v149 offset:3072
	v_add_u32_e32 v176, 0x4000, v150
	v_lshl_add_u64 v[222:223], v[162:163], 0, s[76:77]
	v_readfirstlane_b32 s12, v176
	v_add_u32_e32 v176, 0x6000, v150
	s_mov_b32 m0, s12
	v_readfirstlane_b32 s12, v176
	ds_read_b128 v[190:193], v145 offset:32768
	ds_read_b128 v[194:197], v145 offset:33792
	ds_read_b128 v[198:201], v144 offset:32768
	ds_read_b128 v[202:205], v144 offset:33792
	ds_read_b128 v[206:209], v143 offset:32768
	ds_read_b128 v[210:213], v143 offset:33792
	ds_read_b128 v[214:217], v142 offset:32768
	ds_read_b128 v[218:221], v142 offset:33792
	global_load_lds_dwordx4 v[222:223], off
	v_lshl_add_u64 v[222:223], v[174:175], 0, s[76:77]
	s_mov_b32 m0, s12
	s_nop 0
	global_load_lds_dwordx4 v[222:223], off
	s_waitcnt lgkmcnt(8)
	s_barrier
	s_waitcnt lgkmcnt(0)
	v_mfma_f32_16x16x32_bf16 v[126:129], v[158:161], v[190:193], v[126:129]
	v_mfma_f32_16x16x32_bf16 v[122:125], v[170:173], v[190:193], v[122:125]
	v_mfma_f32_16x16x32_bf16 v[118:121], v[158:161], v[198:201], v[118:121]
	v_mfma_f32_16x16x32_bf16 v[114:117], v[170:173], v[198:201], v[114:117]
	v_mfma_f32_16x16x32_bf16 v[110:113], v[158:161], v[206:209], v[110:113]
	v_mfma_f32_16x16x32_bf16 v[106:109], v[170:173], v[206:209], v[106:109]
	v_mfma_f32_16x16x32_bf16 v[102:105], v[158:161], v[214:217], v[102:105]
	v_mfma_f32_16x16x32_bf16 v[98:101], v[170:173], v[214:217], v[98:101]
	v_mfma_f32_16x16x32_bf16 v[126:129], v[166:169], v[194:197], v[126:129]
	v_mfma_f32_16x16x32_bf16 v[122:125], v[186:189], v[194:197], v[122:125]
	v_mfma_f32_16x16x32_bf16 v[118:121], v[166:169], v[202:205], v[118:121]
	v_mfma_f32_16x16x32_bf16 v[114:117], v[186:189], v[202:205], v[114:117]
	v_mfma_f32_16x16x32_bf16 v[110:113], v[166:169], v[210:213], v[110:113]
	v_mfma_f32_16x16x32_bf16 v[106:109], v[186:189], v[210:213], v[106:109]
	v_mfma_f32_16x16x32_bf16 v[102:105], v[166:169], v[218:221], v[102:105]
	v_mfma_f32_16x16x32_bf16 v[98:101], v[186:189], v[218:221], v[98:101]
	s_barrier
	v_readfirstlane_b32 s12, v148
	v_add_u32_e32 v176, 0x2000, v148
	v_lshl_add_u64 v[240:241], v[182:183], 0, s[28:29]
	s_mov_b32 m0, s12
	v_readfirstlane_b32 s12, v176
	ds_read_b128 v[222:225], v147
	ds_read_b128 v[226:229], v147 offset:1024
	ds_read_b128 v[230:233], v147 offset:2048
	ds_read_b128 v[234:237], v147 offset:3072
	global_load_lds_dwordx4 v[240:241], off
	v_lshl_add_u64 v[240:241], v[238:239], 0, s[28:29]
	s_mov_b32 m0, s12
	s_nop 0
	global_load_lds_dwordx4 v[240:241], off
	s_barrier
	s_waitcnt lgkmcnt(0)
	v_mfma_f32_16x16x32_bf16 v[94:97], v[222:225], v[190:193], v[94:97]
	v_mfma_f32_16x16x32_bf16 v[90:93], v[230:233], v[190:193], v[90:93]
	v_mfma_f32_16x16x32_bf16 v[86:89], v[222:225], v[198:201], v[86:89]
	v_mfma_f32_16x16x32_bf16 v[82:85], v[230:233], v[198:201], v[82:85]
	v_readfirstlane_b32 s12, v151
	v_mfma_f32_16x16x32_bf16 v[78:81], v[222:225], v[206:209], v[78:81]
	v_lshl_add_u64 v[162:163], v[162:163], 0, s[74:75]
	v_mfma_f32_16x16x32_bf16 v[74:77], v[230:233], v[206:209], v[74:77]
	s_mov_b32 m0, s12
	v_mfma_f32_16x16x32_bf16 v[70:73], v[222:225], v[214:217], v[70:73]
	v_readfirstlane_b32 s12, v152
	v_mfma_f32_16x16x32_bf16 v[66:69], v[230:233], v[214:217], v[66:69]
	v_mfma_f32_16x16x32_bf16 v[94:97], v[226:229], v[194:197], v[94:97]
	v_mfma_f32_16x16x32_bf16 v[90:93], v[234:237], v[194:197], v[90:93]
	v_mfma_f32_16x16x32_bf16 v[86:89], v[226:229], v[202:205], v[86:89]
	v_mfma_f32_16x16x32_bf16 v[82:85], v[234:237], v[202:205], v[82:85]
	v_mfma_f32_16x16x32_bf16 v[78:81], v[226:229], v[210:213], v[78:81]
	v_mfma_f32_16x16x32_bf16 v[74:77], v[234:237], v[210:213], v[74:77]
	v_mfma_f32_16x16x32_bf16 v[70:73], v[226:229], v[218:221], v[70:73]
	v_mfma_f32_16x16x32_bf16 v[66:69], v[234:237], v[218:221], v[66:69]
	s_barrier
	ds_read_b128 v[190:193], v145 offset:49152
	ds_read_b128 v[194:197], v145 offset:50176
	ds_read_b128 v[198:201], v144 offset:49152
	ds_read_b128 v[202:205], v144 offset:50176
	ds_read_b128 v[206:209], v143 offset:49152
	ds_read_b128 v[210:213], v143 offset:50176
	ds_read_b128 v[214:217], v142 offset:49152
	ds_read_b128 v[218:221], v142 offset:50176
	global_load_lds_dwordx4 v[162:163], off
	v_lshl_add_u64 v[162:163], v[174:175], 0, s[74:75]
	s_mov_b32 m0, s12
	s_nop 0
	global_load_lds_dwordx4 v[162:163], off
	s_barrier
; #define STAGE_A(P,br,kt) STAGE_G(P,c.A,c.lda,br,(long)(kt)*c.kstr)
; #define STAGE_B(P,br,kt) STAGE_G(P,c.Bt,c.K,br,(long)(kt)*BK)
; #define LDA(dst,b,h) for(int m=0;m<4;++m)for(int k=0;k<2;++k) \
;     dst[m][k]=*reinterpret_cast<const bf16x8*>((char*)SA(b,h)+lds_byte(wr*64+m*16+fr,k*32+fq*8))
; #define LDB(dst,b,h) for(int n=0;n<2;++n)for(int k=0;k<2;++k) \
;     dst[n][k]=*reinterpret_cast<const bf16x8*>((char*)SB(b,h)+lds_byte(wc*32+n*16+fr,k*32+fq*8))
; #define MMA(ai,bj,At,Bt_) do{__builtin_amdgcn_s_setprio(1); \
;     for(int m=0;m<4;++m)for(int n=0;n<2;++n)for(int k=0;k<2;++k) \
;       acc[ai][bj][m][n]=__builtin_amdgcn_mfma_f32_16x16x32_bf16(Bt_[n][k],At[m][k],acc[ai][bj][m][n],0,0,0); \
;     __builtin_amdgcn_s_setprio(0);}while(0)
; #define WAIT_V(n) asm volatile("s_waitcnt vmcnt(" #n ")":::"memory")
; #define WAIT_L(n) asm volatile("s_waitcnt lgkmcnt(" #n ")":::"memory")
; #define BAR __builtin_amdgcn_s_barrier()
; #define SCHED __builtin_amdgcn_sched_barrier(0)
; template <int EPI>
; __device__ __forceinline__ void gemm_run(const GD& c, const bool has_next, const GD& nx, const Ctx& e, bf16* shm, float* rs, float* rs_nxt, float* racc_) {
;     ...
;     WAIT_V(6); BAR; MMA(1,1,At,B1); BAR;
;     LDB(B0,1,0); SCHED; LDA(At,1,0); STAGE_A(SA(0,1),brow+HALF,t+2);
;     WAIT_L(8); BAR; WAIT_L(0); MMA(0,0,At,B0); BAR; SCHED;
;     LDB(B1,1,1); STAGE_B(SB(1,0),bcol,t+3);
;     BAR; WAIT_L(0); MMA(0,1,At,B1); BAR;
;     LDA(At,1,1); STAGE_A(SA(1,0),brow,t+3);
;     BAR; WAIT_L(0); MMA(1,0,At,B0); BAR; SCHED;
;     STAGE_B(SB(1,1),bcol+HALF,t+3);
;     WAIT_V(6); BAR; MMA(1,1,At,B1); BAR;
;   }
;   { LDB(B0,0,0); LDA(At,0,0); STAGE_A(SA(1,1),brow+HALF,nt-1);
;     BAR; WAIT_L(0); MMA(0,0,At,B0); BAR;
;     LDB(B1,0,1); BAR; WAIT_L(0); MMA(0,1,At,B1); BAR;
;     LDA(At,0,1); WAIT_V(4); BAR; WAIT_L(0); MMA(1,0,At,B0); MMA(1,1,At,B1); BAR; }
	s_waitcnt lgkmcnt(0)
	v_mfma_f32_16x16x32_bf16 v[62:65], v[158:161], v[190:193], v[62:65]
	v_mfma_f32_16x16x32_bf16 v[58:61], v[170:173], v[190:193], v[58:61]
	v_mfma_f32_16x16x32_bf16 v[54:57], v[158:161], v[198:201], v[54:57]
	v_mfma_f32_16x16x32_bf16 v[50:53], v[170:173], v[198:201], v[50:53]
	v_mfma_f32_16x16x32_bf16 v[46:49], v[158:161], v[206:209], v[46:49]
	v_mfma_f32_16x16x32_bf16 v[42:45], v[170:173], v[206:209], v[42:45]
	v_mfma_f32_16x16x32_bf16 v[38:41], v[158:161], v[214:217], v[38:41]
	v_mfma_f32_16x16x32_bf16 v[34:37], v[170:173], v[214:217], v[34:37]
	v_mfma_f32_16x16x32_bf16 v[62:65], v[166:169], v[194:197], v[62:65]
	v_mfma_f32_16x16x32_bf16 v[58:61], v[186:189], v[194:197], v[58:61]
	v_mfma_f32_16x16x32_bf16 v[54:57], v[166:169], v[202:205], v[54:57]
	v_mfma_f32_16x16x32_bf16 v[50:53], v[186:189], v[202:205], v[50:53]
	v_mfma_f32_16x16x32_bf16 v[46:49], v[166:169], v[210:213], v[46:49]
	v_mfma_f32_16x16x32_bf16 v[42:45], v[186:189], v[210:213], v[42:45]
	v_mfma_f32_16x16x32_bf16 v[38:41], v[166:169], v[218:221], v[38:41]
	v_mfma_f32_16x16x32_bf16 v[34:37], v[186:189], v[218:221], v[34:37]
	s_barrier
	v_readfirstlane_b32 s12, v153
	v_add_u32_e32 v160, 0x2000, v153
	v_lshl_add_u64 v[158:159], v[182:183], 0, s[30:31]
	s_mov_b32 m0, s12
	v_readfirstlane_b32 s12, v160
	global_load_lds_dwordx4 v[158:159], off
	v_lshl_add_u64 v[158:159], v[238:239], 0, s[30:31]
	s_mov_b32 m0, s12
	s_nop 0
	global_load_lds_dwordx4 v[158:159], off
	s_waitcnt vmcnt(6)
	s_barrier
	v_mfma_f32_16x16x32_bf16 v[30:33], v[222:225], v[190:193], v[30:33]
	v_mfma_f32_16x16x32_bf16 v[26:29], v[230:233], v[190:193], v[26:29]
	v_mfma_f32_16x16x32_bf16 v[22:25], v[222:225], v[198:201], v[22:25]
	v_mfma_f32_16x16x32_bf16 v[18:21], v[230:233], v[198:201], v[18:21]
	v_lshl_add_u64 v[132:133], v[132:133], 0, s[88:89]
	v_mfma_f32_16x16x32_bf16 v[14:17], v[222:225], v[206:209], v[14:17]
	v_lshl_add_u64 v[134:135], v[134:135], 0, s[88:89]
	v_mfma_f32_16x16x32_bf16 v[10:13], v[230:233], v[206:209], v[10:13]
	v_lshl_add_u64 v[136:137], v[136:137], 0, s[88:89]
	v_mfma_f32_16x16x32_bf16 v[6:9], v[222:225], v[214:217], v[6:9]
	s_cmp_lt_u32 s11, s10
	v_mfma_f32_16x16x32_bf16 v[2:5], v[230:233], v[214:217], v[2:5]
	v_lshl_add_u64 v[138:139], v[138:139], 0, s[88:89]
	v_mfma_f32_16x16x32_bf16 v[30:33], v[226:229], v[194:197], v[30:33]
	v_mfma_f32_16x16x32_bf16 v[26:29], v[234:237], v[194:197], v[26:29]
	v_mfma_f32_16x16x32_bf16 v[22:25], v[226:229], v[202:205], v[22:25]
	v_mfma_f32_16x16x32_bf16 v[18:21], v[234:237], v[202:205], v[18:21]
	v_mfma_f32_16x16x32_bf16 v[14:17], v[226:229], v[210:213], v[14:17]
	v_mfma_f32_16x16x32_bf16 v[10:13], v[234:237], v[210:213], v[10:13]
	v_mfma_f32_16x16x32_bf16 v[6:9], v[226:229], v[218:221], v[6:9]
	v_mfma_f32_16x16x32_bf16 v[2:5], v[234:237], v[218:221], v[2:5]
	s_barrier
	s_cbranch_scc1 .LBB0_1505
	s_lshl_b32 s7, s7, 7
	s_add_u32 s2, s2, s7
	s_addc_u32 s3, s3, 0
	s_movk_i32 s8, 0xff80
	v_lshl_add_u64 v[162:163], s[2:3], 0, v[0:1]
	s_mov_b32 s9, -1
	v_readfirstlane_b32 s7, v156
	v_lshl_add_u64 v[162:163], v[162:163], 0, s[8:9]
	s_mov_b32 m0, s7
	v_lshl_add_u64 v[130:131], s[2:3], 0, v[130:131]
	v_readfirstlane_b32 s2, v157
	ds_read_b128 v[132:135], v155
	ds_read_b128 v[136:139], v155 offset:1024
	ds_read_b128 v[150:153], v155 offset:2048
	ds_read_b128 v[158:161], v155 offset:3072
	ds_read_b128 v[166:169], v145
	ds_read_b128 v[170:173], v145 offset:1024
	ds_read_b128 v[186:189], v144
	ds_read_b128 v[190:193], v144 offset:1024
	ds_read_b128 v[194:197], v143
	ds_read_b128 v[198:201], v143 offset:1024
	ds_read_b128 v[202:205], v142
	ds_read_b128 v[206:209], v142 offset:1024
	global_load_lds_dwordx4 v[162:163], off
	v_lshl_add_u64 v[130:131], v[130:131], 0, s[8:9]
	s_mov_b32 m0, s2
	s_nop 0
	global_load_lds_dwordx4 v[130:131], off
	s_barrier
	s_waitcnt lgkmcnt(0)
	v_mfma_f32_16x16x32_bf16 v[126:129], v[132:135], v[166:169], v[126:129]
	v_mfma_f32_16x16x32_bf16 v[122:125], v[150:153], v[166:169], v[122:125]
	v_mfma_f32_16x16x32_bf16 v[118:121], v[132:135], v[186:189], v[118:121]
	v_mfma_f32_16x16x32_bf16 v[114:117], v[150:153], v[186:189], v[114:117]
	v_mfma_f32_16x16x32_bf16 v[110:113], v[132:135], v[194:197], v[110:113]
	v_mfma_f32_16x16x32_bf16 v[106:109], v[150:153], v[194:197], v[106:109]
	v_mfma_f32_16x16x32_bf16 v[102:105], v[132:135], v[202:205], v[102:105]
	v_mfma_f32_16x16x32_bf16 v[98:101], v[150:153], v[202:205], v[98:101]
	v_mfma_f32_16x16x32_bf16 v[126:129], v[136:139], v[170:173], v[126:129]
	v_mfma_f32_16x16x32_bf16 v[122:125], v[158:161], v[170:173], v[122:125]
	v_mfma_f32_16x16x32_bf16 v[118:121], v[136:139], v[190:193], v[118:121]
	v_mfma_f32_16x16x32_bf16 v[114:117], v[158:161], v[190:193], v[114:117]
	v_mfma_f32_16x16x32_bf16 v[110:113], v[136:139], v[198:201], v[110:113]
	v_mfma_f32_16x16x32_bf16 v[106:109], v[158:161], v[198:201], v[106:109]
	v_mfma_f32_16x16x32_bf16 v[102:105], v[136:139], v[206:209], v[102:105]
	v_mfma_f32_16x16x32_bf16 v[98:101], v[158:161], v[206:209], v[98:101]
	s_barrier
	ds_read_b128 v[210:213], v154
	ds_read_b128 v[214:217], v154 offset:1024
	ds_read_b128 v[218:221], v154 offset:2048
	ds_read_b128 v[154:157], v154 offset:3072
	s_barrier
; #define LDA(dst,b,h) for(int m=0;m<4;++m)for(int k=0;k<2;++k) \
;     dst[m][k]=*reinterpret_cast<const bf16x8*>((char*)SA(b,h)+lds_byte(wr*64+m*16+fr,k*32+fq*8))
; #define LDB(dst,b,h) for(int n=0;n<2;++n)for(int k=0;k<2;++k) \
;     dst[n][k]=*reinterpret_cast<const bf16x8*>((char*)SB(b,h)+lds_byte(wc*32+n*16+fr,k*32+fq*8))
; #define MMA(ai,bj,At,Bt_) do{__builtin_amdgcn_s_setprio(1); \
;     for(int m=0;m<4;++m)for(int n=0;n<2;++n)for(int k=0;k<2;++k) \
;       acc[ai][bj][m][n]=__builtin_amdgcn_mfma_f32_16x16x32_bf16(Bt_[n][k],At[m][k],acc[ai][bj][m][n],0,0,0); \
;     __builtin_amdgcn_s_setprio(0);}while(0)
; #define WAIT_V(n) asm volatile("s_waitcnt vmcnt(" #n ")":::"memory")
; #define WAIT_L(n) asm volatile("s_waitcnt lgkmcnt(" #n ")":::"memory")
; #define BAR __builtin_amdgcn_s_barrier()
; template <int EPI>
; __device__ __forceinline__ void gemm_run(const GD& c, const bool has_next, const GD& nx, const Ctx& e, bf16* shm, float* rs, float* rs_nxt, float* racc_) {
;     ...
;     BAR; WAIT_L(0); MMA(0,0,At,B0); BAR;
;     LDB(B1,0,1); BAR; WAIT_L(0); MMA(0,1,At,B1); BAR;
;     LDA(At,0,1); WAIT_V(4); BAR; WAIT_L(0); MMA(1,0,At,B0); MMA(1,1,At,B1); BAR; }
;   { LDB(B0,1,0); LDA(At,1,0); WAIT_V(2); BAR; WAIT_L(0); MMA(0,0,At,B0); BAR;
;     LDB(B1,1,1); WAIT_V(0); BAR; WAIT_L(0); MMA(0,1,At,B1); BAR;
;     LDA(At,1,1); BAR; WAIT_L(0); MMA(1,0,At,B0); MMA(1,1,At,B1); BAR; }
	s_waitcnt lgkmcnt(0)
	v_mfma_f32_16x16x32_bf16 v[94:97], v[210:213], v[166:169], v[94:97]
	v_mfma_f32_16x16x32_bf16 v[90:93], v[218:221], v[166:169], v[90:93]
	v_mfma_f32_16x16x32_bf16 v[86:89], v[210:213], v[186:189], v[86:89]
	v_mfma_f32_16x16x32_bf16 v[82:85], v[218:221], v[186:189], v[82:85]
	v_mfma_f32_16x16x32_bf16 v[74:77], v[218:221], v[194:197], v[74:77]
	v_mfma_f32_16x16x32_bf16 v[70:73], v[210:213], v[202:205], v[70:73]
	v_mfma_f32_16x16x32_bf16 v[94:97], v[214:217], v[170:173], v[94:97]
	v_mfma_f32_16x16x32_bf16 v[90:93], v[154:157], v[170:173], v[90:93]
	v_mfma_f32_16x16x32_bf16 v[86:89], v[214:217], v[190:193], v[86:89]
	v_mfma_f32_16x16x32_bf16 v[82:85], v[154:157], v[190:193], v[82:85]
	v_mfma_f32_16x16x32_bf16 v[78:81], v[210:213], v[194:197], v[78:81]
	v_mfma_f32_16x16x32_bf16 v[74:77], v[154:157], v[198:201], v[74:77]
	v_mfma_f32_16x16x32_bf16 v[70:73], v[214:217], v[206:209], v[70:73]
	v_mfma_f32_16x16x32_bf16 v[66:69], v[218:221], v[202:205], v[66:69]
	v_mfma_f32_16x16x32_bf16 v[166:169], v[214:217], v[198:201], v[78:81]
	v_mfma_f32_16x16x32_bf16 v[170:173], v[154:157], v[206:209], v[66:69]
	s_barrier
	s_nop 3
	ds_read_b128 v[66:69], v145 offset:16384
	ds_read_b128 v[78:81], v145 offset:17408
	ds_read_b128 v[186:189], v144 offset:16384
	ds_read_b128 v[190:193], v144 offset:17408
	ds_read_b128 v[194:197], v143 offset:16384
	ds_read_b128 v[198:201], v143 offset:17408
	ds_read_b128 v[202:205], v142 offset:16384
	ds_read_b128 v[206:209], v142 offset:17408
	s_waitcnt vmcnt(4)
	s_barrier
	s_waitcnt lgkmcnt(0)
	v_mfma_f32_16x16x32_bf16 v[62:65], v[132:135], v[66:69], v[62:65]
	v_mfma_f32_16x16x32_bf16 v[54:57], v[132:135], v[186:189], v[54:57]
	v_mfma_f32_16x16x32_bf16 v[46:49], v[132:135], v[194:197], v[46:49]
	v_mfma_f32_16x16x32_bf16 v[38:41], v[132:135], v[202:205], v[38:41]
	v_mfma_f32_16x16x32_bf16 v[62:65], v[136:139], v[78:81], v[62:65]
	v_mfma_f32_16x16x32_bf16 v[58:61], v[150:153], v[66:69], v[58:61]
	v_mfma_f32_16x16x32_bf16 v[54:57], v[136:139], v[190:193], v[54:57]
	v_mfma_f32_16x16x32_bf16 v[50:53], v[150:153], v[186:189], v[50:53]
	v_mfma_f32_16x16x32_bf16 v[46:49], v[136:139], v[198:201], v[46:49]
	v_mfma_f32_16x16x32_bf16 v[42:45], v[150:153], v[194:197], v[42:45]
	v_mfma_f32_16x16x32_bf16 v[38:41], v[136:139], v[206:209], v[38:41]
	v_mfma_f32_16x16x32_bf16 v[34:37], v[150:153], v[202:205], v[34:37]
	v_mfma_f32_16x16x32_bf16 v[222:225], v[158:161], v[78:81], v[58:61]
	v_mfma_f32_16x16x32_bf16 v[226:229], v[158:161], v[190:193], v[50:53]
	v_mfma_f32_16x16x32_bf16 v[230:233], v[158:161], v[198:201], v[42:45]
	v_mfma_f32_16x16x32_bf16 v[130:133], v[158:161], v[206:209], v[34:37]
	v_mfma_f32_16x16x32_bf16 v[30:33], v[210:213], v[66:69], v[30:33]
	v_mfma_f32_16x16x32_bf16 v[26:29], v[218:221], v[66:69], v[26:29]
	v_mfma_f32_16x16x32_bf16 v[22:25], v[210:213], v[186:189], v[22:25]
	v_mfma_f32_16x16x32_bf16 v[18:21], v[218:221], v[186:189], v[18:21]
	v_mfma_f32_16x16x32_bf16 v[14:17], v[210:213], v[194:197], v[14:17]
	v_mfma_f32_16x16x32_bf16 v[10:13], v[218:221], v[194:197], v[10:13]
	v_mfma_f32_16x16x32_bf16 v[6:9], v[210:213], v[202:205], v[6:9]
	v_mfma_f32_16x16x32_bf16 v[2:5], v[218:221], v[202:205], v[2:5]
	v_mfma_f32_16x16x32_bf16 v[134:137], v[214:217], v[78:81], v[30:33]
	v_mfma_f32_16x16x32_bf16 v[150:153], v[154:157], v[78:81], v[26:29]
	v_mfma_f32_16x16x32_bf16 v[158:161], v[214:217], v[190:193], v[22:25]
	v_mfma_f32_16x16x32_bf16 v[186:189], v[154:157], v[190:193], v[18:21]
	v_mfma_f32_16x16x32_bf16 v[190:193], v[214:217], v[198:201], v[14:17]
	v_mfma_f32_16x16x32_bf16 v[194:197], v[154:157], v[198:201], v[10:13]
	v_mfma_f32_16x16x32_bf16 v[198:201], v[214:217], v[206:209], v[6:9]
	v_mfma_f32_16x16x32_bf16 v[154:157], v[154:157], v[206:209], v[2:5]
	s_barrier
	ds_read_b128 v[34:37], v149
	ds_read_b128 v[202:205], v149 offset:1024
	ds_read_b128 v[206:209], v149 offset:2048
	ds_read_b128 v[210:213], v149 offset:3072
	ds_read_b128 v[42:45], v145 offset:32768
	ds_read_b128 v[50:53], v145 offset:33792
	ds_read_b128 v[58:61], v144 offset:32768
	ds_read_b128 v[66:69], v144 offset:33792
	ds_read_b128 v[214:217], v143 offset:32768
	ds_read_b128 v[218:221], v143 offset:33792
	ds_read_b128 v[234:237], v142 offset:32768
	ds_read_b128 v[238:241], v142 offset:33792
	s_waitcnt vmcnt(2)
	s_barrier
; #define LDA(dst,b,h) for(int m=0;m<4;++m)for(int k=0;k<2;++k) \
;     dst[m][k]=*reinterpret_cast<const bf16x8*>((char*)SA(b,h)+lds_byte(wr*64+m*16+fr,k*32+fq*8))
; #define LDB(dst,b,h) for(int n=0;n<2;++n)for(int k=0;k<2;++k) \
;     dst[n][k]=*reinterpret_cast<const bf16x8*>((char*)SB(b,h)+lds_byte(wc*32+n*16+fr,k*32+fq*8))
; #define MMA(ai,bj,At,Bt_) do{__builtin_amdgcn_s_setprio(1); \
;     for(int m=0;m<4;++m)for(int n=0;n<2;++n)for(int k=0;k<2;++k) \
;       acc[ai][bj][m][n]=__builtin_amdgcn_mfma_f32_16x16x32_bf16(Bt_[n][k],At[m][k],acc[ai][bj][m][n],0,0,0); \
;     __builtin_amdgcn_s_setprio(0);}while(0)
; #define WAIT_V(n) asm volatile("s_waitcnt vmcnt(" #n ")":::"memory")
; #define WAIT_L(n) asm volatile("s_waitcnt lgkmcnt(" #n ")":::"memory")
; #define BAR __builtin_amdgcn_s_barrier()
; template <int EPI>
; __device__ __forceinline__ void gemm_run(const GD& c, const bool has_next, const GD& nx, const Ctx& e, bf16* shm, float* rs, float* rs_nxt, float* racc_) {
;     ...
;     LDA(At,0,1); WAIT_V(4); BAR; WAIT_L(0); MMA(1,0,At,B0); MMA(1,1,At,B1); BAR; }
;   { LDB(B0,1,0); LDA(At,1,0); WAIT_V(2); BAR; WAIT_L(0); MMA(0,0,At,B0); BAR;
;     LDB(B1,1,1); WAIT_V(0); BAR; WAIT_L(0); MMA(0,1,At,B1); BAR;
;     LDA(At,1,1); BAR; WAIT_L(0); MMA(1,0,At,B0); MMA(1,1,At,B1); BAR; }
;   if(wr==0)BAR;
	s_waitcnt lgkmcnt(0)
	v_mfma_f32_16x16x32_bf16 v[2:5], v[34:37], v[42:45], v[126:129]
	v_mfma_f32_16x16x32_bf16 v[26:29], v[202:205], v[50:53], v[2:5]
	v_mfma_f32_16x16x32_bf16 v[2:5], v[206:209], v[42:45], v[122:125]
	v_mfma_f32_16x16x32_bf16 v[30:33], v[210:213], v[50:53], v[2:5]
	v_mfma_f32_16x16x32_bf16 v[2:5], v[34:37], v[58:61], v[118:121]
	v_mfma_f32_16x16x32_bf16 v[18:21], v[202:205], v[66:69], v[2:5]
	v_mfma_f32_16x16x32_bf16 v[2:5], v[206:209], v[58:61], v[114:117]
	v_mfma_f32_16x16x32_bf16 v[22:25], v[210:213], v[66:69], v[2:5]
	v_mfma_f32_16x16x32_bf16 v[2:5], v[34:37], v[214:217], v[110:113]
	v_mfma_f32_16x16x32_bf16 v[10:13], v[202:205], v[218:221], v[2:5]
	v_mfma_f32_16x16x32_bf16 v[2:5], v[206:209], v[214:217], v[106:109]
	v_mfma_f32_16x16x32_bf16 v[14:17], v[210:213], v[218:221], v[2:5]
	v_mfma_f32_16x16x32_bf16 v[2:5], v[34:37], v[234:237], v[102:105]
	v_mfma_f32_16x16x32_bf16 v[6:9], v[206:209], v[234:237], v[98:101]
	v_mfma_f32_16x16x32_bf16 v[2:5], v[202:205], v[238:241], v[2:5]
	v_mfma_f32_16x16x32_bf16 v[6:9], v[210:213], v[238:241], v[6:9]
	s_barrier
	ds_read_b128 v[242:245], v147
	ds_read_b128 v[246:249], v147 offset:1024
	ds_read_b128 v[250:253], v147 offset:2048
	ds_read_b128 v[146:149], v147 offset:3072
	s_waitcnt vmcnt(0)
	s_barrier
	s_waitcnt lgkmcnt(0)
	v_mfma_f32_16x16x32_bf16 v[78:81], v[242:245], v[42:45], v[94:97]
	v_mfma_f32_16x16x32_bf16 v[42:45], v[250:253], v[42:45], v[90:93]
	v_mfma_f32_16x16x32_bf16 v[102:105], v[146:149], v[50:53], v[42:45]
	v_mfma_f32_16x16x32_bf16 v[42:45], v[242:245], v[58:61], v[86:89]
	v_mfma_f32_16x16x32_bf16 v[98:101], v[246:249], v[50:53], v[78:81]
	v_mfma_f32_16x16x32_bf16 v[78:81], v[246:249], v[66:69], v[42:45]
	v_mfma_f32_16x16x32_bf16 v[42:45], v[250:253], v[58:61], v[82:85]
	v_mfma_f32_16x16x32_bf16 v[86:89], v[146:149], v[66:69], v[42:45]
	v_mfma_f32_16x16x32_bf16 v[42:45], v[242:245], v[214:217], v[166:169]
	v_mfma_f32_16x16x32_bf16 v[58:61], v[246:249], v[218:221], v[42:45]
	v_mfma_f32_16x16x32_bf16 v[42:45], v[250:253], v[214:217], v[74:77]
	v_mfma_f32_16x16x32_bf16 v[66:69], v[146:149], v[218:221], v[42:45]
	v_mfma_f32_16x16x32_bf16 v[42:45], v[242:245], v[234:237], v[70:73]
	v_mfma_f32_16x16x32_bf16 v[50:53], v[250:253], v[234:237], v[170:173]
	v_mfma_f32_16x16x32_bf16 v[42:45], v[246:249], v[238:241], v[42:45]
	v_mfma_f32_16x16x32_bf16 v[50:53], v[146:149], v[238:241], v[50:53]
	s_barrier
	ds_read_b128 v[74:77], v145 offset:49152
	ds_read_b128 v[94:97], v145 offset:50176
	ds_read_b128 v[106:109], v144 offset:49152
	ds_read_b128 v[110:113], v144 offset:50176
	ds_read_b128 v[166:169], v143 offset:49152
	ds_read_b128 v[170:173], v143 offset:50176
	ds_read_b128 v[214:217], v142 offset:49152
	ds_read_b128 v[142:145], v142 offset:50176
	s_barrier
	s_waitcnt lgkmcnt(0)
	v_mfma_f32_16x16x32_bf16 v[62:65], v[34:37], v[74:77], v[62:65]
	v_mfma_f32_16x16x32_bf16 v[82:85], v[202:205], v[94:97], v[62:65]
	v_mfma_f32_16x16x32_bf16 v[62:65], v[206:209], v[74:77], v[222:225]
	v_mfma_f32_16x16x32_bf16 v[54:57], v[34:37], v[106:109], v[54:57]
	v_mfma_f32_16x16x32_bf16 v[90:93], v[210:213], v[94:97], v[62:65]
	v_mfma_f32_16x16x32_bf16 v[62:65], v[202:205], v[110:113], v[54:57]
	v_mfma_f32_16x16x32_bf16 v[54:57], v[206:209], v[106:109], v[226:229]
	v_mfma_f32_16x16x32_bf16 v[70:73], v[210:213], v[110:113], v[54:57]
	v_mfma_f32_16x16x32_bf16 v[46:49], v[34:37], v[166:169], v[46:49]
	v_mfma_f32_16x16x32_bf16 v[54:57], v[206:209], v[166:169], v[230:233]
	v_mfma_f32_16x16x32_bf16 v[34:37], v[34:37], v[214:217], v[38:41]
	v_mfma_f32_16x16x32_bf16 v[38:41], v[206:209], v[214:217], v[130:133]
	v_mfma_f32_16x16x32_bf16 v[46:49], v[202:205], v[170:173], v[46:49]
	v_mfma_f32_16x16x32_bf16 v[54:57], v[210:213], v[170:173], v[54:57]
	v_mfma_f32_16x16x32_bf16 v[34:37], v[202:205], v[142:145], v[34:37]
	v_mfma_f32_16x16x32_bf16 v[38:41], v[210:213], v[142:145], v[38:41]
	v_mfma_f32_16x16x32_bf16 v[114:117], v[242:245], v[74:77], v[134:137]
	v_mfma_f32_16x16x32_bf16 v[74:77], v[250:253], v[74:77], v[150:153]
	v_mfma_f32_16x16x32_bf16 v[126:129], v[146:149], v[94:97], v[74:77]
	v_mfma_f32_16x16x32_bf16 v[74:77], v[242:245], v[106:109], v[158:161]
	v_mfma_f32_16x16x32_bf16 v[122:125], v[246:249], v[94:97], v[114:117]
	v_mfma_f32_16x16x32_bf16 v[114:117], v[246:249], v[110:113], v[74:77]
	v_mfma_f32_16x16x32_bf16 v[74:77], v[250:253], v[106:109], v[186:189]
	v_mfma_f32_16x16x32_bf16 v[118:121], v[146:149], v[110:113], v[74:77]
	v_mfma_f32_16x16x32_bf16 v[74:77], v[242:245], v[166:169], v[190:193]
	v_mfma_f32_16x16x32_bf16 v[106:109], v[246:249], v[170:173], v[74:77]
	v_mfma_f32_16x16x32_bf16 v[74:77], v[250:253], v[166:169], v[194:197]
	v_mfma_f32_16x16x32_bf16 v[110:113], v[146:149], v[170:173], v[74:77]
	v_mfma_f32_16x16x32_bf16 v[74:77], v[242:245], v[214:217], v[198:201]
	v_mfma_f32_16x16x32_bf16 v[94:97], v[246:249], v[142:145], v[74:77]
	v_mfma_f32_16x16x32_bf16 v[74:77], v[250:253], v[214:217], v[154:157]
	v_mfma_f32_16x16x32_bf16 v[74:77], v[146:149], v[142:145], v[74:77]
	v_cmp_gt_u32_e32 vcc, s96, v141
	s_barrier
	s_and_saveexec_b64 s[2:3], vcc
	s_cbranch_execz .LBB0_1501
	s_barrier
	s_branch .LBB0_1501
